# last MFMA segment of every GEMM loop body issues its two embedded LDS-DMA groups after MFMA 2 and 6 (was 14 and 30) so tile epilogues wait less behind them
# speedup vs baseline: 1.0012x; 1.0012x over previous
; #define PG8_STAGE(bufoff, gbase, voff) do { _Pragma("unroll") for (int _i = 0; _i < 2; ++_i) \
;         __builtin_amdgcn_global_load_lds((const unsigned*)((const char*)(gbase) + (voff)[_i]), (PG8_LAS unsigned*)(lds + (bufoff) + ldsw + _i * 8192), 16, 0, 0); } while (0)
; #define PG8_LDA(dst, b, h) do { _Pragma("unroll") for (int m = 0; m < 4; ++m) _Pragma("unroll") for (int k = 0; k < 2; ++k) dst[m][k] = *(const PG8_LAS bf16x8*)(lds + PG8_SA(b, h) + aoff + m * 2048 + k * 1024); } while (0)
; #define PG8_LDB(dst, b, h) do { _Pragma("unroll") for (int n = 0; n < 2; ++n) _Pragma("unroll") for (int k = 0; k < 2; ++k) dst[n][k] = *(const PG8_LAS bf16x8*)(lds + PG8_SB(b, h) + boff + n * 2048 + k * 1024); } while (0)
; #define PG8_MMA(ai, bj, At, Bt) do { __builtin_amdgcn_s_setprio(1); _Pragma("unroll") for (int m = 0; m < 4; ++m) _Pragma("unroll") for (int n = 0; n < 2; ++n) _Pragma("unroll") for (int k = 0; k < 2; ++k) \
;         acc[ai][bj][m][n] = __builtin_amdgcn_mfma_f32_16x16x32_bf16(Bt[n][k], At[m][k], acc[ai][bj][m][n], 0, 0, 0); __builtin_amdgcn_s_setprio(0); } while (0)
; #define PG8_WAIT_V(n) asm volatile("s_waitcnt vmcnt(" #n ")" ::: "memory")
; #define PG8_WAIT_L(n) asm volatile("s_waitcnt lgkmcnt(" #n ")" ::: "memory")
; #define PG8_BAR __builtin_amdgcn_s_barrier()
; #define PG8_SCHED __builtin_amdgcn_sched_barrier(0)
; template <class Epi, class Sched, bool ALIGN_EPI = false, bool SP2 = false>
; __device__ __forceinline__ void gemm_phase(PG8_LAS unsigned char* lds, const Gemm g, const Sched& S, const Epi& E) {
;     ...
;         for (int t = 0; t < nt; t += 2) {
;             const bool last = (t == nt - 2);
;             const char* a1 = cA + (size_t)(t + 1) * kstep;
;             const char* a2 = last ? nA : cA + (size_t)(t + 2) * kstep; const char* b2 = last ? nB : cB + (size_t)(t + 2) * kstep;
;             const char* a3 = a2 + kstep; const char* b3 = b2 + kstep;
;             if (last && has_next) S.a_ready(nxt);
;             if constexpr (SP2) {
;             PG8_LDB(B0, 0, 0); PG8_LDB(B1, 0, 1); PG8_SCHED; PG8_LDA(At, 0, 0); PG8_STAGE(PG8_SA(1, 1), a1 + hstep, voffA);
;             PG8_WAIT_V(8); PG8_WAIT_L(0); PG8_BAR; PG8_MMA(0, 0, At, B0); PG8_MMA(0, 1, At, B1); PG8_BAR; PG8_SCHED;
;             PG8_LDA(At, 0, 1); PG8_STAGE(PG8_SB(0, 0), b2, voffB); PG8_STAGE(PG8_SB(0, 1), b2 + hstep, voffB); PG8_STAGE(PG8_SA(0, 0), a2, voffA);
.LBB0_191:
	ds_read_b128 v[144:147], v155
	ds_read_b128 v[148:151], v155 offset:1024
	ds_read_b128 v[160:163], v155 offset:2048
	ds_read_b128 v[168:171], v155 offset:3072
	ds_read_b128 v[172:175], v156
	ds_read_b128 v[176:179], v156 offset:1024
	ds_read_b128 v[182:185], v156 offset:2048
	ds_read_b128 v[186:189], v156 offset:3072
	s_add_u32 s3, s48, 0xfffc0080
	s_addc_u32 s14, s49, -1
	s_cmp_eq_u32 s89, 12
	s_cselect_b32 s55, s27, s14
	s_cselect_b32 s54, s67, s3
	s_cselect_b32 s51, s25, s88
	s_cselect_b32 s50, s86, s87
	v_lshl_add_u64 v[164:165], s[48:49], 0, v[136:137]
	s_add_i32 m0, s45, 0xc000
	ds_read_b128 v[190:193], v157
	ds_read_b128 v[194:197], v157 offset:1024
	ds_read_b128 v[198:201], v157 offset:2048
	ds_read_b128 v[208:211], v157 offset:3072
	ds_read_b128 v[212:215], v157 offset:4096
	ds_read_b128 v[216:219], v157 offset:5120
	ds_read_b128 v[220:223], v157 offset:6144
	ds_read_b128 v[224:227], v157 offset:7168
	global_load_lds_dwordx4 v[164:165], off
	v_lshl_add_u64 v[164:165], s[48:49], 0, v[138:139]
	s_add_i32 m0, s45, 0xe000
	s_nop 0
	global_load_lds_dwordx4 v[164:165], off
	s_waitcnt vmcnt(8)
	s_waitcnt lgkmcnt(0)
	s_barrier
	s_setprio 1
	s_waitcnt lgkmcnt(0)
	v_mfma_f32_16x16x32_bf16 v[124:127], v[144:147], v[190:193], v[124:127]
	v_mfma_f32_16x16x32_bf16 v[120:123], v[160:163], v[190:193], v[120:123]
	v_mfma_f32_16x16x32_bf16 v[108:111], v[144:147], v[198:201], v[108:111]
	v_mfma_f32_16x16x32_bf16 v[104:107], v[160:163], v[198:201], v[104:107]
	v_mfma_f32_16x16x32_bf16 v[92:95], v[144:147], v[212:215], v[92:95]
	v_mfma_f32_16x16x32_bf16 v[88:91], v[160:163], v[212:215], v[88:91]
	v_mfma_f32_16x16x32_bf16 v[76:79], v[144:147], v[220:223], v[76:79]
	v_mfma_f32_16x16x32_bf16 v[72:75], v[160:163], v[220:223], v[72:75]
	v_mfma_f32_16x16x32_bf16 v[124:127], v[148:151], v[194:197], v[124:127]
	v_mfma_f32_16x16x32_bf16 v[120:123], v[168:171], v[194:197], v[120:123]
	v_mfma_f32_16x16x32_bf16 v[108:111], v[148:151], v[208:211], v[108:111]
	v_mfma_f32_16x16x32_bf16 v[104:107], v[168:171], v[208:211], v[104:107]
	v_mfma_f32_16x16x32_bf16 v[92:95], v[148:151], v[216:219], v[92:95]
	v_mfma_f32_16x16x32_bf16 v[88:91], v[168:171], v[216:219], v[88:91]
	v_mfma_f32_16x16x32_bf16 v[76:79], v[148:151], v[224:227], v[76:79]
	v_mfma_f32_16x16x32_bf16 v[72:75], v[168:171], v[224:227], v[72:75]
	s_setprio 0
	s_setprio 1
	v_mfma_f32_16x16x32_bf16 v[116:119], v[172:175], v[190:193], v[116:119]
	v_mfma_f32_16x16x32_bf16 v[112:115], v[182:185], v[190:193], v[112:115]
	v_mfma_f32_16x16x32_bf16 v[100:103], v[172:175], v[198:201], v[100:103]
	v_mfma_f32_16x16x32_bf16 v[96:99], v[182:185], v[198:201], v[96:99]
	v_mfma_f32_16x16x32_bf16 v[84:87], v[172:175], v[212:215], v[84:87]
	v_mfma_f32_16x16x32_bf16 v[80:83], v[182:185], v[212:215], v[80:83]
	v_mfma_f32_16x16x32_bf16 v[68:71], v[172:175], v[220:223], v[68:71]
	v_mfma_f32_16x16x32_bf16 v[64:67], v[182:185], v[220:223], v[64:67]
	v_mfma_f32_16x16x32_bf16 v[116:119], v[176:179], v[194:197], v[116:119]
	v_mfma_f32_16x16x32_bf16 v[112:115], v[186:189], v[194:197], v[112:115]
	v_mfma_f32_16x16x32_bf16 v[100:103], v[176:179], v[208:211], v[100:103]
	v_mfma_f32_16x16x32_bf16 v[96:99], v[186:189], v[208:211], v[96:99]
	v_mfma_f32_16x16x32_bf16 v[84:87], v[176:179], v[216:219], v[84:87]
	v_mfma_f32_16x16x32_bf16 v[80:83], v[186:189], v[216:219], v[80:83]
	v_mfma_f32_16x16x32_bf16 v[68:71], v[176:179], v[224:227], v[68:71]
	v_mfma_f32_16x16x32_bf16 v[64:67], v[186:189], v[224:227], v[64:67]
	s_setprio 0
	s_barrier
	s_add_i32 s3, s63, s43
	v_lshl_add_u64 v[164:165], s[50:51], 0, v[132:133]
	s_mov_b32 m0, s3
	ds_read_b128 v[190:193], v157 offset:16384
	ds_read_b128 v[194:197], v157 offset:17408
	ds_read_b128 v[198:201], v157 offset:18432
	ds_read_b128 v[208:211], v157 offset:19456
	ds_read_b128 v[212:215], v157 offset:20480
	ds_read_b128 v[216:219], v157 offset:21504
	ds_read_b128 v[220:223], v157 offset:22528
	ds_read_b128 v[224:227], v157 offset:23552
	global_load_lds_dwordx4 v[164:165], off
	s_add_i32 m0, s3, 0x2000
	s_add_u32 s14, s50, 0x40000
	v_lshl_add_u64 v[202:203], s[50:51], 0, v[128:129]
	s_addc_u32 s15, s51, 0
	s_add_i32 s3, s64, s43
	global_load_lds_dwordx4 v[202:203], off
	v_lshl_add_u64 v[228:229], s[14:15], 0, v[132:133]
	s_mov_b32 m0, s3
	global_load_lds_dwordx4 v[228:229], off
	v_lshl_add_u64 v[228:229], s[14:15], 0, v[128:129]
	s_add_i32 m0, s3, 0x2000
	s_nop 0
	global_load_lds_dwordx4 v[228:229], off
	s_waitcnt vmcnt(6)
	s_waitcnt lgkmcnt(0)
	s_barrier
; #define PG8_STAGE(bufoff, gbase, voff) do { _Pragma("unroll") for (int _i = 0; _i < 2; ++_i) \
;         __builtin_amdgcn_global_load_lds((const unsigned*)((const char*)(gbase) + (voff)[_i]), (PG8_LAS unsigned*)(lds + (bufoff) + ldsw + _i * 8192), 16, 0, 0); } while (0)
; #define PG8_LDA(dst, b, h) do { _Pragma("unroll") for (int m = 0; m < 4; ++m) _Pragma("unroll") for (int k = 0; k < 2; ++k) dst[m][k] = *(const PG8_LAS bf16x8*)(lds + PG8_SA(b, h) + aoff + m * 2048 + k * 1024); } while (0)
; #define PG8_LDB(dst, b, h) do { _Pragma("unroll") for (int n = 0; n < 2; ++n) _Pragma("unroll") for (int k = 0; k < 2; ++k) dst[n][k] = *(const PG8_LAS bf16x8*)(lds + PG8_SB(b, h) + boff + n * 2048 + k * 1024); } while (0)
; #define PG8_MMA(ai, bj, At, Bt) do { __builtin_amdgcn_s_setprio(1); _Pragma("unroll") for (int m = 0; m < 4; ++m) _Pragma("unroll") for (int n = 0; n < 2; ++n) _Pragma("unroll") for (int k = 0; k < 2; ++k) \
;         acc[ai][bj][m][n] = __builtin_amdgcn_mfma_f32_16x16x32_bf16(Bt[n][k], At[m][k], acc[ai][bj][m][n], 0, 0, 0); __builtin_amdgcn_s_setprio(0); } while (0)
; #define PG8_WAIT_V(n) asm volatile("s_waitcnt vmcnt(" #n ")" ::: "memory")
; #define PG8_WAIT_L(n) asm volatile("s_waitcnt lgkmcnt(" #n ")" ::: "memory")
; #define PG8_BAR __builtin_amdgcn_s_barrier()
; #define PG8_SCHED __builtin_amdgcn_sched_barrier(0)
; template <class Epi, class Sched, bool ALIGN_EPI = false, bool SP2 = false>
; __device__ __forceinline__ void gemm_phase(PG8_LAS unsigned char* lds, const Gemm g, const Sched& S, const Epi& E) {
;     ...
;             PG8_LDA(At, 0, 1); PG8_STAGE(PG8_SB(0, 0), b2, voffB); PG8_STAGE(PG8_SB(0, 1), b2 + hstep, voffB); PG8_STAGE(PG8_SA(0, 0), a2, voffA);
;             PG8_WAIT_V(8); PG8_WAIT_L(0); PG8_BAR; PG8_MMA(1, 0, At, B0); PG8_MMA(1, 1, At, B1); PG8_BAR; PG8_SCHED;
;             PG8_LDB(B0, 1, 0); PG8_LDB(B1, 1, 1); PG8_SCHED; PG8_LDA(At, 1, 0); PG8_STAGE(PG8_SA(0, 1), a2 + hstep, voffA);
;             PG8_WAIT_V(8); PG8_WAIT_L(0); PG8_BAR; PG8_MMA(0, 0, At, B0); PG8_MMA(0, 1, At, B1); PG8_BAR; PG8_SCHED;
	s_setprio 1
	s_waitcnt lgkmcnt(0)
	v_mfma_f32_16x16x32_bf16 v[60:63], v[144:147], v[190:193], v[60:63]
	v_mfma_f32_16x16x32_bf16 v[56:59], v[160:163], v[190:193], v[56:59]
	v_mfma_f32_16x16x32_bf16 v[44:47], v[144:147], v[198:201], v[44:47]
	v_mfma_f32_16x16x32_bf16 v[40:43], v[160:163], v[198:201], v[40:43]
	v_mfma_f32_16x16x32_bf16 v[28:31], v[144:147], v[212:215], v[28:31]
	v_mfma_f32_16x16x32_bf16 v[24:27], v[160:163], v[212:215], v[24:27]
	v_mfma_f32_16x16x32_bf16 v[12:15], v[144:147], v[220:223], v[12:15]
	v_mfma_f32_16x16x32_bf16 v[8:11], v[160:163], v[220:223], v[8:11]
	v_mfma_f32_16x16x32_bf16 v[60:63], v[148:151], v[194:197], v[60:63]
	v_mfma_f32_16x16x32_bf16 v[56:59], v[168:171], v[194:197], v[56:59]
	v_mfma_f32_16x16x32_bf16 v[44:47], v[148:151], v[208:211], v[44:47]
	v_mfma_f32_16x16x32_bf16 v[40:43], v[168:171], v[208:211], v[40:43]
	v_mfma_f32_16x16x32_bf16 v[28:31], v[148:151], v[216:219], v[28:31]
	v_mfma_f32_16x16x32_bf16 v[24:27], v[168:171], v[216:219], v[24:27]
	v_lshl_add_u64 v[228:229], s[54:55], 0, v[134:135]
	s_mov_b32 m0, s45
	s_nop 0
	global_load_lds_dwordx4 v[228:229], off
	v_mfma_f32_16x16x32_bf16 v[12:15], v[148:151], v[224:227], v[12:15]
	v_mfma_f32_16x16x32_bf16 v[8:11], v[168:171], v[224:227], v[8:11]
	s_setprio 0
	s_setprio 1
	v_mfma_f32_16x16x32_bf16 v[52:55], v[172:175], v[190:193], v[52:55]
	v_mfma_f32_16x16x32_bf16 v[48:51], v[182:185], v[190:193], v[48:51]
	v_mfma_f32_16x16x32_bf16 v[36:39], v[172:175], v[198:201], v[36:39]
	v_mfma_f32_16x16x32_bf16 v[32:35], v[182:185], v[198:201], v[32:35]
	v_mfma_f32_16x16x32_bf16 v[20:23], v[172:175], v[212:215], v[20:23]
	v_mfma_f32_16x16x32_bf16 v[16:19], v[182:185], v[212:215], v[16:19]
	v_mfma_f32_16x16x32_bf16 v[4:7], v[172:175], v[220:223], v[4:7]
	v_mfma_f32_16x16x32_bf16 v[0:3], v[182:185], v[220:223], v[0:3]
	v_mfma_f32_16x16x32_bf16 v[52:55], v[176:179], v[194:197], v[52:55]
	v_mfma_f32_16x16x32_bf16 v[48:51], v[186:189], v[194:197], v[48:51]
	v_mfma_f32_16x16x32_bf16 v[36:39], v[176:179], v[208:211], v[36:39]
	v_mfma_f32_16x16x32_bf16 v[32:35], v[186:189], v[208:211], v[32:35]
	v_mfma_f32_16x16x32_bf16 v[20:23], v[176:179], v[216:219], v[20:23]
	v_mfma_f32_16x16x32_bf16 v[16:19], v[186:189], v[216:219], v[16:19]
	v_lshl_add_u64 v[230:231], s[54:55], 0, v[130:131]
	s_mov_b32 m0, s57
	s_nop 0
	global_load_lds_dwordx4 v[230:231], off
	v_mfma_f32_16x16x32_bf16 v[4:7], v[176:179], v[224:227], v[4:7]
	v_mfma_f32_16x16x32_bf16 v[0:3], v[186:189], v[224:227], v[0:3]
	s_setprio 0
	s_barrier
	s_add_i32 s3, 0, 0x18000
	v_add_u32_e32 v159, s3, v153
	s_add_i32 s33, 0, 0x1c000
	ds_read_b128 v[144:147], v159
	ds_read_b128 v[148:151], v159 offset:1024
	ds_read_b128 v[160:163], v159 offset:2048
	ds_read_b128 v[168:171], v159 offset:3072
	v_add_u32_e32 v159, s33, v153
	ds_read_b128 v[172:175], v159
	ds_read_b128 v[176:179], v159 offset:1024
	ds_read_b128 v[182:185], v159 offset:2048
	ds_read_b128 v[186:189], v159 offset:3072
	s_add_u32 s14, s54, 0x40000
	s_addc_u32 s15, s55, 0
	s_mov_b32 m0, s58
	v_lshl_add_u64 v[232:233], s[14:15], 0, v[134:135]
	ds_read_b128 v[190:193], v157 offset:32768
	ds_read_b128 v[194:197], v157 offset:33792
	ds_read_b128 v[198:201], v157 offset:34816
	ds_read_b128 v[208:211], v157 offset:35840
	ds_read_b128 v[212:215], v157 offset:36864
	ds_read_b128 v[216:219], v157 offset:37888
	ds_read_b128 v[220:223], v157 offset:38912
	ds_read_b128 v[224:227], v157 offset:39936
	global_load_lds_dwordx4 v[232:233], off
	v_lshl_add_u64 v[232:233], s[14:15], 0, v[130:131]
	s_mov_b32 m0, s59
	s_nop 0
	global_load_lds_dwordx4 v[232:233], off
	s_waitcnt vmcnt(8)
	s_waitcnt lgkmcnt(0)
	s_barrier
	s_setprio 1
	s_waitcnt lgkmcnt(0)
	v_mfma_f32_16x16x32_bf16 v[124:127], v[144:147], v[190:193], v[124:127]
	v_mfma_f32_16x16x32_bf16 v[120:123], v[160:163], v[190:193], v[120:123]
	v_mfma_f32_16x16x32_bf16 v[108:111], v[144:147], v[198:201], v[108:111]
	v_mfma_f32_16x16x32_bf16 v[104:107], v[160:163], v[198:201], v[104:107]
	v_mfma_f32_16x16x32_bf16 v[92:95], v[144:147], v[212:215], v[92:95]
	v_mfma_f32_16x16x32_bf16 v[88:91], v[160:163], v[212:215], v[88:91]
	v_mfma_f32_16x16x32_bf16 v[76:79], v[144:147], v[220:223], v[76:79]
	v_mfma_f32_16x16x32_bf16 v[72:75], v[160:163], v[220:223], v[72:75]
	v_mfma_f32_16x16x32_bf16 v[124:127], v[148:151], v[194:197], v[124:127]
	v_mfma_f32_16x16x32_bf16 v[120:123], v[168:171], v[194:197], v[120:123]
	v_mfma_f32_16x16x32_bf16 v[108:111], v[148:151], v[208:211], v[108:111]
	v_mfma_f32_16x16x32_bf16 v[104:107], v[168:171], v[208:211], v[104:107]
	v_mfma_f32_16x16x32_bf16 v[92:95], v[148:151], v[216:219], v[92:95]
	v_mfma_f32_16x16x32_bf16 v[88:91], v[168:171], v[216:219], v[88:91]
	v_mfma_f32_16x16x32_bf16 v[76:79], v[148:151], v[224:227], v[76:79]
	v_mfma_f32_16x16x32_bf16 v[72:75], v[168:171], v[224:227], v[72:75]
	s_setprio 0
	s_setprio 1
	v_mfma_f32_16x16x32_bf16 v[116:119], v[172:175], v[190:193], v[116:119]
	v_mfma_f32_16x16x32_bf16 v[112:115], v[182:185], v[190:193], v[112:115]
	v_mfma_f32_16x16x32_bf16 v[100:103], v[172:175], v[198:201], v[100:103]
	v_mfma_f32_16x16x32_bf16 v[96:99], v[182:185], v[198:201], v[96:99]
	v_mfma_f32_16x16x32_bf16 v[84:87], v[172:175], v[212:215], v[84:87]
	v_mfma_f32_16x16x32_bf16 v[80:83], v[182:185], v[212:215], v[80:83]
	v_mfma_f32_16x16x32_bf16 v[68:71], v[172:175], v[220:223], v[68:71]
	v_mfma_f32_16x16x32_bf16 v[64:67], v[182:185], v[220:223], v[64:67]
	v_mfma_f32_16x16x32_bf16 v[116:119], v[176:179], v[194:197], v[116:119]
	v_mfma_f32_16x16x32_bf16 v[112:115], v[186:189], v[194:197], v[112:115]
	v_mfma_f32_16x16x32_bf16 v[100:103], v[176:179], v[208:211], v[100:103]
	v_mfma_f32_16x16x32_bf16 v[96:99], v[186:189], v[208:211], v[96:99]
	v_mfma_f32_16x16x32_bf16 v[84:87], v[176:179], v[216:219], v[84:87]
	v_mfma_f32_16x16x32_bf16 v[80:83], v[186:189], v[216:219], v[80:83]
	v_mfma_f32_16x16x32_bf16 v[68:71], v[176:179], v[224:227], v[68:71]
	v_mfma_f32_16x16x32_bf16 v[64:67], v[186:189], v[224:227], v[64:67]
	s_setprio 0
	s_barrier
; #define PG8_STAGE(bufoff, gbase, voff) do { _Pragma("unroll") for (int _i = 0; _i < 2; ++_i) \
;         __builtin_amdgcn_global_load_lds((const unsigned*)((const char*)(gbase) + (voff)[_i]), (PG8_LAS unsigned*)(lds + (bufoff) + ldsw + _i * 8192), 16, 0, 0); } while (0)
; #define PG8_LDA(dst, b, h) do { _Pragma("unroll") for (int m = 0; m < 4; ++m) _Pragma("unroll") for (int k = 0; k < 2; ++k) dst[m][k] = *(const PG8_LAS bf16x8*)(lds + PG8_SA(b, h) + aoff + m * 2048 + k * 1024); } while (0)
; #define PG8_MMA(ai, bj, At, Bt) do { __builtin_amdgcn_s_setprio(1); _Pragma("unroll") for (int m = 0; m < 4; ++m) _Pragma("unroll") for (int n = 0; n < 2; ++n) _Pragma("unroll") for (int k = 0; k < 2; ++k) \
;         acc[ai][bj][m][n] = __builtin_amdgcn_mfma_f32_16x16x32_bf16(Bt[n][k], At[m][k], acc[ai][bj][m][n], 0, 0, 0); __builtin_amdgcn_s_setprio(0); } while (0)
; #define PG8_WAIT_V(n) asm volatile("s_waitcnt vmcnt(" #n ")" ::: "memory")
; #define PG8_WAIT_L(n) asm volatile("s_waitcnt lgkmcnt(" #n ")" ::: "memory")
; #define PG8_BAR __builtin_amdgcn_s_barrier()
; #define PG8_SCHED __builtin_amdgcn_sched_barrier(0)
;     __device__ __forceinline__ void operator()(const f32x4 (&acc)[2][2][4][2], const Unit& u, int wr, int wc, int fr, int fq) const {
;     ...
;             for (int m = 0; m < 4; ++m) { const int row = row0 + ai * HALF + m * 16; const float rs = row_rs(ss, row);
; template <class Epi, class Sched, bool ALIGN_EPI = false, bool SP2 = false>
; __device__ __forceinline__ void gemm_phase(PG8_LAS unsigned char* lds, const Gemm g, const Sched& S, const Epi& E) {
;     ...
;             PG8_LDA(At, 1, 1); PG8_STAGE(PG8_SB(1, 0), b3, voffB); PG8_STAGE(PG8_SB(1, 1), b3 + hstep, voffB); PG8_STAGE(PG8_SA(1, 0), a3, voffA);
;             PG8_WAIT_V(8); PG8_WAIT_L(0); PG8_BAR; PG8_MMA(1, 0, At, B0); PG8_MMA(1, 1, At, B1); PG8_BAR; PG8_SCHED;
	s_add_i32 s3, s3, s43
	v_lshl_add_u64 v[164:165], v[164:165], 0, s[10:11]
	s_mov_b32 m0, s3
	ds_read_b128 v[190:193], v157 offset:49152
	ds_read_b128 v[194:197], v157 offset:50176
	ds_read_b128 v[198:201], v157 offset:51200
	ds_read_b128 v[208:211], v157 offset:52224
	ds_read_b128 v[212:215], v157 offset:53248
	ds_read_b128 v[216:219], v157 offset:54272
	ds_read_b128 v[220:223], v157 offset:55296
	ds_read_b128 v[224:227], v157 offset:56320
	global_load_lds_dwordx4 v[164:165], off
	s_add_i32 m0, s3, 0x2000
	s_add_u32 s14, s50, 0x40080
	v_lshl_add_u64 v[164:165], v[202:203], 0, s[10:11]
	s_addc_u32 s15, s51, 0
	s_add_i32 s3, s33, s43
	global_load_lds_dwordx4 v[164:165], off
	v_lshl_add_u64 v[164:165], s[14:15], 0, v[132:133]
	s_mov_b32 m0, s3
	s_nop 0
	global_load_lds_dwordx4 v[164:165], off
	v_lshl_add_u64 v[164:165], s[14:15], 0, v[128:129]
	s_add_i32 m0, s3, 0x2000
	s_nop 0
	global_load_lds_dwordx4 v[164:165], off
	s_waitcnt vmcnt(6)
	s_waitcnt lgkmcnt(0)
	s_barrier
	s_setprio 1
	s_waitcnt lgkmcnt(0)
	v_mfma_f32_16x16x32_bf16 v[60:63], v[144:147], v[190:193], v[60:63]
	v_mfma_f32_16x16x32_bf16 v[56:59], v[160:163], v[190:193], v[56:59]
	v_lshl_add_u64 v[164:165], v[228:229], 0, s[10:11]
	s_mov_b32 m0, s61
	s_nop 0
	global_load_lds_dwordx4 v[164:165], off
	v_mfma_f32_16x16x32_bf16 v[44:47], v[144:147], v[198:201], v[44:47]
	v_mfma_f32_16x16x32_bf16 v[40:43], v[160:163], v[198:201], v[40:43]
	v_mfma_f32_16x16x32_bf16 v[28:31], v[144:147], v[212:215], v[28:31]
	v_mfma_f32_16x16x32_bf16 v[24:27], v[160:163], v[212:215], v[24:27]
	v_lshl_add_u64 v[164:165], v[230:231], 0, s[10:11]
	s_mov_b32 m0, s62
	s_nop 0
	global_load_lds_dwordx4 v[164:165], off
	v_mfma_f32_16x16x32_bf16 v[12:15], v[144:147], v[220:223], v[12:15]
	v_mfma_f32_16x16x32_bf16 v[8:11], v[160:163], v[220:223], v[8:11]
	v_mfma_f32_16x16x32_bf16 v[60:63], v[148:151], v[194:197], v[60:63]
	v_mfma_f32_16x16x32_bf16 v[56:59], v[168:171], v[194:197], v[56:59]
	v_mfma_f32_16x16x32_bf16 v[44:47], v[148:151], v[208:211], v[44:47]
	v_mfma_f32_16x16x32_bf16 v[40:43], v[168:171], v[208:211], v[40:43]
	v_mfma_f32_16x16x32_bf16 v[28:31], v[148:151], v[216:219], v[28:31]
	v_mfma_f32_16x16x32_bf16 v[24:27], v[168:171], v[216:219], v[24:27]
	v_mfma_f32_16x16x32_bf16 v[12:15], v[148:151], v[224:227], v[12:15]
	v_mfma_f32_16x16x32_bf16 v[8:11], v[168:171], v[224:227], v[8:11]
	s_setprio 0
	s_setprio 1
	v_mfma_f32_16x16x32_bf16 v[52:55], v[172:175], v[190:193], v[52:55]
	v_mfma_f32_16x16x32_bf16 v[48:51], v[182:185], v[190:193], v[48:51]
	v_mfma_f32_16x16x32_bf16 v[36:39], v[172:175], v[198:201], v[36:39]
	v_mfma_f32_16x16x32_bf16 v[32:35], v[182:185], v[198:201], v[32:35]
	v_mfma_f32_16x16x32_bf16 v[20:23], v[172:175], v[212:215], v[20:23]
	v_mfma_f32_16x16x32_bf16 v[16:19], v[182:185], v[212:215], v[16:19]
	v_mfma_f32_16x16x32_bf16 v[4:7], v[172:175], v[220:223], v[4:7]
	v_mfma_f32_16x16x32_bf16 v[0:3], v[182:185], v[220:223], v[0:3]
	v_mfma_f32_16x16x32_bf16 v[52:55], v[176:179], v[194:197], v[52:55]
	v_mfma_f32_16x16x32_bf16 v[48:51], v[186:189], v[194:197], v[48:51]
	v_mfma_f32_16x16x32_bf16 v[36:39], v[176:179], v[208:211], v[36:39]
	v_mfma_f32_16x16x32_bf16 v[32:35], v[186:189], v[208:211], v[32:35]
	v_mfma_f32_16x16x32_bf16 v[20:23], v[176:179], v[216:219], v[20:23]
	v_mfma_f32_16x16x32_bf16 v[16:19], v[186:189], v[216:219], v[16:19]
	v_mfma_f32_16x16x32_bf16 v[4:7], v[176:179], v[224:227], v[4:7]
	v_mfma_f32_16x16x32_bf16 v[0:3], v[186:189], v[224:227], v[0:3]
	s_setprio 0
	s_barrier
	s_add_i32 s89, s89, 2
	s_add_u32 s48, s48, 0x100
	s_addc_u32 s49, s49, 0
	s_add_u32 s87, s87, 0x100
	s_addc_u32 s88, s88, 0
	s_cmp_gt_u32 s89, 13
	s_cbranch_scc0 .LBB0_191
	v_lshl_add_u32 v144, s44, 8, v152
	v_ashrrev_i32_e32 v145, 31, v144
	v_lshl_add_u64 v[150:151], v[144:145], 3, s[6:7]
	global_load_dwordx2 v[182:183], v[150:151], off
	global_load_dwordx2 v[184:185], v[150:151], off offset:128
	global_load_dwordx2 v[186:187], v[150:151], off offset:256
	global_load_dwordx2 v[188:189], v[150:151], off offset:384
	global_load_dwordx2 v[190:191], v[150:151], off offset:1024
	global_load_dwordx2 v[192:193], v[150:151], off offset:1152
	global_load_dwordx2 v[194:195], v[150:151], off offset:1280
	global_load_dwordx2 v[196:197], v[150:151], off offset:1408
	s_and_b64 vcc, exec, s[16:17]
	s_cbranch_vccz .LBB0_194
	s_barrier

; #define PG8_STAGE(bufoff, gbase, voff) do { _Pragma("unroll") for (int _i = 0; _i < 2; ++_i) \
;         __builtin_amdgcn_global_load_lds((const unsigned*)((const char*)(gbase) + (voff)[_i]), (PG8_LAS unsigned*)(lds + (bufoff) + ldsw + _i * 8192), 16, 0, 0); } while (0)
; #define PG8_LDA(dst, b, h) do { _Pragma("unroll") for (int m = 0; m < 4; ++m) _Pragma("unroll") for (int k = 0; k < 2; ++k) dst[m][k] = *(const PG8_LAS bf16x8*)(lds + PG8_SA(b, h) + aoff + m * 2048 + k * 1024); } while (0)
; #define PG8_LDB(dst, b, h) do { _Pragma("unroll") for (int n = 0; n < 2; ++n) _Pragma("unroll") for (int k = 0; k < 2; ++k) dst[n][k] = *(const PG8_LAS bf16x8*)(lds + PG8_SB(b, h) + boff + n * 2048 + k * 1024); } while (0)
; #define PG8_MMA(ai, bj, At, Bt) do { __builtin_amdgcn_s_setprio(1); _Pragma("unroll") for (int m = 0; m < 4; ++m) _Pragma("unroll") for (int n = 0; n < 2; ++n) _Pragma("unroll") for (int k = 0; k < 2; ++k) \
;         acc[ai][bj][m][n] = __builtin_amdgcn_mfma_f32_16x16x32_bf16(Bt[n][k], At[m][k], acc[ai][bj][m][n], 0, 0, 0); __builtin_amdgcn_s_setprio(0); } while (0)
; #define PG8_WAIT_V(n) asm volatile("s_waitcnt vmcnt(" #n ")" ::: "memory")
; #define PG8_WAIT_L(n) asm volatile("s_waitcnt lgkmcnt(" #n ")" ::: "memory")
; #define PG8_BAR __builtin_amdgcn_s_barrier()
; #define PG8_SCHED __builtin_amdgcn_sched_barrier(0)
; template <class Epi, class Sched, bool ALIGN_EPI = false, bool SP2 = false>
; __device__ __forceinline__ void gemm_phase(PG8_LAS unsigned char* lds, const Gemm g, const Sched& S, const Epi& E) {
;     ...
;         for (int t = 0; t < nt; t += 2) {
;             const bool last = (t == nt - 2);
;             const char* a1 = cA + (size_t)(t + 1) * kstep;
;             const char* a2 = last ? nA : cA + (size_t)(t + 2) * kstep; const char* b2 = last ? nB : cB + (size_t)(t + 2) * kstep;
;             const char* a3 = a2 + kstep; const char* b3 = b2 + kstep;
;             if (last && has_next) S.a_ready(nxt);
;             if constexpr (SP2) {
;             PG8_LDB(B0, 0, 0); PG8_LDB(B1, 0, 1); PG8_SCHED; PG8_LDA(At, 0, 0); PG8_STAGE(PG8_SA(1, 1), a1 + hstep, voffA);
;             PG8_WAIT_V(8); PG8_WAIT_L(0); PG8_BAR; PG8_MMA(0, 0, At, B0); PG8_MMA(0, 1, At, B1); PG8_BAR; PG8_SCHED;
;             PG8_LDA(At, 0, 1); PG8_STAGE(PG8_SB(0, 0), b2, voffB); PG8_STAGE(PG8_SB(0, 1), b2 + hstep, voffB); PG8_STAGE(PG8_SA(0, 0), a2, voffA);
.LBB0_269:
	ds_read_b128 v[128:131], v165
	ds_read_b128 v[132:135], v165 offset:1024
	ds_read_b128 v[152:155], v165 offset:2048
	ds_read_b128 v[156:159], v165 offset:3072
	ds_read_b128 v[172:175], v168
	ds_read_b128 v[176:179], v168 offset:1024
	ds_read_b128 v[182:185], v168 offset:2048
	ds_read_b128 v[186:189], v168 offset:3072
	s_add_u32 s50, s10, 0x100
	s_addc_u32 s51, s11, 0
	s_cmp_eq_u32 s93, 40
	s_cselect_b32 s57, s1, s51
	s_cselect_b32 s56, s0, s50
	s_cselect_b32 s55, s49, s92
	s_cselect_b32 s54, s48, s91
	v_lshl_add_u64 v[160:161], s[10:11], 0, v[144:145]
	s_add_i32 m0, s58, 0xc000
	ds_read_b128 v[190:193], v169
	ds_read_b128 v[194:197], v169 offset:1024
	ds_read_b128 v[198:201], v169 offset:2048
	ds_read_b128 v[208:211], v169 offset:3072
	ds_read_b128 v[212:215], v169 offset:4096
	ds_read_b128 v[216:219], v169 offset:5120
	ds_read_b128 v[220:223], v169 offset:6144
	ds_read_b128 v[224:227], v169 offset:7168
	global_load_lds_dwordx4 v[160:161], off
	v_lshl_add_u64 v[160:161], s[10:11], 0, v[146:147]
	s_add_i32 m0, s58, 0xe000
	s_nop 0
	global_load_lds_dwordx4 v[160:161], off
	s_waitcnt vmcnt(8)
	s_waitcnt lgkmcnt(0)
	s_barrier
	s_setprio 1
	s_waitcnt lgkmcnt(0)
	v_mfma_f32_16x16x32_bf16 v[124:127], v[128:131], v[190:193], v[124:127]
	v_mfma_f32_16x16x32_bf16 v[120:123], v[152:155], v[190:193], v[120:123]
	v_mfma_f32_16x16x32_bf16 v[108:111], v[128:131], v[198:201], v[108:111]
	v_mfma_f32_16x16x32_bf16 v[104:107], v[152:155], v[198:201], v[104:107]
	v_mfma_f32_16x16x32_bf16 v[92:95], v[128:131], v[212:215], v[92:95]
	v_mfma_f32_16x16x32_bf16 v[88:91], v[152:155], v[212:215], v[88:91]
	v_mfma_f32_16x16x32_bf16 v[76:79], v[128:131], v[220:223], v[76:79]
	v_mfma_f32_16x16x32_bf16 v[72:75], v[152:155], v[220:223], v[72:75]
	v_mfma_f32_16x16x32_bf16 v[124:127], v[132:135], v[194:197], v[124:127]
	v_mfma_f32_16x16x32_bf16 v[120:123], v[156:159], v[194:197], v[120:123]
	v_mfma_f32_16x16x32_bf16 v[108:111], v[132:135], v[208:211], v[108:111]
	v_mfma_f32_16x16x32_bf16 v[104:107], v[156:159], v[208:211], v[104:107]
	v_mfma_f32_16x16x32_bf16 v[92:95], v[132:135], v[216:219], v[92:95]
	v_mfma_f32_16x16x32_bf16 v[88:91], v[156:159], v[216:219], v[88:91]
	v_mfma_f32_16x16x32_bf16 v[76:79], v[132:135], v[224:227], v[76:79]
	v_mfma_f32_16x16x32_bf16 v[72:75], v[156:159], v[224:227], v[72:75]
	s_setprio 0
	s_setprio 1
	v_mfma_f32_16x16x32_bf16 v[116:119], v[172:175], v[190:193], v[116:119]
	v_mfma_f32_16x16x32_bf16 v[112:115], v[182:185], v[190:193], v[112:115]
	v_mfma_f32_16x16x32_bf16 v[100:103], v[172:175], v[198:201], v[100:103]
	v_mfma_f32_16x16x32_bf16 v[96:99], v[182:185], v[198:201], v[96:99]
	v_mfma_f32_16x16x32_bf16 v[84:87], v[172:175], v[212:215], v[84:87]
	v_mfma_f32_16x16x32_bf16 v[80:83], v[182:185], v[212:215], v[80:83]
	v_mfma_f32_16x16x32_bf16 v[68:71], v[172:175], v[220:223], v[68:71]
	v_mfma_f32_16x16x32_bf16 v[64:67], v[182:185], v[220:223], v[64:67]
	v_mfma_f32_16x16x32_bf16 v[116:119], v[176:179], v[194:197], v[116:119]
	v_mfma_f32_16x16x32_bf16 v[112:115], v[186:189], v[194:197], v[112:115]
	v_mfma_f32_16x16x32_bf16 v[100:103], v[176:179], v[208:211], v[100:103]
	v_mfma_f32_16x16x32_bf16 v[96:99], v[186:189], v[208:211], v[96:99]
	v_mfma_f32_16x16x32_bf16 v[84:87], v[176:179], v[216:219], v[84:87]
	v_mfma_f32_16x16x32_bf16 v[80:83], v[186:189], v[216:219], v[80:83]
	v_mfma_f32_16x16x32_bf16 v[68:71], v[176:179], v[224:227], v[68:71]
	v_mfma_f32_16x16x32_bf16 v[64:67], v[186:189], v[224:227], v[64:67]
	s_setprio 0
	s_barrier
	s_add_i32 s3, s65, s43
	v_lshl_add_u64 v[160:161], s[54:55], 0, v[138:139]
	s_mov_b32 m0, s3
	ds_read_b128 v[190:193], v169 offset:16384
	ds_read_b128 v[194:197], v169 offset:17408
	ds_read_b128 v[198:201], v169 offset:18432
	ds_read_b128 v[208:211], v169 offset:19456
	ds_read_b128 v[212:215], v169 offset:20480
	ds_read_b128 v[216:219], v169 offset:21504
	ds_read_b128 v[220:223], v169 offset:22528
	ds_read_b128 v[224:227], v169 offset:23552
	global_load_lds_dwordx4 v[160:161], off
	s_add_i32 m0, s3, 0x2000
	s_add_u32 s10, s54, 0xb0000
	v_lshl_add_u64 v[202:203], s[54:55], 0, v[142:143]
	s_addc_u32 s11, s55, 0
	s_add_i32 s3, s66, s43
	global_load_lds_dwordx4 v[202:203], off
	v_lshl_add_u64 v[228:229], s[10:11], 0, v[138:139]
	s_mov_b32 m0, s3
	global_load_lds_dwordx4 v[228:229], off
	v_lshl_add_u64 v[228:229], s[10:11], 0, v[142:143]
	s_add_i32 m0, s3, 0x2000
	s_nop 0
	global_load_lds_dwordx4 v[228:229], off
	s_waitcnt vmcnt(6)
	s_waitcnt lgkmcnt(0)
	s_barrier
; #define PG8_STAGE(bufoff, gbase, voff) do { _Pragma("unroll") for (int _i = 0; _i < 2; ++_i) \
;         __builtin_amdgcn_global_load_lds((const unsigned*)((const char*)(gbase) + (voff)[_i]), (PG8_LAS unsigned*)(lds + (bufoff) + ldsw + _i * 8192), 16, 0, 0); } while (0)
; #define PG8_LDA(dst, b, h) do { _Pragma("unroll") for (int m = 0; m < 4; ++m) _Pragma("unroll") for (int k = 0; k < 2; ++k) dst[m][k] = *(const PG8_LAS bf16x8*)(lds + PG8_SA(b, h) + aoff + m * 2048 + k * 1024); } while (0)
; #define PG8_LDB(dst, b, h) do { _Pragma("unroll") for (int n = 0; n < 2; ++n) _Pragma("unroll") for (int k = 0; k < 2; ++k) dst[n][k] = *(const PG8_LAS bf16x8*)(lds + PG8_SB(b, h) + boff + n * 2048 + k * 1024); } while (0)
; #define PG8_MMA(ai, bj, At, Bt) do { __builtin_amdgcn_s_setprio(1); _Pragma("unroll") for (int m = 0; m < 4; ++m) _Pragma("unroll") for (int n = 0; n < 2; ++n) _Pragma("unroll") for (int k = 0; k < 2; ++k) \
;         acc[ai][bj][m][n] = __builtin_amdgcn_mfma_f32_16x16x32_bf16(Bt[n][k], At[m][k], acc[ai][bj][m][n], 0, 0, 0); __builtin_amdgcn_s_setprio(0); } while (0)
; #define PG8_WAIT_V(n) asm volatile("s_waitcnt vmcnt(" #n ")" ::: "memory")
; #define PG8_WAIT_L(n) asm volatile("s_waitcnt lgkmcnt(" #n ")" ::: "memory")
; #define PG8_BAR __builtin_amdgcn_s_barrier()
; #define PG8_SCHED __builtin_amdgcn_sched_barrier(0)
; template <class Epi, class Sched, bool ALIGN_EPI = false, bool SP2 = false>
; __device__ __forceinline__ void gemm_phase(PG8_LAS unsigned char* lds, const Gemm g, const Sched& S, const Epi& E) {
;     ...
;             PG8_LDA(At, 0, 1); PG8_STAGE(PG8_SB(0, 0), b2, voffB); PG8_STAGE(PG8_SB(0, 1), b2 + hstep, voffB); PG8_STAGE(PG8_SA(0, 0), a2, voffA);
;             PG8_WAIT_V(8); PG8_WAIT_L(0); PG8_BAR; PG8_MMA(1, 0, At, B0); PG8_MMA(1, 1, At, B1); PG8_BAR; PG8_SCHED;
;             PG8_LDB(B0, 1, 0); PG8_LDB(B1, 1, 1); PG8_SCHED; PG8_LDA(At, 1, 0); PG8_STAGE(PG8_SA(0, 1), a2 + hstep, voffA);
;             PG8_WAIT_V(8); PG8_WAIT_L(0); PG8_BAR; PG8_MMA(0, 0, At, B0); PG8_MMA(0, 1, At, B1); PG8_BAR; PG8_SCHED;
	s_setprio 1
	s_waitcnt lgkmcnt(0)
	v_mfma_f32_16x16x32_bf16 v[60:63], v[128:131], v[190:193], v[60:63]
	v_mfma_f32_16x16x32_bf16 v[56:59], v[152:155], v[190:193], v[56:59]
	v_mfma_f32_16x16x32_bf16 v[44:47], v[128:131], v[198:201], v[44:47]
	v_mfma_f32_16x16x32_bf16 v[40:43], v[152:155], v[198:201], v[40:43]
	v_mfma_f32_16x16x32_bf16 v[28:31], v[128:131], v[212:215], v[28:31]
	v_mfma_f32_16x16x32_bf16 v[24:27], v[152:155], v[212:215], v[24:27]
	v_mfma_f32_16x16x32_bf16 v[12:15], v[128:131], v[220:223], v[12:15]
	v_mfma_f32_16x16x32_bf16 v[8:11], v[152:155], v[220:223], v[8:11]
	v_mfma_f32_16x16x32_bf16 v[60:63], v[132:135], v[194:197], v[60:63]
	v_mfma_f32_16x16x32_bf16 v[56:59], v[156:159], v[194:197], v[56:59]
	v_mfma_f32_16x16x32_bf16 v[44:47], v[132:135], v[208:211], v[44:47]
	v_mfma_f32_16x16x32_bf16 v[40:43], v[156:159], v[208:211], v[40:43]
	v_mfma_f32_16x16x32_bf16 v[28:31], v[132:135], v[216:219], v[28:31]
	v_mfma_f32_16x16x32_bf16 v[24:27], v[156:159], v[216:219], v[24:27]
	v_lshl_add_u64 v[228:229], s[56:57], 0, v[136:137]
	s_mov_b32 m0, s58
	s_nop 0
	global_load_lds_dwordx4 v[228:229], off
	v_mfma_f32_16x16x32_bf16 v[12:15], v[132:135], v[224:227], v[12:15]
	v_mfma_f32_16x16x32_bf16 v[8:11], v[156:159], v[224:227], v[8:11]
	s_setprio 0
	s_setprio 1
	v_mfma_f32_16x16x32_bf16 v[52:55], v[172:175], v[190:193], v[52:55]
	v_mfma_f32_16x16x32_bf16 v[48:51], v[182:185], v[190:193], v[48:51]
	v_mfma_f32_16x16x32_bf16 v[36:39], v[172:175], v[198:201], v[36:39]
	v_mfma_f32_16x16x32_bf16 v[32:35], v[182:185], v[198:201], v[32:35]
	v_mfma_f32_16x16x32_bf16 v[20:23], v[172:175], v[212:215], v[20:23]
	v_mfma_f32_16x16x32_bf16 v[16:19], v[182:185], v[212:215], v[16:19]
	v_mfma_f32_16x16x32_bf16 v[4:7], v[172:175], v[220:223], v[4:7]
	v_mfma_f32_16x16x32_bf16 v[0:3], v[182:185], v[220:223], v[0:3]
	v_mfma_f32_16x16x32_bf16 v[52:55], v[176:179], v[194:197], v[52:55]
	v_mfma_f32_16x16x32_bf16 v[48:51], v[186:189], v[194:197], v[48:51]
	v_mfma_f32_16x16x32_bf16 v[36:39], v[176:179], v[208:211], v[36:39]
	v_mfma_f32_16x16x32_bf16 v[32:35], v[186:189], v[208:211], v[32:35]
	v_mfma_f32_16x16x32_bf16 v[20:23], v[176:179], v[216:219], v[20:23]
	v_mfma_f32_16x16x32_bf16 v[16:19], v[186:189], v[216:219], v[16:19]
	v_lshl_add_u64 v[230:231], s[56:57], 0, v[140:141]
	s_mov_b32 m0, s59
	s_nop 0
	global_load_lds_dwordx4 v[230:231], off
	v_mfma_f32_16x16x32_bf16 v[4:7], v[176:179], v[224:227], v[4:7]
	v_mfma_f32_16x16x32_bf16 v[0:3], v[186:189], v[224:227], v[0:3]
	s_setprio 0
	s_barrier
	s_add_i32 s3, 0, 0x18000
	s_add_i32 s14, 0, 0x1c000
	v_add_u32_e32 v156, s3, v163
	v_add_u32_e32 v171, s14, v163
	ds_read_b128 v[128:131], v156
	ds_read_b128 v[132:135], v156 offset:1024
	ds_read_b128 v[152:155], v156 offset:2048
	ds_read_b128 v[156:159], v156 offset:3072
	ds_read_b128 v[172:175], v171
	ds_read_b128 v[176:179], v171 offset:1024
	ds_read_b128 v[182:185], v171 offset:2048
	ds_read_b128 v[186:189], v171 offset:3072
	s_add_u32 s10, s56, 0xb0000
	s_addc_u32 s11, s57, 0
	s_mov_b32 m0, s60
	v_lshl_add_u64 v[232:233], s[10:11], 0, v[136:137]
	ds_read_b128 v[190:193], v169 offset:32768
	ds_read_b128 v[194:197], v169 offset:33792
	ds_read_b128 v[198:201], v169 offset:34816
	ds_read_b128 v[208:211], v169 offset:35840
	ds_read_b128 v[212:215], v169 offset:36864
	ds_read_b128 v[216:219], v169 offset:37888
	ds_read_b128 v[220:223], v169 offset:38912
	ds_read_b128 v[224:227], v169 offset:39936
	global_load_lds_dwordx4 v[232:233], off
	v_lshl_add_u64 v[232:233], s[10:11], 0, v[140:141]
	s_mov_b32 m0, s61
	s_nop 0
	global_load_lds_dwordx4 v[232:233], off
	s_waitcnt vmcnt(8)
	s_waitcnt lgkmcnt(0)
	s_barrier
	s_setprio 1
	s_waitcnt lgkmcnt(0)
	v_mfma_f32_16x16x32_bf16 v[124:127], v[128:131], v[190:193], v[124:127]
	v_mfma_f32_16x16x32_bf16 v[120:123], v[152:155], v[190:193], v[120:123]
	v_mfma_f32_16x16x32_bf16 v[108:111], v[128:131], v[198:201], v[108:111]
	v_mfma_f32_16x16x32_bf16 v[104:107], v[152:155], v[198:201], v[104:107]
	v_mfma_f32_16x16x32_bf16 v[92:95], v[128:131], v[212:215], v[92:95]
	v_mfma_f32_16x16x32_bf16 v[88:91], v[152:155], v[212:215], v[88:91]
	v_mfma_f32_16x16x32_bf16 v[76:79], v[128:131], v[220:223], v[76:79]
	v_mfma_f32_16x16x32_bf16 v[72:75], v[152:155], v[220:223], v[72:75]
	v_mfma_f32_16x16x32_bf16 v[124:127], v[132:135], v[194:197], v[124:127]
	v_mfma_f32_16x16x32_bf16 v[120:123], v[156:159], v[194:197], v[120:123]
	v_mfma_f32_16x16x32_bf16 v[108:111], v[132:135], v[208:211], v[108:111]
	v_mfma_f32_16x16x32_bf16 v[104:107], v[156:159], v[208:211], v[104:107]
	v_mfma_f32_16x16x32_bf16 v[92:95], v[132:135], v[216:219], v[92:95]
	v_mfma_f32_16x16x32_bf16 v[88:91], v[156:159], v[216:219], v[88:91]
	v_mfma_f32_16x16x32_bf16 v[76:79], v[132:135], v[224:227], v[76:79]
	v_mfma_f32_16x16x32_bf16 v[72:75], v[156:159], v[224:227], v[72:75]
	s_setprio 0
	s_setprio 1
	v_mfma_f32_16x16x32_bf16 v[116:119], v[172:175], v[190:193], v[116:119]
	v_mfma_f32_16x16x32_bf16 v[112:115], v[182:185], v[190:193], v[112:115]
	v_mfma_f32_16x16x32_bf16 v[100:103], v[172:175], v[198:201], v[100:103]
	v_mfma_f32_16x16x32_bf16 v[96:99], v[182:185], v[198:201], v[96:99]
	v_mfma_f32_16x16x32_bf16 v[84:87], v[172:175], v[212:215], v[84:87]
	v_mfma_f32_16x16x32_bf16 v[80:83], v[182:185], v[212:215], v[80:83]
	v_mfma_f32_16x16x32_bf16 v[68:71], v[172:175], v[220:223], v[68:71]
	v_mfma_f32_16x16x32_bf16 v[64:67], v[182:185], v[220:223], v[64:67]
	v_mfma_f32_16x16x32_bf16 v[116:119], v[176:179], v[194:197], v[116:119]
	v_mfma_f32_16x16x32_bf16 v[112:115], v[186:189], v[194:197], v[112:115]
	v_mfma_f32_16x16x32_bf16 v[100:103], v[176:179], v[208:211], v[100:103]
	v_mfma_f32_16x16x32_bf16 v[96:99], v[186:189], v[208:211], v[96:99]
	v_mfma_f32_16x16x32_bf16 v[84:87], v[176:179], v[216:219], v[84:87]
	v_mfma_f32_16x16x32_bf16 v[80:83], v[186:189], v[216:219], v[80:83]
	v_mfma_f32_16x16x32_bf16 v[68:71], v[176:179], v[224:227], v[68:71]
	v_mfma_f32_16x16x32_bf16 v[64:67], v[186:189], v[224:227], v[64:67]
	s_setprio 0
	s_barrier
; #define PG8_STAGE(bufoff, gbase, voff) do { _Pragma("unroll") for (int _i = 0; _i < 2; ++_i) \
;         __builtin_amdgcn_global_load_lds((const unsigned*)((const char*)(gbase) + (voff)[_i]), (PG8_LAS unsigned*)(lds + (bufoff) + ldsw + _i * 8192), 16, 0, 0); } while (0)
; #define PG8_LDA(dst, b, h) do { _Pragma("unroll") for (int m = 0; m < 4; ++m) _Pragma("unroll") for (int k = 0; k < 2; ++k) dst[m][k] = *(const PG8_LAS bf16x8*)(lds + PG8_SA(b, h) + aoff + m * 2048 + k * 1024); } while (0)
; #define PG8_MMA(ai, bj, At, Bt) do { __builtin_amdgcn_s_setprio(1); _Pragma("unroll") for (int m = 0; m < 4; ++m) _Pragma("unroll") for (int n = 0; n < 2; ++n) _Pragma("unroll") for (int k = 0; k < 2; ++k) \
;         acc[ai][bj][m][n] = __builtin_amdgcn_mfma_f32_16x16x32_bf16(Bt[n][k], At[m][k], acc[ai][bj][m][n], 0, 0, 0); __builtin_amdgcn_s_setprio(0); } while (0)
; #define PG8_WAIT_V(n) asm volatile("s_waitcnt vmcnt(" #n ")" ::: "memory")
; #define PG8_WAIT_L(n) asm volatile("s_waitcnt lgkmcnt(" #n ")" ::: "memory")
; #define PG8_BAR __builtin_amdgcn_s_barrier()
; #define PG8_SCHED __builtin_amdgcn_sched_barrier(0)
; template <class Epi, class Sched, bool ALIGN_EPI = false, bool SP2 = false>
; __device__ __forceinline__ void gemm_phase(PG8_LAS unsigned char* lds, const Gemm g, const Sched& S, const Epi& E) {
;     ...
;             PG8_LDA(At, 1, 1); PG8_STAGE(PG8_SB(1, 0), b3, voffB); PG8_STAGE(PG8_SB(1, 1), b3 + hstep, voffB); PG8_STAGE(PG8_SA(1, 0), a3, voffA);
;             PG8_WAIT_V(8); PG8_WAIT_L(0); PG8_BAR; PG8_MMA(1, 0, At, B0); PG8_MMA(1, 1, At, B1); PG8_BAR; PG8_SCHED;
	s_add_i32 s3, s3, s43
	v_lshl_add_u64 v[160:161], v[160:161], 0, s[40:41]
	s_mov_b32 m0, s3
	ds_read_b128 v[190:193], v169 offset:49152
	ds_read_b128 v[194:197], v169 offset:50176
	ds_read_b128 v[198:201], v169 offset:51200
	ds_read_b128 v[208:211], v169 offset:52224
	ds_read_b128 v[212:215], v169 offset:53248
	ds_read_b128 v[216:219], v169 offset:54272
	ds_read_b128 v[220:223], v169 offset:55296
	ds_read_b128 v[224:227], v169 offset:56320
	global_load_lds_dwordx4 v[160:161], off
	s_add_i32 m0, s3, 0x2000
	s_add_u32 s10, s54, 0xb0080
	v_lshl_add_u64 v[160:161], v[202:203], 0, s[40:41]
	s_addc_u32 s11, s55, 0
	s_add_i32 s3, s14, s43
	global_load_lds_dwordx4 v[160:161], off
	v_lshl_add_u64 v[160:161], s[10:11], 0, v[138:139]
	s_mov_b32 m0, s3
	s_nop 0
	global_load_lds_dwordx4 v[160:161], off
	v_lshl_add_u64 v[160:161], s[10:11], 0, v[142:143]
	s_add_i32 m0, s3, 0x2000
	s_nop 0
	global_load_lds_dwordx4 v[160:161], off
	s_waitcnt vmcnt(6)
	s_waitcnt lgkmcnt(0)
	s_barrier
	s_setprio 1
	s_waitcnt lgkmcnt(0)
	v_mfma_f32_16x16x32_bf16 v[60:63], v[128:131], v[190:193], v[60:63]
	v_mfma_f32_16x16x32_bf16 v[56:59], v[152:155], v[190:193], v[56:59]
	v_lshl_add_u64 v[160:161], v[228:229], 0, s[40:41]
	s_mov_b32 m0, s63
	s_nop 0
	global_load_lds_dwordx4 v[160:161], off
	v_mfma_f32_16x16x32_bf16 v[44:47], v[128:131], v[198:201], v[44:47]
	v_mfma_f32_16x16x32_bf16 v[40:43], v[152:155], v[198:201], v[40:43]
	v_mfma_f32_16x16x32_bf16 v[28:31], v[128:131], v[212:215], v[28:31]
	v_mfma_f32_16x16x32_bf16 v[24:27], v[152:155], v[212:215], v[24:27]
	v_lshl_add_u64 v[160:161], v[230:231], 0, s[40:41]
	s_mov_b32 m0, s64
	s_nop 0
	global_load_lds_dwordx4 v[160:161], off
	v_mfma_f32_16x16x32_bf16 v[12:15], v[128:131], v[220:223], v[12:15]
	v_mfma_f32_16x16x32_bf16 v[8:11], v[152:155], v[220:223], v[8:11]
	v_mfma_f32_16x16x32_bf16 v[60:63], v[132:135], v[194:197], v[60:63]
	v_mfma_f32_16x16x32_bf16 v[56:59], v[156:159], v[194:197], v[56:59]
	v_mfma_f32_16x16x32_bf16 v[44:47], v[132:135], v[208:211], v[44:47]
	v_mfma_f32_16x16x32_bf16 v[40:43], v[156:159], v[208:211], v[40:43]
	v_mfma_f32_16x16x32_bf16 v[28:31], v[132:135], v[216:219], v[28:31]
	v_mfma_f32_16x16x32_bf16 v[24:27], v[156:159], v[216:219], v[24:27]
	v_mfma_f32_16x16x32_bf16 v[12:15], v[132:135], v[224:227], v[12:15]
	v_mfma_f32_16x16x32_bf16 v[8:11], v[156:159], v[224:227], v[8:11]
	s_setprio 0
	s_setprio 1
	v_mfma_f32_16x16x32_bf16 v[52:55], v[172:175], v[190:193], v[52:55]
	v_mfma_f32_16x16x32_bf16 v[48:51], v[182:185], v[190:193], v[48:51]
	v_mfma_f32_16x16x32_bf16 v[36:39], v[172:175], v[198:201], v[36:39]
	v_mfma_f32_16x16x32_bf16 v[32:35], v[182:185], v[198:201], v[32:35]
	v_mfma_f32_16x16x32_bf16 v[20:23], v[172:175], v[212:215], v[20:23]
	v_mfma_f32_16x16x32_bf16 v[16:19], v[182:185], v[212:215], v[16:19]
	v_mfma_f32_16x16x32_bf16 v[4:7], v[172:175], v[220:223], v[4:7]
	v_mfma_f32_16x16x32_bf16 v[0:3], v[182:185], v[220:223], v[0:3]
	v_mfma_f32_16x16x32_bf16 v[52:55], v[176:179], v[194:197], v[52:55]
	v_mfma_f32_16x16x32_bf16 v[48:51], v[186:189], v[194:197], v[48:51]
	v_mfma_f32_16x16x32_bf16 v[36:39], v[176:179], v[208:211], v[36:39]
	v_mfma_f32_16x16x32_bf16 v[32:35], v[186:189], v[208:211], v[32:35]
	v_mfma_f32_16x16x32_bf16 v[20:23], v[176:179], v[216:219], v[20:23]
	v_mfma_f32_16x16x32_bf16 v[16:19], v[186:189], v[216:219], v[16:19]
	v_mfma_f32_16x16x32_bf16 v[4:7], v[176:179], v[224:227], v[4:7]
	v_mfma_f32_16x16x32_bf16 v[0:3], v[186:189], v[224:227], v[0:3]
	s_setprio 0
	s_barrier
	s_add_i32 s93, s93, 2
	s_add_u32 s91, s91, 0x100
	s_addc_u32 s92, s92, 0
	s_cmp_gt_u32 s93, 41
	s_mov_b64 s[10:11], s[50:51]
	s_cbranch_scc0 .LBB0_269
	s_and_b64 vcc, exec, s[44:45]
	s_cbranch_vccz .LBB0_272
	s_barrier

; #define PG8_STAGE(bufoff, gbase, voff) do { _Pragma("unroll") for (int _i = 0; _i < 2; ++_i) \
;         __builtin_amdgcn_global_load_lds((const unsigned*)((const char*)(gbase) + (voff)[_i]), (PG8_LAS unsigned*)(lds + (bufoff) + ldsw + _i * 8192), 16, 0, 0); } while (0)
; #define PG8_LDA(dst, b, h) do { _Pragma("unroll") for (int m = 0; m < 4; ++m) _Pragma("unroll") for (int k = 0; k < 2; ++k) dst[m][k] = *(const PG8_LAS bf16x8*)(lds + PG8_SA(b, h) + aoff + m * 2048 + k * 1024); } while (0)
; #define PG8_LDB(dst, b, h) do { _Pragma("unroll") for (int n = 0; n < 2; ++n) _Pragma("unroll") for (int k = 0; k < 2; ++k) dst[n][k] = *(const PG8_LAS bf16x8*)(lds + PG8_SB(b, h) + boff + n * 2048 + k * 1024); } while (0)
; #define PG8_MMA(ai, bj, At, Bt) do { __builtin_amdgcn_s_setprio(1); _Pragma("unroll") for (int m = 0; m < 4; ++m) _Pragma("unroll") for (int n = 0; n < 2; ++n) _Pragma("unroll") for (int k = 0; k < 2; ++k) \
;         acc[ai][bj][m][n] = __builtin_amdgcn_mfma_f32_16x16x32_bf16(Bt[n][k], At[m][k], acc[ai][bj][m][n], 0, 0, 0); __builtin_amdgcn_s_setprio(0); } while (0)
; #define PG8_WAIT_V(n) asm volatile("s_waitcnt vmcnt(" #n ")" ::: "memory")
; #define PG8_WAIT_L(n) asm volatile("s_waitcnt lgkmcnt(" #n ")" ::: "memory")
; #define PG8_BAR __builtin_amdgcn_s_barrier()
; #define PG8_SCHED __builtin_amdgcn_sched_barrier(0)
; template <class Epi, class Sched, bool ALIGN_EPI = false, bool SP2 = false>
; __device__ __forceinline__ void gemm_phase(PG8_LAS unsigned char* lds, const Gemm g, const Sched& S, const Epi& E) {
;     ...
;         for (int t = 0; t < nt; t += 2) {
;             const bool last = (t == nt - 2);
;             const char* a1 = cA + (size_t)(t + 1) * kstep;
;             const char* a2 = last ? nA : cA + (size_t)(t + 2) * kstep; const char* b2 = last ? nB : cB + (size_t)(t + 2) * kstep;
;             const char* a3 = a2 + kstep; const char* b3 = b2 + kstep;
;             if (last && has_next) S.a_ready(nxt);
;             if constexpr (SP2) {
;             PG8_LDB(B0, 0, 0); PG8_LDB(B1, 0, 1); PG8_SCHED; PG8_LDA(At, 0, 0); PG8_STAGE(PG8_SA(1, 1), a1 + hstep, voffA);
;             PG8_WAIT_V(8); PG8_WAIT_L(0); PG8_BAR; PG8_MMA(0, 0, At, B0); PG8_MMA(0, 1, At, B1); PG8_BAR; PG8_SCHED;
;             PG8_LDA(At, 0, 1); PG8_STAGE(PG8_SB(0, 0), b2, voffB); PG8_STAGE(PG8_SB(0, 1), b2 + hstep, voffB); PG8_STAGE(PG8_SA(0, 0), a2, voffA);
.LBB0_417:
	ds_read_b128 v[154:157], v169
	ds_read_b128 v[158:161], v169 offset:1024
	ds_read_b128 v[162:165], v169 offset:2048
	ds_read_b128 v[174:177], v169 offset:3072
	ds_read_b128 v[182:185], v170
	ds_read_b128 v[186:189], v170 offset:1024
	ds_read_b128 v[190:193], v170 offset:2048
	ds_read_b128 v[194:197], v170 offset:3072
	s_add_u32 s3, s54, 0xfffc0080
	s_addc_u32 s14, s55, -1
	s_cmp_eq_u32 s93, 12
	s_cselect_b32 s59, s45, s14
	s_cselect_b32 s58, s89, s3
	s_cselect_b32 s57, s41, s92
	s_cselect_b32 s56, s90, s91
	v_lshl_add_u64 v[178:179], s[54:55], 0, v[146:147]
	s_add_i32 m0, s60, 0xc000
	ds_read_b128 v[198:201], v171
	ds_read_b128 v[208:211], v171 offset:1024
	ds_read_b128 v[212:215], v171 offset:2048
	ds_read_b128 v[216:219], v171 offset:3072
	ds_read_b128 v[220:223], v171 offset:4096
	ds_read_b128 v[224:227], v171 offset:5120
	ds_read_b128 v[228:231], v171 offset:6144
	ds_read_b128 v[232:235], v171 offset:7168
	global_load_lds_dwordx4 v[178:179], off
	v_lshl_add_u64 v[178:179], s[54:55], 0, v[148:149]
	s_add_i32 m0, s60, 0xe000
	s_nop 0
	global_load_lds_dwordx4 v[178:179], off
	s_waitcnt vmcnt(8)
	s_waitcnt lgkmcnt(0)
	s_barrier
	s_setprio 1
	s_waitcnt lgkmcnt(0)
	v_mfma_f32_16x16x32_bf16 v[124:127], v[154:157], v[198:201], v[124:127]
	v_mfma_f32_16x16x32_bf16 v[120:123], v[162:165], v[198:201], v[120:123]
	v_mfma_f32_16x16x32_bf16 v[116:119], v[154:157], v[212:215], v[116:119]
	v_mfma_f32_16x16x32_bf16 v[112:115], v[162:165], v[212:215], v[112:115]
	v_mfma_f32_16x16x32_bf16 v[108:111], v[154:157], v[220:223], v[108:111]
	v_mfma_f32_16x16x32_bf16 v[104:107], v[162:165], v[220:223], v[104:107]
	v_mfma_f32_16x16x32_bf16 v[100:103], v[154:157], v[228:231], v[100:103]
	v_mfma_f32_16x16x32_bf16 v[96:99], v[162:165], v[228:231], v[96:99]
	v_mfma_f32_16x16x32_bf16 v[124:127], v[158:161], v[208:211], v[124:127]
	v_mfma_f32_16x16x32_bf16 v[120:123], v[174:177], v[208:211], v[120:123]
	v_mfma_f32_16x16x32_bf16 v[116:119], v[158:161], v[216:219], v[116:119]
	v_mfma_f32_16x16x32_bf16 v[112:115], v[174:177], v[216:219], v[112:115]
	v_mfma_f32_16x16x32_bf16 v[108:111], v[158:161], v[224:227], v[108:111]
	v_mfma_f32_16x16x32_bf16 v[104:107], v[174:177], v[224:227], v[104:107]
	v_mfma_f32_16x16x32_bf16 v[100:103], v[158:161], v[232:235], v[100:103]
	v_mfma_f32_16x16x32_bf16 v[96:99], v[174:177], v[232:235], v[96:99]
	s_setprio 0
	s_setprio 1
	v_mfma_f32_16x16x32_bf16 v[68:71], v[182:185], v[198:201], v[68:71]
	v_mfma_f32_16x16x32_bf16 v[64:67], v[190:193], v[198:201], v[64:67]
	v_mfma_f32_16x16x32_bf16 v[52:55], v[182:185], v[212:215], v[52:55]
	v_mfma_f32_16x16x32_bf16 v[48:51], v[190:193], v[212:215], v[48:51]
	v_mfma_f32_16x16x32_bf16 v[44:47], v[182:185], v[220:223], v[44:47]
	v_mfma_f32_16x16x32_bf16 v[40:43], v[190:193], v[220:223], v[40:43]
	v_mfma_f32_16x16x32_bf16 v[36:39], v[182:185], v[228:231], v[36:39]
	v_mfma_f32_16x16x32_bf16 v[32:35], v[190:193], v[228:231], v[32:35]
	v_mfma_f32_16x16x32_bf16 v[68:71], v[186:189], v[208:211], v[68:71]
	v_mfma_f32_16x16x32_bf16 v[64:67], v[194:197], v[208:211], v[64:67]
	v_mfma_f32_16x16x32_bf16 v[52:55], v[186:189], v[216:219], v[52:55]
	v_mfma_f32_16x16x32_bf16 v[48:51], v[194:197], v[216:219], v[48:51]
	v_mfma_f32_16x16x32_bf16 v[44:47], v[186:189], v[224:227], v[44:47]
	v_mfma_f32_16x16x32_bf16 v[40:43], v[194:197], v[224:227], v[40:43]
	v_mfma_f32_16x16x32_bf16 v[36:39], v[186:189], v[232:235], v[36:39]
	v_mfma_f32_16x16x32_bf16 v[32:35], v[194:197], v[232:235], v[32:35]
	s_setprio 0
	s_barrier
	s_add_i32 s3, s86, s34
	v_lshl_add_u64 v[178:179], s[56:57], 0, v[132:133]
	s_mov_b32 m0, s3
	ds_read_b128 v[198:201], v171 offset:16384
	ds_read_b128 v[208:211], v171 offset:17408
	ds_read_b128 v[212:215], v171 offset:18432
	ds_read_b128 v[216:219], v171 offset:19456
	ds_read_b128 v[220:223], v171 offset:20480
	ds_read_b128 v[224:227], v171 offset:21504
	ds_read_b128 v[228:231], v171 offset:22528
	ds_read_b128 v[232:235], v171 offset:23552
	global_load_lds_dwordx4 v[178:179], off
	s_add_i32 m0, s3, 0x2000
	s_add_u32 s14, s56, 0x40000
	v_lshl_add_u64 v[202:203], s[56:57], 0, v[128:129]
	s_addc_u32 s15, s57, 0
	s_add_i32 s3, s87, s34
	global_load_lds_dwordx4 v[202:203], off
	v_lshl_add_u64 v[236:237], s[14:15], 0, v[132:133]
	s_mov_b32 m0, s3
	global_load_lds_dwordx4 v[236:237], off
	v_lshl_add_u64 v[236:237], s[14:15], 0, v[128:129]
	s_add_i32 m0, s3, 0x2000
	s_nop 0
	global_load_lds_dwordx4 v[236:237], off
	s_waitcnt vmcnt(6)
	s_waitcnt lgkmcnt(0)
	s_barrier
; #define PG8_STAGE(bufoff, gbase, voff) do { _Pragma("unroll") for (int _i = 0; _i < 2; ++_i) \
;         __builtin_amdgcn_global_load_lds((const unsigned*)((const char*)(gbase) + (voff)[_i]), (PG8_LAS unsigned*)(lds + (bufoff) + ldsw + _i * 8192), 16, 0, 0); } while (0)
; #define PG8_LDA(dst, b, h) do { _Pragma("unroll") for (int m = 0; m < 4; ++m) _Pragma("unroll") for (int k = 0; k < 2; ++k) dst[m][k] = *(const PG8_LAS bf16x8*)(lds + PG8_SA(b, h) + aoff + m * 2048 + k * 1024); } while (0)
; #define PG8_LDB(dst, b, h) do { _Pragma("unroll") for (int n = 0; n < 2; ++n) _Pragma("unroll") for (int k = 0; k < 2; ++k) dst[n][k] = *(const PG8_LAS bf16x8*)(lds + PG8_SB(b, h) + boff + n * 2048 + k * 1024); } while (0)
; #define PG8_MMA(ai, bj, At, Bt) do { __builtin_amdgcn_s_setprio(1); _Pragma("unroll") for (int m = 0; m < 4; ++m) _Pragma("unroll") for (int n = 0; n < 2; ++n) _Pragma("unroll") for (int k = 0; k < 2; ++k) \
;         acc[ai][bj][m][n] = __builtin_amdgcn_mfma_f32_16x16x32_bf16(Bt[n][k], At[m][k], acc[ai][bj][m][n], 0, 0, 0); __builtin_amdgcn_s_setprio(0); } while (0)
; #define PG8_WAIT_V(n) asm volatile("s_waitcnt vmcnt(" #n ")" ::: "memory")
; #define PG8_WAIT_L(n) asm volatile("s_waitcnt lgkmcnt(" #n ")" ::: "memory")
; #define PG8_BAR __builtin_amdgcn_s_barrier()
; #define PG8_SCHED __builtin_amdgcn_sched_barrier(0)
; template <class Epi, class Sched, bool ALIGN_EPI = false, bool SP2 = false>
; __device__ __forceinline__ void gemm_phase(PG8_LAS unsigned char* lds, const Gemm g, const Sched& S, const Epi& E) {
;     ...
;             PG8_LDA(At, 0, 1); PG8_STAGE(PG8_SB(0, 0), b2, voffB); PG8_STAGE(PG8_SB(0, 1), b2 + hstep, voffB); PG8_STAGE(PG8_SA(0, 0), a2, voffA);
;             PG8_WAIT_V(8); PG8_WAIT_L(0); PG8_BAR; PG8_MMA(1, 0, At, B0); PG8_MMA(1, 1, At, B1); PG8_BAR; PG8_SCHED;
;             PG8_LDB(B0, 1, 0); PG8_LDB(B1, 1, 1); PG8_SCHED; PG8_LDA(At, 1, 0); PG8_STAGE(PG8_SA(0, 1), a2 + hstep, voffA);
;             PG8_WAIT_V(8); PG8_WAIT_L(0); PG8_BAR; PG8_MMA(0, 0, At, B0); PG8_MMA(0, 1, At, B1); PG8_BAR; PG8_SCHED;
	s_setprio 1
	s_waitcnt lgkmcnt(0)
	v_mfma_f32_16x16x32_bf16 v[92:95], v[154:157], v[198:201], v[92:95]
	v_mfma_f32_16x16x32_bf16 v[88:91], v[162:165], v[198:201], v[88:91]
	v_mfma_f32_16x16x32_bf16 v[84:87], v[154:157], v[212:215], v[84:87]
	v_mfma_f32_16x16x32_bf16 v[80:83], v[162:165], v[212:215], v[80:83]
	v_mfma_f32_16x16x32_bf16 v[76:79], v[154:157], v[220:223], v[76:79]
	v_mfma_f32_16x16x32_bf16 v[72:75], v[162:165], v[220:223], v[72:75]
	v_mfma_f32_16x16x32_bf16 v[60:63], v[154:157], v[228:231], v[60:63]
	v_mfma_f32_16x16x32_bf16 v[56:59], v[162:165], v[228:231], v[56:59]
	v_mfma_f32_16x16x32_bf16 v[92:95], v[158:161], v[208:211], v[92:95]
	v_mfma_f32_16x16x32_bf16 v[88:91], v[174:177], v[208:211], v[88:91]
	v_mfma_f32_16x16x32_bf16 v[84:87], v[158:161], v[216:219], v[84:87]
	v_mfma_f32_16x16x32_bf16 v[80:83], v[174:177], v[216:219], v[80:83]
	v_mfma_f32_16x16x32_bf16 v[76:79], v[158:161], v[224:227], v[76:79]
	v_mfma_f32_16x16x32_bf16 v[72:75], v[174:177], v[224:227], v[72:75]
	v_lshl_add_u64 v[236:237], s[58:59], 0, v[134:135]
	s_mov_b32 m0, s60
	s_nop 0
	global_load_lds_dwordx4 v[236:237], off
	v_mfma_f32_16x16x32_bf16 v[60:63], v[158:161], v[232:235], v[60:63]
	v_mfma_f32_16x16x32_bf16 v[56:59], v[174:177], v[232:235], v[56:59]
	s_setprio 0
	s_setprio 1
	v_mfma_f32_16x16x32_bf16 v[28:31], v[182:185], v[198:201], v[28:31]
	v_mfma_f32_16x16x32_bf16 v[24:27], v[190:193], v[198:201], v[24:27]
	v_mfma_f32_16x16x32_bf16 v[20:23], v[182:185], v[212:215], v[20:23]
	v_mfma_f32_16x16x32_bf16 v[16:19], v[190:193], v[212:215], v[16:19]
	v_mfma_f32_16x16x32_bf16 v[12:15], v[182:185], v[220:223], v[12:15]
	v_mfma_f32_16x16x32_bf16 v[8:11], v[190:193], v[220:223], v[8:11]
	v_mfma_f32_16x16x32_bf16 v[4:7], v[182:185], v[228:231], v[4:7]
	v_mfma_f32_16x16x32_bf16 v[0:3], v[190:193], v[228:231], v[0:3]
	v_mfma_f32_16x16x32_bf16 v[28:31], v[186:189], v[208:211], v[28:31]
	v_mfma_f32_16x16x32_bf16 v[24:27], v[194:197], v[208:211], v[24:27]
	v_mfma_f32_16x16x32_bf16 v[20:23], v[186:189], v[216:219], v[20:23]
	v_mfma_f32_16x16x32_bf16 v[16:19], v[194:197], v[216:219], v[16:19]
	v_mfma_f32_16x16x32_bf16 v[12:15], v[186:189], v[224:227], v[12:15]
	v_mfma_f32_16x16x32_bf16 v[8:11], v[194:197], v[224:227], v[8:11]
	v_lshl_add_u64 v[238:239], s[58:59], 0, v[130:131]
	s_mov_b32 m0, s61
	s_nop 0
	global_load_lds_dwordx4 v[238:239], off
	v_mfma_f32_16x16x32_bf16 v[4:7], v[186:189], v[232:235], v[4:7]
	v_mfma_f32_16x16x32_bf16 v[0:3], v[194:197], v[232:235], v[0:3]
	s_setprio 0
	s_barrier
	s_add_i32 s3, 0, 0x18000
	v_add_u32_e32 v136, s3, v143
	s_add_i32 s33, 0, 0x1c000
	ds_read_b128 v[154:157], v136
	ds_read_b128 v[158:161], v136 offset:1024
	ds_read_b128 v[162:165], v136 offset:2048
	ds_read_b128 v[174:177], v136 offset:3072
	v_add_u32_e32 v136, s33, v143
	ds_read_b128 v[182:185], v136
	ds_read_b128 v[186:189], v136 offset:1024
	ds_read_b128 v[190:193], v136 offset:2048
	ds_read_b128 v[194:197], v136 offset:3072
	s_add_u32 s14, s58, 0x40000
	s_addc_u32 s15, s59, 0
	s_mov_b32 m0, s62
	v_lshl_add_u64 v[240:241], s[14:15], 0, v[134:135]
	ds_read_b128 v[198:201], v171 offset:32768
	ds_read_b128 v[208:211], v171 offset:33792
	ds_read_b128 v[212:215], v171 offset:34816
	ds_read_b128 v[216:219], v171 offset:35840
	ds_read_b128 v[220:223], v171 offset:36864
	ds_read_b128 v[224:227], v171 offset:37888
	ds_read_b128 v[228:231], v171 offset:38912
	ds_read_b128 v[232:235], v171 offset:39936
	global_load_lds_dwordx4 v[240:241], off
	v_lshl_add_u64 v[240:241], s[14:15], 0, v[130:131]
	s_mov_b32 m0, s63
	s_nop 0
	global_load_lds_dwordx4 v[240:241], off
	s_waitcnt vmcnt(8)
	s_waitcnt lgkmcnt(0)
	s_barrier
	s_setprio 1
	s_waitcnt lgkmcnt(0)
	v_mfma_f32_16x16x32_bf16 v[124:127], v[154:157], v[198:201], v[124:127]
	v_mfma_f32_16x16x32_bf16 v[120:123], v[162:165], v[198:201], v[120:123]
	v_mfma_f32_16x16x32_bf16 v[116:119], v[154:157], v[212:215], v[116:119]
	v_mfma_f32_16x16x32_bf16 v[112:115], v[162:165], v[212:215], v[112:115]
	v_mfma_f32_16x16x32_bf16 v[108:111], v[154:157], v[220:223], v[108:111]
	v_mfma_f32_16x16x32_bf16 v[104:107], v[162:165], v[220:223], v[104:107]
	v_mfma_f32_16x16x32_bf16 v[100:103], v[154:157], v[228:231], v[100:103]
	v_mfma_f32_16x16x32_bf16 v[96:99], v[162:165], v[228:231], v[96:99]
	v_mfma_f32_16x16x32_bf16 v[124:127], v[158:161], v[208:211], v[124:127]
	v_mfma_f32_16x16x32_bf16 v[120:123], v[174:177], v[208:211], v[120:123]
	v_mfma_f32_16x16x32_bf16 v[116:119], v[158:161], v[216:219], v[116:119]
	v_mfma_f32_16x16x32_bf16 v[112:115], v[174:177], v[216:219], v[112:115]
	v_mfma_f32_16x16x32_bf16 v[108:111], v[158:161], v[224:227], v[108:111]
	v_mfma_f32_16x16x32_bf16 v[104:107], v[174:177], v[224:227], v[104:107]
	v_mfma_f32_16x16x32_bf16 v[100:103], v[158:161], v[232:235], v[100:103]
	v_mfma_f32_16x16x32_bf16 v[96:99], v[174:177], v[232:235], v[96:99]
	s_setprio 0
	s_setprio 1
	v_mfma_f32_16x16x32_bf16 v[68:71], v[182:185], v[198:201], v[68:71]
	v_mfma_f32_16x16x32_bf16 v[64:67], v[190:193], v[198:201], v[64:67]
	v_mfma_f32_16x16x32_bf16 v[52:55], v[182:185], v[212:215], v[52:55]
	v_mfma_f32_16x16x32_bf16 v[48:51], v[190:193], v[212:215], v[48:51]
	v_mfma_f32_16x16x32_bf16 v[44:47], v[182:185], v[220:223], v[44:47]
	v_mfma_f32_16x16x32_bf16 v[40:43], v[190:193], v[220:223], v[40:43]
	v_mfma_f32_16x16x32_bf16 v[36:39], v[182:185], v[228:231], v[36:39]
	v_mfma_f32_16x16x32_bf16 v[32:35], v[190:193], v[228:231], v[32:35]
	v_mfma_f32_16x16x32_bf16 v[68:71], v[186:189], v[208:211], v[68:71]
	v_mfma_f32_16x16x32_bf16 v[64:67], v[194:197], v[208:211], v[64:67]
	v_mfma_f32_16x16x32_bf16 v[52:55], v[186:189], v[216:219], v[52:55]
	v_mfma_f32_16x16x32_bf16 v[48:51], v[194:197], v[216:219], v[48:51]
	v_mfma_f32_16x16x32_bf16 v[44:47], v[186:189], v[224:227], v[44:47]
	v_mfma_f32_16x16x32_bf16 v[40:43], v[194:197], v[224:227], v[40:43]
	v_mfma_f32_16x16x32_bf16 v[36:39], v[186:189], v[232:235], v[36:39]
	v_mfma_f32_16x16x32_bf16 v[32:35], v[194:197], v[232:235], v[32:35]
	s_setprio 0
	s_barrier
; #define PG8_STAGE(bufoff, gbase, voff) do { _Pragma("unroll") for (int _i = 0; _i < 2; ++_i) \
;         __builtin_amdgcn_global_load_lds((const unsigned*)((const char*)(gbase) + (voff)[_i]), (PG8_LAS unsigned*)(lds + (bufoff) + ldsw + _i * 8192), 16, 0, 0); } while (0)
; #define PG8_LDA(dst, b, h) do { _Pragma("unroll") for (int m = 0; m < 4; ++m) _Pragma("unroll") for (int k = 0; k < 2; ++k) dst[m][k] = *(const PG8_LAS bf16x8*)(lds + PG8_SA(b, h) + aoff + m * 2048 + k * 1024); } while (0)
; #define PG8_MMA(ai, bj, At, Bt) do { __builtin_amdgcn_s_setprio(1); _Pragma("unroll") for (int m = 0; m < 4; ++m) _Pragma("unroll") for (int n = 0; n < 2; ++n) _Pragma("unroll") for (int k = 0; k < 2; ++k) \
;         acc[ai][bj][m][n] = __builtin_amdgcn_mfma_f32_16x16x32_bf16(Bt[n][k], At[m][k], acc[ai][bj][m][n], 0, 0, 0); __builtin_amdgcn_s_setprio(0); } while (0)
; #define PG8_WAIT_V(n) asm volatile("s_waitcnt vmcnt(" #n ")" ::: "memory")
; #define PG8_WAIT_L(n) asm volatile("s_waitcnt lgkmcnt(" #n ")" ::: "memory")
; #define PG8_BAR __builtin_amdgcn_s_barrier()
; #define PG8_SCHED __builtin_amdgcn_sched_barrier(0)
; template <class Epi, class Sched, bool ALIGN_EPI = false, bool SP2 = false>
; __device__ __forceinline__ void gemm_phase(PG8_LAS unsigned char* lds, const Gemm g, const Sched& S, const Epi& E) {
;     ...
;             PG8_LDA(At, 1, 1); PG8_STAGE(PG8_SB(1, 0), b3, voffB); PG8_STAGE(PG8_SB(1, 1), b3 + hstep, voffB); PG8_STAGE(PG8_SA(1, 0), a3, voffA);
;             PG8_WAIT_V(8); PG8_WAIT_L(0); PG8_BAR; PG8_MMA(1, 0, At, B0); PG8_MMA(1, 1, At, B1); PG8_BAR; PG8_SCHED;
;     ...
;         if constexpr (ALIGN_EPI) { if (wr == 0) PG8_BAR; }
	s_add_i32 s3, s3, s34
	v_lshl_add_u64 v[178:179], v[178:179], 0, s[8:9]
	s_mov_b32 m0, s3
	ds_read_b128 v[198:201], v171 offset:49152
	ds_read_b128 v[208:211], v171 offset:50176
	ds_read_b128 v[212:215], v171 offset:51200
	ds_read_b128 v[216:219], v171 offset:52224
	ds_read_b128 v[220:223], v171 offset:53248
	ds_read_b128 v[224:227], v171 offset:54272
	ds_read_b128 v[228:231], v171 offset:55296
	ds_read_b128 v[232:235], v171 offset:56320
	global_load_lds_dwordx4 v[178:179], off
	s_add_i32 m0, s3, 0x2000
	s_add_u32 s14, s56, 0x40080
	v_lshl_add_u64 v[178:179], v[202:203], 0, s[8:9]
	s_addc_u32 s15, s57, 0
	s_add_i32 s3, s33, s34
	global_load_lds_dwordx4 v[178:179], off
	v_lshl_add_u64 v[178:179], s[14:15], 0, v[132:133]
	s_mov_b32 m0, s3
	s_nop 0
	global_load_lds_dwordx4 v[178:179], off
	v_lshl_add_u64 v[178:179], s[14:15], 0, v[128:129]
	s_add_i32 m0, s3, 0x2000
	s_nop 0
	global_load_lds_dwordx4 v[178:179], off
	s_waitcnt vmcnt(6)
	s_waitcnt lgkmcnt(0)
	s_barrier
	s_setprio 1
	s_waitcnt lgkmcnt(0)
	v_mfma_f32_16x16x32_bf16 v[92:95], v[154:157], v[198:201], v[92:95]
	v_mfma_f32_16x16x32_bf16 v[88:91], v[162:165], v[198:201], v[88:91]
	v_lshl_add_u64 v[178:179], v[236:237], 0, s[8:9]
	s_mov_b32 m0, s66
	s_nop 0
	global_load_lds_dwordx4 v[178:179], off
	v_mfma_f32_16x16x32_bf16 v[84:87], v[154:157], v[212:215], v[84:87]
	v_mfma_f32_16x16x32_bf16 v[80:83], v[162:165], v[212:215], v[80:83]
	v_mfma_f32_16x16x32_bf16 v[76:79], v[154:157], v[220:223], v[76:79]
	v_mfma_f32_16x16x32_bf16 v[72:75], v[162:165], v[220:223], v[72:75]
	v_lshl_add_u64 v[178:179], v[238:239], 0, s[8:9]
	s_mov_b32 m0, s67
	s_nop 0
	global_load_lds_dwordx4 v[178:179], off
	v_mfma_f32_16x16x32_bf16 v[60:63], v[154:157], v[228:231], v[60:63]
	v_mfma_f32_16x16x32_bf16 v[56:59], v[162:165], v[228:231], v[56:59]
	v_mfma_f32_16x16x32_bf16 v[92:95], v[158:161], v[208:211], v[92:95]
	v_mfma_f32_16x16x32_bf16 v[88:91], v[174:177], v[208:211], v[88:91]
	v_mfma_f32_16x16x32_bf16 v[84:87], v[158:161], v[216:219], v[84:87]
	v_mfma_f32_16x16x32_bf16 v[80:83], v[174:177], v[216:219], v[80:83]
	v_mfma_f32_16x16x32_bf16 v[76:79], v[158:161], v[224:227], v[76:79]
	v_mfma_f32_16x16x32_bf16 v[72:75], v[174:177], v[224:227], v[72:75]
	v_mfma_f32_16x16x32_bf16 v[60:63], v[158:161], v[232:235], v[60:63]
	v_mfma_f32_16x16x32_bf16 v[56:59], v[174:177], v[232:235], v[56:59]
	s_setprio 0
	s_setprio 1
	v_mfma_f32_16x16x32_bf16 v[28:31], v[182:185], v[198:201], v[28:31]
	v_mfma_f32_16x16x32_bf16 v[24:27], v[190:193], v[198:201], v[24:27]
	v_mfma_f32_16x16x32_bf16 v[20:23], v[182:185], v[212:215], v[20:23]
	v_mfma_f32_16x16x32_bf16 v[16:19], v[190:193], v[212:215], v[16:19]
	v_mfma_f32_16x16x32_bf16 v[12:15], v[182:185], v[220:223], v[12:15]
	v_mfma_f32_16x16x32_bf16 v[8:11], v[190:193], v[220:223], v[8:11]
	v_mfma_f32_16x16x32_bf16 v[4:7], v[182:185], v[228:231], v[4:7]
	v_mfma_f32_16x16x32_bf16 v[0:3], v[190:193], v[228:231], v[0:3]
	v_mfma_f32_16x16x32_bf16 v[28:31], v[186:189], v[208:211], v[28:31]
	v_mfma_f32_16x16x32_bf16 v[24:27], v[194:197], v[208:211], v[24:27]
	v_mfma_f32_16x16x32_bf16 v[20:23], v[186:189], v[216:219], v[20:23]
	v_mfma_f32_16x16x32_bf16 v[16:19], v[194:197], v[216:219], v[16:19]
	v_mfma_f32_16x16x32_bf16 v[12:15], v[186:189], v[224:227], v[12:15]
	v_mfma_f32_16x16x32_bf16 v[8:11], v[194:197], v[224:227], v[8:11]
	v_mfma_f32_16x16x32_bf16 v[4:7], v[186:189], v[232:235], v[4:7]
	v_mfma_f32_16x16x32_bf16 v[0:3], v[194:197], v[232:235], v[0:3]
	s_setprio 0
	s_barrier
	s_add_i32 s93, s93, 2
	s_add_u32 s54, s54, 0x100
	s_addc_u32 s55, s55, 0
	s_add_u32 s91, s91, 0x100
	s_addc_u32 s92, s92, 0
	s_cmp_gt_u32 s93, 13
	s_cbranch_scc0 .LBB0_417
	s_and_b64 vcc, exec, s[10:11]
	s_cbranch_vccz .LBB0_420
	s_barrier

; #define PG8_STAGE(bufoff, gbase, voff) do { _Pragma("unroll") for (int _i = 0; _i < 2; ++_i) \
;         __builtin_amdgcn_global_load_lds((const unsigned*)((const char*)(gbase) + (voff)[_i]), (PG8_LAS unsigned*)(lds + (bufoff) + ldsw + _i * 8192), 16, 0, 0); } while (0)
; #define PG8_LDA(dst, b, h) do { _Pragma("unroll") for (int m = 0; m < 4; ++m) _Pragma("unroll") for (int k = 0; k < 2; ++k) dst[m][k] = *(const PG8_LAS bf16x8*)(lds + PG8_SA(b, h) + aoff + m * 2048 + k * 1024); } while (0)
; #define PG8_LDB(dst, b, h) do { _Pragma("unroll") for (int n = 0; n < 2; ++n) _Pragma("unroll") for (int k = 0; k < 2; ++k) dst[n][k] = *(const PG8_LAS bf16x8*)(lds + PG8_SB(b, h) + boff + n * 2048 + k * 1024); } while (0)
; #define PG8_MMA(ai, bj, At, Bt) do { __builtin_amdgcn_s_setprio(1); _Pragma("unroll") for (int m = 0; m < 4; ++m) _Pragma("unroll") for (int n = 0; n < 2; ++n) _Pragma("unroll") for (int k = 0; k < 2; ++k) \
;         acc[ai][bj][m][n] = __builtin_amdgcn_mfma_f32_16x16x32_bf16(Bt[n][k], At[m][k], acc[ai][bj][m][n], 0, 0, 0); __builtin_amdgcn_s_setprio(0); } while (0)
; #define PG8_WAIT_V(n) asm volatile("s_waitcnt vmcnt(" #n ")" ::: "memory")
; #define PG8_WAIT_L(n) asm volatile("s_waitcnt lgkmcnt(" #n ")" ::: "memory")
; #define PG8_BAR __builtin_amdgcn_s_barrier()
; #define PG8_SCHED __builtin_amdgcn_sched_barrier(0)
; template <class Epi, class Sched, bool ALIGN_EPI = false, bool SP2 = false>
; __device__ __forceinline__ void gemm_phase(PG8_LAS unsigned char* lds, const Gemm g, const Sched& S, const Epi& E) {
;     ...
;             const bool last = (t == nt - 2);
;             const char* a1 = cA + (size_t)(t + 1) * kstep;
;             const char* a2 = last ? nA : cA + (size_t)(t + 2) * kstep; const char* b2 = last ? nB : cB + (size_t)(t + 2) * kstep;
;             const char* a3 = a2 + kstep; const char* b3 = b2 + kstep;
;             if (last && has_next) S.a_ready(nxt);
;             if constexpr (SP2) {
;             PG8_LDB(B0, 0, 0); PG8_LDB(B1, 0, 1); PG8_SCHED; PG8_LDA(At, 0, 0); PG8_STAGE(PG8_SA(1, 1), a1 + hstep, voffA);
;             PG8_WAIT_V(8); PG8_WAIT_L(0); PG8_BAR; PG8_MMA(0, 0, At, B0); PG8_MMA(0, 1, At, B1); PG8_BAR; PG8_SCHED;
;             PG8_LDA(At, 0, 1); PG8_STAGE(PG8_SB(0, 0), b2, voffB); PG8_STAGE(PG8_SB(0, 1), b2 + hstep, voffB); PG8_STAGE(PG8_SA(0, 0), a2, voffA);
.LBB0_459:
	ds_read_b128 v[170:173], v165
	ds_read_b128 v[174:177], v165 offset:1024
	ds_read_b128 v[182:185], v165 offset:2048
	ds_read_b128 v[186:189], v165 offset:3072
	ds_read_b128 v[190:193], v168
	ds_read_b128 v[194:197], v168 offset:1024
	ds_read_b128 v[198:201], v168 offset:2048
	ds_read_b128 v[208:211], v168 offset:3072
	s_add_u32 s3, s58, 0xfffc0080
	s_addc_u32 s14, s59, -1
	s_cmp_eq_u32 vcc_lo, 12
	s_cselect_b32 s63, s49, s14
	s_cselect_b32 s62, s55, s3
	s_cselect_b32 s61, s45, s97
	s_cselect_b32 s60, s57, s96
	v_lshl_add_u64 v[178:179], s[58:59], 0, v[160:161]
	s_add_i32 m0, s85, 0xc000
	ds_read_b128 v[212:215], v164
	ds_read_b128 v[216:219], v164 offset:1024
	ds_read_b128 v[220:223], v164 offset:2048
	ds_read_b128 v[224:227], v164 offset:3072
	ds_read_b128 v[228:231], v164 offset:4096
	ds_read_b128 v[232:235], v164 offset:5120
	ds_read_b128 v[236:239], v164 offset:6144
	ds_read_b128 v[240:243], v164 offset:7168
	global_load_lds_dwordx4 v[178:179], off
	v_lshl_add_u64 v[178:179], s[58:59], 0, v[162:163]
	s_add_i32 m0, s85, 0xe000
	s_nop 0
	global_load_lds_dwordx4 v[178:179], off
	s_waitcnt vmcnt(8)
	s_waitcnt lgkmcnt(0)
	s_barrier
	s_setprio 1
	s_waitcnt lgkmcnt(0)
	v_mfma_f32_16x16x32_bf16 v[124:127], v[170:173], v[212:215], v[124:127]
	v_mfma_f32_16x16x32_bf16 v[120:123], v[182:185], v[212:215], v[120:123]
	v_mfma_f32_16x16x32_bf16 v[116:119], v[170:173], v[220:223], v[116:119]
	v_mfma_f32_16x16x32_bf16 v[112:115], v[182:185], v[220:223], v[112:115]
	v_mfma_f32_16x16x32_bf16 v[108:111], v[170:173], v[228:231], v[108:111]
	v_mfma_f32_16x16x32_bf16 v[104:107], v[182:185], v[228:231], v[104:107]
	v_mfma_f32_16x16x32_bf16 v[100:103], v[170:173], v[236:239], v[100:103]
	v_mfma_f32_16x16x32_bf16 v[96:99], v[182:185], v[236:239], v[96:99]
	v_mfma_f32_16x16x32_bf16 v[124:127], v[174:177], v[216:219], v[124:127]
	v_mfma_f32_16x16x32_bf16 v[120:123], v[186:189], v[216:219], v[120:123]
	v_mfma_f32_16x16x32_bf16 v[116:119], v[174:177], v[224:227], v[116:119]
	v_mfma_f32_16x16x32_bf16 v[112:115], v[186:189], v[224:227], v[112:115]
	v_mfma_f32_16x16x32_bf16 v[108:111], v[174:177], v[232:235], v[108:111]
	v_mfma_f32_16x16x32_bf16 v[104:107], v[186:189], v[232:235], v[104:107]
	v_mfma_f32_16x16x32_bf16 v[100:103], v[174:177], v[240:243], v[100:103]
	v_mfma_f32_16x16x32_bf16 v[96:99], v[186:189], v[240:243], v[96:99]
	s_setprio 0
	s_setprio 1
	v_mfma_f32_16x16x32_bf16 v[60:63], v[190:193], v[212:215], v[60:63]
	v_mfma_f32_16x16x32_bf16 v[56:59], v[198:201], v[212:215], v[56:59]
	v_mfma_f32_16x16x32_bf16 v[52:55], v[190:193], v[220:223], v[52:55]
	v_mfma_f32_16x16x32_bf16 v[48:51], v[198:201], v[220:223], v[48:51]
	v_mfma_f32_16x16x32_bf16 v[44:47], v[190:193], v[228:231], v[44:47]
	v_mfma_f32_16x16x32_bf16 v[40:43], v[198:201], v[228:231], v[40:43]
	v_mfma_f32_16x16x32_bf16 v[36:39], v[190:193], v[236:239], v[36:39]
	v_mfma_f32_16x16x32_bf16 v[32:35], v[198:201], v[236:239], v[32:35]
	v_mfma_f32_16x16x32_bf16 v[60:63], v[194:197], v[216:219], v[60:63]
	v_mfma_f32_16x16x32_bf16 v[56:59], v[208:211], v[216:219], v[56:59]
	v_mfma_f32_16x16x32_bf16 v[52:55], v[194:197], v[224:227], v[52:55]
	v_mfma_f32_16x16x32_bf16 v[48:51], v[208:211], v[224:227], v[48:51]
	v_mfma_f32_16x16x32_bf16 v[44:47], v[194:197], v[232:235], v[44:47]
	v_mfma_f32_16x16x32_bf16 v[40:43], v[208:211], v[232:235], v[40:43]
	v_mfma_f32_16x16x32_bf16 v[36:39], v[194:197], v[240:243], v[36:39]
	v_mfma_f32_16x16x32_bf16 v[32:35], v[208:211], v[240:243], v[32:35]
	s_setprio 0
	s_barrier
	s_add_i32 s3, s94, s84
	v_lshl_add_u64 v[178:179], s[60:61], 0, v[130:131]
	s_mov_b32 m0, s3
	ds_read_b128 v[212:215], v164 offset:16384
	ds_read_b128 v[216:219], v164 offset:17408
	ds_read_b128 v[220:223], v164 offset:18432
	ds_read_b128 v[224:227], v164 offset:19456
	ds_read_b128 v[228:231], v164 offset:20480
	ds_read_b128 v[232:235], v164 offset:21504
	ds_read_b128 v[236:239], v164 offset:22528
	ds_read_b128 v[240:243], v164 offset:23552
	global_load_lds_dwordx4 v[178:179], off
	s_add_i32 m0, s3, 0x2000
	s_add_u32 s14, s60, 0x40000
	v_lshl_add_u64 v[202:203], s[60:61], 0, v[134:135]
	s_addc_u32 s15, s61, 0
	s_add_i32 s3, s95, s84
	global_load_lds_dwordx4 v[202:203], off
	v_lshl_add_u64 v[244:245], s[14:15], 0, v[130:131]
	s_mov_b32 m0, s3
	global_load_lds_dwordx4 v[244:245], off
	v_lshl_add_u64 v[244:245], s[14:15], 0, v[134:135]
	s_add_i32 m0, s3, 0x2000
	s_nop 0
	global_load_lds_dwordx4 v[244:245], off
	s_waitcnt vmcnt(6)
	s_waitcnt lgkmcnt(0)
	s_barrier
; #define PG8_STAGE(bufoff, gbase, voff) do { _Pragma("unroll") for (int _i = 0; _i < 2; ++_i) \
;         __builtin_amdgcn_global_load_lds((const unsigned*)((const char*)(gbase) + (voff)[_i]), (PG8_LAS unsigned*)(lds + (bufoff) + ldsw + _i * 8192), 16, 0, 0); } while (0)
; #define PG8_LDA(dst, b, h) do { _Pragma("unroll") for (int m = 0; m < 4; ++m) _Pragma("unroll") for (int k = 0; k < 2; ++k) dst[m][k] = *(const PG8_LAS bf16x8*)(lds + PG8_SA(b, h) + aoff + m * 2048 + k * 1024); } while (0)
; #define PG8_LDB(dst, b, h) do { _Pragma("unroll") for (int n = 0; n < 2; ++n) _Pragma("unroll") for (int k = 0; k < 2; ++k) dst[n][k] = *(const PG8_LAS bf16x8*)(lds + PG8_SB(b, h) + boff + n * 2048 + k * 1024); } while (0)
; #define PG8_MMA(ai, bj, At, Bt) do { __builtin_amdgcn_s_setprio(1); _Pragma("unroll") for (int m = 0; m < 4; ++m) _Pragma("unroll") for (int n = 0; n < 2; ++n) _Pragma("unroll") for (int k = 0; k < 2; ++k) \
;         acc[ai][bj][m][n] = __builtin_amdgcn_mfma_f32_16x16x32_bf16(Bt[n][k], At[m][k], acc[ai][bj][m][n], 0, 0, 0); __builtin_amdgcn_s_setprio(0); } while (0)
; #define PG8_WAIT_V(n) asm volatile("s_waitcnt vmcnt(" #n ")" ::: "memory")
; #define PG8_WAIT_L(n) asm volatile("s_waitcnt lgkmcnt(" #n ")" ::: "memory")
; #define PG8_BAR __builtin_amdgcn_s_barrier()
; #define PG8_SCHED __builtin_amdgcn_sched_barrier(0)
; template <class Epi, class Sched, bool ALIGN_EPI = false, bool SP2 = false>
; __device__ __forceinline__ void gemm_phase(PG8_LAS unsigned char* lds, const Gemm g, const Sched& S, const Epi& E) {
;     ...
;             PG8_LDA(At, 0, 1); PG8_STAGE(PG8_SB(0, 0), b2, voffB); PG8_STAGE(PG8_SB(0, 1), b2 + hstep, voffB); PG8_STAGE(PG8_SA(0, 0), a2, voffA);
;             PG8_WAIT_V(8); PG8_WAIT_L(0); PG8_BAR; PG8_MMA(1, 0, At, B0); PG8_MMA(1, 1, At, B1); PG8_BAR; PG8_SCHED;
;             PG8_LDB(B0, 1, 0); PG8_LDB(B1, 1, 1); PG8_SCHED; PG8_LDA(At, 1, 0); PG8_STAGE(PG8_SA(0, 1), a2 + hstep, voffA);
;             PG8_WAIT_V(8); PG8_WAIT_L(0); PG8_BAR; PG8_MMA(0, 0, At, B0); PG8_MMA(0, 1, At, B1); PG8_BAR; PG8_SCHED;
	s_setprio 1
	s_waitcnt lgkmcnt(0)
	v_mfma_f32_16x16x32_bf16 v[92:95], v[170:173], v[212:215], v[92:95]
	v_mfma_f32_16x16x32_bf16 v[88:91], v[182:185], v[212:215], v[88:91]
	v_mfma_f32_16x16x32_bf16 v[84:87], v[170:173], v[220:223], v[84:87]
	v_mfma_f32_16x16x32_bf16 v[80:83], v[182:185], v[220:223], v[80:83]
	v_mfma_f32_16x16x32_bf16 v[76:79], v[170:173], v[228:231], v[76:79]
	v_mfma_f32_16x16x32_bf16 v[72:75], v[182:185], v[228:231], v[72:75]
	v_mfma_f32_16x16x32_bf16 v[68:71], v[170:173], v[236:239], v[68:71]
	v_mfma_f32_16x16x32_bf16 v[64:67], v[182:185], v[236:239], v[64:67]
	v_mfma_f32_16x16x32_bf16 v[92:95], v[174:177], v[216:219], v[92:95]
	v_mfma_f32_16x16x32_bf16 v[88:91], v[186:189], v[216:219], v[88:91]
	v_mfma_f32_16x16x32_bf16 v[84:87], v[174:177], v[224:227], v[84:87]
	v_mfma_f32_16x16x32_bf16 v[80:83], v[186:189], v[224:227], v[80:83]
	v_mfma_f32_16x16x32_bf16 v[76:79], v[174:177], v[232:235], v[76:79]
	v_mfma_f32_16x16x32_bf16 v[72:75], v[186:189], v[232:235], v[72:75]
	v_lshl_add_u64 v[244:245], s[62:63], 0, v[128:129]
	s_mov_b32 m0, s85
	s_nop 0
	global_load_lds_dwordx4 v[244:245], off
	v_mfma_f32_16x16x32_bf16 v[68:71], v[174:177], v[240:243], v[68:71]
	v_mfma_f32_16x16x32_bf16 v[64:67], v[186:189], v[240:243], v[64:67]
	s_setprio 0
	s_setprio 1
	v_mfma_f32_16x16x32_bf16 v[28:31], v[190:193], v[212:215], v[28:31]
	v_mfma_f32_16x16x32_bf16 v[24:27], v[198:201], v[212:215], v[24:27]
	v_mfma_f32_16x16x32_bf16 v[20:23], v[190:193], v[220:223], v[20:23]
	v_mfma_f32_16x16x32_bf16 v[16:19], v[198:201], v[220:223], v[16:19]
	v_mfma_f32_16x16x32_bf16 v[12:15], v[190:193], v[228:231], v[12:15]
	v_mfma_f32_16x16x32_bf16 v[8:11], v[198:201], v[228:231], v[8:11]
	v_mfma_f32_16x16x32_bf16 v[4:7], v[190:193], v[236:239], v[4:7]
	v_mfma_f32_16x16x32_bf16 v[0:3], v[198:201], v[236:239], v[0:3]
	v_mfma_f32_16x16x32_bf16 v[28:31], v[194:197], v[216:219], v[28:31]
	v_mfma_f32_16x16x32_bf16 v[24:27], v[208:211], v[216:219], v[24:27]
	v_mfma_f32_16x16x32_bf16 v[20:23], v[194:197], v[224:227], v[20:23]
	v_mfma_f32_16x16x32_bf16 v[16:19], v[208:211], v[224:227], v[16:19]
	v_mfma_f32_16x16x32_bf16 v[12:15], v[194:197], v[232:235], v[12:15]
	v_mfma_f32_16x16x32_bf16 v[8:11], v[208:211], v[232:235], v[8:11]
	v_lshl_add_u64 v[246:247], s[62:63], 0, v[132:133]
	s_mov_b32 m0, s86
	s_nop 0
	global_load_lds_dwordx4 v[246:247], off
	v_mfma_f32_16x16x32_bf16 v[4:7], v[194:197], v[240:243], v[4:7]
	v_mfma_f32_16x16x32_bf16 v[0:3], v[208:211], v[240:243], v[0:3]
	s_setprio 0
	s_barrier
	s_add_i32 s3, 0, 0x18000
	v_add_u32_e32 v136, s3, v141
	s_add_i32 s33, 0, 0x1c000
	ds_read_b128 v[170:173], v136
	ds_read_b128 v[174:177], v136 offset:1024
	ds_read_b128 v[182:185], v136 offset:2048
	ds_read_b128 v[186:189], v136 offset:3072
	v_add_u32_e32 v136, s33, v141
	ds_read_b128 v[190:193], v136
	ds_read_b128 v[194:197], v136 offset:1024
	ds_read_b128 v[198:201], v136 offset:2048
	ds_read_b128 v[208:211], v136 offset:3072
	s_add_u32 s14, s62, 0x40000
	s_addc_u32 s15, s63, 0
	s_mov_b32 m0, s87
	v_lshl_add_u64 v[248:249], s[14:15], 0, v[128:129]
	ds_read_b128 v[212:215], v164 offset:32768
	ds_read_b128 v[216:219], v164 offset:33792
	ds_read_b128 v[220:223], v164 offset:34816
	ds_read_b128 v[224:227], v164 offset:35840
	ds_read_b128 v[228:231], v164 offset:36864
	ds_read_b128 v[232:235], v164 offset:37888
	ds_read_b128 v[236:239], v164 offset:38912
	ds_read_b128 v[240:243], v164 offset:39936
	global_load_lds_dwordx4 v[248:249], off
	v_lshl_add_u64 v[248:249], s[14:15], 0, v[132:133]
	s_mov_b32 m0, s88
	s_nop 0
	global_load_lds_dwordx4 v[248:249], off
	s_waitcnt vmcnt(8)
	s_waitcnt lgkmcnt(0)
	s_barrier
	s_setprio 1
	s_waitcnt lgkmcnt(0)
	v_mfma_f32_16x16x32_bf16 v[124:127], v[170:173], v[212:215], v[124:127]
	v_mfma_f32_16x16x32_bf16 v[120:123], v[182:185], v[212:215], v[120:123]
	v_mfma_f32_16x16x32_bf16 v[116:119], v[170:173], v[220:223], v[116:119]
	v_mfma_f32_16x16x32_bf16 v[112:115], v[182:185], v[220:223], v[112:115]
	v_mfma_f32_16x16x32_bf16 v[108:111], v[170:173], v[228:231], v[108:111]
	v_mfma_f32_16x16x32_bf16 v[104:107], v[182:185], v[228:231], v[104:107]
	v_mfma_f32_16x16x32_bf16 v[100:103], v[170:173], v[236:239], v[100:103]
	v_mfma_f32_16x16x32_bf16 v[96:99], v[182:185], v[236:239], v[96:99]
	v_mfma_f32_16x16x32_bf16 v[124:127], v[174:177], v[216:219], v[124:127]
	v_mfma_f32_16x16x32_bf16 v[120:123], v[186:189], v[216:219], v[120:123]
	v_mfma_f32_16x16x32_bf16 v[116:119], v[174:177], v[224:227], v[116:119]
	v_mfma_f32_16x16x32_bf16 v[112:115], v[186:189], v[224:227], v[112:115]
	v_mfma_f32_16x16x32_bf16 v[108:111], v[174:177], v[232:235], v[108:111]
	v_mfma_f32_16x16x32_bf16 v[104:107], v[186:189], v[232:235], v[104:107]
	v_mfma_f32_16x16x32_bf16 v[100:103], v[174:177], v[240:243], v[100:103]
	v_mfma_f32_16x16x32_bf16 v[96:99], v[186:189], v[240:243], v[96:99]
	s_setprio 0
	s_setprio 1
	v_mfma_f32_16x16x32_bf16 v[60:63], v[190:193], v[212:215], v[60:63]
	v_mfma_f32_16x16x32_bf16 v[56:59], v[198:201], v[212:215], v[56:59]
	v_mfma_f32_16x16x32_bf16 v[52:55], v[190:193], v[220:223], v[52:55]
	v_mfma_f32_16x16x32_bf16 v[48:51], v[198:201], v[220:223], v[48:51]
	v_mfma_f32_16x16x32_bf16 v[44:47], v[190:193], v[228:231], v[44:47]
	v_mfma_f32_16x16x32_bf16 v[40:43], v[198:201], v[228:231], v[40:43]
	v_mfma_f32_16x16x32_bf16 v[36:39], v[190:193], v[236:239], v[36:39]
	v_mfma_f32_16x16x32_bf16 v[32:35], v[198:201], v[236:239], v[32:35]
	v_mfma_f32_16x16x32_bf16 v[60:63], v[194:197], v[216:219], v[60:63]
	v_mfma_f32_16x16x32_bf16 v[56:59], v[208:211], v[216:219], v[56:59]
	v_mfma_f32_16x16x32_bf16 v[52:55], v[194:197], v[224:227], v[52:55]
	v_mfma_f32_16x16x32_bf16 v[48:51], v[208:211], v[224:227], v[48:51]
	v_mfma_f32_16x16x32_bf16 v[44:47], v[194:197], v[232:235], v[44:47]
	v_mfma_f32_16x16x32_bf16 v[40:43], v[208:211], v[232:235], v[40:43]
	v_mfma_f32_16x16x32_bf16 v[36:39], v[194:197], v[240:243], v[36:39]
	v_mfma_f32_16x16x32_bf16 v[32:35], v[208:211], v[240:243], v[32:35]
	s_setprio 0
	s_barrier
; #define PG8_STAGE(bufoff, gbase, voff) do { _Pragma("unroll") for (int _i = 0; _i < 2; ++_i) \
;         __builtin_amdgcn_global_load_lds((const unsigned*)((const char*)(gbase) + (voff)[_i]), (PG8_LAS unsigned*)(lds + (bufoff) + ldsw + _i * 8192), 16, 0, 0); } while (0)
; #define PG8_LDA(dst, b, h) do { _Pragma("unroll") for (int m = 0; m < 4; ++m) _Pragma("unroll") for (int k = 0; k < 2; ++k) dst[m][k] = *(const PG8_LAS bf16x8*)(lds + PG8_SA(b, h) + aoff + m * 2048 + k * 1024); } while (0)
; #define PG8_MMA(ai, bj, At, Bt) do { __builtin_amdgcn_s_setprio(1); _Pragma("unroll") for (int m = 0; m < 4; ++m) _Pragma("unroll") for (int n = 0; n < 2; ++n) _Pragma("unroll") for (int k = 0; k < 2; ++k) \
;         acc[ai][bj][m][n] = __builtin_amdgcn_mfma_f32_16x16x32_bf16(Bt[n][k], At[m][k], acc[ai][bj][m][n], 0, 0, 0); __builtin_amdgcn_s_setprio(0); } while (0)
; #define PG8_WAIT_V(n) asm volatile("s_waitcnt vmcnt(" #n ")" ::: "memory")
; #define PG8_WAIT_L(n) asm volatile("s_waitcnt lgkmcnt(" #n ")" ::: "memory")
; #define PG8_BAR __builtin_amdgcn_s_barrier()
; #define PG8_SCHED __builtin_amdgcn_sched_barrier(0)
; template <class Epi, class Sched, bool ALIGN_EPI = false, bool SP2 = false>
; __device__ __forceinline__ void gemm_phase(PG8_LAS unsigned char* lds, const Gemm g, const Sched& S, const Epi& E) {
;     ...
;             PG8_LDA(At, 1, 1); PG8_STAGE(PG8_SB(1, 0), b3, voffB); PG8_STAGE(PG8_SB(1, 1), b3 + hstep, voffB); PG8_STAGE(PG8_SA(1, 0), a3, voffA);
;             PG8_WAIT_V(8); PG8_WAIT_L(0); PG8_BAR; PG8_MMA(1, 0, At, B0); PG8_MMA(1, 1, At, B1); PG8_BAR; PG8_SCHED;
;     ...
;         if constexpr (ALIGN_EPI) { if (wr == 0) PG8_BAR; }
	s_add_i32 s3, s3, s84
	v_lshl_add_u64 v[178:179], v[178:179], 0, s[8:9]
	s_mov_b32 m0, s3
	ds_read_b128 v[212:215], v164 offset:49152
	ds_read_b128 v[216:219], v164 offset:50176
	ds_read_b128 v[220:223], v164 offset:51200
	ds_read_b128 v[224:227], v164 offset:52224
	ds_read_b128 v[228:231], v164 offset:53248
	ds_read_b128 v[232:235], v164 offset:54272
	ds_read_b128 v[236:239], v164 offset:55296
	ds_read_b128 v[240:243], v164 offset:56320
	global_load_lds_dwordx4 v[178:179], off
	s_add_i32 m0, s3, 0x2000
	s_add_u32 s14, s60, 0x40080
	v_lshl_add_u64 v[178:179], v[202:203], 0, s[8:9]
	s_addc_u32 s15, s61, 0
	s_add_i32 s3, s33, s84
	global_load_lds_dwordx4 v[178:179], off
	v_lshl_add_u64 v[178:179], s[14:15], 0, v[130:131]
	s_mov_b32 m0, s3
	s_nop 0
	global_load_lds_dwordx4 v[178:179], off
	v_lshl_add_u64 v[178:179], s[14:15], 0, v[134:135]
	s_add_i32 m0, s3, 0x2000
	s_nop 0
	global_load_lds_dwordx4 v[178:179], off
	s_waitcnt vmcnt(6)
	s_waitcnt lgkmcnt(0)
	s_barrier
	s_setprio 1
	s_waitcnt lgkmcnt(0)
	v_mfma_f32_16x16x32_bf16 v[92:95], v[170:173], v[212:215], v[92:95]
	v_mfma_f32_16x16x32_bf16 v[88:91], v[182:185], v[212:215], v[88:91]
	v_lshl_add_u64 v[178:179], v[244:245], 0, s[8:9]
	s_mov_b32 m0, s90
	s_nop 0
	global_load_lds_dwordx4 v[178:179], off
	v_mfma_f32_16x16x32_bf16 v[84:87], v[170:173], v[220:223], v[84:87]
	v_mfma_f32_16x16x32_bf16 v[80:83], v[182:185], v[220:223], v[80:83]
	v_mfma_f32_16x16x32_bf16 v[76:79], v[170:173], v[228:231], v[76:79]
	v_mfma_f32_16x16x32_bf16 v[72:75], v[182:185], v[228:231], v[72:75]
	v_lshl_add_u64 v[178:179], v[246:247], 0, s[8:9]
	s_mov_b32 m0, s91
	s_nop 0
	global_load_lds_dwordx4 v[178:179], off
	v_mfma_f32_16x16x32_bf16 v[68:71], v[170:173], v[236:239], v[68:71]
	v_mfma_f32_16x16x32_bf16 v[64:67], v[182:185], v[236:239], v[64:67]
	v_mfma_f32_16x16x32_bf16 v[92:95], v[174:177], v[216:219], v[92:95]
	v_mfma_f32_16x16x32_bf16 v[88:91], v[186:189], v[216:219], v[88:91]
	v_mfma_f32_16x16x32_bf16 v[84:87], v[174:177], v[224:227], v[84:87]
	v_mfma_f32_16x16x32_bf16 v[80:83], v[186:189], v[224:227], v[80:83]
	v_mfma_f32_16x16x32_bf16 v[76:79], v[174:177], v[232:235], v[76:79]
	v_mfma_f32_16x16x32_bf16 v[72:75], v[186:189], v[232:235], v[72:75]
	v_mfma_f32_16x16x32_bf16 v[68:71], v[174:177], v[240:243], v[68:71]
	v_mfma_f32_16x16x32_bf16 v[64:67], v[186:189], v[240:243], v[64:67]
	s_setprio 0
	s_setprio 1
	v_mfma_f32_16x16x32_bf16 v[28:31], v[190:193], v[212:215], v[28:31]
	v_mfma_f32_16x16x32_bf16 v[24:27], v[198:201], v[212:215], v[24:27]
	v_mfma_f32_16x16x32_bf16 v[20:23], v[190:193], v[220:223], v[20:23]
	v_mfma_f32_16x16x32_bf16 v[16:19], v[198:201], v[220:223], v[16:19]
	v_mfma_f32_16x16x32_bf16 v[12:15], v[190:193], v[228:231], v[12:15]
	v_mfma_f32_16x16x32_bf16 v[8:11], v[198:201], v[228:231], v[8:11]
	v_mfma_f32_16x16x32_bf16 v[4:7], v[190:193], v[236:239], v[4:7]
	v_mfma_f32_16x16x32_bf16 v[0:3], v[198:201], v[236:239], v[0:3]
	v_mfma_f32_16x16x32_bf16 v[28:31], v[194:197], v[216:219], v[28:31]
	v_mfma_f32_16x16x32_bf16 v[24:27], v[208:211], v[216:219], v[24:27]
	v_mfma_f32_16x16x32_bf16 v[20:23], v[194:197], v[224:227], v[20:23]
	v_mfma_f32_16x16x32_bf16 v[16:19], v[208:211], v[224:227], v[16:19]
	v_mfma_f32_16x16x32_bf16 v[12:15], v[194:197], v[232:235], v[12:15]
	v_mfma_f32_16x16x32_bf16 v[8:11], v[208:211], v[232:235], v[8:11]
	v_mfma_f32_16x16x32_bf16 v[4:7], v[194:197], v[240:243], v[4:7]
	v_mfma_f32_16x16x32_bf16 v[0:3], v[208:211], v[240:243], v[0:3]
	s_setprio 0
	s_barrier
	s_add_i32 vcc_lo, vcc_lo, 2
	s_add_u32 s58, s58, 0x100
	s_addc_u32 s59, s59, 0
	s_add_u32 s96, s96, 0x100
	s_addc_u32 s97, s97, 0
	s_cmp_gt_u32 vcc_lo, 13
	s_cbranch_scc0 .LBB0_459
	s_and_b64 vcc, exec, s[10:11]
	s_cbranch_vccz .LBB0_462
	s_barrier

; #define PG8_STAGE(bufoff, gbase, voff) do { _Pragma("unroll") for (int _i = 0; _i < 2; ++_i) \
;         __builtin_amdgcn_global_load_lds((const unsigned*)((const char*)(gbase) + (voff)[_i]), (PG8_LAS unsigned*)(lds + (bufoff) + ldsw + _i * 8192), 16, 0, 0); } while (0)
; #define PG8_LDA(dst, b, h) do { _Pragma("unroll") for (int m = 0; m < 4; ++m) _Pragma("unroll") for (int k = 0; k < 2; ++k) dst[m][k] = *(const PG8_LAS bf16x8*)(lds + PG8_SA(b, h) + aoff + m * 2048 + k * 1024); } while (0)
; #define PG8_LDB(dst, b, h) do { _Pragma("unroll") for (int n = 0; n < 2; ++n) _Pragma("unroll") for (int k = 0; k < 2; ++k) dst[n][k] = *(const PG8_LAS bf16x8*)(lds + PG8_SB(b, h) + boff + n * 2048 + k * 1024); } while (0)
; #define PG8_MMA(ai, bj, At, Bt) do { __builtin_amdgcn_s_setprio(1); _Pragma("unroll") for (int m = 0; m < 4; ++m) _Pragma("unroll") for (int n = 0; n < 2; ++n) _Pragma("unroll") for (int k = 0; k < 2; ++k) \
;         acc[ai][bj][m][n] = __builtin_amdgcn_mfma_f32_16x16x32_bf16(Bt[n][k], At[m][k], acc[ai][bj][m][n], 0, 0, 0); __builtin_amdgcn_s_setprio(0); } while (0)
; #define PG8_WAIT_V(n) asm volatile("s_waitcnt vmcnt(" #n ")" ::: "memory")
; #define PG8_WAIT_L(n) asm volatile("s_waitcnt lgkmcnt(" #n ")" ::: "memory")
; #define PG8_BAR __builtin_amdgcn_s_barrier()
; #define PG8_SCHED __builtin_amdgcn_sched_barrier(0)
; template <class Epi, class Sched, bool ALIGN_EPI = false, bool SP2 = false>
; __device__ __forceinline__ void gemm_phase(PG8_LAS unsigned char* lds, const Gemm g, const Sched& S, const Epi& E) {
;     ...
;             const bool last = (t == nt - 2);
;             const char* a1 = cA + (size_t)(t + 1) * kstep;
;             const char* a2 = last ? nA : cA + (size_t)(t + 2) * kstep; const char* b2 = last ? nB : cB + (size_t)(t + 2) * kstep;
;             const char* a3 = a2 + kstep; const char* b3 = b2 + kstep;
;             if (last && has_next) S.a_ready(nxt);
;             if constexpr (SP2) {
;             PG8_LDB(B0, 0, 0); PG8_LDB(B1, 0, 1); PG8_SCHED; PG8_LDA(At, 0, 0); PG8_STAGE(PG8_SA(1, 1), a1 + hstep, voffA);
;             PG8_WAIT_V(8); PG8_WAIT_L(0); PG8_BAR; PG8_MMA(0, 0, At, B0); PG8_MMA(0, 1, At, B1); PG8_BAR; PG8_SCHED;
;             PG8_LDA(At, 0, 1); PG8_STAGE(PG8_SB(0, 0), b2, voffB); PG8_STAGE(PG8_SB(0, 1), b2 + hstep, voffB); PG8_STAGE(PG8_SA(0, 0), a2, voffA);
.LBB0_495:
	ds_read_b128 v[170:173], v165
	ds_read_b128 v[174:177], v165 offset:1024
	ds_read_b128 v[182:185], v165 offset:2048
	ds_read_b128 v[186:189], v165 offset:3072
	ds_read_b128 v[190:193], v168
	ds_read_b128 v[194:197], v168 offset:1024
	ds_read_b128 v[198:201], v168 offset:2048
	ds_read_b128 v[208:211], v168 offset:3072
	s_add_u32 s3, s60, 0xfffc0080
	s_addc_u32 s14, s61, -1
	s_cmp_eq_u32 s97, 12
	s_cselect_b32 s65, s49, s14
	s_cselect_b32 s64, s57, s3
	s_cselect_b32 s63, s45, s96
	s_cselect_b32 s62, s94, s95
	v_lshl_add_u64 v[178:179], s[60:61], 0, v[160:161]
	s_add_i32 m0, s59, 0xc000
	ds_read_b128 v[212:215], v164
	ds_read_b128 v[216:219], v164 offset:1024
	ds_read_b128 v[220:223], v164 offset:2048
	ds_read_b128 v[224:227], v164 offset:3072
	ds_read_b128 v[228:231], v164 offset:4096
	ds_read_b128 v[232:235], v164 offset:5120
	ds_read_b128 v[236:239], v164 offset:6144
	ds_read_b128 v[240:243], v164 offset:7168
	global_load_lds_dwordx4 v[178:179], off
	v_lshl_add_u64 v[178:179], s[60:61], 0, v[162:163]
	s_add_i32 m0, s59, 0xe000
	s_nop 0
	global_load_lds_dwordx4 v[178:179], off
	s_waitcnt vmcnt(8)
	s_waitcnt lgkmcnt(0)
	s_barrier
	s_setprio 1
	s_waitcnt lgkmcnt(0)
	v_mfma_f32_16x16x32_bf16 v[124:127], v[170:173], v[212:215], v[124:127]
	v_mfma_f32_16x16x32_bf16 v[120:123], v[182:185], v[212:215], v[120:123]
	v_mfma_f32_16x16x32_bf16 v[116:119], v[170:173], v[220:223], v[116:119]
	v_mfma_f32_16x16x32_bf16 v[112:115], v[182:185], v[220:223], v[112:115]
	v_mfma_f32_16x16x32_bf16 v[108:111], v[170:173], v[228:231], v[108:111]
	v_mfma_f32_16x16x32_bf16 v[104:107], v[182:185], v[228:231], v[104:107]
	v_mfma_f32_16x16x32_bf16 v[100:103], v[170:173], v[236:239], v[100:103]
	v_mfma_f32_16x16x32_bf16 v[96:99], v[182:185], v[236:239], v[96:99]
	v_mfma_f32_16x16x32_bf16 v[124:127], v[174:177], v[216:219], v[124:127]
	v_mfma_f32_16x16x32_bf16 v[120:123], v[186:189], v[216:219], v[120:123]
	v_mfma_f32_16x16x32_bf16 v[116:119], v[174:177], v[224:227], v[116:119]
	v_mfma_f32_16x16x32_bf16 v[112:115], v[186:189], v[224:227], v[112:115]
	v_mfma_f32_16x16x32_bf16 v[108:111], v[174:177], v[232:235], v[108:111]
	v_mfma_f32_16x16x32_bf16 v[104:107], v[186:189], v[232:235], v[104:107]
	v_mfma_f32_16x16x32_bf16 v[100:103], v[174:177], v[240:243], v[100:103]
	v_mfma_f32_16x16x32_bf16 v[96:99], v[186:189], v[240:243], v[96:99]
	s_setprio 0
	s_setprio 1
	v_mfma_f32_16x16x32_bf16 v[60:63], v[190:193], v[212:215], v[60:63]
	v_mfma_f32_16x16x32_bf16 v[56:59], v[198:201], v[212:215], v[56:59]
	v_mfma_f32_16x16x32_bf16 v[52:55], v[190:193], v[220:223], v[52:55]
	v_mfma_f32_16x16x32_bf16 v[48:51], v[198:201], v[220:223], v[48:51]
	v_mfma_f32_16x16x32_bf16 v[44:47], v[190:193], v[228:231], v[44:47]
	v_mfma_f32_16x16x32_bf16 v[40:43], v[198:201], v[228:231], v[40:43]
	v_mfma_f32_16x16x32_bf16 v[36:39], v[190:193], v[236:239], v[36:39]
	v_mfma_f32_16x16x32_bf16 v[32:35], v[198:201], v[236:239], v[32:35]
	v_mfma_f32_16x16x32_bf16 v[60:63], v[194:197], v[216:219], v[60:63]
	v_mfma_f32_16x16x32_bf16 v[56:59], v[208:211], v[216:219], v[56:59]
	v_mfma_f32_16x16x32_bf16 v[52:55], v[194:197], v[224:227], v[52:55]
	v_mfma_f32_16x16x32_bf16 v[48:51], v[208:211], v[224:227], v[48:51]
	v_mfma_f32_16x16x32_bf16 v[44:47], v[194:197], v[232:235], v[44:47]
	v_mfma_f32_16x16x32_bf16 v[40:43], v[208:211], v[232:235], v[40:43]
	v_mfma_f32_16x16x32_bf16 v[36:39], v[194:197], v[240:243], v[36:39]
	v_mfma_f32_16x16x32_bf16 v[32:35], v[208:211], v[240:243], v[32:35]
	s_setprio 0
	s_barrier
	s_add_i32 s3, s92, s75
	v_lshl_add_u64 v[178:179], s[62:63], 0, v[130:131]
	s_mov_b32 m0, s3
	ds_read_b128 v[212:215], v164 offset:16384
	ds_read_b128 v[216:219], v164 offset:17408
	ds_read_b128 v[220:223], v164 offset:18432
	ds_read_b128 v[224:227], v164 offset:19456
	ds_read_b128 v[228:231], v164 offset:20480
	ds_read_b128 v[232:235], v164 offset:21504
	ds_read_b128 v[236:239], v164 offset:22528
	ds_read_b128 v[240:243], v164 offset:23552
	global_load_lds_dwordx4 v[178:179], off
	s_add_i32 m0, s3, 0x2000
	s_add_u32 s14, s62, 0x40000
	v_lshl_add_u64 v[202:203], s[62:63], 0, v[134:135]
	s_addc_u32 s15, s63, 0
	s_add_i32 s3, s93, s75
	global_load_lds_dwordx4 v[202:203], off
	v_lshl_add_u64 v[244:245], s[14:15], 0, v[130:131]
	s_mov_b32 m0, s3
	global_load_lds_dwordx4 v[244:245], off
	v_lshl_add_u64 v[244:245], s[14:15], 0, v[134:135]
	s_add_i32 m0, s3, 0x2000
	s_nop 0
	global_load_lds_dwordx4 v[244:245], off
	s_waitcnt vmcnt(6)
	s_waitcnt lgkmcnt(0)
	s_barrier
; #define PG8_STAGE(bufoff, gbase, voff) do { _Pragma("unroll") for (int _i = 0; _i < 2; ++_i) \
;         __builtin_amdgcn_global_load_lds((const unsigned*)((const char*)(gbase) + (voff)[_i]), (PG8_LAS unsigned*)(lds + (bufoff) + ldsw + _i * 8192), 16, 0, 0); } while (0)
; #define PG8_LDA(dst, b, h) do { _Pragma("unroll") for (int m = 0; m < 4; ++m) _Pragma("unroll") for (int k = 0; k < 2; ++k) dst[m][k] = *(const PG8_LAS bf16x8*)(lds + PG8_SA(b, h) + aoff + m * 2048 + k * 1024); } while (0)
; #define PG8_LDB(dst, b, h) do { _Pragma("unroll") for (int n = 0; n < 2; ++n) _Pragma("unroll") for (int k = 0; k < 2; ++k) dst[n][k] = *(const PG8_LAS bf16x8*)(lds + PG8_SB(b, h) + boff + n * 2048 + k * 1024); } while (0)
; #define PG8_MMA(ai, bj, At, Bt) do { __builtin_amdgcn_s_setprio(1); _Pragma("unroll") for (int m = 0; m < 4; ++m) _Pragma("unroll") for (int n = 0; n < 2; ++n) _Pragma("unroll") for (int k = 0; k < 2; ++k) \
;         acc[ai][bj][m][n] = __builtin_amdgcn_mfma_f32_16x16x32_bf16(Bt[n][k], At[m][k], acc[ai][bj][m][n], 0, 0, 0); __builtin_amdgcn_s_setprio(0); } while (0)
; #define PG8_WAIT_V(n) asm volatile("s_waitcnt vmcnt(" #n ")" ::: "memory")
; #define PG8_WAIT_L(n) asm volatile("s_waitcnt lgkmcnt(" #n ")" ::: "memory")
; #define PG8_BAR __builtin_amdgcn_s_barrier()
; #define PG8_SCHED __builtin_amdgcn_sched_barrier(0)
; template <class Epi, class Sched, bool ALIGN_EPI = false, bool SP2 = false>
; __device__ __forceinline__ void gemm_phase(PG8_LAS unsigned char* lds, const Gemm g, const Sched& S, const Epi& E) {
;     ...
;             PG8_LDA(At, 0, 1); PG8_STAGE(PG8_SB(0, 0), b2, voffB); PG8_STAGE(PG8_SB(0, 1), b2 + hstep, voffB); PG8_STAGE(PG8_SA(0, 0), a2, voffA);
;             PG8_WAIT_V(8); PG8_WAIT_L(0); PG8_BAR; PG8_MMA(1, 0, At, B0); PG8_MMA(1, 1, At, B1); PG8_BAR; PG8_SCHED;
;             PG8_LDB(B0, 1, 0); PG8_LDB(B1, 1, 1); PG8_SCHED; PG8_LDA(At, 1, 0); PG8_STAGE(PG8_SA(0, 1), a2 + hstep, voffA);
;             PG8_WAIT_V(8); PG8_WAIT_L(0); PG8_BAR; PG8_MMA(0, 0, At, B0); PG8_MMA(0, 1, At, B1); PG8_BAR; PG8_SCHED;
	s_setprio 1
	s_waitcnt lgkmcnt(0)
	v_mfma_f32_16x16x32_bf16 v[92:95], v[170:173], v[212:215], v[92:95]
	v_mfma_f32_16x16x32_bf16 v[88:91], v[182:185], v[212:215], v[88:91]
	v_mfma_f32_16x16x32_bf16 v[84:87], v[170:173], v[220:223], v[84:87]
	v_mfma_f32_16x16x32_bf16 v[80:83], v[182:185], v[220:223], v[80:83]
	v_mfma_f32_16x16x32_bf16 v[76:79], v[170:173], v[228:231], v[76:79]
	v_mfma_f32_16x16x32_bf16 v[72:75], v[182:185], v[228:231], v[72:75]
	v_mfma_f32_16x16x32_bf16 v[68:71], v[170:173], v[236:239], v[68:71]
	v_mfma_f32_16x16x32_bf16 v[64:67], v[182:185], v[236:239], v[64:67]
	v_mfma_f32_16x16x32_bf16 v[92:95], v[174:177], v[216:219], v[92:95]
	v_mfma_f32_16x16x32_bf16 v[88:91], v[186:189], v[216:219], v[88:91]
	v_mfma_f32_16x16x32_bf16 v[84:87], v[174:177], v[224:227], v[84:87]
	v_mfma_f32_16x16x32_bf16 v[80:83], v[186:189], v[224:227], v[80:83]
	v_mfma_f32_16x16x32_bf16 v[76:79], v[174:177], v[232:235], v[76:79]
	v_mfma_f32_16x16x32_bf16 v[72:75], v[186:189], v[232:235], v[72:75]
	v_lshl_add_u64 v[244:245], s[64:65], 0, v[128:129]
	s_mov_b32 m0, s59
	s_nop 0
	global_load_lds_dwordx4 v[244:245], off
	v_mfma_f32_16x16x32_bf16 v[68:71], v[174:177], v[240:243], v[68:71]
	v_mfma_f32_16x16x32_bf16 v[64:67], v[186:189], v[240:243], v[64:67]
	s_setprio 0
	s_setprio 1
	v_mfma_f32_16x16x32_bf16 v[28:31], v[190:193], v[212:215], v[28:31]
	v_mfma_f32_16x16x32_bf16 v[24:27], v[198:201], v[212:215], v[24:27]
	v_mfma_f32_16x16x32_bf16 v[20:23], v[190:193], v[220:223], v[20:23]
	v_mfma_f32_16x16x32_bf16 v[16:19], v[198:201], v[220:223], v[16:19]
	v_mfma_f32_16x16x32_bf16 v[12:15], v[190:193], v[228:231], v[12:15]
	v_mfma_f32_16x16x32_bf16 v[8:11], v[198:201], v[228:231], v[8:11]
	v_mfma_f32_16x16x32_bf16 v[4:7], v[190:193], v[236:239], v[4:7]
	v_mfma_f32_16x16x32_bf16 v[0:3], v[198:201], v[236:239], v[0:3]
	v_mfma_f32_16x16x32_bf16 v[28:31], v[194:197], v[216:219], v[28:31]
	v_mfma_f32_16x16x32_bf16 v[24:27], v[208:211], v[216:219], v[24:27]
	v_mfma_f32_16x16x32_bf16 v[20:23], v[194:197], v[224:227], v[20:23]
	v_mfma_f32_16x16x32_bf16 v[16:19], v[208:211], v[224:227], v[16:19]
	v_mfma_f32_16x16x32_bf16 v[12:15], v[194:197], v[232:235], v[12:15]
	v_mfma_f32_16x16x32_bf16 v[8:11], v[208:211], v[232:235], v[8:11]
	v_lshl_add_u64 v[246:247], s[64:65], 0, v[132:133]
	s_mov_b32 m0, s84
	s_nop 0
	global_load_lds_dwordx4 v[246:247], off
	v_mfma_f32_16x16x32_bf16 v[4:7], v[194:197], v[240:243], v[4:7]
	v_mfma_f32_16x16x32_bf16 v[0:3], v[208:211], v[240:243], v[0:3]
	s_setprio 0
	s_barrier
	s_add_i32 s3, 0, 0x18000
	v_add_u32_e32 v136, s3, v141
	s_add_i32 s33, 0, 0x1c000
	ds_read_b128 v[170:173], v136
	ds_read_b128 v[174:177], v136 offset:1024
	ds_read_b128 v[182:185], v136 offset:2048
	ds_read_b128 v[186:189], v136 offset:3072
	v_add_u32_e32 v136, s33, v141
	ds_read_b128 v[190:193], v136
	ds_read_b128 v[194:197], v136 offset:1024
	ds_read_b128 v[198:201], v136 offset:2048
	ds_read_b128 v[208:211], v136 offset:3072
	s_add_u32 s14, s64, 0x40000
	s_addc_u32 s15, s65, 0
	s_mov_b32 m0, s85
	v_lshl_add_u64 v[248:249], s[14:15], 0, v[128:129]
	ds_read_b128 v[212:215], v164 offset:32768
	ds_read_b128 v[216:219], v164 offset:33792
	ds_read_b128 v[220:223], v164 offset:34816
	ds_read_b128 v[224:227], v164 offset:35840
	ds_read_b128 v[228:231], v164 offset:36864
	ds_read_b128 v[232:235], v164 offset:37888
	ds_read_b128 v[236:239], v164 offset:38912
	ds_read_b128 v[240:243], v164 offset:39936
	global_load_lds_dwordx4 v[248:249], off
	v_lshl_add_u64 v[248:249], s[14:15], 0, v[132:133]
	s_mov_b32 m0, s86
	s_nop 0
	global_load_lds_dwordx4 v[248:249], off
	s_waitcnt vmcnt(8)
	s_waitcnt lgkmcnt(0)
	s_barrier
	s_setprio 1
	s_waitcnt lgkmcnt(0)
	v_mfma_f32_16x16x32_bf16 v[124:127], v[170:173], v[212:215], v[124:127]
	v_mfma_f32_16x16x32_bf16 v[120:123], v[182:185], v[212:215], v[120:123]
	v_mfma_f32_16x16x32_bf16 v[116:119], v[170:173], v[220:223], v[116:119]
	v_mfma_f32_16x16x32_bf16 v[112:115], v[182:185], v[220:223], v[112:115]
	v_mfma_f32_16x16x32_bf16 v[108:111], v[170:173], v[228:231], v[108:111]
	v_mfma_f32_16x16x32_bf16 v[104:107], v[182:185], v[228:231], v[104:107]
	v_mfma_f32_16x16x32_bf16 v[100:103], v[170:173], v[236:239], v[100:103]
	v_mfma_f32_16x16x32_bf16 v[96:99], v[182:185], v[236:239], v[96:99]
	v_mfma_f32_16x16x32_bf16 v[124:127], v[174:177], v[216:219], v[124:127]
	v_mfma_f32_16x16x32_bf16 v[120:123], v[186:189], v[216:219], v[120:123]
	v_mfma_f32_16x16x32_bf16 v[116:119], v[174:177], v[224:227], v[116:119]
	v_mfma_f32_16x16x32_bf16 v[112:115], v[186:189], v[224:227], v[112:115]
	v_mfma_f32_16x16x32_bf16 v[108:111], v[174:177], v[232:235], v[108:111]
	v_mfma_f32_16x16x32_bf16 v[104:107], v[186:189], v[232:235], v[104:107]
	v_mfma_f32_16x16x32_bf16 v[100:103], v[174:177], v[240:243], v[100:103]
	v_mfma_f32_16x16x32_bf16 v[96:99], v[186:189], v[240:243], v[96:99]
	s_setprio 0
	s_setprio 1
	v_mfma_f32_16x16x32_bf16 v[60:63], v[190:193], v[212:215], v[60:63]
	v_mfma_f32_16x16x32_bf16 v[56:59], v[198:201], v[212:215], v[56:59]
	v_mfma_f32_16x16x32_bf16 v[52:55], v[190:193], v[220:223], v[52:55]
	v_mfma_f32_16x16x32_bf16 v[48:51], v[198:201], v[220:223], v[48:51]
	v_mfma_f32_16x16x32_bf16 v[44:47], v[190:193], v[228:231], v[44:47]
	v_mfma_f32_16x16x32_bf16 v[40:43], v[198:201], v[228:231], v[40:43]
	v_mfma_f32_16x16x32_bf16 v[36:39], v[190:193], v[236:239], v[36:39]
	v_mfma_f32_16x16x32_bf16 v[32:35], v[198:201], v[236:239], v[32:35]
	v_mfma_f32_16x16x32_bf16 v[60:63], v[194:197], v[216:219], v[60:63]
	v_mfma_f32_16x16x32_bf16 v[56:59], v[208:211], v[216:219], v[56:59]
	v_mfma_f32_16x16x32_bf16 v[52:55], v[194:197], v[224:227], v[52:55]
	v_mfma_f32_16x16x32_bf16 v[48:51], v[208:211], v[224:227], v[48:51]
	v_mfma_f32_16x16x32_bf16 v[44:47], v[194:197], v[232:235], v[44:47]
	v_mfma_f32_16x16x32_bf16 v[40:43], v[208:211], v[232:235], v[40:43]
	v_mfma_f32_16x16x32_bf16 v[36:39], v[194:197], v[240:243], v[36:39]
	v_mfma_f32_16x16x32_bf16 v[32:35], v[208:211], v[240:243], v[32:35]
	s_setprio 0
	s_barrier
; #define PG8_STAGE(bufoff, gbase, voff) do { _Pragma("unroll") for (int _i = 0; _i < 2; ++_i) \
;         __builtin_amdgcn_global_load_lds((const unsigned*)((const char*)(gbase) + (voff)[_i]), (PG8_LAS unsigned*)(lds + (bufoff) + ldsw + _i * 8192), 16, 0, 0); } while (0)
; #define PG8_LDA(dst, b, h) do { _Pragma("unroll") for (int m = 0; m < 4; ++m) _Pragma("unroll") for (int k = 0; k < 2; ++k) dst[m][k] = *(const PG8_LAS bf16x8*)(lds + PG8_SA(b, h) + aoff + m * 2048 + k * 1024); } while (0)
; #define PG8_MMA(ai, bj, At, Bt) do { __builtin_amdgcn_s_setprio(1); _Pragma("unroll") for (int m = 0; m < 4; ++m) _Pragma("unroll") for (int n = 0; n < 2; ++n) _Pragma("unroll") for (int k = 0; k < 2; ++k) \
;         acc[ai][bj][m][n] = __builtin_amdgcn_mfma_f32_16x16x32_bf16(Bt[n][k], At[m][k], acc[ai][bj][m][n], 0, 0, 0); __builtin_amdgcn_s_setprio(0); } while (0)
; #define PG8_WAIT_V(n) asm volatile("s_waitcnt vmcnt(" #n ")" ::: "memory")
; #define PG8_WAIT_L(n) asm volatile("s_waitcnt lgkmcnt(" #n ")" ::: "memory")
; #define PG8_BAR __builtin_amdgcn_s_barrier()
; #define PG8_SCHED __builtin_amdgcn_sched_barrier(0)
; template <class Epi, class Sched, bool ALIGN_EPI = false, bool SP2 = false>
; __device__ __forceinline__ void gemm_phase(PG8_LAS unsigned char* lds, const Gemm g, const Sched& S, const Epi& E) {
;     ...
;             PG8_LDA(At, 1, 1); PG8_STAGE(PG8_SB(1, 0), b3, voffB); PG8_STAGE(PG8_SB(1, 1), b3 + hstep, voffB); PG8_STAGE(PG8_SA(1, 0), a3, voffA);
;             PG8_WAIT_V(8); PG8_WAIT_L(0); PG8_BAR; PG8_MMA(1, 0, At, B0); PG8_MMA(1, 1, At, B1); PG8_BAR; PG8_SCHED;
;     ...
;         if constexpr (ALIGN_EPI) { if (wr == 0) PG8_BAR; }
	s_add_i32 s3, s3, s75
	v_lshl_add_u64 v[178:179], v[178:179], 0, s[10:11]
	s_mov_b32 m0, s3
	ds_read_b128 v[212:215], v164 offset:49152
	ds_read_b128 v[216:219], v164 offset:50176
	ds_read_b128 v[220:223], v164 offset:51200
	ds_read_b128 v[224:227], v164 offset:52224
	ds_read_b128 v[228:231], v164 offset:53248
	ds_read_b128 v[232:235], v164 offset:54272
	ds_read_b128 v[236:239], v164 offset:55296
	ds_read_b128 v[240:243], v164 offset:56320
	global_load_lds_dwordx4 v[178:179], off
	s_add_i32 m0, s3, 0x2000
	s_add_u32 s14, s62, 0x40080
	v_lshl_add_u64 v[178:179], v[202:203], 0, s[10:11]
	s_addc_u32 s15, s63, 0
	s_add_i32 s3, s33, s75
	global_load_lds_dwordx4 v[178:179], off
	v_lshl_add_u64 v[178:179], s[14:15], 0, v[130:131]
	s_mov_b32 m0, s3
	s_nop 0
	global_load_lds_dwordx4 v[178:179], off
	v_lshl_add_u64 v[178:179], s[14:15], 0, v[134:135]
	s_add_i32 m0, s3, 0x2000
	s_nop 0
	global_load_lds_dwordx4 v[178:179], off
	s_waitcnt vmcnt(6)
	s_waitcnt lgkmcnt(0)
	s_barrier
	s_setprio 1
	s_waitcnt lgkmcnt(0)
	v_mfma_f32_16x16x32_bf16 v[92:95], v[170:173], v[212:215], v[92:95]
	v_mfma_f32_16x16x32_bf16 v[88:91], v[182:185], v[212:215], v[88:91]
	v_lshl_add_u64 v[178:179], v[244:245], 0, s[10:11]
	s_mov_b32 m0, s88
	s_nop 0
	global_load_lds_dwordx4 v[178:179], off
	v_mfma_f32_16x16x32_bf16 v[84:87], v[170:173], v[220:223], v[84:87]
	v_mfma_f32_16x16x32_bf16 v[80:83], v[182:185], v[220:223], v[80:83]
	v_mfma_f32_16x16x32_bf16 v[76:79], v[170:173], v[228:231], v[76:79]
	v_mfma_f32_16x16x32_bf16 v[72:75], v[182:185], v[228:231], v[72:75]
	v_lshl_add_u64 v[178:179], v[246:247], 0, s[10:11]
	s_mov_b32 m0, s89
	s_nop 0
	global_load_lds_dwordx4 v[178:179], off
	v_mfma_f32_16x16x32_bf16 v[68:71], v[170:173], v[236:239], v[68:71]
	v_mfma_f32_16x16x32_bf16 v[64:67], v[182:185], v[236:239], v[64:67]
	v_mfma_f32_16x16x32_bf16 v[92:95], v[174:177], v[216:219], v[92:95]
	v_mfma_f32_16x16x32_bf16 v[88:91], v[186:189], v[216:219], v[88:91]
	v_mfma_f32_16x16x32_bf16 v[84:87], v[174:177], v[224:227], v[84:87]
	v_mfma_f32_16x16x32_bf16 v[80:83], v[186:189], v[224:227], v[80:83]
	v_mfma_f32_16x16x32_bf16 v[76:79], v[174:177], v[232:235], v[76:79]
	v_mfma_f32_16x16x32_bf16 v[72:75], v[186:189], v[232:235], v[72:75]
	v_mfma_f32_16x16x32_bf16 v[68:71], v[174:177], v[240:243], v[68:71]
	v_mfma_f32_16x16x32_bf16 v[64:67], v[186:189], v[240:243], v[64:67]
	s_setprio 0
	s_setprio 1
	v_mfma_f32_16x16x32_bf16 v[28:31], v[190:193], v[212:215], v[28:31]
	v_mfma_f32_16x16x32_bf16 v[24:27], v[198:201], v[212:215], v[24:27]
	v_mfma_f32_16x16x32_bf16 v[20:23], v[190:193], v[220:223], v[20:23]
	v_mfma_f32_16x16x32_bf16 v[16:19], v[198:201], v[220:223], v[16:19]
	v_mfma_f32_16x16x32_bf16 v[12:15], v[190:193], v[228:231], v[12:15]
	v_mfma_f32_16x16x32_bf16 v[8:11], v[198:201], v[228:231], v[8:11]
	v_mfma_f32_16x16x32_bf16 v[4:7], v[190:193], v[236:239], v[4:7]
	v_mfma_f32_16x16x32_bf16 v[0:3], v[198:201], v[236:239], v[0:3]
	v_mfma_f32_16x16x32_bf16 v[28:31], v[194:197], v[216:219], v[28:31]
	v_mfma_f32_16x16x32_bf16 v[24:27], v[208:211], v[216:219], v[24:27]
	v_mfma_f32_16x16x32_bf16 v[20:23], v[194:197], v[224:227], v[20:23]
	v_mfma_f32_16x16x32_bf16 v[16:19], v[208:211], v[224:227], v[16:19]
	v_mfma_f32_16x16x32_bf16 v[12:15], v[194:197], v[232:235], v[12:15]
	v_mfma_f32_16x16x32_bf16 v[8:11], v[208:211], v[232:235], v[8:11]
	v_mfma_f32_16x16x32_bf16 v[4:7], v[194:197], v[240:243], v[4:7]
	v_mfma_f32_16x16x32_bf16 v[0:3], v[208:211], v[240:243], v[0:3]
	s_setprio 0
	s_barrier
	s_add_i32 s97, s97, 2
	s_add_u32 s60, s60, 0x100
	s_addc_u32 s61, s61, 0
	s_add_u32 s95, s95, 0x100
	s_addc_u32 s96, s96, 0
	s_cmp_lt_u32 s97, 14
	s_cbranch_scc1 .LBB0_495
	s_andn2_b64 vcc, exec, s[40:41]
	s_cbranch_vccnz .LBB0_498
	s_barrier

; #define PG8_STAGE(bufoff, gbase, voff) do { _Pragma("unroll") for (int _i = 0; _i < 2; ++_i) \
;         __builtin_amdgcn_global_load_lds((const unsigned*)((const char*)(gbase) + (voff)[_i]), (PG8_LAS unsigned*)(lds + (bufoff) + ldsw + _i * 8192), 16, 0, 0); } while (0)
; #define PG8_LDA(dst, b, h) do { _Pragma("unroll") for (int m = 0; m < 4; ++m) _Pragma("unroll") for (int k = 0; k < 2; ++k) dst[m][k] = *(const PG8_LAS bf16x8*)(lds + PG8_SA(b, h) + aoff + m * 2048 + k * 1024); } while (0)
; #define PG8_LDB(dst, b, h) do { _Pragma("unroll") for (int n = 0; n < 2; ++n) _Pragma("unroll") for (int k = 0; k < 2; ++k) dst[n][k] = *(const PG8_LAS bf16x8*)(lds + PG8_SB(b, h) + boff + n * 2048 + k * 1024); } while (0)
; #define PG8_MMA(ai, bj, At, Bt) do { __builtin_amdgcn_s_setprio(1); _Pragma("unroll") for (int m = 0; m < 4; ++m) _Pragma("unroll") for (int n = 0; n < 2; ++n) _Pragma("unroll") for (int k = 0; k < 2; ++k) \
;         acc[ai][bj][m][n] = __builtin_amdgcn_mfma_f32_16x16x32_bf16(Bt[n][k], At[m][k], acc[ai][bj][m][n], 0, 0, 0); __builtin_amdgcn_s_setprio(0); } while (0)
; #define PG8_WAIT_V(n) asm volatile("s_waitcnt vmcnt(" #n ")" ::: "memory")
; #define PG8_WAIT_L(n) asm volatile("s_waitcnt lgkmcnt(" #n ")" ::: "memory")
; #define PG8_BAR __builtin_amdgcn_s_barrier()
; #define PG8_SCHED __builtin_amdgcn_sched_barrier(0)
; template <class Epi, class Sched, bool ALIGN_EPI = false, bool SP2 = false>
; __device__ __forceinline__ void gemm_phase(PG8_LAS unsigned char* lds, const Gemm g, const Sched& S, const Epi& E) {
;     ...
;             const bool last = (t == nt - 2);
;             const char* a1 = cA + (size_t)(t + 1) * kstep;
;             const char* a2 = last ? nA : cA + (size_t)(t + 2) * kstep; const char* b2 = last ? nB : cB + (size_t)(t + 2) * kstep;
;             const char* a3 = a2 + kstep; const char* b3 = b2 + kstep;
;             if (last && has_next) S.a_ready(nxt);
;             if constexpr (SP2) {
;             PG8_LDB(B0, 0, 0); PG8_LDB(B1, 0, 1); PG8_SCHED; PG8_LDA(At, 0, 0); PG8_STAGE(PG8_SA(1, 1), a1 + hstep, voffA);
;             PG8_WAIT_V(8); PG8_WAIT_L(0); PG8_BAR; PG8_MMA(0, 0, At, B0); PG8_MMA(0, 1, At, B1); PG8_BAR; PG8_SCHED;
;             PG8_LDA(At, 0, 1); PG8_STAGE(PG8_SB(0, 0), b2, voffB); PG8_STAGE(PG8_SB(0, 1), b2 + hstep, voffB); PG8_STAGE(PG8_SA(0, 0), a2, voffA);
.LBB0_650:
	ds_read_b128 v[148:151], v155
	ds_read_b128 v[160:163], v155 offset:1024
	ds_read_b128 v[164:167], v155 offset:2048
	ds_read_b128 v[168:171], v155 offset:3072
	ds_read_b128 v[172:175], v156
	ds_read_b128 v[176:179], v156 offset:1024
	ds_read_b128 v[182:185], v156 offset:2048
	ds_read_b128 v[186:189], v156 offset:3072
	s_add_u32 s3, s60, 0xfffc0080
	s_addc_u32 s14, s61, -1
	s_cmp_eq_u32 s92, 12
	s_cselect_b32 s65, s51, s14
	s_cselect_b32 s64, s57, s3
	s_cselect_b32 s63, s49, s91
	s_cselect_b32 s62, s89, s90
	v_lshl_add_u64 v[202:203], s[60:61], 0, v[140:141]
	s_add_i32 m0, s43, 0xc000
	ds_read_b128 v[190:193], v157
	ds_read_b128 v[194:197], v157 offset:1024
	ds_read_b128 v[198:201], v157 offset:2048
	ds_read_b128 v[208:211], v157 offset:3072
	ds_read_b128 v[212:215], v157 offset:4096
	ds_read_b128 v[216:219], v157 offset:5120
	ds_read_b128 v[220:223], v157 offset:6144
	ds_read_b128 v[224:227], v157 offset:7168
	global_load_lds_dwordx4 v[202:203], off
	v_lshl_add_u64 v[202:203], s[60:61], 0, v[142:143]
	s_add_i32 m0, s43, 0xe000
	s_nop 0
	global_load_lds_dwordx4 v[202:203], off
	s_waitcnt vmcnt(8)
	s_waitcnt lgkmcnt(0)
	s_barrier
	s_setprio 1
	s_waitcnt lgkmcnt(0)
	v_mfma_f32_16x16x32_bf16 v[124:127], v[148:151], v[190:193], v[124:127]
	v_mfma_f32_16x16x32_bf16 v[120:123], v[164:167], v[190:193], v[120:123]
	v_mfma_f32_16x16x32_bf16 v[108:111], v[148:151], v[198:201], v[108:111]
	v_mfma_f32_16x16x32_bf16 v[104:107], v[164:167], v[198:201], v[104:107]
	v_mfma_f32_16x16x32_bf16 v[92:95], v[148:151], v[212:215], v[92:95]
	v_mfma_f32_16x16x32_bf16 v[88:91], v[164:167], v[212:215], v[88:91]
	v_mfma_f32_16x16x32_bf16 v[76:79], v[148:151], v[220:223], v[76:79]
	v_mfma_f32_16x16x32_bf16 v[72:75], v[164:167], v[220:223], v[72:75]
	v_mfma_f32_16x16x32_bf16 v[124:127], v[160:163], v[194:197], v[124:127]
	v_mfma_f32_16x16x32_bf16 v[120:123], v[168:171], v[194:197], v[120:123]
	v_mfma_f32_16x16x32_bf16 v[108:111], v[160:163], v[208:211], v[108:111]
	v_mfma_f32_16x16x32_bf16 v[104:107], v[168:171], v[208:211], v[104:107]
	v_mfma_f32_16x16x32_bf16 v[92:95], v[160:163], v[216:219], v[92:95]
	v_mfma_f32_16x16x32_bf16 v[88:91], v[168:171], v[216:219], v[88:91]
	v_mfma_f32_16x16x32_bf16 v[76:79], v[160:163], v[224:227], v[76:79]
	v_mfma_f32_16x16x32_bf16 v[72:75], v[168:171], v[224:227], v[72:75]
	s_setprio 0
	s_setprio 1
	v_mfma_f32_16x16x32_bf16 v[116:119], v[172:175], v[190:193], v[116:119]
	v_mfma_f32_16x16x32_bf16 v[112:115], v[182:185], v[190:193], v[112:115]
	v_mfma_f32_16x16x32_bf16 v[100:103], v[172:175], v[198:201], v[100:103]
	v_mfma_f32_16x16x32_bf16 v[96:99], v[182:185], v[198:201], v[96:99]
	v_mfma_f32_16x16x32_bf16 v[84:87], v[172:175], v[212:215], v[84:87]
	v_mfma_f32_16x16x32_bf16 v[80:83], v[182:185], v[212:215], v[80:83]
	v_mfma_f32_16x16x32_bf16 v[68:71], v[172:175], v[220:223], v[68:71]
	v_mfma_f32_16x16x32_bf16 v[64:67], v[182:185], v[220:223], v[64:67]
	v_mfma_f32_16x16x32_bf16 v[116:119], v[176:179], v[194:197], v[116:119]
	v_mfma_f32_16x16x32_bf16 v[112:115], v[186:189], v[194:197], v[112:115]
	v_mfma_f32_16x16x32_bf16 v[100:103], v[176:179], v[208:211], v[100:103]
	v_mfma_f32_16x16x32_bf16 v[96:99], v[186:189], v[208:211], v[96:99]
	v_mfma_f32_16x16x32_bf16 v[84:87], v[176:179], v[216:219], v[84:87]
	v_mfma_f32_16x16x32_bf16 v[80:83], v[186:189], v[216:219], v[80:83]
	v_mfma_f32_16x16x32_bf16 v[68:71], v[176:179], v[224:227], v[68:71]
	v_mfma_f32_16x16x32_bf16 v[64:67], v[186:189], v[224:227], v[64:67]
	s_setprio 0
	s_barrier
	s_add_i32 s3, s85, s34
	v_lshl_add_u64 v[202:203], s[62:63], 0, v[134:135]
	s_mov_b32 m0, s3
	ds_read_b128 v[190:193], v157 offset:16384
	ds_read_b128 v[194:197], v157 offset:17408
	ds_read_b128 v[198:201], v157 offset:18432
	ds_read_b128 v[208:211], v157 offset:19456
	ds_read_b128 v[212:215], v157 offset:20480
	ds_read_b128 v[216:219], v157 offset:21504
	ds_read_b128 v[220:223], v157 offset:22528
	ds_read_b128 v[224:227], v157 offset:23552
	global_load_lds_dwordx4 v[202:203], off
	s_add_i32 m0, s3, 0x2000
	s_add_u32 s14, s62, 0x40000
	v_lshl_add_u64 v[228:229], s[62:63], 0, v[138:139]
	s_addc_u32 s15, s63, 0
	s_add_i32 s3, s86, s34
	global_load_lds_dwordx4 v[228:229], off
	v_lshl_add_u64 v[230:231], s[14:15], 0, v[134:135]
	s_mov_b32 m0, s3
	global_load_lds_dwordx4 v[230:231], off
	v_lshl_add_u64 v[230:231], s[14:15], 0, v[138:139]
	s_add_i32 m0, s3, 0x2000
	s_nop 0
	global_load_lds_dwordx4 v[230:231], off
	s_waitcnt vmcnt(6)
	s_waitcnt lgkmcnt(0)
	s_barrier
; #define PG8_STAGE(bufoff, gbase, voff) do { _Pragma("unroll") for (int _i = 0; _i < 2; ++_i) \
;         __builtin_amdgcn_global_load_lds((const unsigned*)((const char*)(gbase) + (voff)[_i]), (PG8_LAS unsigned*)(lds + (bufoff) + ldsw + _i * 8192), 16, 0, 0); } while (0)
; #define PG8_LDA(dst, b, h) do { _Pragma("unroll") for (int m = 0; m < 4; ++m) _Pragma("unroll") for (int k = 0; k < 2; ++k) dst[m][k] = *(const PG8_LAS bf16x8*)(lds + PG8_SA(b, h) + aoff + m * 2048 + k * 1024); } while (0)
; #define PG8_LDB(dst, b, h) do { _Pragma("unroll") for (int n = 0; n < 2; ++n) _Pragma("unroll") for (int k = 0; k < 2; ++k) dst[n][k] = *(const PG8_LAS bf16x8*)(lds + PG8_SB(b, h) + boff + n * 2048 + k * 1024); } while (0)
; #define PG8_MMA(ai, bj, At, Bt) do { __builtin_amdgcn_s_setprio(1); _Pragma("unroll") for (int m = 0; m < 4; ++m) _Pragma("unroll") for (int n = 0; n < 2; ++n) _Pragma("unroll") for (int k = 0; k < 2; ++k) \
;         acc[ai][bj][m][n] = __builtin_amdgcn_mfma_f32_16x16x32_bf16(Bt[n][k], At[m][k], acc[ai][bj][m][n], 0, 0, 0); __builtin_amdgcn_s_setprio(0); } while (0)
; #define PG8_WAIT_V(n) asm volatile("s_waitcnt vmcnt(" #n ")" ::: "memory")
; #define PG8_WAIT_L(n) asm volatile("s_waitcnt lgkmcnt(" #n ")" ::: "memory")
; #define PG8_BAR __builtin_amdgcn_s_barrier()
; #define PG8_SCHED __builtin_amdgcn_sched_barrier(0)
; template <class Epi, class Sched, bool ALIGN_EPI = false, bool SP2 = false>
; __device__ __forceinline__ void gemm_phase(PG8_LAS unsigned char* lds, const Gemm g, const Sched& S, const Epi& E) {
;     ...
;             PG8_LDA(At, 0, 1); PG8_STAGE(PG8_SB(0, 0), b2, voffB); PG8_STAGE(PG8_SB(0, 1), b2 + hstep, voffB); PG8_STAGE(PG8_SA(0, 0), a2, voffA);
;             PG8_WAIT_V(8); PG8_WAIT_L(0); PG8_BAR; PG8_MMA(1, 0, At, B0); PG8_MMA(1, 1, At, B1); PG8_BAR; PG8_SCHED;
;             PG8_LDB(B0, 1, 0); PG8_LDB(B1, 1, 1); PG8_SCHED; PG8_LDA(At, 1, 0); PG8_STAGE(PG8_SA(0, 1), a2 + hstep, voffA);
;             PG8_WAIT_V(8); PG8_WAIT_L(0); PG8_BAR; PG8_MMA(0, 0, At, B0); PG8_MMA(0, 1, At, B1); PG8_BAR; PG8_SCHED;
	s_setprio 1
	s_waitcnt lgkmcnt(0)
	v_mfma_f32_16x16x32_bf16 v[60:63], v[148:151], v[190:193], v[60:63]
	v_mfma_f32_16x16x32_bf16 v[56:59], v[164:167], v[190:193], v[56:59]
	v_mfma_f32_16x16x32_bf16 v[44:47], v[148:151], v[198:201], v[44:47]
	v_mfma_f32_16x16x32_bf16 v[40:43], v[164:167], v[198:201], v[40:43]
	v_mfma_f32_16x16x32_bf16 v[28:31], v[148:151], v[212:215], v[28:31]
	v_mfma_f32_16x16x32_bf16 v[24:27], v[164:167], v[212:215], v[24:27]
	v_mfma_f32_16x16x32_bf16 v[12:15], v[148:151], v[220:223], v[12:15]
	v_mfma_f32_16x16x32_bf16 v[8:11], v[164:167], v[220:223], v[8:11]
	v_mfma_f32_16x16x32_bf16 v[60:63], v[160:163], v[194:197], v[60:63]
	v_mfma_f32_16x16x32_bf16 v[56:59], v[168:171], v[194:197], v[56:59]
	v_mfma_f32_16x16x32_bf16 v[44:47], v[160:163], v[208:211], v[44:47]
	v_mfma_f32_16x16x32_bf16 v[40:43], v[168:171], v[208:211], v[40:43]
	v_mfma_f32_16x16x32_bf16 v[28:31], v[160:163], v[216:219], v[28:31]
	v_mfma_f32_16x16x32_bf16 v[24:27], v[168:171], v[216:219], v[24:27]
	v_lshl_add_u64 v[230:231], s[64:65], 0, v[132:133]
	s_mov_b32 m0, s43
	s_nop 0
	global_load_lds_dwordx4 v[230:231], off
	v_mfma_f32_16x16x32_bf16 v[12:15], v[160:163], v[224:227], v[12:15]
	v_mfma_f32_16x16x32_bf16 v[8:11], v[168:171], v[224:227], v[8:11]
	s_setprio 0
	s_setprio 1
	v_mfma_f32_16x16x32_bf16 v[52:55], v[172:175], v[190:193], v[52:55]
	v_mfma_f32_16x16x32_bf16 v[48:51], v[182:185], v[190:193], v[48:51]
	v_mfma_f32_16x16x32_bf16 v[36:39], v[172:175], v[198:201], v[36:39]
	v_mfma_f32_16x16x32_bf16 v[32:35], v[182:185], v[198:201], v[32:35]
	v_mfma_f32_16x16x32_bf16 v[20:23], v[172:175], v[212:215], v[20:23]
	v_mfma_f32_16x16x32_bf16 v[16:19], v[182:185], v[212:215], v[16:19]
	v_mfma_f32_16x16x32_bf16 v[4:7], v[172:175], v[220:223], v[4:7]
	v_mfma_f32_16x16x32_bf16 v[0:3], v[182:185], v[220:223], v[0:3]
	v_mfma_f32_16x16x32_bf16 v[52:55], v[176:179], v[194:197], v[52:55]
	v_mfma_f32_16x16x32_bf16 v[48:51], v[186:189], v[194:197], v[48:51]
	v_mfma_f32_16x16x32_bf16 v[36:39], v[176:179], v[208:211], v[36:39]
	v_mfma_f32_16x16x32_bf16 v[32:35], v[186:189], v[208:211], v[32:35]
	v_mfma_f32_16x16x32_bf16 v[20:23], v[176:179], v[216:219], v[20:23]
	v_mfma_f32_16x16x32_bf16 v[16:19], v[186:189], v[216:219], v[16:19]
	v_lshl_add_u64 v[232:233], s[64:65], 0, v[136:137]
	s_mov_b32 m0, s59
	s_nop 0
	global_load_lds_dwordx4 v[232:233], off
	v_mfma_f32_16x16x32_bf16 v[4:7], v[176:179], v[224:227], v[4:7]
	v_mfma_f32_16x16x32_bf16 v[0:3], v[186:189], v[224:227], v[0:3]
	s_setprio 0
	s_barrier
	s_add_i32 s3, 0, 0x18000
	v_add_u32_e32 v159, s3, v131
	s_add_i32 s33, 0, 0x1c000
	ds_read_b128 v[148:151], v159
	ds_read_b128 v[160:163], v159 offset:1024
	ds_read_b128 v[164:167], v159 offset:2048
	ds_read_b128 v[168:171], v159 offset:3072
	v_add_u32_e32 v159, s33, v131
	ds_read_b128 v[172:175], v159
	ds_read_b128 v[176:179], v159 offset:1024
	ds_read_b128 v[182:185], v159 offset:2048
	ds_read_b128 v[186:189], v159 offset:3072
	s_add_u32 s14, s64, 0x40000
	s_addc_u32 s15, s65, 0
	s_mov_b32 m0, s66
	v_lshl_add_u64 v[234:235], s[14:15], 0, v[132:133]
	ds_read_b128 v[190:193], v157 offset:32768
	ds_read_b128 v[194:197], v157 offset:33792
	ds_read_b128 v[198:201], v157 offset:34816
	ds_read_b128 v[208:211], v157 offset:35840
	ds_read_b128 v[212:215], v157 offset:36864
	ds_read_b128 v[216:219], v157 offset:37888
	ds_read_b128 v[220:223], v157 offset:38912
	ds_read_b128 v[224:227], v157 offset:39936
	global_load_lds_dwordx4 v[234:235], off
	v_lshl_add_u64 v[234:235], s[14:15], 0, v[136:137]
	s_mov_b32 m0, s67
	s_nop 0
	global_load_lds_dwordx4 v[234:235], off
	s_waitcnt vmcnt(8)
	s_waitcnt lgkmcnt(0)
	s_barrier
	s_setprio 1
	s_waitcnt lgkmcnt(0)
	v_mfma_f32_16x16x32_bf16 v[124:127], v[148:151], v[190:193], v[124:127]
	v_mfma_f32_16x16x32_bf16 v[120:123], v[164:167], v[190:193], v[120:123]
	v_mfma_f32_16x16x32_bf16 v[108:111], v[148:151], v[198:201], v[108:111]
	v_mfma_f32_16x16x32_bf16 v[104:107], v[164:167], v[198:201], v[104:107]
	v_mfma_f32_16x16x32_bf16 v[92:95], v[148:151], v[212:215], v[92:95]
	v_mfma_f32_16x16x32_bf16 v[88:91], v[164:167], v[212:215], v[88:91]
	v_mfma_f32_16x16x32_bf16 v[76:79], v[148:151], v[220:223], v[76:79]
	v_mfma_f32_16x16x32_bf16 v[72:75], v[164:167], v[220:223], v[72:75]
	v_mfma_f32_16x16x32_bf16 v[124:127], v[160:163], v[194:197], v[124:127]
	v_mfma_f32_16x16x32_bf16 v[120:123], v[168:171], v[194:197], v[120:123]
	v_mfma_f32_16x16x32_bf16 v[108:111], v[160:163], v[208:211], v[108:111]
	v_mfma_f32_16x16x32_bf16 v[104:107], v[168:171], v[208:211], v[104:107]
	v_mfma_f32_16x16x32_bf16 v[92:95], v[160:163], v[216:219], v[92:95]
	v_mfma_f32_16x16x32_bf16 v[88:91], v[168:171], v[216:219], v[88:91]
	v_mfma_f32_16x16x32_bf16 v[76:79], v[160:163], v[224:227], v[76:79]
	v_mfma_f32_16x16x32_bf16 v[72:75], v[168:171], v[224:227], v[72:75]
	s_setprio 0
	s_setprio 1
	v_mfma_f32_16x16x32_bf16 v[116:119], v[172:175], v[190:193], v[116:119]
	v_mfma_f32_16x16x32_bf16 v[112:115], v[182:185], v[190:193], v[112:115]
	v_mfma_f32_16x16x32_bf16 v[100:103], v[172:175], v[198:201], v[100:103]
	v_mfma_f32_16x16x32_bf16 v[96:99], v[182:185], v[198:201], v[96:99]
	v_mfma_f32_16x16x32_bf16 v[84:87], v[172:175], v[212:215], v[84:87]
	v_mfma_f32_16x16x32_bf16 v[80:83], v[182:185], v[212:215], v[80:83]
	v_mfma_f32_16x16x32_bf16 v[68:71], v[172:175], v[220:223], v[68:71]
	v_mfma_f32_16x16x32_bf16 v[64:67], v[182:185], v[220:223], v[64:67]
	v_mfma_f32_16x16x32_bf16 v[116:119], v[176:179], v[194:197], v[116:119]
	v_mfma_f32_16x16x32_bf16 v[112:115], v[186:189], v[194:197], v[112:115]
	v_mfma_f32_16x16x32_bf16 v[100:103], v[176:179], v[208:211], v[100:103]
	v_mfma_f32_16x16x32_bf16 v[96:99], v[186:189], v[208:211], v[96:99]
	v_mfma_f32_16x16x32_bf16 v[84:87], v[176:179], v[216:219], v[84:87]
	v_mfma_f32_16x16x32_bf16 v[80:83], v[186:189], v[216:219], v[80:83]
	v_mfma_f32_16x16x32_bf16 v[68:71], v[176:179], v[224:227], v[68:71]
	v_mfma_f32_16x16x32_bf16 v[64:67], v[186:189], v[224:227], v[64:67]
	s_setprio 0
	s_barrier
; #define PG8_STAGE(bufoff, gbase, voff) do { _Pragma("unroll") for (int _i = 0; _i < 2; ++_i) \
;         __builtin_amdgcn_global_load_lds((const unsigned*)((const char*)(gbase) + (voff)[_i]), (PG8_LAS unsigned*)(lds + (bufoff) + ldsw + _i * 8192), 16, 0, 0); } while (0)
; #define PG8_LDA(dst, b, h) do { _Pragma("unroll") for (int m = 0; m < 4; ++m) _Pragma("unroll") for (int k = 0; k < 2; ++k) dst[m][k] = *(const PG8_LAS bf16x8*)(lds + PG8_SA(b, h) + aoff + m * 2048 + k * 1024); } while (0)
; #define PG8_MMA(ai, bj, At, Bt) do { __builtin_amdgcn_s_setprio(1); _Pragma("unroll") for (int m = 0; m < 4; ++m) _Pragma("unroll") for (int n = 0; n < 2; ++n) _Pragma("unroll") for (int k = 0; k < 2; ++k) \
;         acc[ai][bj][m][n] = __builtin_amdgcn_mfma_f32_16x16x32_bf16(Bt[n][k], At[m][k], acc[ai][bj][m][n], 0, 0, 0); __builtin_amdgcn_s_setprio(0); } while (0)
; #define PG8_WAIT_V(n) asm volatile("s_waitcnt vmcnt(" #n ")" ::: "memory")
; #define PG8_WAIT_L(n) asm volatile("s_waitcnt lgkmcnt(" #n ")" ::: "memory")
; #define PG8_BAR __builtin_amdgcn_s_barrier()
; #define PG8_SCHED __builtin_amdgcn_sched_barrier(0)
; template <class Epi, class Sched, bool ALIGN_EPI = false, bool SP2 = false>
; __device__ __forceinline__ void gemm_phase(PG8_LAS unsigned char* lds, const Gemm g, const Sched& S, const Epi& E) {
;     ...
;             PG8_LDA(At, 1, 1); PG8_STAGE(PG8_SB(1, 0), b3, voffB); PG8_STAGE(PG8_SB(1, 1), b3 + hstep, voffB); PG8_STAGE(PG8_SA(1, 0), a3, voffA);
;             PG8_WAIT_V(8); PG8_WAIT_L(0); PG8_BAR; PG8_MMA(1, 0, At, B0); PG8_MMA(1, 1, At, B1); PG8_BAR; PG8_SCHED;
;     ...
;         if constexpr (ALIGN_EPI) { if (wr == 0) PG8_BAR; }
	s_add_i32 s3, s3, s34
	v_lshl_add_u64 v[202:203], v[202:203], 0, s[38:39]
	s_mov_b32 m0, s3
	ds_read_b128 v[190:193], v157 offset:49152
	ds_read_b128 v[194:197], v157 offset:50176
	ds_read_b128 v[198:201], v157 offset:51200
	ds_read_b128 v[208:211], v157 offset:52224
	ds_read_b128 v[212:215], v157 offset:53248
	ds_read_b128 v[216:219], v157 offset:54272
	ds_read_b128 v[220:223], v157 offset:55296
	ds_read_b128 v[224:227], v157 offset:56320
	global_load_lds_dwordx4 v[202:203], off
	s_add_i32 m0, s3, 0x2000
	s_add_u32 s14, s62, 0x40080
	v_lshl_add_u64 v[202:203], v[228:229], 0, s[38:39]
	s_addc_u32 s15, s63, 0
	s_add_i32 s3, s33, s34
	global_load_lds_dwordx4 v[202:203], off
	v_lshl_add_u64 v[202:203], s[14:15], 0, v[134:135]
	s_mov_b32 m0, s3
	s_nop 0
	global_load_lds_dwordx4 v[202:203], off
	v_lshl_add_u64 v[202:203], s[14:15], 0, v[138:139]
	s_add_i32 m0, s3, 0x2000
	s_nop 0
	global_load_lds_dwordx4 v[202:203], off
	s_waitcnt vmcnt(6)
	s_waitcnt lgkmcnt(0)
	s_barrier
	s_setprio 1
	s_waitcnt lgkmcnt(0)
	v_mfma_f32_16x16x32_bf16 v[60:63], v[148:151], v[190:193], v[60:63]
	v_mfma_f32_16x16x32_bf16 v[56:59], v[164:167], v[190:193], v[56:59]
	v_lshl_add_u64 v[202:203], v[230:231], 0, s[38:39]
	s_mov_b32 m0, s75
	s_nop 0
	global_load_lds_dwordx4 v[202:203], off
	v_mfma_f32_16x16x32_bf16 v[44:47], v[148:151], v[198:201], v[44:47]
	v_mfma_f32_16x16x32_bf16 v[40:43], v[164:167], v[198:201], v[40:43]
	v_mfma_f32_16x16x32_bf16 v[28:31], v[148:151], v[212:215], v[28:31]
	v_mfma_f32_16x16x32_bf16 v[24:27], v[164:167], v[212:215], v[24:27]
	v_lshl_add_u64 v[202:203], v[232:233], 0, s[38:39]
	s_mov_b32 m0, s84
	s_nop 0
	global_load_lds_dwordx4 v[202:203], off
	v_mfma_f32_16x16x32_bf16 v[12:15], v[148:151], v[220:223], v[12:15]
	v_mfma_f32_16x16x32_bf16 v[8:11], v[164:167], v[220:223], v[8:11]
	v_mfma_f32_16x16x32_bf16 v[60:63], v[160:163], v[194:197], v[60:63]
	v_mfma_f32_16x16x32_bf16 v[56:59], v[168:171], v[194:197], v[56:59]
	v_mfma_f32_16x16x32_bf16 v[44:47], v[160:163], v[208:211], v[44:47]
	v_mfma_f32_16x16x32_bf16 v[40:43], v[168:171], v[208:211], v[40:43]
	v_mfma_f32_16x16x32_bf16 v[28:31], v[160:163], v[216:219], v[28:31]
	v_mfma_f32_16x16x32_bf16 v[24:27], v[168:171], v[216:219], v[24:27]
	v_mfma_f32_16x16x32_bf16 v[12:15], v[160:163], v[224:227], v[12:15]
	v_mfma_f32_16x16x32_bf16 v[8:11], v[168:171], v[224:227], v[8:11]
	s_setprio 0
	s_setprio 1
	v_mfma_f32_16x16x32_bf16 v[52:55], v[172:175], v[190:193], v[52:55]
	v_mfma_f32_16x16x32_bf16 v[48:51], v[182:185], v[190:193], v[48:51]
	v_mfma_f32_16x16x32_bf16 v[36:39], v[172:175], v[198:201], v[36:39]
	v_mfma_f32_16x16x32_bf16 v[32:35], v[182:185], v[198:201], v[32:35]
	v_mfma_f32_16x16x32_bf16 v[20:23], v[172:175], v[212:215], v[20:23]
	v_mfma_f32_16x16x32_bf16 v[16:19], v[182:185], v[212:215], v[16:19]
	v_mfma_f32_16x16x32_bf16 v[4:7], v[172:175], v[220:223], v[4:7]
	v_mfma_f32_16x16x32_bf16 v[0:3], v[182:185], v[220:223], v[0:3]
	v_mfma_f32_16x16x32_bf16 v[52:55], v[176:179], v[194:197], v[52:55]
	v_mfma_f32_16x16x32_bf16 v[48:51], v[186:189], v[194:197], v[48:51]
	v_mfma_f32_16x16x32_bf16 v[36:39], v[176:179], v[208:211], v[36:39]
	v_mfma_f32_16x16x32_bf16 v[32:35], v[186:189], v[208:211], v[32:35]
	v_mfma_f32_16x16x32_bf16 v[20:23], v[176:179], v[216:219], v[20:23]
	v_mfma_f32_16x16x32_bf16 v[16:19], v[186:189], v[216:219], v[16:19]
	v_mfma_f32_16x16x32_bf16 v[4:7], v[176:179], v[224:227], v[4:7]
	v_mfma_f32_16x16x32_bf16 v[0:3], v[186:189], v[224:227], v[0:3]
	s_setprio 0
	s_barrier
	s_add_i32 s92, s92, 2
	s_add_u32 s60, s60, 0x100
	s_addc_u32 s61, s61, 0
	s_add_u32 s90, s90, 0x100
	s_addc_u32 s91, s91, 0
	s_cmp_gt_u32 s92, 13
	s_cbranch_scc0 .LBB0_650
	s_and_b64 vcc, exec, s[44:45]
	s_cbranch_vccz .LBB0_653
	s_barrier

; #define PG8_STAGE(bufoff, gbase, voff) do { _Pragma("unroll") for (int _i = 0; _i < 2; ++_i) \
;         __builtin_amdgcn_global_load_lds((const unsigned*)((const char*)(gbase) + (voff)[_i]), (PG8_LAS unsigned*)(lds + (bufoff) + ldsw + _i * 8192), 16, 0, 0); } while (0)
; #define PG8_LDA(dst, b, h) do { _Pragma("unroll") for (int m = 0; m < 4; ++m) _Pragma("unroll") for (int k = 0; k < 2; ++k) dst[m][k] = *(const PG8_LAS bf16x8*)(lds + PG8_SA(b, h) + aoff + m * 2048 + k * 1024); } while (0)
; #define PG8_LDB(dst, b, h) do { _Pragma("unroll") for (int n = 0; n < 2; ++n) _Pragma("unroll") for (int k = 0; k < 2; ++k) dst[n][k] = *(const PG8_LAS bf16x8*)(lds + PG8_SB(b, h) + boff + n * 2048 + k * 1024); } while (0)
; #define PG8_MMA(ai, bj, At, Bt) do { __builtin_amdgcn_s_setprio(1); _Pragma("unroll") for (int m = 0; m < 4; ++m) _Pragma("unroll") for (int n = 0; n < 2; ++n) _Pragma("unroll") for (int k = 0; k < 2; ++k) \
;         acc[ai][bj][m][n] = __builtin_amdgcn_mfma_f32_16x16x32_bf16(Bt[n][k], At[m][k], acc[ai][bj][m][n], 0, 0, 0); __builtin_amdgcn_s_setprio(0); } while (0)
; #define PG8_WAIT_V(n) asm volatile("s_waitcnt vmcnt(" #n ")" ::: "memory")
; #define PG8_WAIT_L(n) asm volatile("s_waitcnt lgkmcnt(" #n ")" ::: "memory")
; #define PG8_BAR __builtin_amdgcn_s_barrier()
; #define PG8_SCHED __builtin_amdgcn_sched_barrier(0)
; template <class Epi, class Sched, bool ALIGN_EPI = false, bool SP2 = false>
; __device__ __forceinline__ void gemm_phase(PG8_LAS unsigned char* lds, const Gemm g, const Sched& S, const Epi& E) {
;     ...
;             const bool last = (t == nt - 2);
;             const char* a1 = cA + (size_t)(t + 1) * kstep;
;             const char* a2 = last ? nA : cA + (size_t)(t + 2) * kstep; const char* b2 = last ? nB : cB + (size_t)(t + 2) * kstep;
;             const char* a3 = a2 + kstep; const char* b3 = b2 + kstep;
;             if (last && has_next) S.a_ready(nxt);
;             if constexpr (SP2) {
;             PG8_LDB(B0, 0, 0); PG8_LDB(B1, 0, 1); PG8_SCHED; PG8_LDA(At, 0, 0); PG8_STAGE(PG8_SA(1, 1), a1 + hstep, voffA);
;             PG8_WAIT_V(8); PG8_WAIT_L(0); PG8_BAR; PG8_MMA(0, 0, At, B0); PG8_MMA(0, 1, At, B1); PG8_BAR; PG8_SCHED;
;             PG8_LDA(At, 0, 1); PG8_STAGE(PG8_SB(0, 0), b2, voffB); PG8_STAGE(PG8_SB(0, 1), b2 + hstep, voffB); PG8_STAGE(PG8_SA(0, 0), a2, voffA);
.LBB0_738:
	ds_read_b128 v[148:151], v155
	ds_read_b128 v[160:163], v155 offset:1024
	ds_read_b128 v[164:167], v155 offset:2048
	ds_read_b128 v[168:171], v155 offset:3072
	ds_read_b128 v[172:175], v156
	ds_read_b128 v[176:179], v156 offset:1024
	ds_read_b128 v[182:185], v156 offset:2048
	ds_read_b128 v[186:189], v156 offset:3072
	s_add_u32 s3, s56, 0xfffc0080
	s_addc_u32 s14, s57, -1
	s_cmp_eq_u32 s86, 12
	s_cselect_b32 s61, s51, s14
	s_cselect_b32 s60, s82, s3
	s_cselect_b32 s59, s49, s85
	s_cselect_b32 s58, s83, s84
	v_lshl_add_u64 v[202:203], s[56:57], 0, v[140:141]
	s_add_i32 m0, s43, 0xc000
	ds_read_b128 v[190:193], v157
	ds_read_b128 v[194:197], v157 offset:1024
	ds_read_b128 v[198:201], v157 offset:2048
	ds_read_b128 v[208:211], v157 offset:3072
	ds_read_b128 v[212:215], v157 offset:4096
	ds_read_b128 v[216:219], v157 offset:5120
	ds_read_b128 v[220:223], v157 offset:6144
	ds_read_b128 v[224:227], v157 offset:7168
	global_load_lds_dwordx4 v[202:203], off
	v_lshl_add_u64 v[202:203], s[56:57], 0, v[142:143]
	s_add_i32 m0, s43, 0xe000
	s_nop 0
	global_load_lds_dwordx4 v[202:203], off
	s_waitcnt vmcnt(8)
	s_waitcnt lgkmcnt(0)
	s_barrier
	s_setprio 1
	s_waitcnt lgkmcnt(0)
	v_mfma_f32_16x16x32_bf16 v[124:127], v[148:151], v[190:193], v[124:127]
	v_mfma_f32_16x16x32_bf16 v[120:123], v[164:167], v[190:193], v[120:123]
	v_mfma_f32_16x16x32_bf16 v[108:111], v[148:151], v[198:201], v[108:111]
	v_mfma_f32_16x16x32_bf16 v[104:107], v[164:167], v[198:201], v[104:107]
	v_mfma_f32_16x16x32_bf16 v[92:95], v[148:151], v[212:215], v[92:95]
	v_mfma_f32_16x16x32_bf16 v[88:91], v[164:167], v[212:215], v[88:91]
	v_mfma_f32_16x16x32_bf16 v[76:79], v[148:151], v[220:223], v[76:79]
	v_mfma_f32_16x16x32_bf16 v[72:75], v[164:167], v[220:223], v[72:75]
	v_mfma_f32_16x16x32_bf16 v[124:127], v[160:163], v[194:197], v[124:127]
	v_mfma_f32_16x16x32_bf16 v[120:123], v[168:171], v[194:197], v[120:123]
	v_mfma_f32_16x16x32_bf16 v[108:111], v[160:163], v[208:211], v[108:111]
	v_mfma_f32_16x16x32_bf16 v[104:107], v[168:171], v[208:211], v[104:107]
	v_mfma_f32_16x16x32_bf16 v[92:95], v[160:163], v[216:219], v[92:95]
	v_mfma_f32_16x16x32_bf16 v[88:91], v[168:171], v[216:219], v[88:91]
	v_mfma_f32_16x16x32_bf16 v[76:79], v[160:163], v[224:227], v[76:79]
	v_mfma_f32_16x16x32_bf16 v[72:75], v[168:171], v[224:227], v[72:75]
	s_setprio 0
	s_setprio 1
	v_mfma_f32_16x16x32_bf16 v[116:119], v[172:175], v[190:193], v[116:119]
	v_mfma_f32_16x16x32_bf16 v[112:115], v[182:185], v[190:193], v[112:115]
	v_mfma_f32_16x16x32_bf16 v[100:103], v[172:175], v[198:201], v[100:103]
	v_mfma_f32_16x16x32_bf16 v[96:99], v[182:185], v[198:201], v[96:99]
	v_mfma_f32_16x16x32_bf16 v[84:87], v[172:175], v[212:215], v[84:87]
	v_mfma_f32_16x16x32_bf16 v[80:83], v[182:185], v[212:215], v[80:83]
	v_mfma_f32_16x16x32_bf16 v[68:71], v[172:175], v[220:223], v[68:71]
	v_mfma_f32_16x16x32_bf16 v[64:67], v[182:185], v[220:223], v[64:67]
	v_mfma_f32_16x16x32_bf16 v[116:119], v[176:179], v[194:197], v[116:119]
	v_mfma_f32_16x16x32_bf16 v[112:115], v[186:189], v[194:197], v[112:115]
	v_mfma_f32_16x16x32_bf16 v[100:103], v[176:179], v[208:211], v[100:103]
	v_mfma_f32_16x16x32_bf16 v[96:99], v[186:189], v[208:211], v[96:99]
	v_mfma_f32_16x16x32_bf16 v[84:87], v[176:179], v[216:219], v[84:87]
	v_mfma_f32_16x16x32_bf16 v[80:83], v[186:189], v[216:219], v[80:83]
	v_mfma_f32_16x16x32_bf16 v[68:71], v[176:179], v[224:227], v[68:71]
	v_mfma_f32_16x16x32_bf16 v[64:67], v[186:189], v[224:227], v[64:67]
	s_setprio 0
	s_barrier
	s_add_i32 s3, s74, s34
	v_lshl_add_u64 v[202:203], s[58:59], 0, v[136:137]
	s_mov_b32 m0, s3
	ds_read_b128 v[190:193], v157 offset:16384
	ds_read_b128 v[194:197], v157 offset:17408
	ds_read_b128 v[198:201], v157 offset:18432
	ds_read_b128 v[208:211], v157 offset:19456
	ds_read_b128 v[212:215], v157 offset:20480
	ds_read_b128 v[216:219], v157 offset:21504
	ds_read_b128 v[220:223], v157 offset:22528
	ds_read_b128 v[224:227], v157 offset:23552
	global_load_lds_dwordx4 v[202:203], off
	s_add_i32 m0, s3, 0x2000
	s_add_u32 s14, s58, 0x40000
	v_lshl_add_u64 v[228:229], s[58:59], 0, v[132:133]
	s_addc_u32 s15, s59, 0
	s_add_i32 s3, s75, s34
	global_load_lds_dwordx4 v[228:229], off
	v_lshl_add_u64 v[230:231], s[14:15], 0, v[136:137]
	s_mov_b32 m0, s3
	global_load_lds_dwordx4 v[230:231], off
	v_lshl_add_u64 v[230:231], s[14:15], 0, v[132:133]
	s_add_i32 m0, s3, 0x2000
	s_nop 0
	global_load_lds_dwordx4 v[230:231], off
	s_waitcnt vmcnt(6)
	s_waitcnt lgkmcnt(0)
	s_barrier
; #define PG8_STAGE(bufoff, gbase, voff) do { _Pragma("unroll") for (int _i = 0; _i < 2; ++_i) \
;         __builtin_amdgcn_global_load_lds((const unsigned*)((const char*)(gbase) + (voff)[_i]), (PG8_LAS unsigned*)(lds + (bufoff) + ldsw + _i * 8192), 16, 0, 0); } while (0)
; #define PG8_LDA(dst, b, h) do { _Pragma("unroll") for (int m = 0; m < 4; ++m) _Pragma("unroll") for (int k = 0; k < 2; ++k) dst[m][k] = *(const PG8_LAS bf16x8*)(lds + PG8_SA(b, h) + aoff + m * 2048 + k * 1024); } while (0)
; #define PG8_LDB(dst, b, h) do { _Pragma("unroll") for (int n = 0; n < 2; ++n) _Pragma("unroll") for (int k = 0; k < 2; ++k) dst[n][k] = *(const PG8_LAS bf16x8*)(lds + PG8_SB(b, h) + boff + n * 2048 + k * 1024); } while (0)
; #define PG8_MMA(ai, bj, At, Bt) do { __builtin_amdgcn_s_setprio(1); _Pragma("unroll") for (int m = 0; m < 4; ++m) _Pragma("unroll") for (int n = 0; n < 2; ++n) _Pragma("unroll") for (int k = 0; k < 2; ++k) \
;         acc[ai][bj][m][n] = __builtin_amdgcn_mfma_f32_16x16x32_bf16(Bt[n][k], At[m][k], acc[ai][bj][m][n], 0, 0, 0); __builtin_amdgcn_s_setprio(0); } while (0)
; #define PG8_WAIT_V(n) asm volatile("s_waitcnt vmcnt(" #n ")" ::: "memory")
; #define PG8_WAIT_L(n) asm volatile("s_waitcnt lgkmcnt(" #n ")" ::: "memory")
; #define PG8_BAR __builtin_amdgcn_s_barrier()
; #define PG8_SCHED __builtin_amdgcn_sched_barrier(0)
; template <class Epi, class Sched, bool ALIGN_EPI = false, bool SP2 = false>
; __device__ __forceinline__ void gemm_phase(PG8_LAS unsigned char* lds, const Gemm g, const Sched& S, const Epi& E) {
;     ...
;             PG8_LDA(At, 0, 1); PG8_STAGE(PG8_SB(0, 0), b2, voffB); PG8_STAGE(PG8_SB(0, 1), b2 + hstep, voffB); PG8_STAGE(PG8_SA(0, 0), a2, voffA);
;             PG8_WAIT_V(8); PG8_WAIT_L(0); PG8_BAR; PG8_MMA(1, 0, At, B0); PG8_MMA(1, 1, At, B1); PG8_BAR; PG8_SCHED;
;             PG8_LDB(B0, 1, 0); PG8_LDB(B1, 1, 1); PG8_SCHED; PG8_LDA(At, 1, 0); PG8_STAGE(PG8_SA(0, 1), a2 + hstep, voffA);
;             PG8_WAIT_V(8); PG8_WAIT_L(0); PG8_BAR; PG8_MMA(0, 0, At, B0); PG8_MMA(0, 1, At, B1); PG8_BAR; PG8_SCHED;
	s_setprio 1
	s_waitcnt lgkmcnt(0)
	v_mfma_f32_16x16x32_bf16 v[60:63], v[148:151], v[190:193], v[60:63]
	v_mfma_f32_16x16x32_bf16 v[56:59], v[164:167], v[190:193], v[56:59]
	v_mfma_f32_16x16x32_bf16 v[44:47], v[148:151], v[198:201], v[44:47]
	v_mfma_f32_16x16x32_bf16 v[40:43], v[164:167], v[198:201], v[40:43]
	v_mfma_f32_16x16x32_bf16 v[28:31], v[148:151], v[212:215], v[28:31]
	v_mfma_f32_16x16x32_bf16 v[24:27], v[164:167], v[212:215], v[24:27]
	v_mfma_f32_16x16x32_bf16 v[12:15], v[148:151], v[220:223], v[12:15]
	v_mfma_f32_16x16x32_bf16 v[8:11], v[164:167], v[220:223], v[8:11]
	v_mfma_f32_16x16x32_bf16 v[60:63], v[160:163], v[194:197], v[60:63]
	v_mfma_f32_16x16x32_bf16 v[56:59], v[168:171], v[194:197], v[56:59]
	v_mfma_f32_16x16x32_bf16 v[44:47], v[160:163], v[208:211], v[44:47]
	v_mfma_f32_16x16x32_bf16 v[40:43], v[168:171], v[208:211], v[40:43]
	v_mfma_f32_16x16x32_bf16 v[28:31], v[160:163], v[216:219], v[28:31]
	v_mfma_f32_16x16x32_bf16 v[24:27], v[168:171], v[216:219], v[24:27]
	v_lshl_add_u64 v[230:231], s[60:61], 0, v[138:139]
	s_mov_b32 m0, s43
	s_nop 0
	global_load_lds_dwordx4 v[230:231], off
	v_mfma_f32_16x16x32_bf16 v[12:15], v[160:163], v[224:227], v[12:15]
	v_mfma_f32_16x16x32_bf16 v[8:11], v[168:171], v[224:227], v[8:11]
	s_setprio 0
	s_setprio 1
	v_mfma_f32_16x16x32_bf16 v[52:55], v[172:175], v[190:193], v[52:55]
	v_mfma_f32_16x16x32_bf16 v[48:51], v[182:185], v[190:193], v[48:51]
	v_mfma_f32_16x16x32_bf16 v[36:39], v[172:175], v[198:201], v[36:39]
	v_mfma_f32_16x16x32_bf16 v[32:35], v[182:185], v[198:201], v[32:35]
	v_mfma_f32_16x16x32_bf16 v[20:23], v[172:175], v[212:215], v[20:23]
	v_mfma_f32_16x16x32_bf16 v[16:19], v[182:185], v[212:215], v[16:19]
	v_mfma_f32_16x16x32_bf16 v[4:7], v[172:175], v[220:223], v[4:7]
	v_mfma_f32_16x16x32_bf16 v[0:3], v[182:185], v[220:223], v[0:3]
	v_mfma_f32_16x16x32_bf16 v[52:55], v[176:179], v[194:197], v[52:55]
	v_mfma_f32_16x16x32_bf16 v[48:51], v[186:189], v[194:197], v[48:51]
	v_mfma_f32_16x16x32_bf16 v[36:39], v[176:179], v[208:211], v[36:39]
	v_mfma_f32_16x16x32_bf16 v[32:35], v[186:189], v[208:211], v[32:35]
	v_mfma_f32_16x16x32_bf16 v[20:23], v[176:179], v[216:219], v[20:23]
	v_mfma_f32_16x16x32_bf16 v[16:19], v[186:189], v[216:219], v[16:19]
	v_lshl_add_u64 v[232:233], s[60:61], 0, v[134:135]
	s_mov_b32 m0, s62
	s_nop 0
	global_load_lds_dwordx4 v[232:233], off
	v_mfma_f32_16x16x32_bf16 v[4:7], v[176:179], v[224:227], v[4:7]
	v_mfma_f32_16x16x32_bf16 v[0:3], v[186:189], v[224:227], v[0:3]
	s_setprio 0
	s_barrier
	s_add_i32 s3, 0, 0x18000
	v_add_u32_e32 v159, s3, v131
	s_add_i32 s33, 0, 0x1c000
	ds_read_b128 v[148:151], v159
	ds_read_b128 v[160:163], v159 offset:1024
	ds_read_b128 v[164:167], v159 offset:2048
	ds_read_b128 v[168:171], v159 offset:3072
	v_add_u32_e32 v159, s33, v131
	ds_read_b128 v[172:175], v159
	ds_read_b128 v[176:179], v159 offset:1024
	ds_read_b128 v[182:185], v159 offset:2048
	ds_read_b128 v[186:189], v159 offset:3072
	s_add_u32 s14, s60, 0x40000
	s_addc_u32 s15, s61, 0
	s_mov_b32 m0, s63
	v_lshl_add_u64 v[234:235], s[14:15], 0, v[138:139]
	ds_read_b128 v[190:193], v157 offset:32768
	ds_read_b128 v[194:197], v157 offset:33792
	ds_read_b128 v[198:201], v157 offset:34816
	ds_read_b128 v[208:211], v157 offset:35840
	ds_read_b128 v[212:215], v157 offset:36864
	ds_read_b128 v[216:219], v157 offset:37888
	ds_read_b128 v[220:223], v157 offset:38912
	ds_read_b128 v[224:227], v157 offset:39936
	global_load_lds_dwordx4 v[234:235], off
	v_lshl_add_u64 v[234:235], s[14:15], 0, v[134:135]
	s_mov_b32 m0, s64
	s_nop 0
	global_load_lds_dwordx4 v[234:235], off
	s_waitcnt vmcnt(8)
	s_waitcnt lgkmcnt(0)
	s_barrier
	s_setprio 1
	s_waitcnt lgkmcnt(0)
	v_mfma_f32_16x16x32_bf16 v[124:127], v[148:151], v[190:193], v[124:127]
	v_mfma_f32_16x16x32_bf16 v[120:123], v[164:167], v[190:193], v[120:123]
	v_mfma_f32_16x16x32_bf16 v[108:111], v[148:151], v[198:201], v[108:111]
	v_mfma_f32_16x16x32_bf16 v[104:107], v[164:167], v[198:201], v[104:107]
	v_mfma_f32_16x16x32_bf16 v[92:95], v[148:151], v[212:215], v[92:95]
	v_mfma_f32_16x16x32_bf16 v[88:91], v[164:167], v[212:215], v[88:91]
	v_mfma_f32_16x16x32_bf16 v[76:79], v[148:151], v[220:223], v[76:79]
	v_mfma_f32_16x16x32_bf16 v[72:75], v[164:167], v[220:223], v[72:75]
	v_mfma_f32_16x16x32_bf16 v[124:127], v[160:163], v[194:197], v[124:127]
	v_mfma_f32_16x16x32_bf16 v[120:123], v[168:171], v[194:197], v[120:123]
	v_mfma_f32_16x16x32_bf16 v[108:111], v[160:163], v[208:211], v[108:111]
	v_mfma_f32_16x16x32_bf16 v[104:107], v[168:171], v[208:211], v[104:107]
	v_mfma_f32_16x16x32_bf16 v[92:95], v[160:163], v[216:219], v[92:95]
	v_mfma_f32_16x16x32_bf16 v[88:91], v[168:171], v[216:219], v[88:91]
	v_mfma_f32_16x16x32_bf16 v[76:79], v[160:163], v[224:227], v[76:79]
	v_mfma_f32_16x16x32_bf16 v[72:75], v[168:171], v[224:227], v[72:75]
	s_setprio 0
	s_setprio 1
	v_mfma_f32_16x16x32_bf16 v[116:119], v[172:175], v[190:193], v[116:119]
	v_mfma_f32_16x16x32_bf16 v[112:115], v[182:185], v[190:193], v[112:115]
	v_mfma_f32_16x16x32_bf16 v[100:103], v[172:175], v[198:201], v[100:103]
	v_mfma_f32_16x16x32_bf16 v[96:99], v[182:185], v[198:201], v[96:99]
	v_mfma_f32_16x16x32_bf16 v[84:87], v[172:175], v[212:215], v[84:87]
	v_mfma_f32_16x16x32_bf16 v[80:83], v[182:185], v[212:215], v[80:83]
	v_mfma_f32_16x16x32_bf16 v[68:71], v[172:175], v[220:223], v[68:71]
	v_mfma_f32_16x16x32_bf16 v[64:67], v[182:185], v[220:223], v[64:67]
	v_mfma_f32_16x16x32_bf16 v[116:119], v[176:179], v[194:197], v[116:119]
	v_mfma_f32_16x16x32_bf16 v[112:115], v[186:189], v[194:197], v[112:115]
	v_mfma_f32_16x16x32_bf16 v[100:103], v[176:179], v[208:211], v[100:103]
	v_mfma_f32_16x16x32_bf16 v[96:99], v[186:189], v[208:211], v[96:99]
	v_mfma_f32_16x16x32_bf16 v[84:87], v[176:179], v[216:219], v[84:87]
	v_mfma_f32_16x16x32_bf16 v[80:83], v[186:189], v[216:219], v[80:83]
	v_mfma_f32_16x16x32_bf16 v[68:71], v[176:179], v[224:227], v[68:71]
	v_mfma_f32_16x16x32_bf16 v[64:67], v[186:189], v[224:227], v[64:67]
	s_setprio 0
	s_barrier
; #define PG8_STAGE(bufoff, gbase, voff) do { _Pragma("unroll") for (int _i = 0; _i < 2; ++_i) \
;         __builtin_amdgcn_global_load_lds((const unsigned*)((const char*)(gbase) + (voff)[_i]), (PG8_LAS unsigned*)(lds + (bufoff) + ldsw + _i * 8192), 16, 0, 0); } while (0)
; #define PG8_LDA(dst, b, h) do { _Pragma("unroll") for (int m = 0; m < 4; ++m) _Pragma("unroll") for (int k = 0; k < 2; ++k) dst[m][k] = *(const PG8_LAS bf16x8*)(lds + PG8_SA(b, h) + aoff + m * 2048 + k * 1024); } while (0)
; #define PG8_MMA(ai, bj, At, Bt) do { __builtin_amdgcn_s_setprio(1); _Pragma("unroll") for (int m = 0; m < 4; ++m) _Pragma("unroll") for (int n = 0; n < 2; ++n) _Pragma("unroll") for (int k = 0; k < 2; ++k) \
;         acc[ai][bj][m][n] = __builtin_amdgcn_mfma_f32_16x16x32_bf16(Bt[n][k], At[m][k], acc[ai][bj][m][n], 0, 0, 0); __builtin_amdgcn_s_setprio(0); } while (0)
; #define PG8_WAIT_V(n) asm volatile("s_waitcnt vmcnt(" #n ")" ::: "memory")
; #define PG8_WAIT_L(n) asm volatile("s_waitcnt lgkmcnt(" #n ")" ::: "memory")
; #define PG8_BAR __builtin_amdgcn_s_barrier()
; #define PG8_SCHED __builtin_amdgcn_sched_barrier(0)
; template <class Epi, class Sched, bool ALIGN_EPI = false, bool SP2 = false>
; __device__ __forceinline__ void gemm_phase(PG8_LAS unsigned char* lds, const Gemm g, const Sched& S, const Epi& E) {
;     ...
;             PG8_LDA(At, 1, 1); PG8_STAGE(PG8_SB(1, 0), b3, voffB); PG8_STAGE(PG8_SB(1, 1), b3 + hstep, voffB); PG8_STAGE(PG8_SA(1, 0), a3, voffA);
;             PG8_WAIT_V(8); PG8_WAIT_L(0); PG8_BAR; PG8_MMA(1, 0, At, B0); PG8_MMA(1, 1, At, B1); PG8_BAR; PG8_SCHED;
;     ...
;         if constexpr (ALIGN_EPI) { if (wr == 0) PG8_BAR; }
	s_add_i32 s3, s3, s34
	v_lshl_add_u64 v[202:203], v[202:203], 0, s[38:39]
	s_mov_b32 m0, s3
	ds_read_b128 v[190:193], v157 offset:49152
	ds_read_b128 v[194:197], v157 offset:50176
	ds_read_b128 v[198:201], v157 offset:51200
	ds_read_b128 v[208:211], v157 offset:52224
	ds_read_b128 v[212:215], v157 offset:53248
	ds_read_b128 v[216:219], v157 offset:54272
	ds_read_b128 v[220:223], v157 offset:55296
	ds_read_b128 v[224:227], v157 offset:56320
	global_load_lds_dwordx4 v[202:203], off
	s_add_i32 m0, s3, 0x2000
	s_add_u32 s14, s58, 0x40080
	v_lshl_add_u64 v[202:203], v[228:229], 0, s[38:39]
	s_addc_u32 s15, s59, 0
	s_add_i32 s3, s33, s34
	global_load_lds_dwordx4 v[202:203], off
	v_lshl_add_u64 v[202:203], s[14:15], 0, v[136:137]
	s_mov_b32 m0, s3
	s_nop 0
	global_load_lds_dwordx4 v[202:203], off
	v_lshl_add_u64 v[202:203], s[14:15], 0, v[132:133]
	s_add_i32 m0, s3, 0x2000
	s_nop 0
	global_load_lds_dwordx4 v[202:203], off
	s_waitcnt vmcnt(6)
	s_waitcnt lgkmcnt(0)
	s_barrier
	s_setprio 1
	s_waitcnt lgkmcnt(0)
	v_mfma_f32_16x16x32_bf16 v[60:63], v[148:151], v[190:193], v[60:63]
	v_mfma_f32_16x16x32_bf16 v[56:59], v[164:167], v[190:193], v[56:59]
	v_lshl_add_u64 v[202:203], v[230:231], 0, s[38:39]
	s_mov_b32 m0, s66
	s_nop 0
	global_load_lds_dwordx4 v[202:203], off
	v_mfma_f32_16x16x32_bf16 v[44:47], v[148:151], v[198:201], v[44:47]
	v_mfma_f32_16x16x32_bf16 v[40:43], v[164:167], v[198:201], v[40:43]
	v_mfma_f32_16x16x32_bf16 v[28:31], v[148:151], v[212:215], v[28:31]
	v_mfma_f32_16x16x32_bf16 v[24:27], v[164:167], v[212:215], v[24:27]
	v_lshl_add_u64 v[202:203], v[232:233], 0, s[38:39]
	s_mov_b32 m0, s67
	s_nop 0
	global_load_lds_dwordx4 v[202:203], off
	v_mfma_f32_16x16x32_bf16 v[12:15], v[148:151], v[220:223], v[12:15]
	v_mfma_f32_16x16x32_bf16 v[8:11], v[164:167], v[220:223], v[8:11]
	v_mfma_f32_16x16x32_bf16 v[60:63], v[160:163], v[194:197], v[60:63]
	v_mfma_f32_16x16x32_bf16 v[56:59], v[168:171], v[194:197], v[56:59]
	v_mfma_f32_16x16x32_bf16 v[44:47], v[160:163], v[208:211], v[44:47]
	v_mfma_f32_16x16x32_bf16 v[40:43], v[168:171], v[208:211], v[40:43]
	v_mfma_f32_16x16x32_bf16 v[28:31], v[160:163], v[216:219], v[28:31]
	v_mfma_f32_16x16x32_bf16 v[24:27], v[168:171], v[216:219], v[24:27]
	v_mfma_f32_16x16x32_bf16 v[12:15], v[160:163], v[224:227], v[12:15]
	v_mfma_f32_16x16x32_bf16 v[8:11], v[168:171], v[224:227], v[8:11]
	s_setprio 0
	s_setprio 1
	v_mfma_f32_16x16x32_bf16 v[52:55], v[172:175], v[190:193], v[52:55]
	v_mfma_f32_16x16x32_bf16 v[48:51], v[182:185], v[190:193], v[48:51]
	v_mfma_f32_16x16x32_bf16 v[36:39], v[172:175], v[198:201], v[36:39]
	v_mfma_f32_16x16x32_bf16 v[32:35], v[182:185], v[198:201], v[32:35]
	v_mfma_f32_16x16x32_bf16 v[20:23], v[172:175], v[212:215], v[20:23]
	v_mfma_f32_16x16x32_bf16 v[16:19], v[182:185], v[212:215], v[16:19]
	v_mfma_f32_16x16x32_bf16 v[4:7], v[172:175], v[220:223], v[4:7]
	v_mfma_f32_16x16x32_bf16 v[0:3], v[182:185], v[220:223], v[0:3]
	v_mfma_f32_16x16x32_bf16 v[52:55], v[176:179], v[194:197], v[52:55]
	v_mfma_f32_16x16x32_bf16 v[48:51], v[186:189], v[194:197], v[48:51]
	v_mfma_f32_16x16x32_bf16 v[36:39], v[176:179], v[208:211], v[36:39]
	v_mfma_f32_16x16x32_bf16 v[32:35], v[186:189], v[208:211], v[32:35]
	v_mfma_f32_16x16x32_bf16 v[20:23], v[176:179], v[216:219], v[20:23]
	v_mfma_f32_16x16x32_bf16 v[16:19], v[186:189], v[216:219], v[16:19]
	v_mfma_f32_16x16x32_bf16 v[4:7], v[176:179], v[224:227], v[4:7]
	v_mfma_f32_16x16x32_bf16 v[0:3], v[186:189], v[224:227], v[0:3]
	s_setprio 0
	s_barrier
	s_add_i32 s86, s86, 2
	s_add_u32 s56, s56, 0x100
	s_addc_u32 s57, s57, 0
	s_add_u32 s84, s84, 0x100
	s_addc_u32 s85, s85, 0
	s_cmp_gt_u32 s86, 13
	s_cbranch_scc0 .LBB0_738
	s_and_b64 vcc, exec, s[44:45]
	s_cbranch_vccz .LBB0_741
	s_barrier

; #define PG8_STAGE(bufoff, gbase, voff) do { _Pragma("unroll") for (int _i = 0; _i < 2; ++_i) \
;         __builtin_amdgcn_global_load_lds((const unsigned*)((const char*)(gbase) + (voff)[_i]), (PG8_LAS unsigned*)(lds + (bufoff) + ldsw + _i * 8192), 16, 0, 0); } while (0)
; #define PG8_LDA(dst, b, h) do { _Pragma("unroll") for (int m = 0; m < 4; ++m) _Pragma("unroll") for (int k = 0; k < 2; ++k) dst[m][k] = *(const PG8_LAS bf16x8*)(lds + PG8_SA(b, h) + aoff + m * 2048 + k * 1024); } while (0)
; #define PG8_LDB(dst, b, h) do { _Pragma("unroll") for (int n = 0; n < 2; ++n) _Pragma("unroll") for (int k = 0; k < 2; ++k) dst[n][k] = *(const PG8_LAS bf16x8*)(lds + PG8_SB(b, h) + boff + n * 2048 + k * 1024); } while (0)
; #define PG8_MMA(ai, bj, At, Bt) do { __builtin_amdgcn_s_setprio(1); _Pragma("unroll") for (int m = 0; m < 4; ++m) _Pragma("unroll") for (int n = 0; n < 2; ++n) _Pragma("unroll") for (int k = 0; k < 2; ++k) \
;         acc[ai][bj][m][n] = __builtin_amdgcn_mfma_f32_16x16x32_bf16(Bt[n][k], At[m][k], acc[ai][bj][m][n], 0, 0, 0); __builtin_amdgcn_s_setprio(0); } while (0)
; #define PG8_WAIT_V(n) asm volatile("s_waitcnt vmcnt(" #n ")" ::: "memory")
; #define PG8_WAIT_L(n) asm volatile("s_waitcnt lgkmcnt(" #n ")" ::: "memory")
; #define PG8_BAR __builtin_amdgcn_s_barrier()
; #define PG8_SCHED __builtin_amdgcn_sched_barrier(0)
; template <class Epi, class Sched, bool ALIGN_EPI = false, bool SP2 = false>
; __device__ __forceinline__ void gemm_phase(PG8_LAS unsigned char* lds, const Gemm g, const Sched& S, const Epi& E) {
;     ...
;             const bool last = (t == nt - 2);
;             const char* a1 = cA + (size_t)(t + 1) * kstep;
;             const char* a2 = last ? nA : cA + (size_t)(t + 2) * kstep; const char* b2 = last ? nB : cB + (size_t)(t + 2) * kstep;
;             const char* a3 = a2 + kstep; const char* b3 = b2 + kstep;
;             if (last && has_next) S.a_ready(nxt);
;             if constexpr (SP2) {
;             PG8_LDB(B0, 0, 0); PG8_LDB(B1, 0, 1); PG8_SCHED; PG8_LDA(At, 0, 0); PG8_STAGE(PG8_SA(1, 1), a1 + hstep, voffA);
;             PG8_WAIT_V(8); PG8_WAIT_L(0); PG8_BAR; PG8_MMA(0, 0, At, B0); PG8_MMA(0, 1, At, B1); PG8_BAR; PG8_SCHED;
;             PG8_LDA(At, 0, 1); PG8_STAGE(PG8_SB(0, 0), b2, voffB); PG8_STAGE(PG8_SB(0, 1), b2 + hstep, voffB); PG8_STAGE(PG8_SA(0, 0), a2, voffA);
.LBB0_873:
	ds_read_b128 v[144:147], v151
	ds_read_b128 v[156:159], v151 offset:1024
	ds_read_b128 v[160:163], v151 offset:2048
	ds_read_b128 v[164:167], v151 offset:3072
	ds_read_b128 v[168:171], v152
	ds_read_b128 v[172:175], v152 offset:1024
	ds_read_b128 v[176:179], v152 offset:2048
	ds_read_b128 v[182:185], v152 offset:3072
	s_add_u32 s3, s58, 0xfffe0080
	s_addc_u32 s33, s59, -1
	s_cmp_eq_u32 s87, 4
	s_cselect_b32 s63, s49, s33
	s_cselect_b32 s62, s55, s3
	s_cselect_b32 s61, s45, s86
	s_cselect_b32 s60, s84, s85
	v_lshl_add_u64 v[202:203], s[58:59], 0, v[136:137]
	s_add_i32 m0, s15, 0xc000
	ds_read_b128 v[186:189], v153
	ds_read_b128 v[190:193], v153 offset:1024
	ds_read_b128 v[194:197], v153 offset:2048
	ds_read_b128 v[198:201], v153 offset:3072
	ds_read_b128 v[208:211], v153 offset:4096
	ds_read_b128 v[212:215], v153 offset:5120
	ds_read_b128 v[216:219], v153 offset:6144
	ds_read_b128 v[220:223], v153 offset:7168
	global_load_lds_dwordx4 v[202:203], off
	v_lshl_add_u64 v[202:203], s[58:59], 0, v[138:139]
	s_add_i32 m0, s15, 0xe000
	s_nop 0
	global_load_lds_dwordx4 v[202:203], off
	s_waitcnt vmcnt(8)
	s_waitcnt lgkmcnt(0)
	s_barrier
	s_setprio 1
	s_waitcnt lgkmcnt(0)
	v_mfma_f32_16x16x32_bf16 v[124:127], v[144:147], v[186:189], v[124:127]
	v_mfma_f32_16x16x32_bf16 v[120:123], v[160:163], v[186:189], v[120:123]
	v_mfma_f32_16x16x32_bf16 v[108:111], v[144:147], v[194:197], v[108:111]
	v_mfma_f32_16x16x32_bf16 v[104:107], v[160:163], v[194:197], v[104:107]
	v_mfma_f32_16x16x32_bf16 v[92:95], v[144:147], v[208:211], v[92:95]
	v_mfma_f32_16x16x32_bf16 v[88:91], v[160:163], v[208:211], v[88:91]
	v_mfma_f32_16x16x32_bf16 v[76:79], v[144:147], v[216:219], v[76:79]
	v_mfma_f32_16x16x32_bf16 v[72:75], v[160:163], v[216:219], v[72:75]
	v_mfma_f32_16x16x32_bf16 v[124:127], v[156:159], v[190:193], v[124:127]
	v_mfma_f32_16x16x32_bf16 v[120:123], v[164:167], v[190:193], v[120:123]
	v_mfma_f32_16x16x32_bf16 v[108:111], v[156:159], v[198:201], v[108:111]
	v_mfma_f32_16x16x32_bf16 v[104:107], v[164:167], v[198:201], v[104:107]
	v_mfma_f32_16x16x32_bf16 v[92:95], v[156:159], v[212:215], v[92:95]
	v_mfma_f32_16x16x32_bf16 v[88:91], v[164:167], v[212:215], v[88:91]
	v_mfma_f32_16x16x32_bf16 v[76:79], v[156:159], v[220:223], v[76:79]
	v_mfma_f32_16x16x32_bf16 v[72:75], v[164:167], v[220:223], v[72:75]
	s_setprio 0
	s_setprio 1
	v_mfma_f32_16x16x32_bf16 v[116:119], v[168:171], v[186:189], v[116:119]
	v_mfma_f32_16x16x32_bf16 v[112:115], v[176:179], v[186:189], v[112:115]
	v_mfma_f32_16x16x32_bf16 v[100:103], v[168:171], v[194:197], v[100:103]
	v_mfma_f32_16x16x32_bf16 v[96:99], v[176:179], v[194:197], v[96:99]
	v_mfma_f32_16x16x32_bf16 v[84:87], v[168:171], v[208:211], v[84:87]
	v_mfma_f32_16x16x32_bf16 v[80:83], v[176:179], v[208:211], v[80:83]
	v_mfma_f32_16x16x32_bf16 v[68:71], v[168:171], v[216:219], v[68:71]
	v_mfma_f32_16x16x32_bf16 v[64:67], v[176:179], v[216:219], v[64:67]
	v_mfma_f32_16x16x32_bf16 v[116:119], v[172:175], v[190:193], v[116:119]
	v_mfma_f32_16x16x32_bf16 v[112:115], v[182:185], v[190:193], v[112:115]
	v_mfma_f32_16x16x32_bf16 v[100:103], v[172:175], v[198:201], v[100:103]
	v_mfma_f32_16x16x32_bf16 v[96:99], v[182:185], v[198:201], v[96:99]
	v_mfma_f32_16x16x32_bf16 v[84:87], v[172:175], v[212:215], v[84:87]
	v_mfma_f32_16x16x32_bf16 v[80:83], v[182:185], v[212:215], v[80:83]
	v_mfma_f32_16x16x32_bf16 v[68:71], v[172:175], v[220:223], v[68:71]
	v_mfma_f32_16x16x32_bf16 v[64:67], v[182:185], v[220:223], v[64:67]
	s_setprio 0
	s_barrier
	s_add_i32 s3, s74, s14
	v_lshl_add_u64 v[202:203], s[60:61], 0, v[130:131]
	s_mov_b32 m0, s3
	ds_read_b128 v[186:189], v153 offset:16384
	ds_read_b128 v[190:193], v153 offset:17408
	ds_read_b128 v[194:197], v153 offset:18432
	ds_read_b128 v[198:201], v153 offset:19456
	ds_read_b128 v[208:211], v153 offset:20480
	ds_read_b128 v[212:215], v153 offset:21504
	ds_read_b128 v[216:219], v153 offset:22528
	ds_read_b128 v[220:223], v153 offset:23552
	global_load_lds_dwordx4 v[202:203], off
	s_add_i32 m0, s3, 0x2000
	s_add_u32 s78, s60, 0x20000
	v_lshl_add_u64 v[224:225], s[60:61], 0, v[134:135]
	s_addc_u32 s79, s61, 0
	s_add_i32 s3, s75, s14
	global_load_lds_dwordx4 v[224:225], off
	v_lshl_add_u64 v[226:227], s[78:79], 0, v[130:131]
	s_mov_b32 m0, s3
	global_load_lds_dwordx4 v[226:227], off
	v_lshl_add_u64 v[226:227], s[78:79], 0, v[134:135]
	s_add_i32 m0, s3, 0x2000
	s_nop 0
	global_load_lds_dwordx4 v[226:227], off
	s_waitcnt vmcnt(6)
	s_waitcnt lgkmcnt(0)
	s_barrier
; #define PG8_STAGE(bufoff, gbase, voff) do { _Pragma("unroll") for (int _i = 0; _i < 2; ++_i) \
;         __builtin_amdgcn_global_load_lds((const unsigned*)((const char*)(gbase) + (voff)[_i]), (PG8_LAS unsigned*)(lds + (bufoff) + ldsw + _i * 8192), 16, 0, 0); } while (0)
; #define PG8_LDA(dst, b, h) do { _Pragma("unroll") for (int m = 0; m < 4; ++m) _Pragma("unroll") for (int k = 0; k < 2; ++k) dst[m][k] = *(const PG8_LAS bf16x8*)(lds + PG8_SA(b, h) + aoff + m * 2048 + k * 1024); } while (0)
; #define PG8_LDB(dst, b, h) do { _Pragma("unroll") for (int n = 0; n < 2; ++n) _Pragma("unroll") for (int k = 0; k < 2; ++k) dst[n][k] = *(const PG8_LAS bf16x8*)(lds + PG8_SB(b, h) + boff + n * 2048 + k * 1024); } while (0)
; #define PG8_MMA(ai, bj, At, Bt) do { __builtin_amdgcn_s_setprio(1); _Pragma("unroll") for (int m = 0; m < 4; ++m) _Pragma("unroll") for (int n = 0; n < 2; ++n) _Pragma("unroll") for (int k = 0; k < 2; ++k) \
;         acc[ai][bj][m][n] = __builtin_amdgcn_mfma_f32_16x16x32_bf16(Bt[n][k], At[m][k], acc[ai][bj][m][n], 0, 0, 0); __builtin_amdgcn_s_setprio(0); } while (0)
; #define PG8_WAIT_V(n) asm volatile("s_waitcnt vmcnt(" #n ")" ::: "memory")
; #define PG8_WAIT_L(n) asm volatile("s_waitcnt lgkmcnt(" #n ")" ::: "memory")
; #define PG8_BAR __builtin_amdgcn_s_barrier()
; #define PG8_SCHED __builtin_amdgcn_sched_barrier(0)
; template <class Epi, class Sched, bool ALIGN_EPI = false, bool SP2 = false>
; __device__ __forceinline__ void gemm_phase(PG8_LAS unsigned char* lds, const Gemm g, const Sched& S, const Epi& E) {
;     ...
;             PG8_LDA(At, 0, 1); PG8_STAGE(PG8_SB(0, 0), b2, voffB); PG8_STAGE(PG8_SB(0, 1), b2 + hstep, voffB); PG8_STAGE(PG8_SA(0, 0), a2, voffA);
;             PG8_WAIT_V(8); PG8_WAIT_L(0); PG8_BAR; PG8_MMA(1, 0, At, B0); PG8_MMA(1, 1, At, B1); PG8_BAR; PG8_SCHED;
;             PG8_LDB(B0, 1, 0); PG8_LDB(B1, 1, 1); PG8_SCHED; PG8_LDA(At, 1, 0); PG8_STAGE(PG8_SA(0, 1), a2 + hstep, voffA);
;             PG8_WAIT_V(8); PG8_WAIT_L(0); PG8_BAR; PG8_MMA(0, 0, At, B0); PG8_MMA(0, 1, At, B1); PG8_BAR; PG8_SCHED;
	s_setprio 1
	s_waitcnt lgkmcnt(0)
	v_mfma_f32_16x16x32_bf16 v[60:63], v[144:147], v[186:189], v[60:63]
	v_mfma_f32_16x16x32_bf16 v[56:59], v[160:163], v[186:189], v[56:59]
	v_mfma_f32_16x16x32_bf16 v[44:47], v[144:147], v[194:197], v[44:47]
	v_mfma_f32_16x16x32_bf16 v[40:43], v[160:163], v[194:197], v[40:43]
	v_mfma_f32_16x16x32_bf16 v[28:31], v[144:147], v[208:211], v[28:31]
	v_mfma_f32_16x16x32_bf16 v[24:27], v[160:163], v[208:211], v[24:27]
	v_mfma_f32_16x16x32_bf16 v[12:15], v[144:147], v[216:219], v[12:15]
	v_mfma_f32_16x16x32_bf16 v[8:11], v[160:163], v[216:219], v[8:11]
	v_mfma_f32_16x16x32_bf16 v[60:63], v[156:159], v[190:193], v[60:63]
	v_mfma_f32_16x16x32_bf16 v[56:59], v[164:167], v[190:193], v[56:59]
	v_mfma_f32_16x16x32_bf16 v[44:47], v[156:159], v[198:201], v[44:47]
	v_mfma_f32_16x16x32_bf16 v[40:43], v[164:167], v[198:201], v[40:43]
	v_mfma_f32_16x16x32_bf16 v[28:31], v[156:159], v[212:215], v[28:31]
	v_mfma_f32_16x16x32_bf16 v[24:27], v[164:167], v[212:215], v[24:27]
	v_lshl_add_u64 v[226:227], s[62:63], 0, v[128:129]
	s_mov_b32 m0, s15
	s_nop 0
	global_load_lds_dwordx4 v[226:227], off
	v_mfma_f32_16x16x32_bf16 v[12:15], v[156:159], v[220:223], v[12:15]
	v_mfma_f32_16x16x32_bf16 v[8:11], v[164:167], v[220:223], v[8:11]
	s_setprio 0
	s_setprio 1
	v_mfma_f32_16x16x32_bf16 v[52:55], v[168:171], v[186:189], v[52:55]
	v_mfma_f32_16x16x32_bf16 v[48:51], v[176:179], v[186:189], v[48:51]
	v_mfma_f32_16x16x32_bf16 v[36:39], v[168:171], v[194:197], v[36:39]
	v_mfma_f32_16x16x32_bf16 v[32:35], v[176:179], v[194:197], v[32:35]
	v_mfma_f32_16x16x32_bf16 v[20:23], v[168:171], v[208:211], v[20:23]
	v_mfma_f32_16x16x32_bf16 v[16:19], v[176:179], v[208:211], v[16:19]
	v_mfma_f32_16x16x32_bf16 v[4:7], v[168:171], v[216:219], v[4:7]
	v_mfma_f32_16x16x32_bf16 v[0:3], v[176:179], v[216:219], v[0:3]
	v_mfma_f32_16x16x32_bf16 v[52:55], v[172:175], v[190:193], v[52:55]
	v_mfma_f32_16x16x32_bf16 v[48:51], v[182:185], v[190:193], v[48:51]
	v_mfma_f32_16x16x32_bf16 v[36:39], v[172:175], v[198:201], v[36:39]
	v_mfma_f32_16x16x32_bf16 v[32:35], v[182:185], v[198:201], v[32:35]
	v_mfma_f32_16x16x32_bf16 v[20:23], v[172:175], v[212:215], v[20:23]
	v_mfma_f32_16x16x32_bf16 v[16:19], v[182:185], v[212:215], v[16:19]
	v_lshl_add_u64 v[228:229], s[62:63], 0, v[132:133]
	s_mov_b32 m0, s34
	s_nop 0
	global_load_lds_dwordx4 v[228:229], off
	v_mfma_f32_16x16x32_bf16 v[4:7], v[172:175], v[220:223], v[4:7]
	v_mfma_f32_16x16x32_bf16 v[0:3], v[182:185], v[220:223], v[0:3]
	s_setprio 0
	s_barrier
	s_add_i32 s3, 0, 0x18000
	v_add_u32_e32 v155, s3, v149
	s_add_i32 s33, 0, 0x1c000
	ds_read_b128 v[144:147], v155
	ds_read_b128 v[156:159], v155 offset:1024
	ds_read_b128 v[160:163], v155 offset:2048
	ds_read_b128 v[164:167], v155 offset:3072
	v_add_u32_e32 v155, s33, v149
	ds_read_b128 v[168:171], v155
	ds_read_b128 v[172:175], v155 offset:1024
	ds_read_b128 v[176:179], v155 offset:2048
	ds_read_b128 v[182:185], v155 offset:3072
	s_add_u32 s62, s62, 0x20000
	s_addc_u32 s63, s63, 0
	s_mov_b32 m0, s57
	v_lshl_add_u64 v[230:231], s[62:63], 0, v[128:129]
	ds_read_b128 v[186:189], v153 offset:32768
	ds_read_b128 v[190:193], v153 offset:33792
	ds_read_b128 v[194:197], v153 offset:34816
	ds_read_b128 v[198:201], v153 offset:35840
	ds_read_b128 v[208:211], v153 offset:36864
	ds_read_b128 v[212:215], v153 offset:37888
	ds_read_b128 v[216:219], v153 offset:38912
	ds_read_b128 v[220:223], v153 offset:39936
	global_load_lds_dwordx4 v[230:231], off
	v_lshl_add_u64 v[230:231], s[62:63], 0, v[132:133]
	s_mov_b32 m0, s64
	s_nop 0
	global_load_lds_dwordx4 v[230:231], off
	s_waitcnt vmcnt(8)
	s_waitcnt lgkmcnt(0)
	s_barrier
	s_setprio 1
	s_waitcnt lgkmcnt(0)
	v_mfma_f32_16x16x32_bf16 v[124:127], v[144:147], v[186:189], v[124:127]
	v_mfma_f32_16x16x32_bf16 v[120:123], v[160:163], v[186:189], v[120:123]
	v_mfma_f32_16x16x32_bf16 v[108:111], v[144:147], v[194:197], v[108:111]
	v_mfma_f32_16x16x32_bf16 v[104:107], v[160:163], v[194:197], v[104:107]
	v_mfma_f32_16x16x32_bf16 v[92:95], v[144:147], v[208:211], v[92:95]
	v_mfma_f32_16x16x32_bf16 v[88:91], v[160:163], v[208:211], v[88:91]
	v_mfma_f32_16x16x32_bf16 v[76:79], v[144:147], v[216:219], v[76:79]
	v_mfma_f32_16x16x32_bf16 v[72:75], v[160:163], v[216:219], v[72:75]
	v_mfma_f32_16x16x32_bf16 v[124:127], v[156:159], v[190:193], v[124:127]
	v_mfma_f32_16x16x32_bf16 v[120:123], v[164:167], v[190:193], v[120:123]
	v_mfma_f32_16x16x32_bf16 v[108:111], v[156:159], v[198:201], v[108:111]
	v_mfma_f32_16x16x32_bf16 v[104:107], v[164:167], v[198:201], v[104:107]
	v_mfma_f32_16x16x32_bf16 v[92:95], v[156:159], v[212:215], v[92:95]
	v_mfma_f32_16x16x32_bf16 v[88:91], v[164:167], v[212:215], v[88:91]
	v_mfma_f32_16x16x32_bf16 v[76:79], v[156:159], v[220:223], v[76:79]
	v_mfma_f32_16x16x32_bf16 v[72:75], v[164:167], v[220:223], v[72:75]
	s_setprio 0
	s_setprio 1
	v_mfma_f32_16x16x32_bf16 v[116:119], v[168:171], v[186:189], v[116:119]
	v_mfma_f32_16x16x32_bf16 v[112:115], v[176:179], v[186:189], v[112:115]
	v_mfma_f32_16x16x32_bf16 v[100:103], v[168:171], v[194:197], v[100:103]
	v_mfma_f32_16x16x32_bf16 v[96:99], v[176:179], v[194:197], v[96:99]
	v_mfma_f32_16x16x32_bf16 v[84:87], v[168:171], v[208:211], v[84:87]
	v_mfma_f32_16x16x32_bf16 v[80:83], v[176:179], v[208:211], v[80:83]
	v_mfma_f32_16x16x32_bf16 v[68:71], v[168:171], v[216:219], v[68:71]
	v_mfma_f32_16x16x32_bf16 v[64:67], v[176:179], v[216:219], v[64:67]
	v_mfma_f32_16x16x32_bf16 v[116:119], v[172:175], v[190:193], v[116:119]
	v_mfma_f32_16x16x32_bf16 v[112:115], v[182:185], v[190:193], v[112:115]
	v_mfma_f32_16x16x32_bf16 v[100:103], v[172:175], v[198:201], v[100:103]
	v_mfma_f32_16x16x32_bf16 v[96:99], v[182:185], v[198:201], v[96:99]
	v_mfma_f32_16x16x32_bf16 v[84:87], v[172:175], v[212:215], v[84:87]
	v_mfma_f32_16x16x32_bf16 v[80:83], v[182:185], v[212:215], v[80:83]
	v_mfma_f32_16x16x32_bf16 v[68:71], v[172:175], v[220:223], v[68:71]
	v_mfma_f32_16x16x32_bf16 v[64:67], v[182:185], v[220:223], v[64:67]
	s_setprio 0
	s_barrier
; #define PG8_STAGE(bufoff, gbase, voff) do { _Pragma("unroll") for (int _i = 0; _i < 2; ++_i) \
;         __builtin_amdgcn_global_load_lds((const unsigned*)((const char*)(gbase) + (voff)[_i]), (PG8_LAS unsigned*)(lds + (bufoff) + ldsw + _i * 8192), 16, 0, 0); } while (0)
; #define PG8_LDA(dst, b, h) do { _Pragma("unroll") for (int m = 0; m < 4; ++m) _Pragma("unroll") for (int k = 0; k < 2; ++k) dst[m][k] = *(const PG8_LAS bf16x8*)(lds + PG8_SA(b, h) + aoff + m * 2048 + k * 1024); } while (0)
; #define PG8_MMA(ai, bj, At, Bt) do { __builtin_amdgcn_s_setprio(1); _Pragma("unroll") for (int m = 0; m < 4; ++m) _Pragma("unroll") for (int n = 0; n < 2; ++n) _Pragma("unroll") for (int k = 0; k < 2; ++k) \
;         acc[ai][bj][m][n] = __builtin_amdgcn_mfma_f32_16x16x32_bf16(Bt[n][k], At[m][k], acc[ai][bj][m][n], 0, 0, 0); __builtin_amdgcn_s_setprio(0); } while (0)
; #define PG8_WAIT_V(n) asm volatile("s_waitcnt vmcnt(" #n ")" ::: "memory")
; #define PG8_WAIT_L(n) asm volatile("s_waitcnt lgkmcnt(" #n ")" ::: "memory")
; #define PG8_BAR __builtin_amdgcn_s_barrier()
; #define PG8_SCHED __builtin_amdgcn_sched_barrier(0)
; template <class Epi, class Sched, bool ALIGN_EPI = false, bool SP2 = false>
; __device__ __forceinline__ void gemm_phase(PG8_LAS unsigned char* lds, const Gemm g, const Sched& S, const Epi& E) {
;     ...
;             PG8_LDA(At, 1, 1); PG8_STAGE(PG8_SB(1, 0), b3, voffB); PG8_STAGE(PG8_SB(1, 1), b3 + hstep, voffB); PG8_STAGE(PG8_SA(1, 0), a3, voffA);
;             PG8_WAIT_V(8); PG8_WAIT_L(0); PG8_BAR; PG8_MMA(1, 0, At, B0); PG8_MMA(1, 1, At, B1); PG8_BAR; PG8_SCHED;
;     ...
;         if constexpr (ALIGN_EPI) { if (wr == 0) PG8_BAR; }
	s_add_i32 s3, s3, s14
	v_lshl_add_u64 v[202:203], v[202:203], 0, s[38:39]
	s_mov_b32 m0, s3
	ds_read_b128 v[186:189], v153 offset:49152
	ds_read_b128 v[190:193], v153 offset:50176
	ds_read_b128 v[194:197], v153 offset:51200
	ds_read_b128 v[198:201], v153 offset:52224
	ds_read_b128 v[208:211], v153 offset:53248
	ds_read_b128 v[212:215], v153 offset:54272
	ds_read_b128 v[216:219], v153 offset:55296
	ds_read_b128 v[220:223], v153 offset:56320
	global_load_lds_dwordx4 v[202:203], off
	s_add_i32 m0, s3, 0x2000
	s_add_u32 s60, s60, 0x20080
	v_lshl_add_u64 v[202:203], v[224:225], 0, s[38:39]
	s_addc_u32 s61, s61, 0
	s_add_i32 s3, s33, s14
	global_load_lds_dwordx4 v[202:203], off
	v_lshl_add_u64 v[202:203], s[60:61], 0, v[130:131]
	s_mov_b32 m0, s3
	s_nop 0
	global_load_lds_dwordx4 v[202:203], off
	v_lshl_add_u64 v[202:203], s[60:61], 0, v[134:135]
	s_add_i32 m0, s3, 0x2000
	s_nop 0
	global_load_lds_dwordx4 v[202:203], off
	s_waitcnt vmcnt(6)
	s_waitcnt lgkmcnt(0)
	s_barrier
	s_setprio 1
	s_waitcnt lgkmcnt(0)
	v_mfma_f32_16x16x32_bf16 v[60:63], v[144:147], v[186:189], v[60:63]
	v_mfma_f32_16x16x32_bf16 v[56:59], v[160:163], v[186:189], v[56:59]
	v_lshl_add_u64 v[202:203], v[226:227], 0, s[38:39]
	s_mov_b32 m0, s66
	s_nop 0
	global_load_lds_dwordx4 v[202:203], off
	v_mfma_f32_16x16x32_bf16 v[44:47], v[144:147], v[194:197], v[44:47]
	v_mfma_f32_16x16x32_bf16 v[40:43], v[160:163], v[194:197], v[40:43]
	v_mfma_f32_16x16x32_bf16 v[28:31], v[144:147], v[208:211], v[28:31]
	v_mfma_f32_16x16x32_bf16 v[24:27], v[160:163], v[208:211], v[24:27]
	v_lshl_add_u64 v[202:203], v[228:229], 0, s[38:39]
	s_mov_b32 m0, s67
	s_nop 0
	global_load_lds_dwordx4 v[202:203], off
	v_mfma_f32_16x16x32_bf16 v[12:15], v[144:147], v[216:219], v[12:15]
	v_mfma_f32_16x16x32_bf16 v[8:11], v[160:163], v[216:219], v[8:11]
	v_mfma_f32_16x16x32_bf16 v[60:63], v[156:159], v[190:193], v[60:63]
	v_mfma_f32_16x16x32_bf16 v[56:59], v[164:167], v[190:193], v[56:59]
	v_mfma_f32_16x16x32_bf16 v[44:47], v[156:159], v[198:201], v[44:47]
	v_mfma_f32_16x16x32_bf16 v[40:43], v[164:167], v[198:201], v[40:43]
	v_mfma_f32_16x16x32_bf16 v[28:31], v[156:159], v[212:215], v[28:31]
	v_mfma_f32_16x16x32_bf16 v[24:27], v[164:167], v[212:215], v[24:27]
	v_mfma_f32_16x16x32_bf16 v[12:15], v[156:159], v[220:223], v[12:15]
	v_mfma_f32_16x16x32_bf16 v[8:11], v[164:167], v[220:223], v[8:11]
	s_setprio 0
	s_setprio 1
	v_mfma_f32_16x16x32_bf16 v[52:55], v[168:171], v[186:189], v[52:55]
	v_mfma_f32_16x16x32_bf16 v[48:51], v[176:179], v[186:189], v[48:51]
	v_mfma_f32_16x16x32_bf16 v[36:39], v[168:171], v[194:197], v[36:39]
	v_mfma_f32_16x16x32_bf16 v[32:35], v[176:179], v[194:197], v[32:35]
	v_mfma_f32_16x16x32_bf16 v[20:23], v[168:171], v[208:211], v[20:23]
	v_mfma_f32_16x16x32_bf16 v[16:19], v[176:179], v[208:211], v[16:19]
	v_mfma_f32_16x16x32_bf16 v[4:7], v[168:171], v[216:219], v[4:7]
	v_mfma_f32_16x16x32_bf16 v[0:3], v[176:179], v[216:219], v[0:3]
	v_mfma_f32_16x16x32_bf16 v[52:55], v[172:175], v[190:193], v[52:55]
	v_mfma_f32_16x16x32_bf16 v[48:51], v[182:185], v[190:193], v[48:51]
	v_mfma_f32_16x16x32_bf16 v[36:39], v[172:175], v[198:201], v[36:39]
	v_mfma_f32_16x16x32_bf16 v[32:35], v[182:185], v[198:201], v[32:35]
	v_mfma_f32_16x16x32_bf16 v[20:23], v[172:175], v[212:215], v[20:23]
	v_mfma_f32_16x16x32_bf16 v[16:19], v[182:185], v[212:215], v[16:19]
	v_mfma_f32_16x16x32_bf16 v[4:7], v[172:175], v[220:223], v[4:7]
	v_mfma_f32_16x16x32_bf16 v[0:3], v[182:185], v[220:223], v[0:3]
	s_setprio 0
	s_barrier
	s_add_i32 s87, s87, 2
	s_add_u32 s58, s58, 0x100
	s_addc_u32 s59, s59, 0
	s_add_u32 s85, s85, 0x100
	s_addc_u32 s86, s86, 0
	s_cmp_gt_u32 s87, 5
	s_cbranch_scc0 .LBB0_873
	s_and_b64 vcc, exec, s[42:43]
	s_cbranch_vccz .LBB0_876
	s_barrier

; #define PG8_STAGE(bufoff, gbase, voff) do { _Pragma("unroll") for (int _i = 0; _i < 2; ++_i) \
;         __builtin_amdgcn_global_load_lds((const unsigned*)((const char*)(gbase) + (voff)[_i]), (PG8_LAS unsigned*)(lds + (bufoff) + ldsw + _i * 8192), 16, 0, 0); } while (0)
; #define PG8_LDA(dst, b, h) do { _Pragma("unroll") for (int m = 0; m < 4; ++m) _Pragma("unroll") for (int k = 0; k < 2; ++k) dst[m][k] = *(const PG8_LAS bf16x8*)(lds + PG8_SA(b, h) + aoff + m * 2048 + k * 1024); } while (0)
; #define PG8_LDB(dst, b, h) do { _Pragma("unroll") for (int n = 0; n < 2; ++n) _Pragma("unroll") for (int k = 0; k < 2; ++k) dst[n][k] = *(const PG8_LAS bf16x8*)(lds + PG8_SB(b, h) + boff + n * 2048 + k * 1024); } while (0)
; #define PG8_MMA(ai, bj, At, Bt) do { __builtin_amdgcn_s_setprio(1); _Pragma("unroll") for (int m = 0; m < 4; ++m) _Pragma("unroll") for (int n = 0; n < 2; ++n) _Pragma("unroll") for (int k = 0; k < 2; ++k) \
;         acc[ai][bj][m][n] = __builtin_amdgcn_mfma_f32_16x16x32_bf16(Bt[n][k], At[m][k], acc[ai][bj][m][n], 0, 0, 0); __builtin_amdgcn_s_setprio(0); } while (0)
; #define PG8_WAIT_V(n) asm volatile("s_waitcnt vmcnt(" #n ")" ::: "memory")
; #define PG8_WAIT_L(n) asm volatile("s_waitcnt lgkmcnt(" #n ")" ::: "memory")
; #define PG8_BAR __builtin_amdgcn_s_barrier()
; #define PG8_SCHED __builtin_amdgcn_sched_barrier(0)
; template <class Epi, class Sched, bool ALIGN_EPI = false, bool SP2 = false>
; __device__ __forceinline__ void gemm_phase(PG8_LAS unsigned char* lds, const Gemm g, const Sched& S, const Epi& E) {
;     ...
;             const bool last = (t == nt - 2);
;             const char* a1 = cA + (size_t)(t + 1) * kstep;
;             const char* a2 = last ? nA : cA + (size_t)(t + 2) * kstep; const char* b2 = last ? nB : cB + (size_t)(t + 2) * kstep;
;             const char* a3 = a2 + kstep; const char* b3 = b2 + kstep;
;             if (last && has_next) S.a_ready(nxt);
;             if constexpr (SP2) {
;             PG8_LDB(B0, 0, 0); PG8_LDB(B1, 0, 1); PG8_SCHED; PG8_LDA(At, 0, 0); PG8_STAGE(PG8_SA(1, 1), a1 + hstep, voffA);
;             PG8_WAIT_V(8); PG8_WAIT_L(0); PG8_BAR; PG8_MMA(0, 0, At, B0); PG8_MMA(0, 1, At, B1); PG8_BAR; PG8_SCHED;
;             PG8_LDA(At, 0, 1); PG8_STAGE(PG8_SB(0, 0), b2, voffB); PG8_STAGE(PG8_SB(0, 1), b2 + hstep, voffB); PG8_STAGE(PG8_SA(0, 0), a2, voffA);
.LBB0_957:
	ds_read_b128 v[144:147], v155
	ds_read_b128 v[148:151], v155 offset:1024
	ds_read_b128 v[160:163], v155 offset:2048
	ds_read_b128 v[164:167], v155 offset:3072
	ds_read_b128 v[168:171], v156
	ds_read_b128 v[172:175], v156 offset:1024
	ds_read_b128 v[176:179], v156 offset:2048
	ds_read_b128 v[182:185], v156 offset:3072
	s_add_u32 s3, s54, 0xfffc0080
	s_addc_u32 s33, s55, -1
	s_cmp_eq_u32 s83, 12
	s_cselect_b32 s59, s45, s33
	s_cselect_b32 s58, s75, s3
	s_cselect_b32 s57, s43, s82
	s_cselect_b32 s56, s76, s77
	v_lshl_add_u64 v[202:203], s[54:55], 0, v[136:137]
	s_add_i32 m0, s34, 0xc000
	ds_read_b128 v[186:189], v157
	ds_read_b128 v[190:193], v157 offset:1024
	ds_read_b128 v[194:197], v157 offset:2048
	ds_read_b128 v[198:201], v157 offset:3072
	ds_read_b128 v[208:211], v157 offset:4096
	ds_read_b128 v[212:215], v157 offset:5120
	ds_read_b128 v[216:219], v157 offset:6144
	ds_read_b128 v[220:223], v157 offset:7168
	global_load_lds_dwordx4 v[202:203], off
	v_lshl_add_u64 v[202:203], s[54:55], 0, v[138:139]
	s_add_i32 m0, s34, 0xe000
	s_nop 0
	global_load_lds_dwordx4 v[202:203], off
	s_waitcnt vmcnt(8)
	s_waitcnt lgkmcnt(0)
	s_barrier
	s_setprio 1
	s_waitcnt lgkmcnt(0)
	v_mfma_f32_16x16x32_bf16 v[124:127], v[144:147], v[186:189], v[124:127]
	v_mfma_f32_16x16x32_bf16 v[120:123], v[160:163], v[186:189], v[120:123]
	v_mfma_f32_16x16x32_bf16 v[108:111], v[144:147], v[194:197], v[108:111]
	v_mfma_f32_16x16x32_bf16 v[104:107], v[160:163], v[194:197], v[104:107]
	v_mfma_f32_16x16x32_bf16 v[92:95], v[144:147], v[208:211], v[92:95]
	v_mfma_f32_16x16x32_bf16 v[88:91], v[160:163], v[208:211], v[88:91]
	v_mfma_f32_16x16x32_bf16 v[76:79], v[144:147], v[216:219], v[76:79]
	v_mfma_f32_16x16x32_bf16 v[72:75], v[160:163], v[216:219], v[72:75]
	v_mfma_f32_16x16x32_bf16 v[124:127], v[148:151], v[190:193], v[124:127]
	v_mfma_f32_16x16x32_bf16 v[120:123], v[164:167], v[190:193], v[120:123]
	v_mfma_f32_16x16x32_bf16 v[108:111], v[148:151], v[198:201], v[108:111]
	v_mfma_f32_16x16x32_bf16 v[104:107], v[164:167], v[198:201], v[104:107]
	v_mfma_f32_16x16x32_bf16 v[92:95], v[148:151], v[212:215], v[92:95]
	v_mfma_f32_16x16x32_bf16 v[88:91], v[164:167], v[212:215], v[88:91]
	v_mfma_f32_16x16x32_bf16 v[76:79], v[148:151], v[220:223], v[76:79]
	v_mfma_f32_16x16x32_bf16 v[72:75], v[164:167], v[220:223], v[72:75]
	s_setprio 0
	s_setprio 1
	v_mfma_f32_16x16x32_bf16 v[116:119], v[168:171], v[186:189], v[116:119]
	v_mfma_f32_16x16x32_bf16 v[112:115], v[176:179], v[186:189], v[112:115]
	v_mfma_f32_16x16x32_bf16 v[100:103], v[168:171], v[194:197], v[100:103]
	v_mfma_f32_16x16x32_bf16 v[96:99], v[176:179], v[194:197], v[96:99]
	v_mfma_f32_16x16x32_bf16 v[84:87], v[168:171], v[208:211], v[84:87]
	v_mfma_f32_16x16x32_bf16 v[80:83], v[176:179], v[208:211], v[80:83]
	v_mfma_f32_16x16x32_bf16 v[68:71], v[168:171], v[216:219], v[68:71]
	v_mfma_f32_16x16x32_bf16 v[64:67], v[176:179], v[216:219], v[64:67]
	v_mfma_f32_16x16x32_bf16 v[116:119], v[172:175], v[190:193], v[116:119]
	v_mfma_f32_16x16x32_bf16 v[112:115], v[182:185], v[190:193], v[112:115]
	v_mfma_f32_16x16x32_bf16 v[100:103], v[172:175], v[198:201], v[100:103]
	v_mfma_f32_16x16x32_bf16 v[96:99], v[182:185], v[198:201], v[96:99]
	v_mfma_f32_16x16x32_bf16 v[84:87], v[172:175], v[212:215], v[84:87]
	v_mfma_f32_16x16x32_bf16 v[80:83], v[182:185], v[212:215], v[80:83]
	v_mfma_f32_16x16x32_bf16 v[68:71], v[172:175], v[220:223], v[68:71]
	v_mfma_f32_16x16x32_bf16 v[64:67], v[182:185], v[220:223], v[64:67]
	s_setprio 0
	s_barrier
	s_add_i32 s3, s65, s14
	v_lshl_add_u64 v[202:203], s[56:57], 0, v[132:133]
	s_mov_b32 m0, s3
	ds_read_b128 v[186:189], v157 offset:16384
	ds_read_b128 v[190:193], v157 offset:17408
	ds_read_b128 v[194:197], v157 offset:18432
	ds_read_b128 v[198:201], v157 offset:19456
	ds_read_b128 v[208:211], v157 offset:20480
	ds_read_b128 v[212:215], v157 offset:21504
	ds_read_b128 v[216:219], v157 offset:22528
	ds_read_b128 v[220:223], v157 offset:23552
	global_load_lds_dwordx4 v[202:203], off
	s_add_i32 m0, s3, 0x2000
	s_add_u32 s78, s56, 0x40000
	v_lshl_add_u64 v[224:225], s[56:57], 0, v[128:129]
	s_addc_u32 s79, s57, 0
	s_add_i32 s3, s66, s14
	global_load_lds_dwordx4 v[224:225], off
	v_lshl_add_u64 v[226:227], s[78:79], 0, v[132:133]
	s_mov_b32 m0, s3
	global_load_lds_dwordx4 v[226:227], off
	v_lshl_add_u64 v[226:227], s[78:79], 0, v[128:129]
	s_add_i32 m0, s3, 0x2000
	s_nop 0
	global_load_lds_dwordx4 v[226:227], off
	s_waitcnt vmcnt(6)
	s_waitcnt lgkmcnt(0)
	s_barrier
; #define PG8_STAGE(bufoff, gbase, voff) do { _Pragma("unroll") for (int _i = 0; _i < 2; ++_i) \
;         __builtin_amdgcn_global_load_lds((const unsigned*)((const char*)(gbase) + (voff)[_i]), (PG8_LAS unsigned*)(lds + (bufoff) + ldsw + _i * 8192), 16, 0, 0); } while (0)
; #define PG8_LDA(dst, b, h) do { _Pragma("unroll") for (int m = 0; m < 4; ++m) _Pragma("unroll") for (int k = 0; k < 2; ++k) dst[m][k] = *(const PG8_LAS bf16x8*)(lds + PG8_SA(b, h) + aoff + m * 2048 + k * 1024); } while (0)
; #define PG8_LDB(dst, b, h) do { _Pragma("unroll") for (int n = 0; n < 2; ++n) _Pragma("unroll") for (int k = 0; k < 2; ++k) dst[n][k] = *(const PG8_LAS bf16x8*)(lds + PG8_SB(b, h) + boff + n * 2048 + k * 1024); } while (0)
; #define PG8_MMA(ai, bj, At, Bt) do { __builtin_amdgcn_s_setprio(1); _Pragma("unroll") for (int m = 0; m < 4; ++m) _Pragma("unroll") for (int n = 0; n < 2; ++n) _Pragma("unroll") for (int k = 0; k < 2; ++k) \
;         acc[ai][bj][m][n] = __builtin_amdgcn_mfma_f32_16x16x32_bf16(Bt[n][k], At[m][k], acc[ai][bj][m][n], 0, 0, 0); __builtin_amdgcn_s_setprio(0); } while (0)
; #define PG8_WAIT_V(n) asm volatile("s_waitcnt vmcnt(" #n ")" ::: "memory")
; #define PG8_WAIT_L(n) asm volatile("s_waitcnt lgkmcnt(" #n ")" ::: "memory")
; #define PG8_BAR __builtin_amdgcn_s_barrier()
; #define PG8_SCHED __builtin_amdgcn_sched_barrier(0)
; template <class Epi, class Sched, bool ALIGN_EPI = false, bool SP2 = false>
; __device__ __forceinline__ void gemm_phase(PG8_LAS unsigned char* lds, const Gemm g, const Sched& S, const Epi& E) {
;     ...
;             PG8_LDA(At, 0, 1); PG8_STAGE(PG8_SB(0, 0), b2, voffB); PG8_STAGE(PG8_SB(0, 1), b2 + hstep, voffB); PG8_STAGE(PG8_SA(0, 0), a2, voffA);
;             PG8_WAIT_V(8); PG8_WAIT_L(0); PG8_BAR; PG8_MMA(1, 0, At, B0); PG8_MMA(1, 1, At, B1); PG8_BAR; PG8_SCHED;
;             PG8_LDB(B0, 1, 0); PG8_LDB(B1, 1, 1); PG8_SCHED; PG8_LDA(At, 1, 0); PG8_STAGE(PG8_SA(0, 1), a2 + hstep, voffA);
;             PG8_WAIT_V(8); PG8_WAIT_L(0); PG8_BAR; PG8_MMA(0, 0, At, B0); PG8_MMA(0, 1, At, B1); PG8_BAR; PG8_SCHED;
	s_setprio 1
	s_waitcnt lgkmcnt(0)
	v_mfma_f32_16x16x32_bf16 v[60:63], v[144:147], v[186:189], v[60:63]
	v_mfma_f32_16x16x32_bf16 v[56:59], v[160:163], v[186:189], v[56:59]
	v_mfma_f32_16x16x32_bf16 v[44:47], v[144:147], v[194:197], v[44:47]
	v_mfma_f32_16x16x32_bf16 v[40:43], v[160:163], v[194:197], v[40:43]
	v_mfma_f32_16x16x32_bf16 v[28:31], v[144:147], v[208:211], v[28:31]
	v_mfma_f32_16x16x32_bf16 v[24:27], v[160:163], v[208:211], v[24:27]
	v_mfma_f32_16x16x32_bf16 v[12:15], v[144:147], v[216:219], v[12:15]
	v_mfma_f32_16x16x32_bf16 v[8:11], v[160:163], v[216:219], v[8:11]
	v_mfma_f32_16x16x32_bf16 v[60:63], v[148:151], v[190:193], v[60:63]
	v_mfma_f32_16x16x32_bf16 v[56:59], v[164:167], v[190:193], v[56:59]
	v_mfma_f32_16x16x32_bf16 v[44:47], v[148:151], v[198:201], v[44:47]
	v_mfma_f32_16x16x32_bf16 v[40:43], v[164:167], v[198:201], v[40:43]
	v_mfma_f32_16x16x32_bf16 v[28:31], v[148:151], v[212:215], v[28:31]
	v_mfma_f32_16x16x32_bf16 v[24:27], v[164:167], v[212:215], v[24:27]
	v_lshl_add_u64 v[226:227], s[58:59], 0, v[134:135]
	s_mov_b32 m0, s34
	s_nop 0
	global_load_lds_dwordx4 v[226:227], off
	v_mfma_f32_16x16x32_bf16 v[12:15], v[148:151], v[220:223], v[12:15]
	v_mfma_f32_16x16x32_bf16 v[8:11], v[164:167], v[220:223], v[8:11]
	s_setprio 0
	s_setprio 1
	v_mfma_f32_16x16x32_bf16 v[52:55], v[168:171], v[186:189], v[52:55]
	v_mfma_f32_16x16x32_bf16 v[48:51], v[176:179], v[186:189], v[48:51]
	v_mfma_f32_16x16x32_bf16 v[36:39], v[168:171], v[194:197], v[36:39]
	v_mfma_f32_16x16x32_bf16 v[32:35], v[176:179], v[194:197], v[32:35]
	v_mfma_f32_16x16x32_bf16 v[20:23], v[168:171], v[208:211], v[20:23]
	v_mfma_f32_16x16x32_bf16 v[16:19], v[176:179], v[208:211], v[16:19]
	v_mfma_f32_16x16x32_bf16 v[4:7], v[168:171], v[216:219], v[4:7]
	v_mfma_f32_16x16x32_bf16 v[0:3], v[176:179], v[216:219], v[0:3]
	v_mfma_f32_16x16x32_bf16 v[52:55], v[172:175], v[190:193], v[52:55]
	v_mfma_f32_16x16x32_bf16 v[48:51], v[182:185], v[190:193], v[48:51]
	v_mfma_f32_16x16x32_bf16 v[36:39], v[172:175], v[198:201], v[36:39]
	v_mfma_f32_16x16x32_bf16 v[32:35], v[182:185], v[198:201], v[32:35]
	v_mfma_f32_16x16x32_bf16 v[20:23], v[172:175], v[212:215], v[20:23]
	v_mfma_f32_16x16x32_bf16 v[16:19], v[182:185], v[212:215], v[16:19]
	v_lshl_add_u64 v[228:229], s[58:59], 0, v[130:131]
	s_mov_b32 m0, s53
	s_nop 0
	global_load_lds_dwordx4 v[228:229], off
	v_mfma_f32_16x16x32_bf16 v[4:7], v[172:175], v[220:223], v[4:7]
	v_mfma_f32_16x16x32_bf16 v[0:3], v[182:185], v[220:223], v[0:3]
	s_setprio 0
	s_barrier
	s_add_i32 s3, 0, 0x18000
	v_add_u32_e32 v159, s3, v153
	s_add_i32 s33, 0, 0x1c000
	ds_read_b128 v[144:147], v159
	ds_read_b128 v[148:151], v159 offset:1024
	ds_read_b128 v[160:163], v159 offset:2048
	ds_read_b128 v[164:167], v159 offset:3072
	v_add_u32_e32 v159, s33, v153
	ds_read_b128 v[168:171], v159
	ds_read_b128 v[172:175], v159 offset:1024
	ds_read_b128 v[176:179], v159 offset:2048
	ds_read_b128 v[182:185], v159 offset:3072
	s_add_u32 s58, s58, 0x40000
	s_addc_u32 s59, s59, 0
	s_mov_b32 m0, s60
	v_lshl_add_u64 v[230:231], s[58:59], 0, v[134:135]
	ds_read_b128 v[186:189], v157 offset:32768
	ds_read_b128 v[190:193], v157 offset:33792
	ds_read_b128 v[194:197], v157 offset:34816
	ds_read_b128 v[198:201], v157 offset:35840
	ds_read_b128 v[208:211], v157 offset:36864
	ds_read_b128 v[212:215], v157 offset:37888
	ds_read_b128 v[216:219], v157 offset:38912
	ds_read_b128 v[220:223], v157 offset:39936
	global_load_lds_dwordx4 v[230:231], off
	v_lshl_add_u64 v[230:231], s[58:59], 0, v[130:131]
	s_mov_b32 m0, s61
	s_nop 0
	global_load_lds_dwordx4 v[230:231], off
	s_waitcnt vmcnt(8)
	s_waitcnt lgkmcnt(0)
	s_barrier
	s_setprio 1
	s_waitcnt lgkmcnt(0)
	v_mfma_f32_16x16x32_bf16 v[124:127], v[144:147], v[186:189], v[124:127]
	v_mfma_f32_16x16x32_bf16 v[120:123], v[160:163], v[186:189], v[120:123]
	v_mfma_f32_16x16x32_bf16 v[108:111], v[144:147], v[194:197], v[108:111]
	v_mfma_f32_16x16x32_bf16 v[104:107], v[160:163], v[194:197], v[104:107]
	v_mfma_f32_16x16x32_bf16 v[92:95], v[144:147], v[208:211], v[92:95]
	v_mfma_f32_16x16x32_bf16 v[88:91], v[160:163], v[208:211], v[88:91]
	v_mfma_f32_16x16x32_bf16 v[76:79], v[144:147], v[216:219], v[76:79]
	v_mfma_f32_16x16x32_bf16 v[72:75], v[160:163], v[216:219], v[72:75]
	v_mfma_f32_16x16x32_bf16 v[124:127], v[148:151], v[190:193], v[124:127]
	v_mfma_f32_16x16x32_bf16 v[120:123], v[164:167], v[190:193], v[120:123]
	v_mfma_f32_16x16x32_bf16 v[108:111], v[148:151], v[198:201], v[108:111]
	v_mfma_f32_16x16x32_bf16 v[104:107], v[164:167], v[198:201], v[104:107]
	v_mfma_f32_16x16x32_bf16 v[92:95], v[148:151], v[212:215], v[92:95]
	v_mfma_f32_16x16x32_bf16 v[88:91], v[164:167], v[212:215], v[88:91]
	v_mfma_f32_16x16x32_bf16 v[76:79], v[148:151], v[220:223], v[76:79]
	v_mfma_f32_16x16x32_bf16 v[72:75], v[164:167], v[220:223], v[72:75]
	s_setprio 0
	s_setprio 1
	v_mfma_f32_16x16x32_bf16 v[116:119], v[168:171], v[186:189], v[116:119]
	v_mfma_f32_16x16x32_bf16 v[112:115], v[176:179], v[186:189], v[112:115]
	v_mfma_f32_16x16x32_bf16 v[100:103], v[168:171], v[194:197], v[100:103]
	v_mfma_f32_16x16x32_bf16 v[96:99], v[176:179], v[194:197], v[96:99]
	v_mfma_f32_16x16x32_bf16 v[84:87], v[168:171], v[208:211], v[84:87]
	v_mfma_f32_16x16x32_bf16 v[80:83], v[176:179], v[208:211], v[80:83]
	v_mfma_f32_16x16x32_bf16 v[68:71], v[168:171], v[216:219], v[68:71]
	v_mfma_f32_16x16x32_bf16 v[64:67], v[176:179], v[216:219], v[64:67]
	v_mfma_f32_16x16x32_bf16 v[116:119], v[172:175], v[190:193], v[116:119]
	v_mfma_f32_16x16x32_bf16 v[112:115], v[182:185], v[190:193], v[112:115]
	v_mfma_f32_16x16x32_bf16 v[100:103], v[172:175], v[198:201], v[100:103]
	v_mfma_f32_16x16x32_bf16 v[96:99], v[182:185], v[198:201], v[96:99]
	v_mfma_f32_16x16x32_bf16 v[84:87], v[172:175], v[212:215], v[84:87]
	v_mfma_f32_16x16x32_bf16 v[80:83], v[182:185], v[212:215], v[80:83]
	v_mfma_f32_16x16x32_bf16 v[68:71], v[172:175], v[220:223], v[68:71]
	v_mfma_f32_16x16x32_bf16 v[64:67], v[182:185], v[220:223], v[64:67]
	s_setprio 0
	s_barrier
; #define PG8_STAGE(bufoff, gbase, voff) do { _Pragma("unroll") for (int _i = 0; _i < 2; ++_i) \
;         __builtin_amdgcn_global_load_lds((const unsigned*)((const char*)(gbase) + (voff)[_i]), (PG8_LAS unsigned*)(lds + (bufoff) + ldsw + _i * 8192), 16, 0, 0); } while (0)
; #define PG8_LDA(dst, b, h) do { _Pragma("unroll") for (int m = 0; m < 4; ++m) _Pragma("unroll") for (int k = 0; k < 2; ++k) dst[m][k] = *(const PG8_LAS bf16x8*)(lds + PG8_SA(b, h) + aoff + m * 2048 + k * 1024); } while (0)
; #define PG8_MMA(ai, bj, At, Bt) do { __builtin_amdgcn_s_setprio(1); _Pragma("unroll") for (int m = 0; m < 4; ++m) _Pragma("unroll") for (int n = 0; n < 2; ++n) _Pragma("unroll") for (int k = 0; k < 2; ++k) \
;         acc[ai][bj][m][n] = __builtin_amdgcn_mfma_f32_16x16x32_bf16(Bt[n][k], At[m][k], acc[ai][bj][m][n], 0, 0, 0); __builtin_amdgcn_s_setprio(0); } while (0)
; #define PG8_WAIT_V(n) asm volatile("s_waitcnt vmcnt(" #n ")" ::: "memory")
; #define PG8_WAIT_L(n) asm volatile("s_waitcnt lgkmcnt(" #n ")" ::: "memory")
; #define PG8_BAR __builtin_amdgcn_s_barrier()
; #define PG8_SCHED __builtin_amdgcn_sched_barrier(0)
; __device__ __forceinline__ float row_rs(const float* ssp, int row) { const unsigned long long v = ((const unsigned long long*)ssp)[row];
;     return __builtin_amdgcn_rsqf((float)v * (1.0f / 4294967296.0f) * (1.0f / 1024.0f) + RMS_EPS); }
; template <class Epi, class Sched, bool ALIGN_EPI = false, bool SP2 = false>
; __device__ __forceinline__ void gemm_phase(PG8_LAS unsigned char* lds, const Gemm g, const Sched& S, const Epi& E) {
;     ...
;             PG8_LDA(At, 1, 1); PG8_STAGE(PG8_SB(1, 0), b3, voffB); PG8_STAGE(PG8_SB(1, 1), b3 + hstep, voffB); PG8_STAGE(PG8_SA(1, 0), a3, voffA);
;             PG8_WAIT_V(8); PG8_WAIT_L(0); PG8_BAR; PG8_MMA(1, 0, At, B0); PG8_MMA(1, 1, At, B1); PG8_BAR; PG8_SCHED;
	s_add_i32 s3, s3, s14
	v_lshl_add_u64 v[202:203], v[202:203], 0, s[36:37]
	s_mov_b32 m0, s3
	ds_read_b128 v[186:189], v157 offset:49152
	ds_read_b128 v[190:193], v157 offset:50176
	ds_read_b128 v[194:197], v157 offset:51200
	ds_read_b128 v[198:201], v157 offset:52224
	ds_read_b128 v[208:211], v157 offset:53248
	ds_read_b128 v[212:215], v157 offset:54272
	ds_read_b128 v[216:219], v157 offset:55296
	ds_read_b128 v[220:223], v157 offset:56320
	global_load_lds_dwordx4 v[202:203], off
	s_add_i32 m0, s3, 0x2000
	s_add_u32 s56, s56, 0x40080
	v_lshl_add_u64 v[202:203], v[224:225], 0, s[36:37]
	s_addc_u32 s57, s57, 0
	s_add_i32 s3, s33, s14
	global_load_lds_dwordx4 v[202:203], off
	v_lshl_add_u64 v[202:203], s[56:57], 0, v[132:133]
	s_mov_b32 m0, s3
	s_nop 0
	global_load_lds_dwordx4 v[202:203], off
	v_lshl_add_u64 v[202:203], s[56:57], 0, v[128:129]
	s_add_i32 m0, s3, 0x2000
	s_nop 0
	global_load_lds_dwordx4 v[202:203], off
	s_waitcnt vmcnt(6)
	s_waitcnt lgkmcnt(0)
	s_barrier
	s_setprio 1
	s_waitcnt lgkmcnt(0)
	v_mfma_f32_16x16x32_bf16 v[60:63], v[144:147], v[186:189], v[60:63]
	v_mfma_f32_16x16x32_bf16 v[56:59], v[160:163], v[186:189], v[56:59]
	v_lshl_add_u64 v[202:203], v[226:227], 0, s[36:37]
	s_mov_b32 m0, s63
	s_nop 0
	global_load_lds_dwordx4 v[202:203], off
	v_mfma_f32_16x16x32_bf16 v[44:47], v[144:147], v[194:197], v[44:47]
	v_mfma_f32_16x16x32_bf16 v[40:43], v[160:163], v[194:197], v[40:43]
	v_mfma_f32_16x16x32_bf16 v[28:31], v[144:147], v[208:211], v[28:31]
	v_mfma_f32_16x16x32_bf16 v[24:27], v[160:163], v[208:211], v[24:27]
	v_lshl_add_u64 v[202:203], v[228:229], 0, s[36:37]
	s_mov_b32 m0, s64
	s_nop 0
	global_load_lds_dwordx4 v[202:203], off
	v_mfma_f32_16x16x32_bf16 v[12:15], v[144:147], v[216:219], v[12:15]
	v_mfma_f32_16x16x32_bf16 v[8:11], v[160:163], v[216:219], v[8:11]
	v_mfma_f32_16x16x32_bf16 v[60:63], v[148:151], v[190:193], v[60:63]
	v_mfma_f32_16x16x32_bf16 v[56:59], v[164:167], v[190:193], v[56:59]
	v_mfma_f32_16x16x32_bf16 v[44:47], v[148:151], v[198:201], v[44:47]
	v_mfma_f32_16x16x32_bf16 v[40:43], v[164:167], v[198:201], v[40:43]
	v_mfma_f32_16x16x32_bf16 v[28:31], v[148:151], v[212:215], v[28:31]
	v_mfma_f32_16x16x32_bf16 v[24:27], v[164:167], v[212:215], v[24:27]
	v_mfma_f32_16x16x32_bf16 v[12:15], v[148:151], v[220:223], v[12:15]
	v_mfma_f32_16x16x32_bf16 v[8:11], v[164:167], v[220:223], v[8:11]
	s_setprio 0
	s_setprio 1
	v_mfma_f32_16x16x32_bf16 v[52:55], v[168:171], v[186:189], v[52:55]
	v_mfma_f32_16x16x32_bf16 v[48:51], v[176:179], v[186:189], v[48:51]
	v_mfma_f32_16x16x32_bf16 v[36:39], v[168:171], v[194:197], v[36:39]
	v_mfma_f32_16x16x32_bf16 v[32:35], v[176:179], v[194:197], v[32:35]
	v_mfma_f32_16x16x32_bf16 v[20:23], v[168:171], v[208:211], v[20:23]
	v_mfma_f32_16x16x32_bf16 v[16:19], v[176:179], v[208:211], v[16:19]
	v_mfma_f32_16x16x32_bf16 v[4:7], v[168:171], v[216:219], v[4:7]
	v_mfma_f32_16x16x32_bf16 v[0:3], v[176:179], v[216:219], v[0:3]
	v_mfma_f32_16x16x32_bf16 v[52:55], v[172:175], v[190:193], v[52:55]
	v_mfma_f32_16x16x32_bf16 v[48:51], v[182:185], v[190:193], v[48:51]
	v_mfma_f32_16x16x32_bf16 v[36:39], v[172:175], v[198:201], v[36:39]
	v_mfma_f32_16x16x32_bf16 v[32:35], v[182:185], v[198:201], v[32:35]
	v_mfma_f32_16x16x32_bf16 v[20:23], v[172:175], v[212:215], v[20:23]
	v_mfma_f32_16x16x32_bf16 v[16:19], v[182:185], v[212:215], v[16:19]
	v_mfma_f32_16x16x32_bf16 v[4:7], v[172:175], v[220:223], v[4:7]
	v_mfma_f32_16x16x32_bf16 v[0:3], v[182:185], v[220:223], v[0:3]
	s_setprio 0
	s_barrier
	s_add_i32 s83, s83, 2
	s_add_u32 s54, s54, 0x100
	s_addc_u32 s55, s55, 0
	s_add_u32 s77, s77, 0x100
	s_addc_u32 s82, s82, 0
	s_cmp_gt_u32 s83, 13
	s_cbranch_scc0 .LBB0_957
	v_lshl_add_u32 v144, s52, 8, v152
	v_ashrrev_i32_e32 v145, 31, v144
	v_lshl_add_u64 v[150:151], v[144:145], 3, s[0:1]
	global_load_dwordx2 v[182:183], v[150:151], off
	global_load_dwordx2 v[184:185], v[150:151], off offset:128
	global_load_dwordx2 v[186:187], v[150:151], off offset:256
	global_load_dwordx2 v[188:189], v[150:151], off offset:384
	global_load_dwordx2 v[190:191], v[150:151], off offset:1024
	global_load_dwordx2 v[192:193], v[150:151], off offset:1152
	global_load_dwordx2 v[194:195], v[150:151], off offset:1280
	global_load_dwordx2 v[196:197], v[150:151], off offset:1408
	s_and_b64 vcc, exec, s[38:39]
	s_cbranch_vccz .LBB0_960
	s_barrier

; #define PG8_STAGE(bufoff, gbase, voff) do { _Pragma("unroll") for (int _i = 0; _i < 2; ++_i) \
;         __builtin_amdgcn_global_load_lds((const unsigned*)((const char*)(gbase) + (voff)[_i]), (PG8_LAS unsigned*)(lds + (bufoff) + ldsw + _i * 8192), 16, 0, 0); } while (0)
; #define PG8_LDA(dst, b, h) do { _Pragma("unroll") for (int m = 0; m < 4; ++m) _Pragma("unroll") for (int k = 0; k < 2; ++k) dst[m][k] = *(const PG8_LAS bf16x8*)(lds + PG8_SA(b, h) + aoff + m * 2048 + k * 1024); } while (0)
; #define PG8_LDB(dst, b, h) do { _Pragma("unroll") for (int n = 0; n < 2; ++n) _Pragma("unroll") for (int k = 0; k < 2; ++k) dst[n][k] = *(const PG8_LAS bf16x8*)(lds + PG8_SB(b, h) + boff + n * 2048 + k * 1024); } while (0)
; #define PG8_MMA(ai, bj, At, Bt) do { __builtin_amdgcn_s_setprio(1); _Pragma("unroll") for (int m = 0; m < 4; ++m) _Pragma("unroll") for (int n = 0; n < 2; ++n) _Pragma("unroll") for (int k = 0; k < 2; ++k) \
;         acc[ai][bj][m][n] = __builtin_amdgcn_mfma_f32_16x16x32_bf16(Bt[n][k], At[m][k], acc[ai][bj][m][n], 0, 0, 0); __builtin_amdgcn_s_setprio(0); } while (0)
; #define PG8_WAIT_V(n) asm volatile("s_waitcnt vmcnt(" #n ")" ::: "memory")
; #define PG8_WAIT_L(n) asm volatile("s_waitcnt lgkmcnt(" #n ")" ::: "memory")
; #define PG8_BAR __builtin_amdgcn_s_barrier()
; #define PG8_SCHED __builtin_amdgcn_sched_barrier(0)
; template <class Epi, class Sched, bool ALIGN_EPI = false, bool SP2 = false>
; __device__ __forceinline__ void gemm_phase(PG8_LAS unsigned char* lds, const Gemm g, const Sched& S, const Epi& E) {
;     ...
;             const bool last = (t == nt - 2);
;             const char* a1 = cA + (size_t)(t + 1) * kstep;
;             const char* a2 = last ? nA : cA + (size_t)(t + 2) * kstep; const char* b2 = last ? nB : cB + (size_t)(t + 2) * kstep;
;             const char* a3 = a2 + kstep; const char* b3 = b2 + kstep;
;             if (last && has_next) S.a_ready(nxt);
;             if constexpr (SP2) {
;             PG8_LDB(B0, 0, 0); PG8_LDB(B1, 0, 1); PG8_SCHED; PG8_LDA(At, 0, 0); PG8_STAGE(PG8_SA(1, 1), a1 + hstep, voffA);
;             PG8_WAIT_V(8); PG8_WAIT_L(0); PG8_BAR; PG8_MMA(0, 0, At, B0); PG8_MMA(0, 1, At, B1); PG8_BAR; PG8_SCHED;
;             PG8_LDA(At, 0, 1); PG8_STAGE(PG8_SB(0, 0), b2, voffB); PG8_STAGE(PG8_SB(0, 1), b2 + hstep, voffB); PG8_STAGE(PG8_SA(0, 0), a2, voffA);
.LBB0_1035:
	ds_read_b128 v[144:147], v151
	ds_read_b128 v[156:159], v151 offset:1024
	ds_read_b128 v[160:163], v151 offset:2048
	ds_read_b128 v[164:167], v151 offset:3072
	ds_read_b128 v[168:171], v152
	ds_read_b128 v[172:175], v152 offset:1024
	ds_read_b128 v[176:179], v152 offset:2048
	ds_read_b128 v[182:185], v152 offset:3072
	s_add_u32 s52, s50, 0x100
	s_addc_u32 s53, s51, 0
	s_cmp_eq_u32 s77, 40
	s_cselect_b32 s57, s1, s53
	s_cselect_b32 s56, s0, s52
	s_cselect_b32 s55, s49, s76
	s_cselect_b32 s54, s48, s75
	v_lshl_add_u64 v[202:203], s[50:51], 0, v[136:137]
	s_add_i32 m0, s14, 0xc000
	ds_read_b128 v[186:189], v153
	ds_read_b128 v[190:193], v153 offset:1024
	ds_read_b128 v[194:197], v153 offset:2048
	ds_read_b128 v[198:201], v153 offset:3072
	ds_read_b128 v[208:211], v153 offset:4096
	ds_read_b128 v[212:215], v153 offset:5120
	ds_read_b128 v[216:219], v153 offset:6144
	ds_read_b128 v[220:223], v153 offset:7168
	global_load_lds_dwordx4 v[202:203], off
	v_lshl_add_u64 v[202:203], s[50:51], 0, v[138:139]
	s_add_i32 m0, s14, 0xe000
	s_nop 0
	global_load_lds_dwordx4 v[202:203], off
	s_waitcnt vmcnt(8)
	s_waitcnt lgkmcnt(0)
	s_barrier
	s_setprio 1
	s_waitcnt lgkmcnt(0)
	v_mfma_f32_16x16x32_bf16 v[124:127], v[144:147], v[186:189], v[124:127]
	v_mfma_f32_16x16x32_bf16 v[120:123], v[160:163], v[186:189], v[120:123]
	v_mfma_f32_16x16x32_bf16 v[108:111], v[144:147], v[194:197], v[108:111]
	v_mfma_f32_16x16x32_bf16 v[104:107], v[160:163], v[194:197], v[104:107]
	v_mfma_f32_16x16x32_bf16 v[92:95], v[144:147], v[208:211], v[92:95]
	v_mfma_f32_16x16x32_bf16 v[88:91], v[160:163], v[208:211], v[88:91]
	v_mfma_f32_16x16x32_bf16 v[76:79], v[144:147], v[216:219], v[76:79]
	v_mfma_f32_16x16x32_bf16 v[72:75], v[160:163], v[216:219], v[72:75]
	v_mfma_f32_16x16x32_bf16 v[124:127], v[156:159], v[190:193], v[124:127]
	v_mfma_f32_16x16x32_bf16 v[120:123], v[164:167], v[190:193], v[120:123]
	v_mfma_f32_16x16x32_bf16 v[108:111], v[156:159], v[198:201], v[108:111]
	v_mfma_f32_16x16x32_bf16 v[104:107], v[164:167], v[198:201], v[104:107]
	v_mfma_f32_16x16x32_bf16 v[92:95], v[156:159], v[212:215], v[92:95]
	v_mfma_f32_16x16x32_bf16 v[88:91], v[164:167], v[212:215], v[88:91]
	v_mfma_f32_16x16x32_bf16 v[76:79], v[156:159], v[220:223], v[76:79]
	v_mfma_f32_16x16x32_bf16 v[72:75], v[164:167], v[220:223], v[72:75]
	s_setprio 0
	s_setprio 1
	v_mfma_f32_16x16x32_bf16 v[116:119], v[168:171], v[186:189], v[116:119]
	v_mfma_f32_16x16x32_bf16 v[112:115], v[176:179], v[186:189], v[112:115]
	v_mfma_f32_16x16x32_bf16 v[100:103], v[168:171], v[194:197], v[100:103]
	v_mfma_f32_16x16x32_bf16 v[96:99], v[176:179], v[194:197], v[96:99]
	v_mfma_f32_16x16x32_bf16 v[84:87], v[168:171], v[208:211], v[84:87]
	v_mfma_f32_16x16x32_bf16 v[80:83], v[176:179], v[208:211], v[80:83]
	v_mfma_f32_16x16x32_bf16 v[68:71], v[168:171], v[216:219], v[68:71]
	v_mfma_f32_16x16x32_bf16 v[64:67], v[176:179], v[216:219], v[64:67]
	v_mfma_f32_16x16x32_bf16 v[116:119], v[172:175], v[190:193], v[116:119]
	v_mfma_f32_16x16x32_bf16 v[112:115], v[182:185], v[190:193], v[112:115]
	v_mfma_f32_16x16x32_bf16 v[100:103], v[172:175], v[198:201], v[100:103]
	v_mfma_f32_16x16x32_bf16 v[96:99], v[182:185], v[198:201], v[96:99]
	v_mfma_f32_16x16x32_bf16 v[84:87], v[172:175], v[212:215], v[84:87]
	v_mfma_f32_16x16x32_bf16 v[80:83], v[182:185], v[212:215], v[80:83]
	v_mfma_f32_16x16x32_bf16 v[68:71], v[172:175], v[220:223], v[68:71]
	v_mfma_f32_16x16x32_bf16 v[64:67], v[182:185], v[220:223], v[64:67]
	s_setprio 0
	s_barrier
	s_add_i32 s50, s61, s3
	v_lshl_add_u64 v[202:203], s[54:55], 0, v[130:131]
	s_mov_b32 m0, s50
	ds_read_b128 v[186:189], v153 offset:16384
	ds_read_b128 v[190:193], v153 offset:17408
	ds_read_b128 v[194:197], v153 offset:18432
	ds_read_b128 v[198:201], v153 offset:19456
	ds_read_b128 v[208:211], v153 offset:20480
	ds_read_b128 v[212:215], v153 offset:21504
	ds_read_b128 v[216:219], v153 offset:22528
	ds_read_b128 v[220:223], v153 offset:23552
	global_load_lds_dwordx4 v[202:203], off
	s_add_i32 m0, s50, 0x2000
	s_add_u32 s50, s54, 0xb0000
	v_lshl_add_u64 v[224:225], s[54:55], 0, v[134:135]
	s_addc_u32 s51, s55, 0
	s_add_i32 s78, s62, s3
	global_load_lds_dwordx4 v[224:225], off
	v_lshl_add_u64 v[226:227], s[50:51], 0, v[130:131]
	s_mov_b32 m0, s78
	global_load_lds_dwordx4 v[226:227], off
	v_lshl_add_u64 v[226:227], s[50:51], 0, v[134:135]
	s_add_i32 m0, s78, 0x2000
	s_nop 0
	global_load_lds_dwordx4 v[226:227], off
	s_waitcnt vmcnt(6)
	s_waitcnt lgkmcnt(0)
	s_barrier
; #define PG8_STAGE(bufoff, gbase, voff) do { _Pragma("unroll") for (int _i = 0; _i < 2; ++_i) \
;         __builtin_amdgcn_global_load_lds((const unsigned*)((const char*)(gbase) + (voff)[_i]), (PG8_LAS unsigned*)(lds + (bufoff) + ldsw + _i * 8192), 16, 0, 0); } while (0)
; #define PG8_LDA(dst, b, h) do { _Pragma("unroll") for (int m = 0; m < 4; ++m) _Pragma("unroll") for (int k = 0; k < 2; ++k) dst[m][k] = *(const PG8_LAS bf16x8*)(lds + PG8_SA(b, h) + aoff + m * 2048 + k * 1024); } while (0)
; #define PG8_LDB(dst, b, h) do { _Pragma("unroll") for (int n = 0; n < 2; ++n) _Pragma("unroll") for (int k = 0; k < 2; ++k) dst[n][k] = *(const PG8_LAS bf16x8*)(lds + PG8_SB(b, h) + boff + n * 2048 + k * 1024); } while (0)
; #define PG8_MMA(ai, bj, At, Bt) do { __builtin_amdgcn_s_setprio(1); _Pragma("unroll") for (int m = 0; m < 4; ++m) _Pragma("unroll") for (int n = 0; n < 2; ++n) _Pragma("unroll") for (int k = 0; k < 2; ++k) \
;         acc[ai][bj][m][n] = __builtin_amdgcn_mfma_f32_16x16x32_bf16(Bt[n][k], At[m][k], acc[ai][bj][m][n], 0, 0, 0); __builtin_amdgcn_s_setprio(0); } while (0)
; #define PG8_WAIT_V(n) asm volatile("s_waitcnt vmcnt(" #n ")" ::: "memory")
; #define PG8_WAIT_L(n) asm volatile("s_waitcnt lgkmcnt(" #n ")" ::: "memory")
; #define PG8_BAR __builtin_amdgcn_s_barrier()
; #define PG8_SCHED __builtin_amdgcn_sched_barrier(0)
; template <class Epi, class Sched, bool ALIGN_EPI = false, bool SP2 = false>
; __device__ __forceinline__ void gemm_phase(PG8_LAS unsigned char* lds, const Gemm g, const Sched& S, const Epi& E) {
;     ...
;             PG8_LDA(At, 0, 1); PG8_STAGE(PG8_SB(0, 0), b2, voffB); PG8_STAGE(PG8_SB(0, 1), b2 + hstep, voffB); PG8_STAGE(PG8_SA(0, 0), a2, voffA);
;             PG8_WAIT_V(8); PG8_WAIT_L(0); PG8_BAR; PG8_MMA(1, 0, At, B0); PG8_MMA(1, 1, At, B1); PG8_BAR; PG8_SCHED;
;             PG8_LDB(B0, 1, 0); PG8_LDB(B1, 1, 1); PG8_SCHED; PG8_LDA(At, 1, 0); PG8_STAGE(PG8_SA(0, 1), a2 + hstep, voffA);
;             PG8_WAIT_V(8); PG8_WAIT_L(0); PG8_BAR; PG8_MMA(0, 0, At, B0); PG8_MMA(0, 1, At, B1); PG8_BAR; PG8_SCHED;
	s_setprio 1
	s_waitcnt lgkmcnt(0)
	v_mfma_f32_16x16x32_bf16 v[60:63], v[144:147], v[186:189], v[60:63]
	v_mfma_f32_16x16x32_bf16 v[56:59], v[160:163], v[186:189], v[56:59]
	v_mfma_f32_16x16x32_bf16 v[44:47], v[144:147], v[194:197], v[44:47]
	v_mfma_f32_16x16x32_bf16 v[40:43], v[160:163], v[194:197], v[40:43]
	v_mfma_f32_16x16x32_bf16 v[28:31], v[144:147], v[208:211], v[28:31]
	v_mfma_f32_16x16x32_bf16 v[24:27], v[160:163], v[208:211], v[24:27]
	v_mfma_f32_16x16x32_bf16 v[12:15], v[144:147], v[216:219], v[12:15]
	v_mfma_f32_16x16x32_bf16 v[8:11], v[160:163], v[216:219], v[8:11]
	v_mfma_f32_16x16x32_bf16 v[60:63], v[156:159], v[190:193], v[60:63]
	v_mfma_f32_16x16x32_bf16 v[56:59], v[164:167], v[190:193], v[56:59]
	v_mfma_f32_16x16x32_bf16 v[44:47], v[156:159], v[198:201], v[44:47]
	v_mfma_f32_16x16x32_bf16 v[40:43], v[164:167], v[198:201], v[40:43]
	v_mfma_f32_16x16x32_bf16 v[28:31], v[156:159], v[212:215], v[28:31]
	v_mfma_f32_16x16x32_bf16 v[24:27], v[164:167], v[212:215], v[24:27]
	v_lshl_add_u64 v[226:227], s[56:57], 0, v[128:129]
	s_mov_b32 m0, s14
	s_nop 0
	global_load_lds_dwordx4 v[226:227], off
	v_mfma_f32_16x16x32_bf16 v[12:15], v[156:159], v[220:223], v[12:15]
	v_mfma_f32_16x16x32_bf16 v[8:11], v[164:167], v[220:223], v[8:11]
	s_setprio 0
	s_setprio 1
	v_mfma_f32_16x16x32_bf16 v[52:55], v[168:171], v[186:189], v[52:55]
	v_mfma_f32_16x16x32_bf16 v[48:51], v[176:179], v[186:189], v[48:51]
	v_mfma_f32_16x16x32_bf16 v[36:39], v[168:171], v[194:197], v[36:39]
	v_mfma_f32_16x16x32_bf16 v[32:35], v[176:179], v[194:197], v[32:35]
	v_mfma_f32_16x16x32_bf16 v[20:23], v[168:171], v[208:211], v[20:23]
	v_mfma_f32_16x16x32_bf16 v[16:19], v[176:179], v[208:211], v[16:19]
	v_mfma_f32_16x16x32_bf16 v[4:7], v[168:171], v[216:219], v[4:7]
	v_mfma_f32_16x16x32_bf16 v[0:3], v[176:179], v[216:219], v[0:3]
	v_mfma_f32_16x16x32_bf16 v[52:55], v[172:175], v[190:193], v[52:55]
	v_mfma_f32_16x16x32_bf16 v[48:51], v[182:185], v[190:193], v[48:51]
	v_mfma_f32_16x16x32_bf16 v[36:39], v[172:175], v[198:201], v[36:39]
	v_mfma_f32_16x16x32_bf16 v[32:35], v[182:185], v[198:201], v[32:35]
	v_mfma_f32_16x16x32_bf16 v[20:23], v[172:175], v[212:215], v[20:23]
	v_mfma_f32_16x16x32_bf16 v[16:19], v[182:185], v[212:215], v[16:19]
	v_lshl_add_u64 v[228:229], s[56:57], 0, v[132:133]
	s_mov_b32 m0, s15
	s_nop 0
	global_load_lds_dwordx4 v[228:229], off
	v_mfma_f32_16x16x32_bf16 v[4:7], v[172:175], v[220:223], v[4:7]
	v_mfma_f32_16x16x32_bf16 v[0:3], v[182:185], v[220:223], v[0:3]
	s_setprio 0
	s_barrier
	s_add_i32 s78, 0, 0x18000
	v_add_u32_e32 v155, s78, v149
	s_add_i32 s79, 0, 0x1c000
	ds_read_b128 v[144:147], v155
	ds_read_b128 v[156:159], v155 offset:1024
	ds_read_b128 v[160:163], v155 offset:2048
	ds_read_b128 v[164:167], v155 offset:3072
	v_add_u32_e32 v155, s79, v149
	ds_read_b128 v[168:171], v155
	ds_read_b128 v[172:175], v155 offset:1024
	ds_read_b128 v[176:179], v155 offset:2048
	ds_read_b128 v[182:185], v155 offset:3072
	s_add_u32 s50, s56, 0xb0000
	s_addc_u32 s51, s57, 0
	s_mov_b32 m0, s33
	v_lshl_add_u64 v[230:231], s[50:51], 0, v[128:129]
	ds_read_b128 v[186:189], v153 offset:32768
	ds_read_b128 v[190:193], v153 offset:33792
	ds_read_b128 v[194:197], v153 offset:34816
	ds_read_b128 v[198:201], v153 offset:35840
	ds_read_b128 v[208:211], v153 offset:36864
	ds_read_b128 v[212:215], v153 offset:37888
	ds_read_b128 v[216:219], v153 offset:38912
	ds_read_b128 v[220:223], v153 offset:39936
	global_load_lds_dwordx4 v[230:231], off
	v_lshl_add_u64 v[230:231], s[50:51], 0, v[132:133]
	s_mov_b32 m0, s34
	s_nop 0
	global_load_lds_dwordx4 v[230:231], off
	s_waitcnt vmcnt(8)
	s_waitcnt lgkmcnt(0)
	s_barrier
	s_setprio 1
	s_waitcnt lgkmcnt(0)
	v_mfma_f32_16x16x32_bf16 v[124:127], v[144:147], v[186:189], v[124:127]
	v_mfma_f32_16x16x32_bf16 v[120:123], v[160:163], v[186:189], v[120:123]
	v_mfma_f32_16x16x32_bf16 v[108:111], v[144:147], v[194:197], v[108:111]
	v_mfma_f32_16x16x32_bf16 v[104:107], v[160:163], v[194:197], v[104:107]
	v_mfma_f32_16x16x32_bf16 v[92:95], v[144:147], v[208:211], v[92:95]
	v_mfma_f32_16x16x32_bf16 v[88:91], v[160:163], v[208:211], v[88:91]
	v_mfma_f32_16x16x32_bf16 v[76:79], v[144:147], v[216:219], v[76:79]
	v_mfma_f32_16x16x32_bf16 v[72:75], v[160:163], v[216:219], v[72:75]
	v_mfma_f32_16x16x32_bf16 v[124:127], v[156:159], v[190:193], v[124:127]
	v_mfma_f32_16x16x32_bf16 v[120:123], v[164:167], v[190:193], v[120:123]
	v_mfma_f32_16x16x32_bf16 v[108:111], v[156:159], v[198:201], v[108:111]
	v_mfma_f32_16x16x32_bf16 v[104:107], v[164:167], v[198:201], v[104:107]
	v_mfma_f32_16x16x32_bf16 v[92:95], v[156:159], v[212:215], v[92:95]
	v_mfma_f32_16x16x32_bf16 v[88:91], v[164:167], v[212:215], v[88:91]
	v_mfma_f32_16x16x32_bf16 v[76:79], v[156:159], v[220:223], v[76:79]
	v_mfma_f32_16x16x32_bf16 v[72:75], v[164:167], v[220:223], v[72:75]
	s_setprio 0
	s_setprio 1
	v_mfma_f32_16x16x32_bf16 v[116:119], v[168:171], v[186:189], v[116:119]
	v_mfma_f32_16x16x32_bf16 v[112:115], v[176:179], v[186:189], v[112:115]
	v_mfma_f32_16x16x32_bf16 v[100:103], v[168:171], v[194:197], v[100:103]
	v_mfma_f32_16x16x32_bf16 v[96:99], v[176:179], v[194:197], v[96:99]
	v_mfma_f32_16x16x32_bf16 v[84:87], v[168:171], v[208:211], v[84:87]
	v_mfma_f32_16x16x32_bf16 v[80:83], v[176:179], v[208:211], v[80:83]
	v_mfma_f32_16x16x32_bf16 v[68:71], v[168:171], v[216:219], v[68:71]
	v_mfma_f32_16x16x32_bf16 v[64:67], v[176:179], v[216:219], v[64:67]
	v_mfma_f32_16x16x32_bf16 v[116:119], v[172:175], v[190:193], v[116:119]
	v_mfma_f32_16x16x32_bf16 v[112:115], v[182:185], v[190:193], v[112:115]
	v_mfma_f32_16x16x32_bf16 v[100:103], v[172:175], v[198:201], v[100:103]
	v_mfma_f32_16x16x32_bf16 v[96:99], v[182:185], v[198:201], v[96:99]
	v_mfma_f32_16x16x32_bf16 v[84:87], v[172:175], v[212:215], v[84:87]
	v_mfma_f32_16x16x32_bf16 v[80:83], v[182:185], v[212:215], v[80:83]
	v_mfma_f32_16x16x32_bf16 v[68:71], v[172:175], v[220:223], v[68:71]
	v_mfma_f32_16x16x32_bf16 v[64:67], v[182:185], v[220:223], v[64:67]
	s_setprio 0
	s_barrier
; #define PG8_STAGE(bufoff, gbase, voff) do { _Pragma("unroll") for (int _i = 0; _i < 2; ++_i) \
;         __builtin_amdgcn_global_load_lds((const unsigned*)((const char*)(gbase) + (voff)[_i]), (PG8_LAS unsigned*)(lds + (bufoff) + ldsw + _i * 8192), 16, 0, 0); } while (0)
; #define PG8_LDA(dst, b, h) do { _Pragma("unroll") for (int m = 0; m < 4; ++m) _Pragma("unroll") for (int k = 0; k < 2; ++k) dst[m][k] = *(const PG8_LAS bf16x8*)(lds + PG8_SA(b, h) + aoff + m * 2048 + k * 1024); } while (0)
; #define PG8_MMA(ai, bj, At, Bt) do { __builtin_amdgcn_s_setprio(1); _Pragma("unroll") for (int m = 0; m < 4; ++m) _Pragma("unroll") for (int n = 0; n < 2; ++n) _Pragma("unroll") for (int k = 0; k < 2; ++k) \
;         acc[ai][bj][m][n] = __builtin_amdgcn_mfma_f32_16x16x32_bf16(Bt[n][k], At[m][k], acc[ai][bj][m][n], 0, 0, 0); __builtin_amdgcn_s_setprio(0); } while (0)
; #define PG8_WAIT_V(n) asm volatile("s_waitcnt vmcnt(" #n ")" ::: "memory")
; #define PG8_WAIT_L(n) asm volatile("s_waitcnt lgkmcnt(" #n ")" ::: "memory")
; #define PG8_BAR __builtin_amdgcn_s_barrier()
; #define PG8_SCHED __builtin_amdgcn_sched_barrier(0)
; template <class Epi, class Sched, bool ALIGN_EPI = false, bool SP2 = false>
; __device__ __forceinline__ void gemm_phase(PG8_LAS unsigned char* lds, const Gemm g, const Sched& S, const Epi& E) {
;     ...
;             PG8_LDA(At, 1, 1); PG8_STAGE(PG8_SB(1, 0), b3, voffB); PG8_STAGE(PG8_SB(1, 1), b3 + hstep, voffB); PG8_STAGE(PG8_SA(1, 0), a3, voffA);
;             PG8_WAIT_V(8); PG8_WAIT_L(0); PG8_BAR; PG8_MMA(1, 0, At, B0); PG8_MMA(1, 1, At, B1); PG8_BAR; PG8_SCHED;
;     ...
;         if constexpr (ALIGN_EPI) { if (wr == 0) PG8_BAR; }
	s_add_i32 s50, s78, s3
	v_lshl_add_u64 v[202:203], v[202:203], 0, s[42:43]
	s_mov_b32 m0, s50
	ds_read_b128 v[186:189], v153 offset:49152
	ds_read_b128 v[190:193], v153 offset:50176
	ds_read_b128 v[194:197], v153 offset:51200
	ds_read_b128 v[198:201], v153 offset:52224
	ds_read_b128 v[208:211], v153 offset:53248
	ds_read_b128 v[212:215], v153 offset:54272
	ds_read_b128 v[216:219], v153 offset:55296
	ds_read_b128 v[220:223], v153 offset:56320
	global_load_lds_dwordx4 v[202:203], off
	s_add_i32 m0, s50, 0x2000
	s_add_u32 s50, s54, 0xb0080
	v_lshl_add_u64 v[202:203], v[224:225], 0, s[42:43]
	s_addc_u32 s51, s55, 0
	s_add_i32 s54, s79, s3
	global_load_lds_dwordx4 v[202:203], off
	v_lshl_add_u64 v[202:203], s[50:51], 0, v[130:131]
	s_mov_b32 m0, s54
	s_nop 0
	global_load_lds_dwordx4 v[202:203], off
	v_lshl_add_u64 v[202:203], s[50:51], 0, v[134:135]
	s_add_i32 m0, s54, 0x2000
	s_nop 0
	global_load_lds_dwordx4 v[202:203], off
	s_waitcnt vmcnt(6)
	s_waitcnt lgkmcnt(0)
	s_barrier
	s_setprio 1
	s_waitcnt lgkmcnt(0)
	v_mfma_f32_16x16x32_bf16 v[60:63], v[144:147], v[186:189], v[60:63]
	v_mfma_f32_16x16x32_bf16 v[56:59], v[160:163], v[186:189], v[56:59]
	v_lshl_add_u64 v[202:203], v[226:227], 0, s[42:43]
	s_mov_b32 m0, s59
	s_nop 0
	global_load_lds_dwordx4 v[202:203], off
	v_mfma_f32_16x16x32_bf16 v[44:47], v[144:147], v[194:197], v[44:47]
	v_mfma_f32_16x16x32_bf16 v[40:43], v[160:163], v[194:197], v[40:43]
	v_mfma_f32_16x16x32_bf16 v[28:31], v[144:147], v[208:211], v[28:31]
	v_mfma_f32_16x16x32_bf16 v[24:27], v[160:163], v[208:211], v[24:27]
	v_lshl_add_u64 v[202:203], v[228:229], 0, s[42:43]
	s_mov_b32 m0, s60
	s_nop 0
	global_load_lds_dwordx4 v[202:203], off
	v_mfma_f32_16x16x32_bf16 v[12:15], v[144:147], v[216:219], v[12:15]
	v_mfma_f32_16x16x32_bf16 v[8:11], v[160:163], v[216:219], v[8:11]
	v_mfma_f32_16x16x32_bf16 v[60:63], v[156:159], v[190:193], v[60:63]
	v_mfma_f32_16x16x32_bf16 v[56:59], v[164:167], v[190:193], v[56:59]
	v_mfma_f32_16x16x32_bf16 v[44:47], v[156:159], v[198:201], v[44:47]
	v_mfma_f32_16x16x32_bf16 v[40:43], v[164:167], v[198:201], v[40:43]
	v_mfma_f32_16x16x32_bf16 v[28:31], v[156:159], v[212:215], v[28:31]
	v_mfma_f32_16x16x32_bf16 v[24:27], v[164:167], v[212:215], v[24:27]
	v_mfma_f32_16x16x32_bf16 v[12:15], v[156:159], v[220:223], v[12:15]
	v_mfma_f32_16x16x32_bf16 v[8:11], v[164:167], v[220:223], v[8:11]
	s_setprio 0
	s_setprio 1
	v_mfma_f32_16x16x32_bf16 v[52:55], v[168:171], v[186:189], v[52:55]
	v_mfma_f32_16x16x32_bf16 v[48:51], v[176:179], v[186:189], v[48:51]
	v_mfma_f32_16x16x32_bf16 v[36:39], v[168:171], v[194:197], v[36:39]
	v_mfma_f32_16x16x32_bf16 v[32:35], v[176:179], v[194:197], v[32:35]
	v_mfma_f32_16x16x32_bf16 v[20:23], v[168:171], v[208:211], v[20:23]
	v_mfma_f32_16x16x32_bf16 v[16:19], v[176:179], v[208:211], v[16:19]
	v_mfma_f32_16x16x32_bf16 v[4:7], v[168:171], v[216:219], v[4:7]
	v_mfma_f32_16x16x32_bf16 v[0:3], v[176:179], v[216:219], v[0:3]
	v_mfma_f32_16x16x32_bf16 v[52:55], v[172:175], v[190:193], v[52:55]
	v_mfma_f32_16x16x32_bf16 v[48:51], v[182:185], v[190:193], v[48:51]
	v_mfma_f32_16x16x32_bf16 v[36:39], v[172:175], v[198:201], v[36:39]
	v_mfma_f32_16x16x32_bf16 v[32:35], v[182:185], v[198:201], v[32:35]
	v_mfma_f32_16x16x32_bf16 v[20:23], v[172:175], v[212:215], v[20:23]
	v_mfma_f32_16x16x32_bf16 v[16:19], v[182:185], v[212:215], v[16:19]
	v_mfma_f32_16x16x32_bf16 v[4:7], v[172:175], v[220:223], v[4:7]
	v_mfma_f32_16x16x32_bf16 v[0:3], v[182:185], v[220:223], v[0:3]
	s_setprio 0
	s_barrier
	s_add_i32 s77, s77, 2
	s_add_u32 s75, s75, 0x100
	s_addc_u32 s76, s76, 0
	s_cmp_gt_u32 s77, 41
	s_mov_b64 s[50:51], s[52:53]
	s_cbranch_scc0 .LBB0_1035
	s_and_b64 vcc, exec, s[44:45]
	s_cbranch_vccz .LBB0_1038
	s_barrier

; #define PG8_STAGE(bufoff, gbase, voff) do { _Pragma("unroll") for (int _i = 0; _i < 2; ++_i) \
;         __builtin_amdgcn_global_load_lds((const unsigned*)((const char*)(gbase) + (voff)[_i]), (PG8_LAS unsigned*)(lds + (bufoff) + ldsw + _i * 8192), 16, 0, 0); } while (0)
; #define PG8_LDA(dst, b, h) do { _Pragma("unroll") for (int m = 0; m < 4; ++m) _Pragma("unroll") for (int k = 0; k < 2; ++k) dst[m][k] = *(const PG8_LAS bf16x8*)(lds + PG8_SA(b, h) + aoff + m * 2048 + k * 1024); } while (0)
; #define PG8_LDB(dst, b, h) do { _Pragma("unroll") for (int n = 0; n < 2; ++n) _Pragma("unroll") for (int k = 0; k < 2; ++k) dst[n][k] = *(const PG8_LAS bf16x8*)(lds + PG8_SB(b, h) + boff + n * 2048 + k * 1024); } while (0)
; #define PG8_MMA(ai, bj, At, Bt) do { __builtin_amdgcn_s_setprio(1); _Pragma("unroll") for (int m = 0; m < 4; ++m) _Pragma("unroll") for (int n = 0; n < 2; ++n) _Pragma("unroll") for (int k = 0; k < 2; ++k) \
;         acc[ai][bj][m][n] = __builtin_amdgcn_mfma_f32_16x16x32_bf16(Bt[n][k], At[m][k], acc[ai][bj][m][n], 0, 0, 0); __builtin_amdgcn_s_setprio(0); } while (0)
; #define PG8_WAIT_V(n) asm volatile("s_waitcnt vmcnt(" #n ")" ::: "memory")
; #define PG8_WAIT_L(n) asm volatile("s_waitcnt lgkmcnt(" #n ")" ::: "memory")
; #define PG8_BAR __builtin_amdgcn_s_barrier()
; #define PG8_SCHED __builtin_amdgcn_sched_barrier(0)
; template <class Epi, class Sched, bool ALIGN_EPI = false, bool SP2 = false>
; __device__ __forceinline__ void gemm_phase(PG8_LAS unsigned char* lds, const Gemm g, const Sched& S, const Epi& E) {
;     ...
;             const bool last = (t == nt - 2);
;             const char* a1 = cA + (size_t)(t + 1) * kstep;
;             const char* a2 = last ? nA : cA + (size_t)(t + 2) * kstep; const char* b2 = last ? nB : cB + (size_t)(t + 2) * kstep;
;             const char* a3 = a2 + kstep; const char* b3 = b2 + kstep;
;             if (last && has_next) S.a_ready(nxt);
;             if constexpr (SP2) {
;             PG8_LDB(B0, 0, 0); PG8_LDB(B1, 0, 1); PG8_SCHED; PG8_LDA(At, 0, 0); PG8_STAGE(PG8_SA(1, 1), a1 + hstep, voffA);
;             PG8_WAIT_V(8); PG8_WAIT_L(0); PG8_BAR; PG8_MMA(0, 0, At, B0); PG8_MMA(0, 1, At, B1); PG8_BAR; PG8_SCHED;
;             PG8_LDA(At, 0, 1); PG8_STAGE(PG8_SB(0, 0), b2, voffB); PG8_STAGE(PG8_SB(0, 1), b2 + hstep, voffB); PG8_STAGE(PG8_SA(0, 0), a2, voffA);
.LBB0_1119:
	ds_read_b128 v[144:147], v155
	ds_read_b128 v[148:151], v155 offset:1024
	ds_read_b128 v[160:163], v155 offset:2048
	ds_read_b128 v[164:167], v155 offset:3072
	ds_read_b128 v[168:171], v156
	ds_read_b128 v[172:175], v156 offset:1024
	ds_read_b128 v[176:179], v156 offset:2048
	ds_read_b128 v[182:185], v156 offset:3072
	s_add_u32 s56, s54, 0xfffc0080
	s_addc_u32 s57, s55, -1
	s_cmp_eq_u32 s84, 12
	s_cselect_b32 s59, s45, s57
	s_cselect_b32 s58, s76, s56
	s_cselect_b32 s57, s43, s83
	s_cselect_b32 s56, s77, s82
	v_lshl_add_u64 v[224:225], s[54:55], 0, v[136:137]
	s_add_i32 m0, s53, 0xc000
	ds_read_b128 v[186:189], v157
	ds_read_b128 v[190:193], v157 offset:1024
	ds_read_b128 v[194:197], v157 offset:2048
	ds_read_b128 v[198:201], v157 offset:3072
	ds_read_b128 v[208:211], v157 offset:4096
	ds_read_b128 v[212:215], v157 offset:5120
	ds_read_b128 v[216:219], v157 offset:6144
	ds_read_b128 v[220:223], v157 offset:7168
	global_load_lds_dwordx4 v[224:225], off
	v_lshl_add_u64 v[224:225], s[54:55], 0, v[138:139]
	s_add_i32 m0, s53, 0xe000
	s_nop 0
	global_load_lds_dwordx4 v[224:225], off
	s_waitcnt vmcnt(8)
	s_waitcnt lgkmcnt(0)
	s_barrier
	s_setprio 1
	s_waitcnt lgkmcnt(0)
	v_mfma_f32_16x16x32_bf16 v[124:127], v[144:147], v[186:189], v[124:127]
	v_mfma_f32_16x16x32_bf16 v[120:123], v[160:163], v[186:189], v[120:123]
	v_mfma_f32_16x16x32_bf16 v[108:111], v[144:147], v[194:197], v[108:111]
	v_mfma_f32_16x16x32_bf16 v[104:107], v[160:163], v[194:197], v[104:107]
	v_mfma_f32_16x16x32_bf16 v[92:95], v[144:147], v[208:211], v[92:95]
	v_mfma_f32_16x16x32_bf16 v[88:91], v[160:163], v[208:211], v[88:91]
	v_mfma_f32_16x16x32_bf16 v[76:79], v[144:147], v[216:219], v[76:79]
	v_mfma_f32_16x16x32_bf16 v[72:75], v[160:163], v[216:219], v[72:75]
	v_mfma_f32_16x16x32_bf16 v[124:127], v[148:151], v[190:193], v[124:127]
	v_mfma_f32_16x16x32_bf16 v[120:123], v[164:167], v[190:193], v[120:123]
	v_mfma_f32_16x16x32_bf16 v[108:111], v[148:151], v[198:201], v[108:111]
	v_mfma_f32_16x16x32_bf16 v[104:107], v[164:167], v[198:201], v[104:107]
	v_mfma_f32_16x16x32_bf16 v[92:95], v[148:151], v[212:215], v[92:95]
	v_mfma_f32_16x16x32_bf16 v[88:91], v[164:167], v[212:215], v[88:91]
	v_mfma_f32_16x16x32_bf16 v[76:79], v[148:151], v[220:223], v[76:79]
	v_mfma_f32_16x16x32_bf16 v[72:75], v[164:167], v[220:223], v[72:75]
	s_setprio 0
	s_setprio 1
	v_mfma_f32_16x16x32_bf16 v[116:119], v[168:171], v[186:189], v[116:119]
	v_mfma_f32_16x16x32_bf16 v[112:115], v[176:179], v[186:189], v[112:115]
	v_mfma_f32_16x16x32_bf16 v[100:103], v[168:171], v[194:197], v[100:103]
	v_mfma_f32_16x16x32_bf16 v[96:99], v[176:179], v[194:197], v[96:99]
	v_mfma_f32_16x16x32_bf16 v[84:87], v[168:171], v[208:211], v[84:87]
	v_mfma_f32_16x16x32_bf16 v[80:83], v[176:179], v[208:211], v[80:83]
	v_mfma_f32_16x16x32_bf16 v[68:71], v[168:171], v[216:219], v[68:71]
	v_mfma_f32_16x16x32_bf16 v[64:67], v[176:179], v[216:219], v[64:67]
	v_mfma_f32_16x16x32_bf16 v[116:119], v[172:175], v[190:193], v[116:119]
	v_mfma_f32_16x16x32_bf16 v[112:115], v[182:185], v[190:193], v[112:115]
	v_mfma_f32_16x16x32_bf16 v[100:103], v[172:175], v[198:201], v[100:103]
	v_mfma_f32_16x16x32_bf16 v[96:99], v[182:185], v[198:201], v[96:99]
	v_mfma_f32_16x16x32_bf16 v[84:87], v[172:175], v[212:215], v[84:87]
	v_mfma_f32_16x16x32_bf16 v[80:83], v[182:185], v[212:215], v[80:83]
	v_mfma_f32_16x16x32_bf16 v[68:71], v[172:175], v[220:223], v[68:71]
	v_mfma_f32_16x16x32_bf16 v[64:67], v[182:185], v[220:223], v[64:67]
	s_setprio 0
	s_barrier
	s_add_i32 s78, s66, s33
	v_lshl_add_u64 v[224:225], s[56:57], 0, v[132:133]
	s_mov_b32 m0, s78
	ds_read_b128 v[186:189], v157 offset:16384
	ds_read_b128 v[190:193], v157 offset:17408
	ds_read_b128 v[194:197], v157 offset:18432
	ds_read_b128 v[198:201], v157 offset:19456
	ds_read_b128 v[208:211], v157 offset:20480
	ds_read_b128 v[212:215], v157 offset:21504
	ds_read_b128 v[216:219], v157 offset:22528
	ds_read_b128 v[220:223], v157 offset:23552
	global_load_lds_dwordx4 v[224:225], off
	s_add_i32 m0, s78, 0x2000
	s_add_u32 s78, s56, 0x40000
	v_lshl_add_u64 v[226:227], s[56:57], 0, v[128:129]
	s_addc_u32 s79, s57, 0
	s_add_i32 s85, s67, s33
	global_load_lds_dwordx4 v[226:227], off
	v_lshl_add_u64 v[228:229], s[78:79], 0, v[132:133]
	s_mov_b32 m0, s85
	global_load_lds_dwordx4 v[228:229], off
	v_lshl_add_u64 v[228:229], s[78:79], 0, v[128:129]
	s_add_i32 m0, s85, 0x2000
	s_nop 0
	global_load_lds_dwordx4 v[228:229], off
	s_waitcnt vmcnt(6)
	s_waitcnt lgkmcnt(0)
	s_barrier
; #define PG8_STAGE(bufoff, gbase, voff) do { _Pragma("unroll") for (int _i = 0; _i < 2; ++_i) \
;         __builtin_amdgcn_global_load_lds((const unsigned*)((const char*)(gbase) + (voff)[_i]), (PG8_LAS unsigned*)(lds + (bufoff) + ldsw + _i * 8192), 16, 0, 0); } while (0)
; #define PG8_LDA(dst, b, h) do { _Pragma("unroll") for (int m = 0; m < 4; ++m) _Pragma("unroll") for (int k = 0; k < 2; ++k) dst[m][k] = *(const PG8_LAS bf16x8*)(lds + PG8_SA(b, h) + aoff + m * 2048 + k * 1024); } while (0)
; #define PG8_LDB(dst, b, h) do { _Pragma("unroll") for (int n = 0; n < 2; ++n) _Pragma("unroll") for (int k = 0; k < 2; ++k) dst[n][k] = *(const PG8_LAS bf16x8*)(lds + PG8_SB(b, h) + boff + n * 2048 + k * 1024); } while (0)
; #define PG8_MMA(ai, bj, At, Bt) do { __builtin_amdgcn_s_setprio(1); _Pragma("unroll") for (int m = 0; m < 4; ++m) _Pragma("unroll") for (int n = 0; n < 2; ++n) _Pragma("unroll") for (int k = 0; k < 2; ++k) \
;         acc[ai][bj][m][n] = __builtin_amdgcn_mfma_f32_16x16x32_bf16(Bt[n][k], At[m][k], acc[ai][bj][m][n], 0, 0, 0); __builtin_amdgcn_s_setprio(0); } while (0)
; #define PG8_WAIT_V(n) asm volatile("s_waitcnt vmcnt(" #n ")" ::: "memory")
; #define PG8_WAIT_L(n) asm volatile("s_waitcnt lgkmcnt(" #n ")" ::: "memory")
; #define PG8_BAR __builtin_amdgcn_s_barrier()
; #define PG8_SCHED __builtin_amdgcn_sched_barrier(0)
; template <class Epi, class Sched, bool ALIGN_EPI = false, bool SP2 = false>
; __device__ __forceinline__ void gemm_phase(PG8_LAS unsigned char* lds, const Gemm g, const Sched& S, const Epi& E) {
;     ...
;             PG8_LDA(At, 0, 1); PG8_STAGE(PG8_SB(0, 0), b2, voffB); PG8_STAGE(PG8_SB(0, 1), b2 + hstep, voffB); PG8_STAGE(PG8_SA(0, 0), a2, voffA);
;             PG8_WAIT_V(8); PG8_WAIT_L(0); PG8_BAR; PG8_MMA(1, 0, At, B0); PG8_MMA(1, 1, At, B1); PG8_BAR; PG8_SCHED;
;             PG8_LDB(B0, 1, 0); PG8_LDB(B1, 1, 1); PG8_SCHED; PG8_LDA(At, 1, 0); PG8_STAGE(PG8_SA(0, 1), a2 + hstep, voffA);
;             PG8_WAIT_V(8); PG8_WAIT_L(0); PG8_BAR; PG8_MMA(0, 0, At, B0); PG8_MMA(0, 1, At, B1); PG8_BAR; PG8_SCHED;
	s_setprio 1
	s_waitcnt lgkmcnt(0)
	v_mfma_f32_16x16x32_bf16 v[60:63], v[144:147], v[186:189], v[60:63]
	v_mfma_f32_16x16x32_bf16 v[56:59], v[160:163], v[186:189], v[56:59]
	v_mfma_f32_16x16x32_bf16 v[44:47], v[144:147], v[194:197], v[44:47]
	v_mfma_f32_16x16x32_bf16 v[40:43], v[160:163], v[194:197], v[40:43]
	v_mfma_f32_16x16x32_bf16 v[28:31], v[144:147], v[208:211], v[28:31]
	v_mfma_f32_16x16x32_bf16 v[24:27], v[160:163], v[208:211], v[24:27]
	v_mfma_f32_16x16x32_bf16 v[12:15], v[144:147], v[216:219], v[12:15]
	v_mfma_f32_16x16x32_bf16 v[8:11], v[160:163], v[216:219], v[8:11]
	v_mfma_f32_16x16x32_bf16 v[60:63], v[148:151], v[190:193], v[60:63]
	v_mfma_f32_16x16x32_bf16 v[56:59], v[164:167], v[190:193], v[56:59]
	v_mfma_f32_16x16x32_bf16 v[44:47], v[148:151], v[198:201], v[44:47]
	v_mfma_f32_16x16x32_bf16 v[40:43], v[164:167], v[198:201], v[40:43]
	v_mfma_f32_16x16x32_bf16 v[28:31], v[148:151], v[212:215], v[28:31]
	v_mfma_f32_16x16x32_bf16 v[24:27], v[164:167], v[212:215], v[24:27]
	v_lshl_add_u64 v[228:229], s[58:59], 0, v[134:135]
	s_mov_b32 m0, s53
	s_nop 0
	global_load_lds_dwordx4 v[228:229], off
	v_mfma_f32_16x16x32_bf16 v[12:15], v[148:151], v[220:223], v[12:15]
	v_mfma_f32_16x16x32_bf16 v[8:11], v[164:167], v[220:223], v[8:11]
	s_setprio 0
	s_setprio 1
	v_mfma_f32_16x16x32_bf16 v[52:55], v[168:171], v[186:189], v[52:55]
	v_mfma_f32_16x16x32_bf16 v[48:51], v[176:179], v[186:189], v[48:51]
	v_mfma_f32_16x16x32_bf16 v[36:39], v[168:171], v[194:197], v[36:39]
	v_mfma_f32_16x16x32_bf16 v[32:35], v[176:179], v[194:197], v[32:35]
	v_mfma_f32_16x16x32_bf16 v[20:23], v[168:171], v[208:211], v[20:23]
	v_mfma_f32_16x16x32_bf16 v[16:19], v[176:179], v[208:211], v[16:19]
	v_mfma_f32_16x16x32_bf16 v[4:7], v[168:171], v[216:219], v[4:7]
	v_mfma_f32_16x16x32_bf16 v[0:3], v[176:179], v[216:219], v[0:3]
	v_mfma_f32_16x16x32_bf16 v[52:55], v[172:175], v[190:193], v[52:55]
	v_mfma_f32_16x16x32_bf16 v[48:51], v[182:185], v[190:193], v[48:51]
	v_mfma_f32_16x16x32_bf16 v[36:39], v[172:175], v[198:201], v[36:39]
	v_mfma_f32_16x16x32_bf16 v[32:35], v[182:185], v[198:201], v[32:35]
	v_mfma_f32_16x16x32_bf16 v[20:23], v[172:175], v[212:215], v[20:23]
	v_mfma_f32_16x16x32_bf16 v[16:19], v[182:185], v[212:215], v[16:19]
	v_lshl_add_u64 v[230:231], s[58:59], 0, v[130:131]
	s_mov_b32 m0, s60
	s_nop 0
	global_load_lds_dwordx4 v[230:231], off
	v_mfma_f32_16x16x32_bf16 v[4:7], v[172:175], v[220:223], v[4:7]
	v_mfma_f32_16x16x32_bf16 v[0:3], v[182:185], v[220:223], v[0:3]
	s_setprio 0
	s_barrier
	s_add_i32 s78, 0, 0x18000
	v_add_u32_e32 v159, s78, v153
	s_add_i32 s79, 0, 0x1c000
	ds_read_b128 v[144:147], v159
	ds_read_b128 v[148:151], v159 offset:1024
	ds_read_b128 v[160:163], v159 offset:2048
	ds_read_b128 v[164:167], v159 offset:3072
	v_add_u32_e32 v159, s79, v153
	ds_read_b128 v[168:171], v159
	ds_read_b128 v[172:175], v159 offset:1024
	ds_read_b128 v[176:179], v159 offset:2048
	ds_read_b128 v[182:185], v159 offset:3072
	s_add_u32 s58, s58, 0x40000
	s_addc_u32 s59, s59, 0
	s_mov_b32 m0, s61
	v_lshl_add_u64 v[232:233], s[58:59], 0, v[134:135]
	ds_read_b128 v[186:189], v157 offset:32768
	ds_read_b128 v[190:193], v157 offset:33792
	ds_read_b128 v[194:197], v157 offset:34816
	ds_read_b128 v[198:201], v157 offset:35840
	ds_read_b128 v[208:211], v157 offset:36864
	ds_read_b128 v[212:215], v157 offset:37888
	ds_read_b128 v[216:219], v157 offset:38912
	ds_read_b128 v[220:223], v157 offset:39936
	global_load_lds_dwordx4 v[232:233], off
	v_lshl_add_u64 v[232:233], s[58:59], 0, v[130:131]
	s_mov_b32 m0, s62
	s_nop 0
	global_load_lds_dwordx4 v[232:233], off
	s_waitcnt vmcnt(8)
	s_waitcnt lgkmcnt(0)
	s_barrier
	s_setprio 1
	s_waitcnt lgkmcnt(0)
	v_mfma_f32_16x16x32_bf16 v[124:127], v[144:147], v[186:189], v[124:127]
	v_mfma_f32_16x16x32_bf16 v[120:123], v[160:163], v[186:189], v[120:123]
	v_mfma_f32_16x16x32_bf16 v[108:111], v[144:147], v[194:197], v[108:111]
	v_mfma_f32_16x16x32_bf16 v[104:107], v[160:163], v[194:197], v[104:107]
	v_mfma_f32_16x16x32_bf16 v[92:95], v[144:147], v[208:211], v[92:95]
	v_mfma_f32_16x16x32_bf16 v[88:91], v[160:163], v[208:211], v[88:91]
	v_mfma_f32_16x16x32_bf16 v[76:79], v[144:147], v[216:219], v[76:79]
	v_mfma_f32_16x16x32_bf16 v[72:75], v[160:163], v[216:219], v[72:75]
	v_mfma_f32_16x16x32_bf16 v[124:127], v[148:151], v[190:193], v[124:127]
	v_mfma_f32_16x16x32_bf16 v[120:123], v[164:167], v[190:193], v[120:123]
	v_mfma_f32_16x16x32_bf16 v[108:111], v[148:151], v[198:201], v[108:111]
	v_mfma_f32_16x16x32_bf16 v[104:107], v[164:167], v[198:201], v[104:107]
	v_mfma_f32_16x16x32_bf16 v[92:95], v[148:151], v[212:215], v[92:95]
	v_mfma_f32_16x16x32_bf16 v[88:91], v[164:167], v[212:215], v[88:91]
	v_mfma_f32_16x16x32_bf16 v[76:79], v[148:151], v[220:223], v[76:79]
	v_mfma_f32_16x16x32_bf16 v[72:75], v[164:167], v[220:223], v[72:75]
	s_setprio 0
	s_setprio 1
	v_mfma_f32_16x16x32_bf16 v[116:119], v[168:171], v[186:189], v[116:119]
	v_mfma_f32_16x16x32_bf16 v[112:115], v[176:179], v[186:189], v[112:115]
	v_mfma_f32_16x16x32_bf16 v[100:103], v[168:171], v[194:197], v[100:103]
	v_mfma_f32_16x16x32_bf16 v[96:99], v[176:179], v[194:197], v[96:99]
	v_mfma_f32_16x16x32_bf16 v[84:87], v[168:171], v[208:211], v[84:87]
	v_mfma_f32_16x16x32_bf16 v[80:83], v[176:179], v[208:211], v[80:83]
	v_mfma_f32_16x16x32_bf16 v[68:71], v[168:171], v[216:219], v[68:71]
	v_mfma_f32_16x16x32_bf16 v[64:67], v[176:179], v[216:219], v[64:67]
	v_mfma_f32_16x16x32_bf16 v[116:119], v[172:175], v[190:193], v[116:119]
	v_mfma_f32_16x16x32_bf16 v[112:115], v[182:185], v[190:193], v[112:115]
	v_mfma_f32_16x16x32_bf16 v[100:103], v[172:175], v[198:201], v[100:103]
	v_mfma_f32_16x16x32_bf16 v[96:99], v[182:185], v[198:201], v[96:99]
	v_mfma_f32_16x16x32_bf16 v[84:87], v[172:175], v[212:215], v[84:87]
	v_mfma_f32_16x16x32_bf16 v[80:83], v[182:185], v[212:215], v[80:83]
	v_mfma_f32_16x16x32_bf16 v[68:71], v[172:175], v[220:223], v[68:71]
	v_mfma_f32_16x16x32_bf16 v[64:67], v[182:185], v[220:223], v[64:67]
	s_setprio 0
	s_barrier
; #define PG8_STAGE(bufoff, gbase, voff) do { _Pragma("unroll") for (int _i = 0; _i < 2; ++_i) \
;         __builtin_amdgcn_global_load_lds((const unsigned*)((const char*)(gbase) + (voff)[_i]), (PG8_LAS unsigned*)(lds + (bufoff) + ldsw + _i * 8192), 16, 0, 0); } while (0)
; #define PG8_LDA(dst, b, h) do { _Pragma("unroll") for (int m = 0; m < 4; ++m) _Pragma("unroll") for (int k = 0; k < 2; ++k) dst[m][k] = *(const PG8_LAS bf16x8*)(lds + PG8_SA(b, h) + aoff + m * 2048 + k * 1024); } while (0)
; #define PG8_MMA(ai, bj, At, Bt) do { __builtin_amdgcn_s_setprio(1); _Pragma("unroll") for (int m = 0; m < 4; ++m) _Pragma("unroll") for (int n = 0; n < 2; ++n) _Pragma("unroll") for (int k = 0; k < 2; ++k) \
;         acc[ai][bj][m][n] = __builtin_amdgcn_mfma_f32_16x16x32_bf16(Bt[n][k], At[m][k], acc[ai][bj][m][n], 0, 0, 0); __builtin_amdgcn_s_setprio(0); } while (0)
; #define PG8_WAIT_V(n) asm volatile("s_waitcnt vmcnt(" #n ")" ::: "memory")
; #define PG8_WAIT_L(n) asm volatile("s_waitcnt lgkmcnt(" #n ")" ::: "memory")
; #define PG8_BAR __builtin_amdgcn_s_barrier()
; #define PG8_SCHED __builtin_amdgcn_sched_barrier(0)
; __device__ __forceinline__ float row_rs(const float* ssp, int row) { const unsigned long long v = ((const unsigned long long*)ssp)[row];
;     return __builtin_amdgcn_rsqf((float)v * (1.0f / 4294967296.0f) * (1.0f / 1024.0f) + RMS_EPS); }
; template <class Epi, class Sched, bool ALIGN_EPI = false, bool SP2 = false>
; __device__ __forceinline__ void gemm_phase(PG8_LAS unsigned char* lds, const Gemm g, const Sched& S, const Epi& E) {
;     ...
;             PG8_LDA(At, 1, 1); PG8_STAGE(PG8_SB(1, 0), b3, voffB); PG8_STAGE(PG8_SB(1, 1), b3 + hstep, voffB); PG8_STAGE(PG8_SA(1, 0), a3, voffA);
;             PG8_WAIT_V(8); PG8_WAIT_L(0); PG8_BAR; PG8_MMA(1, 0, At, B0); PG8_MMA(1, 1, At, B1); PG8_BAR; PG8_SCHED;
	s_add_i32 s58, s78, s33
	v_lshl_add_u64 v[224:225], v[224:225], 0, s[12:13]
	s_mov_b32 m0, s58
	ds_read_b128 v[186:189], v157 offset:49152
	ds_read_b128 v[190:193], v157 offset:50176
	ds_read_b128 v[194:197], v157 offset:51200
	ds_read_b128 v[198:201], v157 offset:52224
	ds_read_b128 v[208:211], v157 offset:53248
	ds_read_b128 v[212:215], v157 offset:54272
	ds_read_b128 v[216:219], v157 offset:55296
	ds_read_b128 v[220:223], v157 offset:56320
	global_load_lds_dwordx4 v[224:225], off
	s_add_i32 m0, s58, 0x2000
	s_add_u32 s56, s56, 0x40080
	v_lshl_add_u64 v[224:225], v[226:227], 0, s[12:13]
	s_addc_u32 s57, s57, 0
	s_add_i32 s58, s79, s33
	global_load_lds_dwordx4 v[224:225], off
	v_lshl_add_u64 v[224:225], s[56:57], 0, v[132:133]
	s_mov_b32 m0, s58
	s_nop 0
	global_load_lds_dwordx4 v[224:225], off
	v_lshl_add_u64 v[224:225], s[56:57], 0, v[128:129]
	s_add_i32 m0, s58, 0x2000
	s_nop 0
	global_load_lds_dwordx4 v[224:225], off
	s_waitcnt vmcnt(6)
	s_waitcnt lgkmcnt(0)
	s_barrier
	s_setprio 1
	s_waitcnt lgkmcnt(0)
	v_mfma_f32_16x16x32_bf16 v[60:63], v[144:147], v[186:189], v[60:63]
	v_mfma_f32_16x16x32_bf16 v[56:59], v[160:163], v[186:189], v[56:59]
	v_lshl_add_u64 v[224:225], v[228:229], 0, s[12:13]
	s_mov_b32 m0, s64
	s_nop 0
	global_load_lds_dwordx4 v[224:225], off
	v_mfma_f32_16x16x32_bf16 v[44:47], v[144:147], v[194:197], v[44:47]
	v_mfma_f32_16x16x32_bf16 v[40:43], v[160:163], v[194:197], v[40:43]
	v_mfma_f32_16x16x32_bf16 v[28:31], v[144:147], v[208:211], v[28:31]
	v_mfma_f32_16x16x32_bf16 v[24:27], v[160:163], v[208:211], v[24:27]
	v_lshl_add_u64 v[224:225], v[230:231], 0, s[12:13]
	s_mov_b32 m0, s65
	s_nop 0
	global_load_lds_dwordx4 v[224:225], off
	v_mfma_f32_16x16x32_bf16 v[12:15], v[144:147], v[216:219], v[12:15]
	v_mfma_f32_16x16x32_bf16 v[8:11], v[160:163], v[216:219], v[8:11]
	v_mfma_f32_16x16x32_bf16 v[60:63], v[148:151], v[190:193], v[60:63]
	v_mfma_f32_16x16x32_bf16 v[56:59], v[164:167], v[190:193], v[56:59]
	v_mfma_f32_16x16x32_bf16 v[44:47], v[148:151], v[198:201], v[44:47]
	v_mfma_f32_16x16x32_bf16 v[40:43], v[164:167], v[198:201], v[40:43]
	v_mfma_f32_16x16x32_bf16 v[28:31], v[148:151], v[212:215], v[28:31]
	v_mfma_f32_16x16x32_bf16 v[24:27], v[164:167], v[212:215], v[24:27]
	v_mfma_f32_16x16x32_bf16 v[12:15], v[148:151], v[220:223], v[12:15]
	v_mfma_f32_16x16x32_bf16 v[8:11], v[164:167], v[220:223], v[8:11]
	s_setprio 0
	s_setprio 1
	v_mfma_f32_16x16x32_bf16 v[52:55], v[168:171], v[186:189], v[52:55]
	v_mfma_f32_16x16x32_bf16 v[48:51], v[176:179], v[186:189], v[48:51]
	v_mfma_f32_16x16x32_bf16 v[36:39], v[168:171], v[194:197], v[36:39]
	v_mfma_f32_16x16x32_bf16 v[32:35], v[176:179], v[194:197], v[32:35]
	v_mfma_f32_16x16x32_bf16 v[20:23], v[168:171], v[208:211], v[20:23]
	v_mfma_f32_16x16x32_bf16 v[16:19], v[176:179], v[208:211], v[16:19]
	v_mfma_f32_16x16x32_bf16 v[4:7], v[168:171], v[216:219], v[4:7]
	v_mfma_f32_16x16x32_bf16 v[0:3], v[176:179], v[216:219], v[0:3]
	v_mfma_f32_16x16x32_bf16 v[52:55], v[172:175], v[190:193], v[52:55]
	v_mfma_f32_16x16x32_bf16 v[48:51], v[182:185], v[190:193], v[48:51]
	v_mfma_f32_16x16x32_bf16 v[36:39], v[172:175], v[198:201], v[36:39]
	v_mfma_f32_16x16x32_bf16 v[32:35], v[182:185], v[198:201], v[32:35]
	v_mfma_f32_16x16x32_bf16 v[20:23], v[172:175], v[212:215], v[20:23]
	v_mfma_f32_16x16x32_bf16 v[16:19], v[182:185], v[212:215], v[16:19]
	v_mfma_f32_16x16x32_bf16 v[4:7], v[172:175], v[220:223], v[4:7]
	v_mfma_f32_16x16x32_bf16 v[0:3], v[182:185], v[220:223], v[0:3]
	s_setprio 0
	s_barrier
	s_add_i32 s84, s84, 2
	s_add_u32 s54, s54, 0x100
	s_addc_u32 s55, s55, 0
	s_add_u32 s82, s82, 0x100
	s_addc_u32 s83, s83, 0
	s_cmp_gt_u32 s84, 13
	s_cbranch_scc0 .LBB0_1119
	v_lshl_add_u32 v144, s52, 8, v152
	v_ashrrev_i32_e32 v145, 31, v144
	v_lshl_add_u64 v[150:151], v[144:145], 3, s[36:37]
	global_load_dwordx2 v[182:183], v[150:151], off
	global_load_dwordx2 v[184:185], v[150:151], off offset:128
	global_load_dwordx2 v[186:187], v[150:151], off offset:256
	global_load_dwordx2 v[188:189], v[150:151], off offset:384
	global_load_dwordx2 v[190:191], v[150:151], off offset:1024
	global_load_dwordx2 v[192:193], v[150:151], off offset:1152
	global_load_dwordx2 v[194:195], v[150:151], off offset:1280
	global_load_dwordx2 v[196:197], v[150:151], off offset:1408
	s_and_b64 vcc, exec, s[38:39]
	s_cbranch_vccz .LBB0_1122
	s_barrier

; #define PG8_STAGE(bufoff, gbase, voff) do { _Pragma("unroll") for (int _i = 0; _i < 2; ++_i) \
;         __builtin_amdgcn_global_load_lds((const unsigned*)((const char*)(gbase) + (voff)[_i]), (PG8_LAS unsigned*)(lds + (bufoff) + ldsw + _i * 8192), 16, 0, 0); } while (0)
; #define PG8_LDA(dst, b, h) do { _Pragma("unroll") for (int m = 0; m < 4; ++m) _Pragma("unroll") for (int k = 0; k < 2; ++k) dst[m][k] = *(const PG8_LAS bf16x8*)(lds + PG8_SA(b, h) + aoff + m * 2048 + k * 1024); } while (0)
; #define PG8_LDB(dst, b, h) do { _Pragma("unroll") for (int n = 0; n < 2; ++n) _Pragma("unroll") for (int k = 0; k < 2; ++k) dst[n][k] = *(const PG8_LAS bf16x8*)(lds + PG8_SB(b, h) + boff + n * 2048 + k * 1024); } while (0)
; #define PG8_MMA(ai, bj, At, Bt) do { __builtin_amdgcn_s_setprio(1); _Pragma("unroll") for (int m = 0; m < 4; ++m) _Pragma("unroll") for (int n = 0; n < 2; ++n) _Pragma("unroll") for (int k = 0; k < 2; ++k) \
;         acc[ai][bj][m][n] = __builtin_amdgcn_mfma_f32_16x16x32_bf16(Bt[n][k], At[m][k], acc[ai][bj][m][n], 0, 0, 0); __builtin_amdgcn_s_setprio(0); } while (0)
; #define PG8_WAIT_V(n) asm volatile("s_waitcnt vmcnt(" #n ")" ::: "memory")
; #define PG8_WAIT_L(n) asm volatile("s_waitcnt lgkmcnt(" #n ")" ::: "memory")
; #define PG8_BAR __builtin_amdgcn_s_barrier()
; #define PG8_SCHED __builtin_amdgcn_sched_barrier(0)
; template <class Epi, class Sched, bool ALIGN_EPI = false, bool SP2 = false>
; __device__ __forceinline__ void gemm_phase(PG8_LAS unsigned char* lds, const Gemm g, const Sched& S, const Epi& E) {
;     ...
;         for (int t = 0; t < nt; t += 2) {
;             const bool last = (t == nt - 2);
;             const char* a1 = cA + (size_t)(t + 1) * kstep;
;             const char* a2 = last ? nA : cA + (size_t)(t + 2) * kstep; const char* b2 = last ? nB : cB + (size_t)(t + 2) * kstep;
;             const char* a3 = a2 + kstep; const char* b3 = b2 + kstep;
;             if (last && has_next) S.a_ready(nxt);
;             if constexpr (SP2) {
;             PG8_LDB(B0, 0, 0); PG8_LDB(B1, 0, 1); PG8_SCHED; PG8_LDA(At, 0, 0); PG8_STAGE(PG8_SA(1, 1), a1 + hstep, voffA);
;             PG8_WAIT_V(8); PG8_WAIT_L(0); PG8_BAR; PG8_MMA(0, 0, At, B0); PG8_MMA(0, 1, At, B1); PG8_BAR; PG8_SCHED;
;             PG8_LDA(At, 0, 1); PG8_STAGE(PG8_SB(0, 0), b2, voffB); PG8_STAGE(PG8_SB(0, 1), b2 + hstep, voffB); PG8_STAGE(PG8_SA(0, 0), a2, voffA);
.LBB0_1197:
	ds_read_b128 v[144:147], v151
	ds_read_b128 v[156:159], v151 offset:1024
	ds_read_b128 v[160:163], v151 offset:2048
	ds_read_b128 v[164:167], v151 offset:3072
	ds_read_b128 v[168:171], v152
	ds_read_b128 v[172:175], v152 offset:1024
	ds_read_b128 v[176:179], v152 offset:2048
	ds_read_b128 v[182:185], v152 offset:3072
	s_add_u32 s52, s50, 0x100
	s_addc_u32 s53, s51, 0
	s_cmp_eq_u32 s84, 40
	s_cselect_b32 s57, s1, s53
	s_cselect_b32 s56, s0, s52
	s_cselect_b32 s55, s49, s83
	s_cselect_b32 s54, s48, s82
	v_lshl_add_u64 v[224:225], s[50:51], 0, v[136:137]
	s_add_i32 m0, s34, 0xc000
	ds_read_b128 v[186:189], v153
	ds_read_b128 v[190:193], v153 offset:1024
	ds_read_b128 v[194:197], v153 offset:2048
	ds_read_b128 v[198:201], v153 offset:3072
	ds_read_b128 v[208:211], v153 offset:4096
	ds_read_b128 v[212:215], v153 offset:5120
	ds_read_b128 v[216:219], v153 offset:6144
	ds_read_b128 v[220:223], v153 offset:7168
	global_load_lds_dwordx4 v[224:225], off
	v_lshl_add_u64 v[224:225], s[50:51], 0, v[138:139]
	s_add_i32 m0, s34, 0xe000
	s_nop 0
	global_load_lds_dwordx4 v[224:225], off
	s_waitcnt vmcnt(8)
	s_waitcnt lgkmcnt(0)
	s_barrier
	s_setprio 1
	s_waitcnt lgkmcnt(0)
	v_mfma_f32_16x16x32_bf16 v[124:127], v[144:147], v[186:189], v[124:127]
	v_mfma_f32_16x16x32_bf16 v[120:123], v[160:163], v[186:189], v[120:123]
	v_mfma_f32_16x16x32_bf16 v[108:111], v[144:147], v[194:197], v[108:111]
	v_mfma_f32_16x16x32_bf16 v[104:107], v[160:163], v[194:197], v[104:107]
	v_mfma_f32_16x16x32_bf16 v[92:95], v[144:147], v[208:211], v[92:95]
	v_mfma_f32_16x16x32_bf16 v[88:91], v[160:163], v[208:211], v[88:91]
	v_mfma_f32_16x16x32_bf16 v[76:79], v[144:147], v[216:219], v[76:79]
	v_mfma_f32_16x16x32_bf16 v[72:75], v[160:163], v[216:219], v[72:75]
	v_mfma_f32_16x16x32_bf16 v[124:127], v[156:159], v[190:193], v[124:127]
	v_mfma_f32_16x16x32_bf16 v[120:123], v[164:167], v[190:193], v[120:123]
	v_mfma_f32_16x16x32_bf16 v[108:111], v[156:159], v[198:201], v[108:111]
	v_mfma_f32_16x16x32_bf16 v[104:107], v[164:167], v[198:201], v[104:107]
	v_mfma_f32_16x16x32_bf16 v[92:95], v[156:159], v[212:215], v[92:95]
	v_mfma_f32_16x16x32_bf16 v[88:91], v[164:167], v[212:215], v[88:91]
	v_mfma_f32_16x16x32_bf16 v[76:79], v[156:159], v[220:223], v[76:79]
	v_mfma_f32_16x16x32_bf16 v[72:75], v[164:167], v[220:223], v[72:75]
	s_setprio 0
	s_setprio 1
	v_mfma_f32_16x16x32_bf16 v[116:119], v[168:171], v[186:189], v[116:119]
	v_mfma_f32_16x16x32_bf16 v[112:115], v[176:179], v[186:189], v[112:115]
	v_mfma_f32_16x16x32_bf16 v[100:103], v[168:171], v[194:197], v[100:103]
	v_mfma_f32_16x16x32_bf16 v[96:99], v[176:179], v[194:197], v[96:99]
	v_mfma_f32_16x16x32_bf16 v[84:87], v[168:171], v[208:211], v[84:87]
	v_mfma_f32_16x16x32_bf16 v[80:83], v[176:179], v[208:211], v[80:83]
	v_mfma_f32_16x16x32_bf16 v[68:71], v[168:171], v[216:219], v[68:71]
	v_mfma_f32_16x16x32_bf16 v[64:67], v[176:179], v[216:219], v[64:67]
	v_mfma_f32_16x16x32_bf16 v[116:119], v[172:175], v[190:193], v[116:119]
	v_mfma_f32_16x16x32_bf16 v[112:115], v[182:185], v[190:193], v[112:115]
	v_mfma_f32_16x16x32_bf16 v[100:103], v[172:175], v[198:201], v[100:103]
	v_mfma_f32_16x16x32_bf16 v[96:99], v[182:185], v[198:201], v[96:99]
	v_mfma_f32_16x16x32_bf16 v[84:87], v[172:175], v[212:215], v[84:87]
	v_mfma_f32_16x16x32_bf16 v[80:83], v[182:185], v[212:215], v[80:83]
	v_mfma_f32_16x16x32_bf16 v[68:71], v[172:175], v[220:223], v[68:71]
	v_mfma_f32_16x16x32_bf16 v[64:67], v[182:185], v[220:223], v[64:67]
	s_setprio 0
	s_barrier
	s_add_i32 s50, s64, s33
	v_lshl_add_u64 v[224:225], s[54:55], 0, v[130:131]
	s_mov_b32 m0, s50
	ds_read_b128 v[186:189], v153 offset:16384
	ds_read_b128 v[190:193], v153 offset:17408
	ds_read_b128 v[194:197], v153 offset:18432
	ds_read_b128 v[198:201], v153 offset:19456
	ds_read_b128 v[208:211], v153 offset:20480
	ds_read_b128 v[212:215], v153 offset:21504
	ds_read_b128 v[216:219], v153 offset:22528
	ds_read_b128 v[220:223], v153 offset:23552
	global_load_lds_dwordx4 v[224:225], off
	s_add_i32 m0, s50, 0x2000
	s_add_u32 s50, s54, 0xb0000
	v_lshl_add_u64 v[226:227], s[54:55], 0, v[134:135]
	s_addc_u32 s51, s55, 0
	s_add_i32 s78, s65, s33
	global_load_lds_dwordx4 v[226:227], off
	v_lshl_add_u64 v[228:229], s[50:51], 0, v[130:131]
	s_mov_b32 m0, s78
	global_load_lds_dwordx4 v[228:229], off
	v_lshl_add_u64 v[228:229], s[50:51], 0, v[134:135]
	s_add_i32 m0, s78, 0x2000
	s_nop 0
	global_load_lds_dwordx4 v[228:229], off
	s_waitcnt vmcnt(6)
	s_waitcnt lgkmcnt(0)
	s_barrier
; #define PG8_STAGE(bufoff, gbase, voff) do { _Pragma("unroll") for (int _i = 0; _i < 2; ++_i) \
;         __builtin_amdgcn_global_load_lds((const unsigned*)((const char*)(gbase) + (voff)[_i]), (PG8_LAS unsigned*)(lds + (bufoff) + ldsw + _i * 8192), 16, 0, 0); } while (0)
; #define PG8_LDA(dst, b, h) do { _Pragma("unroll") for (int m = 0; m < 4; ++m) _Pragma("unroll") for (int k = 0; k < 2; ++k) dst[m][k] = *(const PG8_LAS bf16x8*)(lds + PG8_SA(b, h) + aoff + m * 2048 + k * 1024); } while (0)
; #define PG8_LDB(dst, b, h) do { _Pragma("unroll") for (int n = 0; n < 2; ++n) _Pragma("unroll") for (int k = 0; k < 2; ++k) dst[n][k] = *(const PG8_LAS bf16x8*)(lds + PG8_SB(b, h) + boff + n * 2048 + k * 1024); } while (0)
; #define PG8_MMA(ai, bj, At, Bt) do { __builtin_amdgcn_s_setprio(1); _Pragma("unroll") for (int m = 0; m < 4; ++m) _Pragma("unroll") for (int n = 0; n < 2; ++n) _Pragma("unroll") for (int k = 0; k < 2; ++k) \
;         acc[ai][bj][m][n] = __builtin_amdgcn_mfma_f32_16x16x32_bf16(Bt[n][k], At[m][k], acc[ai][bj][m][n], 0, 0, 0); __builtin_amdgcn_s_setprio(0); } while (0)
; #define PG8_WAIT_V(n) asm volatile("s_waitcnt vmcnt(" #n ")" ::: "memory")
; #define PG8_WAIT_L(n) asm volatile("s_waitcnt lgkmcnt(" #n ")" ::: "memory")
; #define PG8_BAR __builtin_amdgcn_s_barrier()
; #define PG8_SCHED __builtin_amdgcn_sched_barrier(0)
; template <class Epi, class Sched, bool ALIGN_EPI = false, bool SP2 = false>
; __device__ __forceinline__ void gemm_phase(PG8_LAS unsigned char* lds, const Gemm g, const Sched& S, const Epi& E) {
;     ...
;             PG8_WAIT_V(8); PG8_WAIT_L(0); PG8_BAR; PG8_MMA(1, 0, At, B0); PG8_MMA(1, 1, At, B1); PG8_BAR; PG8_SCHED;
;             PG8_LDB(B0, 1, 0); PG8_LDB(B1, 1, 1); PG8_SCHED; PG8_LDA(At, 1, 0); PG8_STAGE(PG8_SA(0, 1), a2 + hstep, voffA);
;             PG8_WAIT_V(8); PG8_WAIT_L(0); PG8_BAR; PG8_MMA(0, 0, At, B0); PG8_MMA(0, 1, At, B1); PG8_BAR; PG8_SCHED;
	s_setprio 1
	s_waitcnt lgkmcnt(0)
	v_mfma_f32_16x16x32_bf16 v[60:63], v[144:147], v[186:189], v[60:63]
	v_mfma_f32_16x16x32_bf16 v[56:59], v[160:163], v[186:189], v[56:59]
	v_mfma_f32_16x16x32_bf16 v[44:47], v[144:147], v[194:197], v[44:47]
	v_mfma_f32_16x16x32_bf16 v[40:43], v[160:163], v[194:197], v[40:43]
	v_mfma_f32_16x16x32_bf16 v[28:31], v[144:147], v[208:211], v[28:31]
	v_mfma_f32_16x16x32_bf16 v[24:27], v[160:163], v[208:211], v[24:27]
	v_mfma_f32_16x16x32_bf16 v[12:15], v[144:147], v[216:219], v[12:15]
	v_mfma_f32_16x16x32_bf16 v[8:11], v[160:163], v[216:219], v[8:11]
	v_mfma_f32_16x16x32_bf16 v[60:63], v[156:159], v[190:193], v[60:63]
	v_mfma_f32_16x16x32_bf16 v[56:59], v[164:167], v[190:193], v[56:59]
	v_mfma_f32_16x16x32_bf16 v[44:47], v[156:159], v[198:201], v[44:47]
	v_mfma_f32_16x16x32_bf16 v[40:43], v[164:167], v[198:201], v[40:43]
	v_mfma_f32_16x16x32_bf16 v[28:31], v[156:159], v[212:215], v[28:31]
	v_mfma_f32_16x16x32_bf16 v[24:27], v[164:167], v[212:215], v[24:27]
	v_lshl_add_u64 v[228:229], s[56:57], 0, v[128:129]
	s_mov_b32 m0, s34
	s_nop 0
	global_load_lds_dwordx4 v[228:229], off
	v_mfma_f32_16x16x32_bf16 v[12:15], v[156:159], v[220:223], v[12:15]
	v_mfma_f32_16x16x32_bf16 v[8:11], v[164:167], v[220:223], v[8:11]
	s_setprio 0
	s_setprio 1
	v_mfma_f32_16x16x32_bf16 v[52:55], v[168:171], v[186:189], v[52:55]
	v_mfma_f32_16x16x32_bf16 v[48:51], v[176:179], v[186:189], v[48:51]
	v_mfma_f32_16x16x32_bf16 v[36:39], v[168:171], v[194:197], v[36:39]
	v_mfma_f32_16x16x32_bf16 v[32:35], v[176:179], v[194:197], v[32:35]
	v_mfma_f32_16x16x32_bf16 v[20:23], v[168:171], v[208:211], v[20:23]
	v_mfma_f32_16x16x32_bf16 v[16:19], v[176:179], v[208:211], v[16:19]
	v_mfma_f32_16x16x32_bf16 v[4:7], v[168:171], v[216:219], v[4:7]
	v_mfma_f32_16x16x32_bf16 v[0:3], v[176:179], v[216:219], v[0:3]
	v_mfma_f32_16x16x32_bf16 v[52:55], v[172:175], v[190:193], v[52:55]
	v_mfma_f32_16x16x32_bf16 v[48:51], v[182:185], v[190:193], v[48:51]
	v_mfma_f32_16x16x32_bf16 v[36:39], v[172:175], v[198:201], v[36:39]
	v_mfma_f32_16x16x32_bf16 v[32:35], v[182:185], v[198:201], v[32:35]
	v_mfma_f32_16x16x32_bf16 v[20:23], v[172:175], v[212:215], v[20:23]
	v_mfma_f32_16x16x32_bf16 v[16:19], v[182:185], v[212:215], v[16:19]
	v_lshl_add_u64 v[230:231], s[56:57], 0, v[132:133]
	s_mov_b32 m0, s58
	s_nop 0
	global_load_lds_dwordx4 v[230:231], off
	v_mfma_f32_16x16x32_bf16 v[4:7], v[172:175], v[220:223], v[4:7]
	v_mfma_f32_16x16x32_bf16 v[0:3], v[182:185], v[220:223], v[0:3]
	s_setprio 0
	s_barrier
	s_add_i32 s78, 0, 0x18000
	v_add_u32_e32 v155, s78, v149
	s_add_i32 s79, 0, 0x1c000
	ds_read_b128 v[144:147], v155
	ds_read_b128 v[156:159], v155 offset:1024
	ds_read_b128 v[160:163], v155 offset:2048
	ds_read_b128 v[164:167], v155 offset:3072
	v_add_u32_e32 v155, s79, v149
	ds_read_b128 v[168:171], v155
	ds_read_b128 v[172:175], v155 offset:1024
	ds_read_b128 v[176:179], v155 offset:2048
	ds_read_b128 v[182:185], v155 offset:3072
	s_add_u32 s50, s56, 0xb0000
	s_addc_u32 s51, s57, 0
	s_mov_b32 m0, s59
	v_lshl_add_u64 v[232:233], s[50:51], 0, v[128:129]
	ds_read_b128 v[186:189], v153 offset:32768
	ds_read_b128 v[190:193], v153 offset:33792
	ds_read_b128 v[194:197], v153 offset:34816
	ds_read_b128 v[198:201], v153 offset:35840
	ds_read_b128 v[208:211], v153 offset:36864
	ds_read_b128 v[212:215], v153 offset:37888
	ds_read_b128 v[216:219], v153 offset:38912
	ds_read_b128 v[220:223], v153 offset:39936
	global_load_lds_dwordx4 v[232:233], off
	v_lshl_add_u64 v[232:233], s[50:51], 0, v[132:133]
	s_mov_b32 m0, s60
	s_nop 0
	global_load_lds_dwordx4 v[232:233], off
	s_waitcnt vmcnt(8)
	s_waitcnt lgkmcnt(0)
	s_barrier
	s_setprio 1
	s_waitcnt lgkmcnt(0)
	v_mfma_f32_16x16x32_bf16 v[124:127], v[144:147], v[186:189], v[124:127]
	v_mfma_f32_16x16x32_bf16 v[120:123], v[160:163], v[186:189], v[120:123]
	v_mfma_f32_16x16x32_bf16 v[108:111], v[144:147], v[194:197], v[108:111]
	v_mfma_f32_16x16x32_bf16 v[104:107], v[160:163], v[194:197], v[104:107]
	v_mfma_f32_16x16x32_bf16 v[92:95], v[144:147], v[208:211], v[92:95]
	v_mfma_f32_16x16x32_bf16 v[88:91], v[160:163], v[208:211], v[88:91]
	v_mfma_f32_16x16x32_bf16 v[76:79], v[144:147], v[216:219], v[76:79]
	v_mfma_f32_16x16x32_bf16 v[72:75], v[160:163], v[216:219], v[72:75]
	v_mfma_f32_16x16x32_bf16 v[124:127], v[156:159], v[190:193], v[124:127]
	v_mfma_f32_16x16x32_bf16 v[120:123], v[164:167], v[190:193], v[120:123]
	v_mfma_f32_16x16x32_bf16 v[108:111], v[156:159], v[198:201], v[108:111]
	v_mfma_f32_16x16x32_bf16 v[104:107], v[164:167], v[198:201], v[104:107]
	v_mfma_f32_16x16x32_bf16 v[92:95], v[156:159], v[212:215], v[92:95]
	v_mfma_f32_16x16x32_bf16 v[88:91], v[164:167], v[212:215], v[88:91]
	v_mfma_f32_16x16x32_bf16 v[76:79], v[156:159], v[220:223], v[76:79]
	v_mfma_f32_16x16x32_bf16 v[72:75], v[164:167], v[220:223], v[72:75]
	s_setprio 0
	s_setprio 1
	v_mfma_f32_16x16x32_bf16 v[116:119], v[168:171], v[186:189], v[116:119]
	v_mfma_f32_16x16x32_bf16 v[112:115], v[176:179], v[186:189], v[112:115]
	v_mfma_f32_16x16x32_bf16 v[100:103], v[168:171], v[194:197], v[100:103]
	v_mfma_f32_16x16x32_bf16 v[96:99], v[176:179], v[194:197], v[96:99]
	v_mfma_f32_16x16x32_bf16 v[84:87], v[168:171], v[208:211], v[84:87]
	v_mfma_f32_16x16x32_bf16 v[80:83], v[176:179], v[208:211], v[80:83]
	v_mfma_f32_16x16x32_bf16 v[68:71], v[168:171], v[216:219], v[68:71]
	v_mfma_f32_16x16x32_bf16 v[64:67], v[176:179], v[216:219], v[64:67]
	v_mfma_f32_16x16x32_bf16 v[116:119], v[172:175], v[190:193], v[116:119]
	v_mfma_f32_16x16x32_bf16 v[112:115], v[182:185], v[190:193], v[112:115]
	v_mfma_f32_16x16x32_bf16 v[100:103], v[172:175], v[198:201], v[100:103]
	v_mfma_f32_16x16x32_bf16 v[96:99], v[182:185], v[198:201], v[96:99]
	v_mfma_f32_16x16x32_bf16 v[84:87], v[172:175], v[212:215], v[84:87]
	v_mfma_f32_16x16x32_bf16 v[80:83], v[182:185], v[212:215], v[80:83]
	v_mfma_f32_16x16x32_bf16 v[68:71], v[172:175], v[220:223], v[68:71]
	v_mfma_f32_16x16x32_bf16 v[64:67], v[182:185], v[220:223], v[64:67]
	s_setprio 0
	s_barrier
; #define PG8_STAGE(bufoff, gbase, voff) do { _Pragma("unroll") for (int _i = 0; _i < 2; ++_i) \
;         __builtin_amdgcn_global_load_lds((const unsigned*)((const char*)(gbase) + (voff)[_i]), (PG8_LAS unsigned*)(lds + (bufoff) + ldsw + _i * 8192), 16, 0, 0); } while (0)
; #define PG8_LDA(dst, b, h) do { _Pragma("unroll") for (int m = 0; m < 4; ++m) _Pragma("unroll") for (int k = 0; k < 2; ++k) dst[m][k] = *(const PG8_LAS bf16x8*)(lds + PG8_SA(b, h) + aoff + m * 2048 + k * 1024); } while (0)
; #define PG8_MMA(ai, bj, At, Bt) do { __builtin_amdgcn_s_setprio(1); _Pragma("unroll") for (int m = 0; m < 4; ++m) _Pragma("unroll") for (int n = 0; n < 2; ++n) _Pragma("unroll") for (int k = 0; k < 2; ++k) \
;         acc[ai][bj][m][n] = __builtin_amdgcn_mfma_f32_16x16x32_bf16(Bt[n][k], At[m][k], acc[ai][bj][m][n], 0, 0, 0); __builtin_amdgcn_s_setprio(0); } while (0)
; #define PG8_WAIT_V(n) asm volatile("s_waitcnt vmcnt(" #n ")" ::: "memory")
; #define PG8_WAIT_L(n) asm volatile("s_waitcnt lgkmcnt(" #n ")" ::: "memory")
; #define PG8_BAR __builtin_amdgcn_s_barrier()
; #define PG8_SCHED __builtin_amdgcn_sched_barrier(0)
; template <class Epi, class Sched, bool ALIGN_EPI = false, bool SP2 = false>
; __device__ __forceinline__ void gemm_phase(PG8_LAS unsigned char* lds, const Gemm g, const Sched& S, const Epi& E) {
;     ...
;             PG8_LDA(At, 1, 1); PG8_STAGE(PG8_SB(1, 0), b3, voffB); PG8_STAGE(PG8_SB(1, 1), b3 + hstep, voffB); PG8_STAGE(PG8_SA(1, 0), a3, voffA);
;             PG8_WAIT_V(8); PG8_WAIT_L(0); PG8_BAR; PG8_MMA(1, 0, At, B0); PG8_MMA(1, 1, At, B1); PG8_BAR; PG8_SCHED;
	s_add_i32 s50, s78, s33
	v_lshl_add_u64 v[224:225], v[224:225], 0, s[42:43]
	s_mov_b32 m0, s50
	ds_read_b128 v[186:189], v153 offset:49152
	ds_read_b128 v[190:193], v153 offset:50176
	ds_read_b128 v[194:197], v153 offset:51200
	ds_read_b128 v[198:201], v153 offset:52224
	ds_read_b128 v[208:211], v153 offset:53248
	ds_read_b128 v[212:215], v153 offset:54272
	ds_read_b128 v[216:219], v153 offset:55296
	ds_read_b128 v[220:223], v153 offset:56320
	global_load_lds_dwordx4 v[224:225], off
	s_add_i32 m0, s50, 0x2000
	s_add_u32 s50, s54, 0xb0080
	v_lshl_add_u64 v[224:225], v[226:227], 0, s[42:43]
	s_addc_u32 s51, s55, 0
	s_add_i32 s54, s79, s33
	global_load_lds_dwordx4 v[224:225], off
	v_lshl_add_u64 v[224:225], s[50:51], 0, v[130:131]
	s_mov_b32 m0, s54
	s_nop 0
	global_load_lds_dwordx4 v[224:225], off
	v_lshl_add_u64 v[224:225], s[50:51], 0, v[134:135]
	s_add_i32 m0, s54, 0x2000
	s_nop 0
	global_load_lds_dwordx4 v[224:225], off
	s_waitcnt vmcnt(6)
	s_waitcnt lgkmcnt(0)
	s_barrier
	s_setprio 1
	s_waitcnt lgkmcnt(0)
	v_mfma_f32_16x16x32_bf16 v[60:63], v[144:147], v[186:189], v[60:63]
	v_mfma_f32_16x16x32_bf16 v[56:59], v[160:163], v[186:189], v[56:59]
	v_lshl_add_u64 v[224:225], v[228:229], 0, s[42:43]
	s_mov_b32 m0, s62
	s_nop 0
	global_load_lds_dwordx4 v[224:225], off
	v_mfma_f32_16x16x32_bf16 v[44:47], v[144:147], v[194:197], v[44:47]
	v_mfma_f32_16x16x32_bf16 v[40:43], v[160:163], v[194:197], v[40:43]
	v_mfma_f32_16x16x32_bf16 v[28:31], v[144:147], v[208:211], v[28:31]
	v_mfma_f32_16x16x32_bf16 v[24:27], v[160:163], v[208:211], v[24:27]
	v_lshl_add_u64 v[224:225], v[230:231], 0, s[42:43]
	s_mov_b32 m0, s63
	s_nop 0
	global_load_lds_dwordx4 v[224:225], off
	v_mfma_f32_16x16x32_bf16 v[12:15], v[144:147], v[216:219], v[12:15]
	v_mfma_f32_16x16x32_bf16 v[8:11], v[160:163], v[216:219], v[8:11]
	v_mfma_f32_16x16x32_bf16 v[60:63], v[156:159], v[190:193], v[60:63]
	v_mfma_f32_16x16x32_bf16 v[56:59], v[164:167], v[190:193], v[56:59]
	v_mfma_f32_16x16x32_bf16 v[44:47], v[156:159], v[198:201], v[44:47]
	v_mfma_f32_16x16x32_bf16 v[40:43], v[164:167], v[198:201], v[40:43]
	v_mfma_f32_16x16x32_bf16 v[28:31], v[156:159], v[212:215], v[28:31]
	v_mfma_f32_16x16x32_bf16 v[24:27], v[164:167], v[212:215], v[24:27]
	v_mfma_f32_16x16x32_bf16 v[12:15], v[156:159], v[220:223], v[12:15]
	v_mfma_f32_16x16x32_bf16 v[8:11], v[164:167], v[220:223], v[8:11]
	s_setprio 0
	s_setprio 1
	v_mfma_f32_16x16x32_bf16 v[52:55], v[168:171], v[186:189], v[52:55]
	v_mfma_f32_16x16x32_bf16 v[48:51], v[176:179], v[186:189], v[48:51]
	v_mfma_f32_16x16x32_bf16 v[36:39], v[168:171], v[194:197], v[36:39]
	v_mfma_f32_16x16x32_bf16 v[32:35], v[176:179], v[194:197], v[32:35]
	v_mfma_f32_16x16x32_bf16 v[20:23], v[168:171], v[208:211], v[20:23]
	v_mfma_f32_16x16x32_bf16 v[16:19], v[176:179], v[208:211], v[16:19]
	v_mfma_f32_16x16x32_bf16 v[4:7], v[168:171], v[216:219], v[4:7]
	v_mfma_f32_16x16x32_bf16 v[0:3], v[176:179], v[216:219], v[0:3]
	v_mfma_f32_16x16x32_bf16 v[52:55], v[172:175], v[190:193], v[52:55]
	v_mfma_f32_16x16x32_bf16 v[48:51], v[182:185], v[190:193], v[48:51]
	v_mfma_f32_16x16x32_bf16 v[36:39], v[172:175], v[198:201], v[36:39]
	v_mfma_f32_16x16x32_bf16 v[32:35], v[182:185], v[198:201], v[32:35]
	v_mfma_f32_16x16x32_bf16 v[20:23], v[172:175], v[212:215], v[20:23]
	v_mfma_f32_16x16x32_bf16 v[16:19], v[182:185], v[212:215], v[16:19]
	v_mfma_f32_16x16x32_bf16 v[4:7], v[172:175], v[220:223], v[4:7]
	v_mfma_f32_16x16x32_bf16 v[0:3], v[182:185], v[220:223], v[0:3]
	s_setprio 0
	s_barrier
	s_add_i32 s84, s84, 2
	s_add_u32 s82, s82, 0x100
	s_addc_u32 s83, s83, 0
	s_cmp_gt_u32 s84, 41
	s_mov_b64 s[50:51], s[52:53]
	s_cbranch_scc0 .LBB0_1197
	s_and_b64 vcc, exec, s[44:45]
	s_cbranch_vccz .LBB0_1200
	s_barrier

; #define PG8_STAGE(bufoff, gbase, voff) do { _Pragma("unroll") for (int _i = 0; _i < 2; ++_i) \
;         __builtin_amdgcn_global_load_lds((const unsigned*)((const char*)(gbase) + (voff)[_i]), (PG8_LAS unsigned*)(lds + (bufoff) + ldsw + _i * 8192), 16, 0, 0); } while (0)
; #define PG8_LDA(dst, b, h) do { _Pragma("unroll") for (int m = 0; m < 4; ++m) _Pragma("unroll") for (int k = 0; k < 2; ++k) dst[m][k] = *(const PG8_LAS bf16x8*)(lds + PG8_SA(b, h) + aoff + m * 2048 + k * 1024); } while (0)
; #define PG8_LDB(dst, b, h) do { _Pragma("unroll") for (int n = 0; n < 2; ++n) _Pragma("unroll") for (int k = 0; k < 2; ++k) dst[n][k] = *(const PG8_LAS bf16x8*)(lds + PG8_SB(b, h) + boff + n * 2048 + k * 1024); } while (0)
; #define PG8_MMA(ai, bj, At, Bt) do { __builtin_amdgcn_s_setprio(1); _Pragma("unroll") for (int m = 0; m < 4; ++m) _Pragma("unroll") for (int n = 0; n < 2; ++n) _Pragma("unroll") for (int k = 0; k < 2; ++k) \
;         acc[ai][bj][m][n] = __builtin_amdgcn_mfma_f32_16x16x32_bf16(Bt[n][k], At[m][k], acc[ai][bj][m][n], 0, 0, 0); __builtin_amdgcn_s_setprio(0); } while (0)
; #define PG8_WAIT_V(n) asm volatile("s_waitcnt vmcnt(" #n ")" ::: "memory")
; #define PG8_WAIT_L(n) asm volatile("s_waitcnt lgkmcnt(" #n ")" ::: "memory")
; #define PG8_BAR __builtin_amdgcn_s_barrier()
; #define PG8_SCHED __builtin_amdgcn_sched_barrier(0)
; template <class Epi, class Sched, bool ALIGN_EPI = false, bool SP2 = false>
; __device__ __forceinline__ void gemm_phase(PG8_LAS unsigned char* lds, const Gemm g, const Sched& S, const Epi& E) {
;     ...
;         for (int t = 0; t < nt; t += 2) {
;             const bool last = (t == nt - 2);
;             const char* a1 = cA + (size_t)(t + 1) * kstep;
;             const char* a2 = last ? nA : cA + (size_t)(t + 2) * kstep; const char* b2 = last ? nB : cB + (size_t)(t + 2) * kstep;
;             const char* a3 = a2 + kstep; const char* b3 = b2 + kstep;
;             if (last && has_next) S.a_ready(nxt);
;             if constexpr (SP2) {
;             PG8_LDB(B0, 0, 0); PG8_LDB(B1, 0, 1); PG8_SCHED; PG8_LDA(At, 0, 0); PG8_STAGE(PG8_SA(1, 1), a1 + hstep, voffA);
;             PG8_WAIT_V(8); PG8_WAIT_L(0); PG8_BAR; PG8_MMA(0, 0, At, B0); PG8_MMA(0, 1, At, B1); PG8_BAR; PG8_SCHED;
;             PG8_LDA(At, 0, 1); PG8_STAGE(PG8_SB(0, 0), b2, voffB); PG8_STAGE(PG8_SB(0, 1), b2 + hstep, voffB); PG8_STAGE(PG8_SA(0, 0), a2, voffA);
.LBB0_1287:
	ds_read_b128 v[128:131], v181
	ds_read_b128 v[160:163], v181 offset:1024
	ds_read_b128 v[164:167], v181 offset:2048
	ds_read_b128 v[168:171], v181 offset:3072
	ds_read_b128 v[172:175], v203
	ds_read_b128 v[176:179], v203 offset:1024
	ds_read_b128 v[182:185], v203 offset:2048
	ds_read_b128 v[186:189], v203 offset:3072
	s_add_u32 s62, s58, 0xfffc0080
	s_addc_u32 s63, s59, -1
	s_cmp_eq_u32 s90, 12
	s_cselect_b32 s65, s51, s63
	s_cselect_b32 s64, s61, s62
	s_cselect_b32 s63, s49, s89
	s_cselect_b32 s62, s87, s88
	v_lshl_add_u64 v[232:233], s[58:59], 0, v[152:153]
	s_add_i32 m0, s15, 0xc000
	ds_read_b128 v[190:193], v208
	ds_read_b128 v[194:197], v208 offset:1024
	ds_read_b128 v[198:201], v208 offset:2048
	ds_read_b128 v[212:215], v208 offset:3072
	ds_read_b128 v[216:219], v208 offset:4096
	ds_read_b128 v[220:223], v208 offset:5120
	ds_read_b128 v[224:227], v208 offset:6144
	ds_read_b128 v[228:231], v208 offset:7168
	global_load_lds_dwordx4 v[232:233], off
	v_lshl_add_u64 v[232:233], s[58:59], 0, v[154:155]
	s_add_i32 m0, s15, 0xe000
	s_nop 0
	global_load_lds_dwordx4 v[232:233], off
	s_waitcnt vmcnt(8)
	s_waitcnt lgkmcnt(0)
	s_barrier
	s_setprio 1
	s_waitcnt lgkmcnt(0)
	v_mfma_f32_16x16x32_bf16 v[124:127], v[128:131], v[190:193], v[124:127]
	v_mfma_f32_16x16x32_bf16 v[120:123], v[164:167], v[190:193], v[120:123]
	v_mfma_f32_16x16x32_bf16 v[116:119], v[128:131], v[198:201], v[116:119]
	v_mfma_f32_16x16x32_bf16 v[112:115], v[164:167], v[198:201], v[112:115]
	v_mfma_f32_16x16x32_bf16 v[108:111], v[128:131], v[216:219], v[108:111]
	v_mfma_f32_16x16x32_bf16 v[104:107], v[164:167], v[216:219], v[104:107]
	v_mfma_f32_16x16x32_bf16 v[100:103], v[128:131], v[224:227], v[100:103]
	v_mfma_f32_16x16x32_bf16 v[96:99], v[164:167], v[224:227], v[96:99]
	v_mfma_f32_16x16x32_bf16 v[124:127], v[160:163], v[194:197], v[124:127]
	v_mfma_f32_16x16x32_bf16 v[120:123], v[168:171], v[194:197], v[120:123]
	v_mfma_f32_16x16x32_bf16 v[116:119], v[160:163], v[212:215], v[116:119]
	v_mfma_f32_16x16x32_bf16 v[112:115], v[168:171], v[212:215], v[112:115]
	v_mfma_f32_16x16x32_bf16 v[108:111], v[160:163], v[220:223], v[108:111]
	v_mfma_f32_16x16x32_bf16 v[104:107], v[168:171], v[220:223], v[104:107]
	v_mfma_f32_16x16x32_bf16 v[100:103], v[160:163], v[228:231], v[100:103]
	v_mfma_f32_16x16x32_bf16 v[96:99], v[168:171], v[228:231], v[96:99]
	s_setprio 0
	s_setprio 1
	v_mfma_f32_16x16x32_bf16 v[60:63], v[172:175], v[190:193], v[60:63]
	v_mfma_f32_16x16x32_bf16 v[56:59], v[182:185], v[190:193], v[56:59]
	v_mfma_f32_16x16x32_bf16 v[52:55], v[172:175], v[198:201], v[52:55]
	v_mfma_f32_16x16x32_bf16 v[48:51], v[182:185], v[198:201], v[48:51]
	v_mfma_f32_16x16x32_bf16 v[44:47], v[172:175], v[216:219], v[44:47]
	v_mfma_f32_16x16x32_bf16 v[40:43], v[182:185], v[216:219], v[40:43]
	v_mfma_f32_16x16x32_bf16 v[36:39], v[172:175], v[224:227], v[36:39]
	v_mfma_f32_16x16x32_bf16 v[32:35], v[182:185], v[224:227], v[32:35]
	v_mfma_f32_16x16x32_bf16 v[60:63], v[176:179], v[194:197], v[60:63]
	v_mfma_f32_16x16x32_bf16 v[56:59], v[186:189], v[194:197], v[56:59]
	v_mfma_f32_16x16x32_bf16 v[52:55], v[176:179], v[212:215], v[52:55]
	v_mfma_f32_16x16x32_bf16 v[48:51], v[186:189], v[212:215], v[48:51]
	v_mfma_f32_16x16x32_bf16 v[44:47], v[176:179], v[220:223], v[44:47]
	v_mfma_f32_16x16x32_bf16 v[40:43], v[186:189], v[220:223], v[40:43]
	v_mfma_f32_16x16x32_bf16 v[36:39], v[176:179], v[228:231], v[36:39]
	v_mfma_f32_16x16x32_bf16 v[32:35], v[186:189], v[228:231], v[32:35]
	s_setprio 0
	s_barrier
	s_add_i32 s78, s75, s14
	v_lshl_add_u64 v[232:233], s[62:63], 0, v[134:135]
	s_mov_b32 m0, s78
	ds_read_b128 v[190:193], v208 offset:16384
	ds_read_b128 v[194:197], v208 offset:17408
	ds_read_b128 v[198:201], v208 offset:18432
	ds_read_b128 v[212:215], v208 offset:19456
	ds_read_b128 v[216:219], v208 offset:20480
	ds_read_b128 v[220:223], v208 offset:21504
	ds_read_b128 v[224:227], v208 offset:22528
	ds_read_b128 v[228:231], v208 offset:23552
	global_load_lds_dwordx4 v[232:233], off
	s_add_i32 m0, s78, 0x2000
	s_add_u32 s78, s62, 0x40000
	v_lshl_add_u64 v[234:235], s[62:63], 0, v[138:139]
	s_addc_u32 s79, s63, 0
	s_add_i32 s91, s76, s14
	global_load_lds_dwordx4 v[234:235], off
	v_lshl_add_u64 v[236:237], s[78:79], 0, v[134:135]
	s_mov_b32 m0, s91
	global_load_lds_dwordx4 v[236:237], off
	v_lshl_add_u64 v[236:237], s[78:79], 0, v[138:139]
	s_add_i32 m0, s91, 0x2000
	s_nop 0
	global_load_lds_dwordx4 v[236:237], off
	s_waitcnt vmcnt(6)
	s_waitcnt lgkmcnt(0)
	s_barrier
; #define PG8_STAGE(bufoff, gbase, voff) do { _Pragma("unroll") for (int _i = 0; _i < 2; ++_i) \
;         __builtin_amdgcn_global_load_lds((const unsigned*)((const char*)(gbase) + (voff)[_i]), (PG8_LAS unsigned*)(lds + (bufoff) + ldsw + _i * 8192), 16, 0, 0); } while (0)
; #define PG8_LDA(dst, b, h) do { _Pragma("unroll") for (int m = 0; m < 4; ++m) _Pragma("unroll") for (int k = 0; k < 2; ++k) dst[m][k] = *(const PG8_LAS bf16x8*)(lds + PG8_SA(b, h) + aoff + m * 2048 + k * 1024); } while (0)
; #define PG8_LDB(dst, b, h) do { _Pragma("unroll") for (int n = 0; n < 2; ++n) _Pragma("unroll") for (int k = 0; k < 2; ++k) dst[n][k] = *(const PG8_LAS bf16x8*)(lds + PG8_SB(b, h) + boff + n * 2048 + k * 1024); } while (0)
; #define PG8_MMA(ai, bj, At, Bt) do { __builtin_amdgcn_s_setprio(1); _Pragma("unroll") for (int m = 0; m < 4; ++m) _Pragma("unroll") for (int n = 0; n < 2; ++n) _Pragma("unroll") for (int k = 0; k < 2; ++k) \
;         acc[ai][bj][m][n] = __builtin_amdgcn_mfma_f32_16x16x32_bf16(Bt[n][k], At[m][k], acc[ai][bj][m][n], 0, 0, 0); __builtin_amdgcn_s_setprio(0); } while (0)
; #define PG8_WAIT_V(n) asm volatile("s_waitcnt vmcnt(" #n ")" ::: "memory")
; #define PG8_WAIT_L(n) asm volatile("s_waitcnt lgkmcnt(" #n ")" ::: "memory")
; #define PG8_BAR __builtin_amdgcn_s_barrier()
; #define PG8_SCHED __builtin_amdgcn_sched_barrier(0)
; template <class Epi, class Sched, bool ALIGN_EPI = false, bool SP2 = false>
; __device__ __forceinline__ void gemm_phase(PG8_LAS unsigned char* lds, const Gemm g, const Sched& S, const Epi& E) {
;     ...
;             PG8_WAIT_V(8); PG8_WAIT_L(0); PG8_BAR; PG8_MMA(1, 0, At, B0); PG8_MMA(1, 1, At, B1); PG8_BAR; PG8_SCHED;
;             PG8_LDB(B0, 1, 0); PG8_LDB(B1, 1, 1); PG8_SCHED; PG8_LDA(At, 1, 0); PG8_STAGE(PG8_SA(0, 1), a2 + hstep, voffA);
;             PG8_WAIT_V(8); PG8_WAIT_L(0); PG8_BAR; PG8_MMA(0, 0, At, B0); PG8_MMA(0, 1, At, B1); PG8_BAR; PG8_SCHED;
	s_setprio 1
	s_waitcnt lgkmcnt(0)
	v_mfma_f32_16x16x32_bf16 v[92:95], v[128:131], v[190:193], v[92:95]
	v_mfma_f32_16x16x32_bf16 v[88:91], v[164:167], v[190:193], v[88:91]
	v_mfma_f32_16x16x32_bf16 v[84:87], v[128:131], v[198:201], v[84:87]
	v_mfma_f32_16x16x32_bf16 v[80:83], v[164:167], v[198:201], v[80:83]
	v_mfma_f32_16x16x32_bf16 v[76:79], v[128:131], v[216:219], v[76:79]
	v_mfma_f32_16x16x32_bf16 v[72:75], v[164:167], v[216:219], v[72:75]
	v_mfma_f32_16x16x32_bf16 v[68:71], v[128:131], v[224:227], v[68:71]
	v_mfma_f32_16x16x32_bf16 v[64:67], v[164:167], v[224:227], v[64:67]
	v_mfma_f32_16x16x32_bf16 v[92:95], v[160:163], v[194:197], v[92:95]
	v_mfma_f32_16x16x32_bf16 v[88:91], v[168:171], v[194:197], v[88:91]
	v_mfma_f32_16x16x32_bf16 v[84:87], v[160:163], v[212:215], v[84:87]
	v_mfma_f32_16x16x32_bf16 v[80:83], v[168:171], v[212:215], v[80:83]
	v_mfma_f32_16x16x32_bf16 v[76:79], v[160:163], v[220:223], v[76:79]
	v_mfma_f32_16x16x32_bf16 v[72:75], v[168:171], v[220:223], v[72:75]
	v_lshl_add_u64 v[236:237], s[64:65], 0, v[132:133]
	s_mov_b32 m0, s15
	s_nop 0
	global_load_lds_dwordx4 v[236:237], off
	v_mfma_f32_16x16x32_bf16 v[68:71], v[160:163], v[228:231], v[68:71]
	v_mfma_f32_16x16x32_bf16 v[64:67], v[168:171], v[228:231], v[64:67]
	s_setprio 0
	s_setprio 1
	v_mfma_f32_16x16x32_bf16 v[28:31], v[172:175], v[190:193], v[28:31]
	v_mfma_f32_16x16x32_bf16 v[24:27], v[182:185], v[190:193], v[24:27]
	v_mfma_f32_16x16x32_bf16 v[20:23], v[172:175], v[198:201], v[20:23]
	v_mfma_f32_16x16x32_bf16 v[16:19], v[182:185], v[198:201], v[16:19]
	v_mfma_f32_16x16x32_bf16 v[12:15], v[172:175], v[216:219], v[12:15]
	v_mfma_f32_16x16x32_bf16 v[8:11], v[182:185], v[216:219], v[8:11]
	v_mfma_f32_16x16x32_bf16 v[4:7], v[172:175], v[224:227], v[4:7]
	v_mfma_f32_16x16x32_bf16 v[0:3], v[182:185], v[224:227], v[0:3]
	v_mfma_f32_16x16x32_bf16 v[28:31], v[176:179], v[194:197], v[28:31]
	v_mfma_f32_16x16x32_bf16 v[24:27], v[186:189], v[194:197], v[24:27]
	v_mfma_f32_16x16x32_bf16 v[20:23], v[176:179], v[212:215], v[20:23]
	v_mfma_f32_16x16x32_bf16 v[16:19], v[186:189], v[212:215], v[16:19]
	v_mfma_f32_16x16x32_bf16 v[12:15], v[176:179], v[220:223], v[12:15]
	v_mfma_f32_16x16x32_bf16 v[8:11], v[186:189], v[220:223], v[8:11]
	v_lshl_add_u64 v[238:239], s[64:65], 0, v[136:137]
	s_mov_b32 m0, s33
	s_nop 0
	global_load_lds_dwordx4 v[238:239], off
	v_mfma_f32_16x16x32_bf16 v[4:7], v[176:179], v[228:231], v[4:7]
	v_mfma_f32_16x16x32_bf16 v[0:3], v[186:189], v[228:231], v[0:3]
	s_setprio 0
	s_barrier
	s_add_i32 s78, 0, 0x18000
	v_add_u32_e32 v140, s78, v147
	s_add_i32 s79, 0, 0x1c000
	ds_read_b128 v[128:131], v140
	ds_read_b128 v[160:163], v140 offset:1024
	ds_read_b128 v[164:167], v140 offset:2048
	ds_read_b128 v[168:171], v140 offset:3072
	v_add_u32_e32 v140, s79, v147
	ds_read_b128 v[172:175], v140
	ds_read_b128 v[176:179], v140 offset:1024
	ds_read_b128 v[182:185], v140 offset:2048
	ds_read_b128 v[186:189], v140 offset:3072
	s_add_u32 s64, s64, 0x40000
	s_addc_u32 s65, s65, 0
	s_mov_b32 m0, s34
	v_lshl_add_u64 v[240:241], s[64:65], 0, v[132:133]
	ds_read_b128 v[190:193], v208 offset:32768
	ds_read_b128 v[194:197], v208 offset:33792
	ds_read_b128 v[198:201], v208 offset:34816
	ds_read_b128 v[212:215], v208 offset:35840
	ds_read_b128 v[216:219], v208 offset:36864
	ds_read_b128 v[220:223], v208 offset:37888
	ds_read_b128 v[224:227], v208 offset:38912
	ds_read_b128 v[228:231], v208 offset:39936
	global_load_lds_dwordx4 v[240:241], off
	v_lshl_add_u64 v[240:241], s[64:65], 0, v[136:137]
	s_mov_b32 m0, s57
	s_nop 0
	global_load_lds_dwordx4 v[240:241], off
	s_waitcnt vmcnt(8)
	s_waitcnt lgkmcnt(0)
	s_barrier
	s_setprio 1
	s_waitcnt lgkmcnt(0)
	v_mfma_f32_16x16x32_bf16 v[124:127], v[128:131], v[190:193], v[124:127]
	v_mfma_f32_16x16x32_bf16 v[120:123], v[164:167], v[190:193], v[120:123]
	v_mfma_f32_16x16x32_bf16 v[116:119], v[128:131], v[198:201], v[116:119]
	v_mfma_f32_16x16x32_bf16 v[112:115], v[164:167], v[198:201], v[112:115]
	v_mfma_f32_16x16x32_bf16 v[108:111], v[128:131], v[216:219], v[108:111]
	v_mfma_f32_16x16x32_bf16 v[104:107], v[164:167], v[216:219], v[104:107]
	v_mfma_f32_16x16x32_bf16 v[100:103], v[128:131], v[224:227], v[100:103]
	v_mfma_f32_16x16x32_bf16 v[96:99], v[164:167], v[224:227], v[96:99]
	v_mfma_f32_16x16x32_bf16 v[124:127], v[160:163], v[194:197], v[124:127]
	v_mfma_f32_16x16x32_bf16 v[120:123], v[168:171], v[194:197], v[120:123]
	v_mfma_f32_16x16x32_bf16 v[116:119], v[160:163], v[212:215], v[116:119]
	v_mfma_f32_16x16x32_bf16 v[112:115], v[168:171], v[212:215], v[112:115]
	v_mfma_f32_16x16x32_bf16 v[108:111], v[160:163], v[220:223], v[108:111]
	v_mfma_f32_16x16x32_bf16 v[104:107], v[168:171], v[220:223], v[104:107]
	v_mfma_f32_16x16x32_bf16 v[100:103], v[160:163], v[228:231], v[100:103]
	v_mfma_f32_16x16x32_bf16 v[96:99], v[168:171], v[228:231], v[96:99]
	s_setprio 0
	s_setprio 1
	v_mfma_f32_16x16x32_bf16 v[60:63], v[172:175], v[190:193], v[60:63]
	v_mfma_f32_16x16x32_bf16 v[56:59], v[182:185], v[190:193], v[56:59]
	v_mfma_f32_16x16x32_bf16 v[52:55], v[172:175], v[198:201], v[52:55]
	v_mfma_f32_16x16x32_bf16 v[48:51], v[182:185], v[198:201], v[48:51]
	v_mfma_f32_16x16x32_bf16 v[44:47], v[172:175], v[216:219], v[44:47]
	v_mfma_f32_16x16x32_bf16 v[40:43], v[182:185], v[216:219], v[40:43]
	v_mfma_f32_16x16x32_bf16 v[36:39], v[172:175], v[224:227], v[36:39]
	v_mfma_f32_16x16x32_bf16 v[32:35], v[182:185], v[224:227], v[32:35]
	v_mfma_f32_16x16x32_bf16 v[60:63], v[176:179], v[194:197], v[60:63]
	v_mfma_f32_16x16x32_bf16 v[56:59], v[186:189], v[194:197], v[56:59]
	v_mfma_f32_16x16x32_bf16 v[52:55], v[176:179], v[212:215], v[52:55]
	v_mfma_f32_16x16x32_bf16 v[48:51], v[186:189], v[212:215], v[48:51]
	v_mfma_f32_16x16x32_bf16 v[44:47], v[176:179], v[220:223], v[44:47]
	v_mfma_f32_16x16x32_bf16 v[40:43], v[186:189], v[220:223], v[40:43]
	v_mfma_f32_16x16x32_bf16 v[36:39], v[176:179], v[228:231], v[36:39]
	v_mfma_f32_16x16x32_bf16 v[32:35], v[186:189], v[228:231], v[32:35]
	s_setprio 0
	s_barrier
; #define PG8_STAGE(bufoff, gbase, voff) do { _Pragma("unroll") for (int _i = 0; _i < 2; ++_i) \
;         __builtin_amdgcn_global_load_lds((const unsigned*)((const char*)(gbase) + (voff)[_i]), (PG8_LAS unsigned*)(lds + (bufoff) + ldsw + _i * 8192), 16, 0, 0); } while (0)
; #define PG8_LDA(dst, b, h) do { _Pragma("unroll") for (int m = 0; m < 4; ++m) _Pragma("unroll") for (int k = 0; k < 2; ++k) dst[m][k] = *(const PG8_LAS bf16x8*)(lds + PG8_SA(b, h) + aoff + m * 2048 + k * 1024); } while (0)
; #define PG8_MMA(ai, bj, At, Bt) do { __builtin_amdgcn_s_setprio(1); _Pragma("unroll") for (int m = 0; m < 4; ++m) _Pragma("unroll") for (int n = 0; n < 2; ++n) _Pragma("unroll") for (int k = 0; k < 2; ++k) \
;         acc[ai][bj][m][n] = __builtin_amdgcn_mfma_f32_16x16x32_bf16(Bt[n][k], At[m][k], acc[ai][bj][m][n], 0, 0, 0); __builtin_amdgcn_s_setprio(0); } while (0)
; #define PG8_WAIT_V(n) asm volatile("s_waitcnt vmcnt(" #n ")" ::: "memory")
; #define PG8_WAIT_L(n) asm volatile("s_waitcnt lgkmcnt(" #n ")" ::: "memory")
; #define PG8_BAR __builtin_amdgcn_s_barrier()
; #define PG8_SCHED __builtin_amdgcn_sched_barrier(0)
; template <class Epi, class Sched, bool ALIGN_EPI = false, bool SP2 = false>
; __device__ __forceinline__ void gemm_phase(PG8_LAS unsigned char* lds, const Gemm g, const Sched& S, const Epi& E) {
;     ...
;             PG8_LDA(At, 1, 1); PG8_STAGE(PG8_SB(1, 0), b3, voffB); PG8_STAGE(PG8_SB(1, 1), b3 + hstep, voffB); PG8_STAGE(PG8_SA(1, 0), a3, voffA);
;             PG8_WAIT_V(8); PG8_WAIT_L(0); PG8_BAR; PG8_MMA(1, 0, At, B0); PG8_MMA(1, 1, At, B1); PG8_BAR; PG8_SCHED;
	s_add_i32 s64, s78, s14
	v_lshl_add_u64 v[232:233], v[232:233], 0, s[42:43]
	s_mov_b32 m0, s64
	ds_read_b128 v[190:193], v208 offset:49152
	ds_read_b128 v[194:197], v208 offset:50176
	ds_read_b128 v[198:201], v208 offset:51200
	ds_read_b128 v[212:215], v208 offset:52224
	ds_read_b128 v[216:219], v208 offset:53248
	ds_read_b128 v[220:223], v208 offset:54272
	ds_read_b128 v[224:227], v208 offset:55296
	ds_read_b128 v[228:231], v208 offset:56320
	global_load_lds_dwordx4 v[232:233], off
	s_add_i32 m0, s64, 0x2000
	s_add_u32 s62, s62, 0x40080
	v_lshl_add_u64 v[232:233], v[234:235], 0, s[42:43]
	s_addc_u32 s63, s63, 0
	s_add_i32 s64, s79, s14
	global_load_lds_dwordx4 v[232:233], off
	v_lshl_add_u64 v[232:233], s[62:63], 0, v[134:135]
	s_mov_b32 m0, s64
	s_nop 0
	global_load_lds_dwordx4 v[232:233], off
	v_lshl_add_u64 v[232:233], s[62:63], 0, v[138:139]
	s_add_i32 m0, s64, 0x2000
	s_nop 0
	global_load_lds_dwordx4 v[232:233], off
	s_waitcnt vmcnt(6)
	s_waitcnt lgkmcnt(0)
	s_barrier
	s_setprio 1
	s_waitcnt lgkmcnt(0)
	v_mfma_f32_16x16x32_bf16 v[92:95], v[128:131], v[190:193], v[92:95]
	v_mfma_f32_16x16x32_bf16 v[88:91], v[164:167], v[190:193], v[88:91]
	v_lshl_add_u64 v[232:233], v[236:237], 0, s[42:43]
	s_mov_b32 m0, s67
	s_nop 0
	global_load_lds_dwordx4 v[232:233], off
	v_mfma_f32_16x16x32_bf16 v[84:87], v[128:131], v[198:201], v[84:87]
	v_mfma_f32_16x16x32_bf16 v[80:83], v[164:167], v[198:201], v[80:83]
	v_mfma_f32_16x16x32_bf16 v[76:79], v[128:131], v[216:219], v[76:79]
	v_mfma_f32_16x16x32_bf16 v[72:75], v[164:167], v[216:219], v[72:75]
	v_lshl_add_u64 v[232:233], v[238:239], 0, s[42:43]
	s_mov_b32 m0, s74
	s_nop 0
	global_load_lds_dwordx4 v[232:233], off
	v_mfma_f32_16x16x32_bf16 v[68:71], v[128:131], v[224:227], v[68:71]
	v_mfma_f32_16x16x32_bf16 v[64:67], v[164:167], v[224:227], v[64:67]
	v_mfma_f32_16x16x32_bf16 v[92:95], v[160:163], v[194:197], v[92:95]
	v_mfma_f32_16x16x32_bf16 v[88:91], v[168:171], v[194:197], v[88:91]
	v_mfma_f32_16x16x32_bf16 v[84:87], v[160:163], v[212:215], v[84:87]
	v_mfma_f32_16x16x32_bf16 v[80:83], v[168:171], v[212:215], v[80:83]
	v_mfma_f32_16x16x32_bf16 v[76:79], v[160:163], v[220:223], v[76:79]
	v_mfma_f32_16x16x32_bf16 v[72:75], v[168:171], v[220:223], v[72:75]
	v_mfma_f32_16x16x32_bf16 v[68:71], v[160:163], v[228:231], v[68:71]
	v_mfma_f32_16x16x32_bf16 v[64:67], v[168:171], v[228:231], v[64:67]
	s_setprio 0
	s_setprio 1
	v_mfma_f32_16x16x32_bf16 v[28:31], v[172:175], v[190:193], v[28:31]
	v_mfma_f32_16x16x32_bf16 v[24:27], v[182:185], v[190:193], v[24:27]
	v_mfma_f32_16x16x32_bf16 v[20:23], v[172:175], v[198:201], v[20:23]
	v_mfma_f32_16x16x32_bf16 v[16:19], v[182:185], v[198:201], v[16:19]
	v_mfma_f32_16x16x32_bf16 v[12:15], v[172:175], v[216:219], v[12:15]
	v_mfma_f32_16x16x32_bf16 v[8:11], v[182:185], v[216:219], v[8:11]
	v_mfma_f32_16x16x32_bf16 v[4:7], v[172:175], v[224:227], v[4:7]
	v_mfma_f32_16x16x32_bf16 v[0:3], v[182:185], v[224:227], v[0:3]
	v_mfma_f32_16x16x32_bf16 v[28:31], v[176:179], v[194:197], v[28:31]
	v_mfma_f32_16x16x32_bf16 v[24:27], v[186:189], v[194:197], v[24:27]
	v_mfma_f32_16x16x32_bf16 v[20:23], v[176:179], v[212:215], v[20:23]
	v_mfma_f32_16x16x32_bf16 v[16:19], v[186:189], v[212:215], v[16:19]
	v_mfma_f32_16x16x32_bf16 v[12:15], v[176:179], v[220:223], v[12:15]
	v_mfma_f32_16x16x32_bf16 v[8:11], v[186:189], v[220:223], v[8:11]
	v_mfma_f32_16x16x32_bf16 v[4:7], v[176:179], v[228:231], v[4:7]
	v_mfma_f32_16x16x32_bf16 v[0:3], v[186:189], v[228:231], v[0:3]
	s_setprio 0
	s_barrier
	s_add_i32 s90, s90, 2
	s_add_u32 s58, s58, 0x100
	s_addc_u32 s59, s59, 0
	s_add_u32 s88, s88, 0x100
	s_addc_u32 s89, s89, 0
	s_cmp_gt_u32 s90, 13
	s_cbranch_scc0 .LBB0_1287
	s_and_b64 vcc, exec, s[44:45]
	s_cbranch_vccz .LBB0_1290
	s_barrier

; #define PG8_STAGE(bufoff, gbase, voff) do { _Pragma("unroll") for (int _i = 0; _i < 2; ++_i) \
;         __builtin_amdgcn_global_load_lds((const unsigned*)((const char*)(gbase) + (voff)[_i]), (PG8_LAS unsigned*)(lds + (bufoff) + ldsw + _i * 8192), 16, 0, 0); } while (0)
; #define PG8_LDA(dst, b, h) do { _Pragma("unroll") for (int m = 0; m < 4; ++m) _Pragma("unroll") for (int k = 0; k < 2; ++k) dst[m][k] = *(const PG8_LAS bf16x8*)(lds + PG8_SA(b, h) + aoff + m * 2048 + k * 1024); } while (0)
; #define PG8_LDB(dst, b, h) do { _Pragma("unroll") for (int n = 0; n < 2; ++n) _Pragma("unroll") for (int k = 0; k < 2; ++k) dst[n][k] = *(const PG8_LAS bf16x8*)(lds + PG8_SB(b, h) + boff + n * 2048 + k * 1024); } while (0)
; #define PG8_MMA(ai, bj, At, Bt) do { __builtin_amdgcn_s_setprio(1); _Pragma("unroll") for (int m = 0; m < 4; ++m) _Pragma("unroll") for (int n = 0; n < 2; ++n) _Pragma("unroll") for (int k = 0; k < 2; ++k) \
;         acc[ai][bj][m][n] = __builtin_amdgcn_mfma_f32_16x16x32_bf16(Bt[n][k], At[m][k], acc[ai][bj][m][n], 0, 0, 0); __builtin_amdgcn_s_setprio(0); } while (0)
; #define PG8_WAIT_V(n) asm volatile("s_waitcnt vmcnt(" #n ")" ::: "memory")
; #define PG8_WAIT_L(n) asm volatile("s_waitcnt lgkmcnt(" #n ")" ::: "memory")
; #define PG8_BAR __builtin_amdgcn_s_barrier()
; #define PG8_SCHED __builtin_amdgcn_sched_barrier(0)
; template <class Epi, class Sched, bool ALIGN_EPI = false, bool SP2 = false>
; __device__ __forceinline__ void gemm_phase(PG8_LAS unsigned char* lds, const Gemm g, const Sched& S, const Epi& E) {
;     ...
;         for (int t = 0; t < nt; t += 2) {
;             const bool last = (t == nt - 2);
;             const char* a1 = cA + (size_t)(t + 1) * kstep;
;             const char* a2 = last ? nA : cA + (size_t)(t + 2) * kstep; const char* b2 = last ? nB : cB + (size_t)(t + 2) * kstep;
;             const char* a3 = a2 + kstep; const char* b3 = b2 + kstep;
;             if (last && has_next) S.a_ready(nxt);
;             if constexpr (SP2) {
;             PG8_LDB(B0, 0, 0); PG8_LDB(B1, 0, 1); PG8_SCHED; PG8_LDA(At, 0, 0); PG8_STAGE(PG8_SA(1, 1), a1 + hstep, voffA);
;             PG8_WAIT_V(8); PG8_WAIT_L(0); PG8_BAR; PG8_MMA(0, 0, At, B0); PG8_MMA(0, 1, At, B1); PG8_BAR; PG8_SCHED;
;             PG8_LDA(At, 0, 1); PG8_STAGE(PG8_SB(0, 0), b2, voffB); PG8_STAGE(PG8_SB(0, 1), b2 + hstep, voffB); PG8_STAGE(PG8_SA(0, 0), a2, voffA);
.LBB0_1593:
	ds_read_b128 v[146:149], v152
	ds_read_b128 v[156:159], v152 offset:1024
	ds_read_b128 v[160:163], v152 offset:2048
	ds_read_b128 v[164:167], v152 offset:3072
	ds_read_b128 v[168:171], v153
	ds_read_b128 v[172:175], v153 offset:1024
	ds_read_b128 v[180:183], v153 offset:2048
	ds_read_b128 v[184:187], v153 offset:3072
	s_add_u32 s52, s50, 0xfffc0080
	s_addc_u32 s53, s51, -1
	s_cmp_eq_u32 s67, 12
	s_cselect_b32 s55, s39, s53
	s_cselect_b32 s54, s47, s52
	s_cselect_b32 s53, s37, s66
	s_cselect_b32 s52, s64, s65
	v_lshl_add_u64 v[200:201], s[50:51], 0, v[136:137]
	s_add_i32 m0, s33, 0xc000
	ds_read_b128 v[188:191], v154
	ds_read_b128 v[192:195], v154 offset:1024
	ds_read_b128 v[196:199], v154 offset:2048
	ds_read_b128 v[206:209], v154 offset:3072
	ds_read_b128 v[210:213], v154 offset:4096
	ds_read_b128 v[214:217], v154 offset:5120
	ds_read_b128 v[218:221], v154 offset:6144
	ds_read_b128 v[222:225], v154 offset:7168
	global_load_lds_dwordx4 v[200:201], off
	v_lshl_add_u64 v[200:201], s[50:51], 0, v[138:139]
	s_add_i32 m0, s33, 0xe000
	s_nop 0
	global_load_lds_dwordx4 v[200:201], off
	s_waitcnt vmcnt(8)
	s_waitcnt lgkmcnt(0)
	s_barrier
	s_setprio 1
	s_waitcnt lgkmcnt(0)
	v_mfma_f32_16x16x32_bf16 v[124:127], v[146:149], v[188:191], v[124:127]
	v_mfma_f32_16x16x32_bf16 v[120:123], v[160:163], v[188:191], v[120:123]
	v_mfma_f32_16x16x32_bf16 v[108:111], v[146:149], v[196:199], v[108:111]
	v_mfma_f32_16x16x32_bf16 v[104:107], v[160:163], v[196:199], v[104:107]
	v_mfma_f32_16x16x32_bf16 v[92:95], v[146:149], v[210:213], v[92:95]
	v_mfma_f32_16x16x32_bf16 v[88:91], v[160:163], v[210:213], v[88:91]
	v_mfma_f32_16x16x32_bf16 v[76:79], v[146:149], v[218:221], v[76:79]
	v_mfma_f32_16x16x32_bf16 v[72:75], v[160:163], v[218:221], v[72:75]
	v_mfma_f32_16x16x32_bf16 v[124:127], v[156:159], v[192:195], v[124:127]
	v_mfma_f32_16x16x32_bf16 v[120:123], v[164:167], v[192:195], v[120:123]
	v_mfma_f32_16x16x32_bf16 v[108:111], v[156:159], v[206:209], v[108:111]
	v_mfma_f32_16x16x32_bf16 v[104:107], v[164:167], v[206:209], v[104:107]
	v_mfma_f32_16x16x32_bf16 v[92:95], v[156:159], v[214:217], v[92:95]
	v_mfma_f32_16x16x32_bf16 v[88:91], v[164:167], v[214:217], v[88:91]
	v_mfma_f32_16x16x32_bf16 v[76:79], v[156:159], v[222:225], v[76:79]
	v_mfma_f32_16x16x32_bf16 v[72:75], v[164:167], v[222:225], v[72:75]
	s_setprio 0
	s_setprio 1
	v_mfma_f32_16x16x32_bf16 v[116:119], v[168:171], v[188:191], v[116:119]
	v_mfma_f32_16x16x32_bf16 v[112:115], v[180:183], v[188:191], v[112:115]
	v_mfma_f32_16x16x32_bf16 v[100:103], v[168:171], v[196:199], v[100:103]
	v_mfma_f32_16x16x32_bf16 v[96:99], v[180:183], v[196:199], v[96:99]
	v_mfma_f32_16x16x32_bf16 v[84:87], v[168:171], v[210:213], v[84:87]
	v_mfma_f32_16x16x32_bf16 v[80:83], v[180:183], v[210:213], v[80:83]
	v_mfma_f32_16x16x32_bf16 v[68:71], v[168:171], v[218:221], v[68:71]
	v_mfma_f32_16x16x32_bf16 v[64:67], v[180:183], v[218:221], v[64:67]
	v_mfma_f32_16x16x32_bf16 v[116:119], v[172:175], v[192:195], v[116:119]
	v_mfma_f32_16x16x32_bf16 v[112:115], v[184:187], v[192:195], v[112:115]
	v_mfma_f32_16x16x32_bf16 v[100:103], v[172:175], v[206:209], v[100:103]
	v_mfma_f32_16x16x32_bf16 v[96:99], v[184:187], v[206:209], v[96:99]
	v_mfma_f32_16x16x32_bf16 v[84:87], v[172:175], v[214:217], v[84:87]
	v_mfma_f32_16x16x32_bf16 v[80:83], v[184:187], v[214:217], v[80:83]
	v_mfma_f32_16x16x32_bf16 v[68:71], v[172:175], v[222:225], v[68:71]
	v_mfma_f32_16x16x32_bf16 v[64:67], v[184:187], v[222:225], v[64:67]
	s_setprio 0
	s_barrier
	s_add_i32 s74, s60, s15
	v_lshl_add_u64 v[200:201], s[52:53], 0, v[130:131]
	s_mov_b32 m0, s74
	ds_read_b128 v[188:191], v154 offset:16384
	ds_read_b128 v[192:195], v154 offset:17408
	ds_read_b128 v[196:199], v154 offset:18432
	ds_read_b128 v[206:209], v154 offset:19456
	ds_read_b128 v[210:213], v154 offset:20480
	ds_read_b128 v[214:217], v154 offset:21504
	ds_read_b128 v[218:221], v154 offset:22528
	ds_read_b128 v[222:225], v154 offset:23552
	global_load_lds_dwordx4 v[200:201], off
	s_add_i32 m0, s74, 0x2000
	s_add_u32 s74, s52, 0x40000
	v_lshl_add_u64 v[226:227], s[52:53], 0, v[134:135]
	s_addc_u32 s75, s53, 0
	s_add_i32 s76, s61, s15
	global_load_lds_dwordx4 v[226:227], off
	v_lshl_add_u64 v[228:229], s[74:75], 0, v[130:131]
	s_mov_b32 m0, s76
	global_load_lds_dwordx4 v[228:229], off
	v_lshl_add_u64 v[228:229], s[74:75], 0, v[134:135]
	s_add_i32 m0, s76, 0x2000
	s_nop 0
	global_load_lds_dwordx4 v[228:229], off
	s_waitcnt vmcnt(6)
	s_waitcnt lgkmcnt(0)
	s_barrier
; #define PG8_STAGE(bufoff, gbase, voff) do { _Pragma("unroll") for (int _i = 0; _i < 2; ++_i) \
;         __builtin_amdgcn_global_load_lds((const unsigned*)((const char*)(gbase) + (voff)[_i]), (PG8_LAS unsigned*)(lds + (bufoff) + ldsw + _i * 8192), 16, 0, 0); } while (0)
; #define PG8_LDA(dst, b, h) do { _Pragma("unroll") for (int m = 0; m < 4; ++m) _Pragma("unroll") for (int k = 0; k < 2; ++k) dst[m][k] = *(const PG8_LAS bf16x8*)(lds + PG8_SA(b, h) + aoff + m * 2048 + k * 1024); } while (0)
; #define PG8_LDB(dst, b, h) do { _Pragma("unroll") for (int n = 0; n < 2; ++n) _Pragma("unroll") for (int k = 0; k < 2; ++k) dst[n][k] = *(const PG8_LAS bf16x8*)(lds + PG8_SB(b, h) + boff + n * 2048 + k * 1024); } while (0)
; #define PG8_MMA(ai, bj, At, Bt) do { __builtin_amdgcn_s_setprio(1); _Pragma("unroll") for (int m = 0; m < 4; ++m) _Pragma("unroll") for (int n = 0; n < 2; ++n) _Pragma("unroll") for (int k = 0; k < 2; ++k) \
;         acc[ai][bj][m][n] = __builtin_amdgcn_mfma_f32_16x16x32_bf16(Bt[n][k], At[m][k], acc[ai][bj][m][n], 0, 0, 0); __builtin_amdgcn_s_setprio(0); } while (0)
; #define PG8_WAIT_V(n) asm volatile("s_waitcnt vmcnt(" #n ")" ::: "memory")
; #define PG8_WAIT_L(n) asm volatile("s_waitcnt lgkmcnt(" #n ")" ::: "memory")
; #define PG8_BAR __builtin_amdgcn_s_barrier()
; #define PG8_SCHED __builtin_amdgcn_sched_barrier(0)
; template <class Epi, class Sched, bool ALIGN_EPI = false, bool SP2 = false>
; __device__ __forceinline__ void gemm_phase(PG8_LAS unsigned char* lds, const Gemm g, const Sched& S, const Epi& E) {
;     ...
;             PG8_WAIT_V(8); PG8_WAIT_L(0); PG8_BAR; PG8_MMA(1, 0, At, B0); PG8_MMA(1, 1, At, B1); PG8_BAR; PG8_SCHED;
;             PG8_LDB(B0, 1, 0); PG8_LDB(B1, 1, 1); PG8_SCHED; PG8_LDA(At, 1, 0); PG8_STAGE(PG8_SA(0, 1), a2 + hstep, voffA);
;             PG8_WAIT_V(8); PG8_WAIT_L(0); PG8_BAR; PG8_MMA(0, 0, At, B0); PG8_MMA(0, 1, At, B1); PG8_BAR; PG8_SCHED;
	s_setprio 1
	s_waitcnt lgkmcnt(0)
	v_mfma_f32_16x16x32_bf16 v[60:63], v[146:149], v[188:191], v[60:63]
	v_mfma_f32_16x16x32_bf16 v[56:59], v[160:163], v[188:191], v[56:59]
	v_mfma_f32_16x16x32_bf16 v[44:47], v[146:149], v[196:199], v[44:47]
	v_mfma_f32_16x16x32_bf16 v[40:43], v[160:163], v[196:199], v[40:43]
	v_mfma_f32_16x16x32_bf16 v[28:31], v[146:149], v[210:213], v[28:31]
	v_mfma_f32_16x16x32_bf16 v[24:27], v[160:163], v[210:213], v[24:27]
	v_mfma_f32_16x16x32_bf16 v[12:15], v[146:149], v[218:221], v[12:15]
	v_mfma_f32_16x16x32_bf16 v[8:11], v[160:163], v[218:221], v[8:11]
	v_mfma_f32_16x16x32_bf16 v[60:63], v[156:159], v[192:195], v[60:63]
	v_mfma_f32_16x16x32_bf16 v[56:59], v[164:167], v[192:195], v[56:59]
	v_mfma_f32_16x16x32_bf16 v[44:47], v[156:159], v[206:209], v[44:47]
	v_mfma_f32_16x16x32_bf16 v[40:43], v[164:167], v[206:209], v[40:43]
	v_mfma_f32_16x16x32_bf16 v[28:31], v[156:159], v[214:217], v[28:31]
	v_mfma_f32_16x16x32_bf16 v[24:27], v[164:167], v[214:217], v[24:27]
	v_lshl_add_u64 v[228:229], s[54:55], 0, v[128:129]
	s_mov_b32 m0, s33
	s_nop 0
	global_load_lds_dwordx4 v[228:229], off
	v_mfma_f32_16x16x32_bf16 v[12:15], v[156:159], v[222:225], v[12:15]
	v_mfma_f32_16x16x32_bf16 v[8:11], v[164:167], v[222:225], v[8:11]
	s_setprio 0
	s_setprio 1
	v_mfma_f32_16x16x32_bf16 v[52:55], v[168:171], v[188:191], v[52:55]
	v_mfma_f32_16x16x32_bf16 v[48:51], v[180:183], v[188:191], v[48:51]
	v_mfma_f32_16x16x32_bf16 v[36:39], v[168:171], v[196:199], v[36:39]
	v_mfma_f32_16x16x32_bf16 v[32:35], v[180:183], v[196:199], v[32:35]
	v_mfma_f32_16x16x32_bf16 v[20:23], v[168:171], v[210:213], v[20:23]
	v_mfma_f32_16x16x32_bf16 v[16:19], v[180:183], v[210:213], v[16:19]
	v_mfma_f32_16x16x32_bf16 v[4:7], v[168:171], v[218:221], v[4:7]
	v_mfma_f32_16x16x32_bf16 v[0:3], v[180:183], v[218:221], v[0:3]
	v_mfma_f32_16x16x32_bf16 v[52:55], v[172:175], v[192:195], v[52:55]
	v_mfma_f32_16x16x32_bf16 v[48:51], v[184:187], v[192:195], v[48:51]
	v_mfma_f32_16x16x32_bf16 v[36:39], v[172:175], v[206:209], v[36:39]
	v_mfma_f32_16x16x32_bf16 v[32:35], v[184:187], v[206:209], v[32:35]
	v_mfma_f32_16x16x32_bf16 v[20:23], v[172:175], v[214:217], v[20:23]
	v_mfma_f32_16x16x32_bf16 v[16:19], v[184:187], v[214:217], v[16:19]
	v_lshl_add_u64 v[230:231], s[54:55], 0, v[132:133]
	s_mov_b32 m0, s34
	s_nop 0
	global_load_lds_dwordx4 v[230:231], off
	v_mfma_f32_16x16x32_bf16 v[4:7], v[172:175], v[222:225], v[4:7]
	v_mfma_f32_16x16x32_bf16 v[0:3], v[184:187], v[222:225], v[0:3]
	s_setprio 0
	s_barrier
	s_add_i32 s74, 0, 0x18000
	s_add_i32 s75, 0, 0x1c000
	v_add_u32_e32 v164, s74, v150
	v_add_u32_e32 v179, s75, v150
	ds_read_b128 v[146:149], v164
	ds_read_b128 v[156:159], v164 offset:1024
	ds_read_b128 v[160:163], v164 offset:2048
	ds_read_b128 v[164:167], v164 offset:3072
	ds_read_b128 v[168:171], v179
	ds_read_b128 v[172:175], v179 offset:1024
	ds_read_b128 v[180:183], v179 offset:2048
	ds_read_b128 v[184:187], v179 offset:3072
	s_add_u32 s54, s54, 0x40000
	s_addc_u32 s55, s55, 0
	s_mov_b32 m0, s49
	v_lshl_add_u64 v[232:233], s[54:55], 0, v[128:129]
	ds_read_b128 v[188:191], v154 offset:32768
	ds_read_b128 v[192:195], v154 offset:33792
	ds_read_b128 v[196:199], v154 offset:34816
	ds_read_b128 v[206:209], v154 offset:35840
	ds_read_b128 v[210:213], v154 offset:36864
	ds_read_b128 v[214:217], v154 offset:37888
	ds_read_b128 v[218:221], v154 offset:38912
	ds_read_b128 v[222:225], v154 offset:39936
	global_load_lds_dwordx4 v[232:233], off
	v_lshl_add_u64 v[232:233], s[54:55], 0, v[132:133]
	s_mov_b32 m0, s56
	s_nop 0
	global_load_lds_dwordx4 v[232:233], off
	s_waitcnt vmcnt(8)
	s_waitcnt lgkmcnt(0)
	s_barrier
	s_setprio 1
	s_waitcnt lgkmcnt(0)
	v_mfma_f32_16x16x32_bf16 v[124:127], v[146:149], v[188:191], v[124:127]
	v_mfma_f32_16x16x32_bf16 v[120:123], v[160:163], v[188:191], v[120:123]
	v_mfma_f32_16x16x32_bf16 v[108:111], v[146:149], v[196:199], v[108:111]
	v_mfma_f32_16x16x32_bf16 v[104:107], v[160:163], v[196:199], v[104:107]
	v_mfma_f32_16x16x32_bf16 v[92:95], v[146:149], v[210:213], v[92:95]
	v_mfma_f32_16x16x32_bf16 v[88:91], v[160:163], v[210:213], v[88:91]
	v_mfma_f32_16x16x32_bf16 v[76:79], v[146:149], v[218:221], v[76:79]
	v_mfma_f32_16x16x32_bf16 v[72:75], v[160:163], v[218:221], v[72:75]
	v_mfma_f32_16x16x32_bf16 v[124:127], v[156:159], v[192:195], v[124:127]
	v_mfma_f32_16x16x32_bf16 v[120:123], v[164:167], v[192:195], v[120:123]
	v_mfma_f32_16x16x32_bf16 v[108:111], v[156:159], v[206:209], v[108:111]
	v_mfma_f32_16x16x32_bf16 v[104:107], v[164:167], v[206:209], v[104:107]
	v_mfma_f32_16x16x32_bf16 v[92:95], v[156:159], v[214:217], v[92:95]
	v_mfma_f32_16x16x32_bf16 v[88:91], v[164:167], v[214:217], v[88:91]
	v_mfma_f32_16x16x32_bf16 v[76:79], v[156:159], v[222:225], v[76:79]
	v_mfma_f32_16x16x32_bf16 v[72:75], v[164:167], v[222:225], v[72:75]
	s_setprio 0
	s_setprio 1
	v_mfma_f32_16x16x32_bf16 v[116:119], v[168:171], v[188:191], v[116:119]
	v_mfma_f32_16x16x32_bf16 v[112:115], v[180:183], v[188:191], v[112:115]
	v_mfma_f32_16x16x32_bf16 v[100:103], v[168:171], v[196:199], v[100:103]
	v_mfma_f32_16x16x32_bf16 v[96:99], v[180:183], v[196:199], v[96:99]
	v_mfma_f32_16x16x32_bf16 v[84:87], v[168:171], v[210:213], v[84:87]
	v_mfma_f32_16x16x32_bf16 v[80:83], v[180:183], v[210:213], v[80:83]
	v_mfma_f32_16x16x32_bf16 v[68:71], v[168:171], v[218:221], v[68:71]
	v_mfma_f32_16x16x32_bf16 v[64:67], v[180:183], v[218:221], v[64:67]
	v_mfma_f32_16x16x32_bf16 v[116:119], v[172:175], v[192:195], v[116:119]
	v_mfma_f32_16x16x32_bf16 v[112:115], v[184:187], v[192:195], v[112:115]
	v_mfma_f32_16x16x32_bf16 v[100:103], v[172:175], v[206:209], v[100:103]
	v_mfma_f32_16x16x32_bf16 v[96:99], v[184:187], v[206:209], v[96:99]
	v_mfma_f32_16x16x32_bf16 v[84:87], v[172:175], v[214:217], v[84:87]
	v_mfma_f32_16x16x32_bf16 v[80:83], v[184:187], v[214:217], v[80:83]
	v_mfma_f32_16x16x32_bf16 v[68:71], v[172:175], v[222:225], v[68:71]
	v_mfma_f32_16x16x32_bf16 v[64:67], v[184:187], v[222:225], v[64:67]
	s_setprio 0
	s_barrier
; #define PG8_STAGE(bufoff, gbase, voff) do { _Pragma("unroll") for (int _i = 0; _i < 2; ++_i) \
;         __builtin_amdgcn_global_load_lds((const unsigned*)((const char*)(gbase) + (voff)[_i]), (PG8_LAS unsigned*)(lds + (bufoff) + ldsw + _i * 8192), 16, 0, 0); } while (0)
; #define PG8_LDA(dst, b, h) do { _Pragma("unroll") for (int m = 0; m < 4; ++m) _Pragma("unroll") for (int k = 0; k < 2; ++k) dst[m][k] = *(const PG8_LAS bf16x8*)(lds + PG8_SA(b, h) + aoff + m * 2048 + k * 1024); } while (0)
; #define PG8_MMA(ai, bj, At, Bt) do { __builtin_amdgcn_s_setprio(1); _Pragma("unroll") for (int m = 0; m < 4; ++m) _Pragma("unroll") for (int n = 0; n < 2; ++n) _Pragma("unroll") for (int k = 0; k < 2; ++k) \
;         acc[ai][bj][m][n] = __builtin_amdgcn_mfma_f32_16x16x32_bf16(Bt[n][k], At[m][k], acc[ai][bj][m][n], 0, 0, 0); __builtin_amdgcn_s_setprio(0); } while (0)
; #define PG8_WAIT_V(n) asm volatile("s_waitcnt vmcnt(" #n ")" ::: "memory")
; #define PG8_WAIT_L(n) asm volatile("s_waitcnt lgkmcnt(" #n ")" ::: "memory")
; #define PG8_BAR __builtin_amdgcn_s_barrier()
; #define PG8_SCHED __builtin_amdgcn_sched_barrier(0)
; template <class Epi, class Sched, bool ALIGN_EPI = false, bool SP2 = false>
; __device__ __forceinline__ void gemm_phase(PG8_LAS unsigned char* lds, const Gemm g, const Sched& S, const Epi& E) {
;     ...
;             PG8_LDA(At, 1, 1); PG8_STAGE(PG8_SB(1, 0), b3, voffB); PG8_STAGE(PG8_SB(1, 1), b3 + hstep, voffB); PG8_STAGE(PG8_SA(1, 0), a3, voffA);
;             PG8_WAIT_V(8); PG8_WAIT_L(0); PG8_BAR; PG8_MMA(1, 0, At, B0); PG8_MMA(1, 1, At, B1); PG8_BAR; PG8_SCHED;
	s_add_i32 s54, s74, s15
	v_lshl_add_u64 v[200:201], v[200:201], 0, s[26:27]
	s_mov_b32 m0, s54
	ds_read_b128 v[188:191], v154 offset:49152
	ds_read_b128 v[192:195], v154 offset:50176
	ds_read_b128 v[196:199], v154 offset:51200
	ds_read_b128 v[206:209], v154 offset:52224
	ds_read_b128 v[210:213], v154 offset:53248
	ds_read_b128 v[214:217], v154 offset:54272
	ds_read_b128 v[218:221], v154 offset:55296
	ds_read_b128 v[222:225], v154 offset:56320
	global_load_lds_dwordx4 v[200:201], off
	s_add_i32 m0, s54, 0x2000
	s_add_u32 s52, s52, 0x40080
	v_lshl_add_u64 v[200:201], v[226:227], 0, s[26:27]
	s_addc_u32 s53, s53, 0
	s_add_i32 s54, s75, s15
	global_load_lds_dwordx4 v[200:201], off
	v_lshl_add_u64 v[200:201], s[52:53], 0, v[130:131]
	s_mov_b32 m0, s54
	s_nop 0
	global_load_lds_dwordx4 v[200:201], off
	v_lshl_add_u64 v[200:201], s[52:53], 0, v[134:135]
	s_add_i32 m0, s54, 0x2000
	s_nop 0
	global_load_lds_dwordx4 v[200:201], off
	s_waitcnt vmcnt(6)
	s_waitcnt lgkmcnt(0)
	s_barrier
	s_setprio 1
	s_waitcnt lgkmcnt(0)
	v_mfma_f32_16x16x32_bf16 v[60:63], v[146:149], v[188:191], v[60:63]
	v_mfma_f32_16x16x32_bf16 v[56:59], v[160:163], v[188:191], v[56:59]
	v_lshl_add_u64 v[200:201], v[228:229], 0, s[26:27]
	s_mov_b32 m0, s58
	s_nop 0
	global_load_lds_dwordx4 v[200:201], off
	v_mfma_f32_16x16x32_bf16 v[44:47], v[146:149], v[196:199], v[44:47]
	v_mfma_f32_16x16x32_bf16 v[40:43], v[160:163], v[196:199], v[40:43]
	v_mfma_f32_16x16x32_bf16 v[28:31], v[146:149], v[210:213], v[28:31]
	v_mfma_f32_16x16x32_bf16 v[24:27], v[160:163], v[210:213], v[24:27]
	v_lshl_add_u64 v[200:201], v[230:231], 0, s[26:27]
	s_mov_b32 m0, s59
	s_nop 0
	global_load_lds_dwordx4 v[200:201], off
	v_mfma_f32_16x16x32_bf16 v[12:15], v[146:149], v[218:221], v[12:15]
	v_mfma_f32_16x16x32_bf16 v[8:11], v[160:163], v[218:221], v[8:11]
	v_mfma_f32_16x16x32_bf16 v[60:63], v[156:159], v[192:195], v[60:63]
	v_mfma_f32_16x16x32_bf16 v[56:59], v[164:167], v[192:195], v[56:59]
	v_mfma_f32_16x16x32_bf16 v[44:47], v[156:159], v[206:209], v[44:47]
	v_mfma_f32_16x16x32_bf16 v[40:43], v[164:167], v[206:209], v[40:43]
	v_mfma_f32_16x16x32_bf16 v[28:31], v[156:159], v[214:217], v[28:31]
	v_mfma_f32_16x16x32_bf16 v[24:27], v[164:167], v[214:217], v[24:27]
	v_mfma_f32_16x16x32_bf16 v[12:15], v[156:159], v[222:225], v[12:15]
	v_mfma_f32_16x16x32_bf16 v[8:11], v[164:167], v[222:225], v[8:11]
	s_setprio 0
	s_setprio 1
	v_mfma_f32_16x16x32_bf16 v[52:55], v[168:171], v[188:191], v[52:55]
	v_mfma_f32_16x16x32_bf16 v[48:51], v[180:183], v[188:191], v[48:51]
	v_mfma_f32_16x16x32_bf16 v[36:39], v[168:171], v[196:199], v[36:39]
	v_mfma_f32_16x16x32_bf16 v[32:35], v[180:183], v[196:199], v[32:35]
	v_mfma_f32_16x16x32_bf16 v[20:23], v[168:171], v[210:213], v[20:23]
	v_mfma_f32_16x16x32_bf16 v[16:19], v[180:183], v[210:213], v[16:19]
	v_mfma_f32_16x16x32_bf16 v[4:7], v[168:171], v[218:221], v[4:7]
	v_mfma_f32_16x16x32_bf16 v[0:3], v[180:183], v[218:221], v[0:3]
	v_mfma_f32_16x16x32_bf16 v[52:55], v[172:175], v[192:195], v[52:55]
	v_mfma_f32_16x16x32_bf16 v[48:51], v[184:187], v[192:195], v[48:51]
	v_mfma_f32_16x16x32_bf16 v[36:39], v[172:175], v[206:209], v[36:39]
	v_mfma_f32_16x16x32_bf16 v[32:35], v[184:187], v[206:209], v[32:35]
	v_mfma_f32_16x16x32_bf16 v[20:23], v[172:175], v[214:217], v[20:23]
	v_mfma_f32_16x16x32_bf16 v[16:19], v[184:187], v[214:217], v[16:19]
	v_mfma_f32_16x16x32_bf16 v[4:7], v[172:175], v[222:225], v[4:7]
	v_mfma_f32_16x16x32_bf16 v[0:3], v[184:187], v[222:225], v[0:3]
	s_setprio 0
	s_barrier
	s_add_i32 s67, s67, 2
	s_add_u32 s50, s50, 0x100
	s_addc_u32 s51, s51, 0
	s_add_u32 s65, s65, 0x100
	s_addc_u32 s66, s66, 0
	s_cmp_gt_u32 s67, 13
	s_cbranch_scc0 .LBB0_1593
	s_and_b64 vcc, exec, s[28:29]
	s_cbranch_vccz .LBB0_1596
	s_barrier

; #define PG8_STAGE(bufoff, gbase, voff) do { _Pragma("unroll") for (int _i = 0; _i < 2; ++_i) \
;         __builtin_amdgcn_global_load_lds((const unsigned*)((const char*)(gbase) + (voff)[_i]), (PG8_LAS unsigned*)(lds + (bufoff) + ldsw + _i * 8192), 16, 0, 0); } while (0)
; #define PG8_LDA(dst, b, h) do { _Pragma("unroll") for (int m = 0; m < 4; ++m) _Pragma("unroll") for (int k = 0; k < 2; ++k) dst[m][k] = *(const PG8_LAS bf16x8*)(lds + PG8_SA(b, h) + aoff + m * 2048 + k * 1024); } while (0)
; #define PG8_LDB(dst, b, h) do { _Pragma("unroll") for (int n = 0; n < 2; ++n) _Pragma("unroll") for (int k = 0; k < 2; ++k) dst[n][k] = *(const PG8_LAS bf16x8*)(lds + PG8_SB(b, h) + boff + n * 2048 + k * 1024); } while (0)
; #define PG8_MMA(ai, bj, At, Bt) do { __builtin_amdgcn_s_setprio(1); _Pragma("unroll") for (int m = 0; m < 4; ++m) _Pragma("unroll") for (int n = 0; n < 2; ++n) _Pragma("unroll") for (int k = 0; k < 2; ++k) \
;         acc[ai][bj][m][n] = __builtin_amdgcn_mfma_f32_16x16x32_bf16(Bt[n][k], At[m][k], acc[ai][bj][m][n], 0, 0, 0); __builtin_amdgcn_s_setprio(0); } while (0)
; #define PG8_WAIT_V(n) asm volatile("s_waitcnt vmcnt(" #n ")" ::: "memory")
; #define PG8_WAIT_L(n) asm volatile("s_waitcnt lgkmcnt(" #n ")" ::: "memory")
; #define PG8_BAR __builtin_amdgcn_s_barrier()
; #define PG8_SCHED __builtin_amdgcn_sched_barrier(0)
; template <class Epi, class Sched, bool ALIGN_EPI = false, bool SP2 = false>
; __device__ __forceinline__ void gemm_phase(PG8_LAS unsigned char* lds, const Gemm g, const Sched& S, const Epi& E) {
;     ...
;         for (int t = 0; t < nt; t += 2) {
;             const bool last = (t == nt - 2);
;             const char* a1 = cA + (size_t)(t + 1) * kstep;
;             const char* a2 = last ? nA : cA + (size_t)(t + 2) * kstep; const char* b2 = last ? nB : cB + (size_t)(t + 2) * kstep;
;             const char* a3 = a2 + kstep; const char* b3 = b2 + kstep;
;             if (last && has_next) S.a_ready(nxt);
;             if constexpr (SP2) {
;             PG8_LDB(B0, 0, 0); PG8_LDB(B1, 0, 1); PG8_SCHED; PG8_LDA(At, 0, 0); PG8_STAGE(PG8_SA(1, 1), a1 + hstep, voffA);
;             PG8_WAIT_V(8); PG8_WAIT_L(0); PG8_BAR; PG8_MMA(0, 0, At, B0); PG8_MMA(0, 1, At, B1); PG8_BAR; PG8_SCHED;
;             PG8_LDA(At, 0, 1); PG8_STAGE(PG8_SB(0, 0), b2, voffB); PG8_STAGE(PG8_SB(0, 1), b2 + hstep, voffB); PG8_STAGE(PG8_SA(0, 0), a2, voffA);
.LBB0_1681:
	ds_read_b128 v[146:149], v152
	ds_read_b128 v[156:159], v152 offset:1024
	ds_read_b128 v[160:163], v152 offset:2048
	ds_read_b128 v[164:167], v152 offset:3072
	ds_read_b128 v[168:171], v153
	ds_read_b128 v[172:175], v153 offset:1024
	ds_read_b128 v[180:183], v153 offset:2048
	ds_read_b128 v[184:187], v153 offset:3072
	s_add_u32 s54, s52, 0xfffc0080
	s_addc_u32 s55, s53, -1
	s_cmp_eq_u32 s81, 12
	s_cselect_b32 s57, s47, s55
	s_cselect_b32 s56, s77, s54
	s_cselect_b32 s55, s45, s80
	s_cselect_b32 s54, s78, s79
	v_lshl_add_u64 v[200:201], s[52:53], 0, v[136:137]
	s_add_i32 m0, s58, 0xc000
	ds_read_b128 v[188:191], v154
	ds_read_b128 v[192:195], v154 offset:1024
	ds_read_b128 v[196:199], v154 offset:2048
	ds_read_b128 v[206:209], v154 offset:3072
	ds_read_b128 v[210:213], v154 offset:4096
	ds_read_b128 v[214:217], v154 offset:5120
	ds_read_b128 v[218:221], v154 offset:6144
	ds_read_b128 v[222:225], v154 offset:7168
	global_load_lds_dwordx4 v[200:201], off
	v_lshl_add_u64 v[200:201], s[52:53], 0, v[138:139]
	s_add_i32 m0, s58, 0xe000
	s_nop 0
	global_load_lds_dwordx4 v[200:201], off
	s_waitcnt vmcnt(8)
	s_waitcnt lgkmcnt(0)
	s_barrier
	s_setprio 1
	s_waitcnt lgkmcnt(0)
	v_mfma_f32_16x16x32_bf16 v[124:127], v[146:149], v[188:191], v[124:127]
	v_mfma_f32_16x16x32_bf16 v[120:123], v[160:163], v[188:191], v[120:123]
	v_mfma_f32_16x16x32_bf16 v[108:111], v[146:149], v[196:199], v[108:111]
	v_mfma_f32_16x16x32_bf16 v[104:107], v[160:163], v[196:199], v[104:107]
	v_mfma_f32_16x16x32_bf16 v[92:95], v[146:149], v[210:213], v[92:95]
	v_mfma_f32_16x16x32_bf16 v[88:91], v[160:163], v[210:213], v[88:91]
	v_mfma_f32_16x16x32_bf16 v[76:79], v[146:149], v[218:221], v[76:79]
	v_mfma_f32_16x16x32_bf16 v[72:75], v[160:163], v[218:221], v[72:75]
	v_mfma_f32_16x16x32_bf16 v[124:127], v[156:159], v[192:195], v[124:127]
	v_mfma_f32_16x16x32_bf16 v[120:123], v[164:167], v[192:195], v[120:123]
	v_mfma_f32_16x16x32_bf16 v[108:111], v[156:159], v[206:209], v[108:111]
	v_mfma_f32_16x16x32_bf16 v[104:107], v[164:167], v[206:209], v[104:107]
	v_mfma_f32_16x16x32_bf16 v[92:95], v[156:159], v[214:217], v[92:95]
	v_mfma_f32_16x16x32_bf16 v[88:91], v[164:167], v[214:217], v[88:91]
	v_mfma_f32_16x16x32_bf16 v[76:79], v[156:159], v[222:225], v[76:79]
	v_mfma_f32_16x16x32_bf16 v[72:75], v[164:167], v[222:225], v[72:75]
	s_setprio 0
	s_setprio 1
	v_mfma_f32_16x16x32_bf16 v[116:119], v[168:171], v[188:191], v[116:119]
	v_mfma_f32_16x16x32_bf16 v[112:115], v[180:183], v[188:191], v[112:115]
	v_mfma_f32_16x16x32_bf16 v[100:103], v[168:171], v[196:199], v[100:103]
	v_mfma_f32_16x16x32_bf16 v[96:99], v[180:183], v[196:199], v[96:99]
	v_mfma_f32_16x16x32_bf16 v[84:87], v[168:171], v[210:213], v[84:87]
	v_mfma_f32_16x16x32_bf16 v[80:83], v[180:183], v[210:213], v[80:83]
	v_mfma_f32_16x16x32_bf16 v[68:71], v[168:171], v[218:221], v[68:71]
	v_mfma_f32_16x16x32_bf16 v[64:67], v[180:183], v[218:221], v[64:67]
	v_mfma_f32_16x16x32_bf16 v[116:119], v[172:175], v[192:195], v[116:119]
	v_mfma_f32_16x16x32_bf16 v[112:115], v[184:187], v[192:195], v[112:115]
	v_mfma_f32_16x16x32_bf16 v[100:103], v[172:175], v[206:209], v[100:103]
	v_mfma_f32_16x16x32_bf16 v[96:99], v[184:187], v[206:209], v[96:99]
	v_mfma_f32_16x16x32_bf16 v[84:87], v[172:175], v[214:217], v[84:87]
	v_mfma_f32_16x16x32_bf16 v[80:83], v[184:187], v[214:217], v[80:83]
	v_mfma_f32_16x16x32_bf16 v[68:71], v[172:175], v[222:225], v[68:71]
	v_mfma_f32_16x16x32_bf16 v[64:67], v[184:187], v[222:225], v[64:67]
	s_setprio 0
	s_barrier
	s_add_i32 s82, s65, s34
	v_lshl_add_u64 v[200:201], s[54:55], 0, v[132:133]
	s_mov_b32 m0, s82
	ds_read_b128 v[188:191], v154 offset:16384
	ds_read_b128 v[192:195], v154 offset:17408
	ds_read_b128 v[196:199], v154 offset:18432
	ds_read_b128 v[206:209], v154 offset:19456
	ds_read_b128 v[210:213], v154 offset:20480
	ds_read_b128 v[214:217], v154 offset:21504
	ds_read_b128 v[218:221], v154 offset:22528
	ds_read_b128 v[222:225], v154 offset:23552
	global_load_lds_dwordx4 v[200:201], off
	s_add_i32 m0, s82, 0x2000
	s_add_u32 s82, s54, 0x40000
	v_lshl_add_u64 v[226:227], s[54:55], 0, v[128:129]
	s_addc_u32 s83, s55, 0
	s_add_i32 s84, s66, s34
	global_load_lds_dwordx4 v[226:227], off
	v_lshl_add_u64 v[228:229], s[82:83], 0, v[132:133]
	s_mov_b32 m0, s84
	global_load_lds_dwordx4 v[228:229], off
	v_lshl_add_u64 v[228:229], s[82:83], 0, v[128:129]
	s_add_i32 m0, s84, 0x2000
	s_nop 0
	global_load_lds_dwordx4 v[228:229], off
	s_waitcnt vmcnt(6)
	s_waitcnt lgkmcnt(0)
	s_barrier
; #define PG8_STAGE(bufoff, gbase, voff) do { _Pragma("unroll") for (int _i = 0; _i < 2; ++_i) \
;         __builtin_amdgcn_global_load_lds((const unsigned*)((const char*)(gbase) + (voff)[_i]), (PG8_LAS unsigned*)(lds + (bufoff) + ldsw + _i * 8192), 16, 0, 0); } while (0)
; #define PG8_LDA(dst, b, h) do { _Pragma("unroll") for (int m = 0; m < 4; ++m) _Pragma("unroll") for (int k = 0; k < 2; ++k) dst[m][k] = *(const PG8_LAS bf16x8*)(lds + PG8_SA(b, h) + aoff + m * 2048 + k * 1024); } while (0)
; #define PG8_LDB(dst, b, h) do { _Pragma("unroll") for (int n = 0; n < 2; ++n) _Pragma("unroll") for (int k = 0; k < 2; ++k) dst[n][k] = *(const PG8_LAS bf16x8*)(lds + PG8_SB(b, h) + boff + n * 2048 + k * 1024); } while (0)
; #define PG8_MMA(ai, bj, At, Bt) do { __builtin_amdgcn_s_setprio(1); _Pragma("unroll") for (int m = 0; m < 4; ++m) _Pragma("unroll") for (int n = 0; n < 2; ++n) _Pragma("unroll") for (int k = 0; k < 2; ++k) \
;         acc[ai][bj][m][n] = __builtin_amdgcn_mfma_f32_16x16x32_bf16(Bt[n][k], At[m][k], acc[ai][bj][m][n], 0, 0, 0); __builtin_amdgcn_s_setprio(0); } while (0)
; #define PG8_WAIT_V(n) asm volatile("s_waitcnt vmcnt(" #n ")" ::: "memory")
; #define PG8_WAIT_L(n) asm volatile("s_waitcnt lgkmcnt(" #n ")" ::: "memory")
; #define PG8_BAR __builtin_amdgcn_s_barrier()
; #define PG8_SCHED __builtin_amdgcn_sched_barrier(0)
; template <class Epi, class Sched, bool ALIGN_EPI = false, bool SP2 = false>
; __device__ __forceinline__ void gemm_phase(PG8_LAS unsigned char* lds, const Gemm g, const Sched& S, const Epi& E) {
;     ...
;             PG8_WAIT_V(8); PG8_WAIT_L(0); PG8_BAR; PG8_MMA(1, 0, At, B0); PG8_MMA(1, 1, At, B1); PG8_BAR; PG8_SCHED;
;             PG8_LDB(B0, 1, 0); PG8_LDB(B1, 1, 1); PG8_SCHED; PG8_LDA(At, 1, 0); PG8_STAGE(PG8_SA(0, 1), a2 + hstep, voffA);
;             PG8_WAIT_V(8); PG8_WAIT_L(0); PG8_BAR; PG8_MMA(0, 0, At, B0); PG8_MMA(0, 1, At, B1); PG8_BAR; PG8_SCHED;
	s_setprio 1
	s_waitcnt lgkmcnt(0)
	v_mfma_f32_16x16x32_bf16 v[60:63], v[146:149], v[188:191], v[60:63]
	v_mfma_f32_16x16x32_bf16 v[56:59], v[160:163], v[188:191], v[56:59]
	v_mfma_f32_16x16x32_bf16 v[44:47], v[146:149], v[196:199], v[44:47]
	v_mfma_f32_16x16x32_bf16 v[40:43], v[160:163], v[196:199], v[40:43]
	v_mfma_f32_16x16x32_bf16 v[28:31], v[146:149], v[210:213], v[28:31]
	v_mfma_f32_16x16x32_bf16 v[24:27], v[160:163], v[210:213], v[24:27]
	v_mfma_f32_16x16x32_bf16 v[12:15], v[146:149], v[218:221], v[12:15]
	v_mfma_f32_16x16x32_bf16 v[8:11], v[160:163], v[218:221], v[8:11]
	v_mfma_f32_16x16x32_bf16 v[60:63], v[156:159], v[192:195], v[60:63]
	v_mfma_f32_16x16x32_bf16 v[56:59], v[164:167], v[192:195], v[56:59]
	v_mfma_f32_16x16x32_bf16 v[44:47], v[156:159], v[206:209], v[44:47]
	v_mfma_f32_16x16x32_bf16 v[40:43], v[164:167], v[206:209], v[40:43]
	v_mfma_f32_16x16x32_bf16 v[28:31], v[156:159], v[214:217], v[28:31]
	v_mfma_f32_16x16x32_bf16 v[24:27], v[164:167], v[214:217], v[24:27]
	v_lshl_add_u64 v[228:229], s[56:57], 0, v[134:135]
	s_mov_b32 m0, s58
	s_nop 0
	global_load_lds_dwordx4 v[228:229], off
	v_mfma_f32_16x16x32_bf16 v[12:15], v[156:159], v[222:225], v[12:15]
	v_mfma_f32_16x16x32_bf16 v[8:11], v[164:167], v[222:225], v[8:11]
	s_setprio 0
	s_setprio 1
	v_mfma_f32_16x16x32_bf16 v[52:55], v[168:171], v[188:191], v[52:55]
	v_mfma_f32_16x16x32_bf16 v[48:51], v[180:183], v[188:191], v[48:51]
	v_mfma_f32_16x16x32_bf16 v[36:39], v[168:171], v[196:199], v[36:39]
	v_mfma_f32_16x16x32_bf16 v[32:35], v[180:183], v[196:199], v[32:35]
	v_mfma_f32_16x16x32_bf16 v[20:23], v[168:171], v[210:213], v[20:23]
	v_mfma_f32_16x16x32_bf16 v[16:19], v[180:183], v[210:213], v[16:19]
	v_mfma_f32_16x16x32_bf16 v[4:7], v[168:171], v[218:221], v[4:7]
	v_mfma_f32_16x16x32_bf16 v[0:3], v[180:183], v[218:221], v[0:3]
	v_mfma_f32_16x16x32_bf16 v[52:55], v[172:175], v[192:195], v[52:55]
	v_mfma_f32_16x16x32_bf16 v[48:51], v[184:187], v[192:195], v[48:51]
	v_mfma_f32_16x16x32_bf16 v[36:39], v[172:175], v[206:209], v[36:39]
	v_mfma_f32_16x16x32_bf16 v[32:35], v[184:187], v[206:209], v[32:35]
	v_mfma_f32_16x16x32_bf16 v[20:23], v[172:175], v[214:217], v[20:23]
	v_mfma_f32_16x16x32_bf16 v[16:19], v[184:187], v[214:217], v[16:19]
	v_lshl_add_u64 v[230:231], s[56:57], 0, v[130:131]
	s_mov_b32 m0, s59
	s_nop 0
	global_load_lds_dwordx4 v[230:231], off
	v_mfma_f32_16x16x32_bf16 v[4:7], v[172:175], v[222:225], v[4:7]
	v_mfma_f32_16x16x32_bf16 v[0:3], v[184:187], v[222:225], v[0:3]
	s_setprio 0
	s_barrier
	s_add_i32 s82, 0, 0x18000
	s_add_i32 s83, 0, 0x1c000
	v_add_u32_e32 v164, s82, v150
	v_add_u32_e32 v179, s83, v150
	ds_read_b128 v[146:149], v164
	ds_read_b128 v[156:159], v164 offset:1024
	ds_read_b128 v[160:163], v164 offset:2048
	ds_read_b128 v[164:167], v164 offset:3072
	ds_read_b128 v[168:171], v179
	ds_read_b128 v[172:175], v179 offset:1024
	ds_read_b128 v[180:183], v179 offset:2048
	ds_read_b128 v[184:187], v179 offset:3072
	s_add_u32 s56, s56, 0x40000
	s_addc_u32 s57, s57, 0
	s_mov_b32 m0, s60
	v_lshl_add_u64 v[232:233], s[56:57], 0, v[134:135]
	ds_read_b128 v[188:191], v154 offset:32768
	ds_read_b128 v[192:195], v154 offset:33792
	ds_read_b128 v[196:199], v154 offset:34816
	ds_read_b128 v[206:209], v154 offset:35840
	ds_read_b128 v[210:213], v154 offset:36864
	ds_read_b128 v[214:217], v154 offset:37888
	ds_read_b128 v[218:221], v154 offset:38912
	ds_read_b128 v[222:225], v154 offset:39936
	global_load_lds_dwordx4 v[232:233], off
	v_lshl_add_u64 v[232:233], s[56:57], 0, v[130:131]
	s_mov_b32 m0, s61
	s_nop 0
	global_load_lds_dwordx4 v[232:233], off
	s_waitcnt vmcnt(8)
	s_waitcnt lgkmcnt(0)
	s_barrier
	s_setprio 1
	s_waitcnt lgkmcnt(0)
	v_mfma_f32_16x16x32_bf16 v[124:127], v[146:149], v[188:191], v[124:127]
	v_mfma_f32_16x16x32_bf16 v[120:123], v[160:163], v[188:191], v[120:123]
	v_mfma_f32_16x16x32_bf16 v[108:111], v[146:149], v[196:199], v[108:111]
	v_mfma_f32_16x16x32_bf16 v[104:107], v[160:163], v[196:199], v[104:107]
	v_mfma_f32_16x16x32_bf16 v[92:95], v[146:149], v[210:213], v[92:95]
	v_mfma_f32_16x16x32_bf16 v[88:91], v[160:163], v[210:213], v[88:91]
	v_mfma_f32_16x16x32_bf16 v[76:79], v[146:149], v[218:221], v[76:79]
	v_mfma_f32_16x16x32_bf16 v[72:75], v[160:163], v[218:221], v[72:75]
	v_mfma_f32_16x16x32_bf16 v[124:127], v[156:159], v[192:195], v[124:127]
	v_mfma_f32_16x16x32_bf16 v[120:123], v[164:167], v[192:195], v[120:123]
	v_mfma_f32_16x16x32_bf16 v[108:111], v[156:159], v[206:209], v[108:111]
	v_mfma_f32_16x16x32_bf16 v[104:107], v[164:167], v[206:209], v[104:107]
	v_mfma_f32_16x16x32_bf16 v[92:95], v[156:159], v[214:217], v[92:95]
	v_mfma_f32_16x16x32_bf16 v[88:91], v[164:167], v[214:217], v[88:91]
	v_mfma_f32_16x16x32_bf16 v[76:79], v[156:159], v[222:225], v[76:79]
	v_mfma_f32_16x16x32_bf16 v[72:75], v[164:167], v[222:225], v[72:75]
	s_setprio 0
	s_setprio 1
	v_mfma_f32_16x16x32_bf16 v[116:119], v[168:171], v[188:191], v[116:119]
	v_mfma_f32_16x16x32_bf16 v[112:115], v[180:183], v[188:191], v[112:115]
	v_mfma_f32_16x16x32_bf16 v[100:103], v[168:171], v[196:199], v[100:103]
	v_mfma_f32_16x16x32_bf16 v[96:99], v[180:183], v[196:199], v[96:99]
	v_mfma_f32_16x16x32_bf16 v[84:87], v[168:171], v[210:213], v[84:87]
	v_mfma_f32_16x16x32_bf16 v[80:83], v[180:183], v[210:213], v[80:83]
	v_mfma_f32_16x16x32_bf16 v[68:71], v[168:171], v[218:221], v[68:71]
	v_mfma_f32_16x16x32_bf16 v[64:67], v[180:183], v[218:221], v[64:67]
	v_mfma_f32_16x16x32_bf16 v[116:119], v[172:175], v[192:195], v[116:119]
	v_mfma_f32_16x16x32_bf16 v[112:115], v[184:187], v[192:195], v[112:115]
	v_mfma_f32_16x16x32_bf16 v[100:103], v[172:175], v[206:209], v[100:103]
	v_mfma_f32_16x16x32_bf16 v[96:99], v[184:187], v[206:209], v[96:99]
	v_mfma_f32_16x16x32_bf16 v[84:87], v[172:175], v[214:217], v[84:87]
	v_mfma_f32_16x16x32_bf16 v[80:83], v[184:187], v[214:217], v[80:83]
	v_mfma_f32_16x16x32_bf16 v[68:71], v[172:175], v[222:225], v[68:71]
	v_mfma_f32_16x16x32_bf16 v[64:67], v[184:187], v[222:225], v[64:67]
	s_setprio 0
	s_barrier
; #define PG8_STAGE(bufoff, gbase, voff) do { _Pragma("unroll") for (int _i = 0; _i < 2; ++_i) \
;         __builtin_amdgcn_global_load_lds((const unsigned*)((const char*)(gbase) + (voff)[_i]), (PG8_LAS unsigned*)(lds + (bufoff) + ldsw + _i * 8192), 16, 0, 0); } while (0)
; #define PG8_LDA(dst, b, h) do { _Pragma("unroll") for (int m = 0; m < 4; ++m) _Pragma("unroll") for (int k = 0; k < 2; ++k) dst[m][k] = *(const PG8_LAS bf16x8*)(lds + PG8_SA(b, h) + aoff + m * 2048 + k * 1024); } while (0)
; #define PG8_MMA(ai, bj, At, Bt) do { __builtin_amdgcn_s_setprio(1); _Pragma("unroll") for (int m = 0; m < 4; ++m) _Pragma("unroll") for (int n = 0; n < 2; ++n) _Pragma("unroll") for (int k = 0; k < 2; ++k) \
;         acc[ai][bj][m][n] = __builtin_amdgcn_mfma_f32_16x16x32_bf16(Bt[n][k], At[m][k], acc[ai][bj][m][n], 0, 0, 0); __builtin_amdgcn_s_setprio(0); } while (0)
; #define PG8_WAIT_V(n) asm volatile("s_waitcnt vmcnt(" #n ")" ::: "memory")
; #define PG8_WAIT_L(n) asm volatile("s_waitcnt lgkmcnt(" #n ")" ::: "memory")
; #define PG8_BAR __builtin_amdgcn_s_barrier()
; #define PG8_SCHED __builtin_amdgcn_sched_barrier(0)
; template <class Epi, class Sched, bool ALIGN_EPI = false, bool SP2 = false>
; __device__ __forceinline__ void gemm_phase(PG8_LAS unsigned char* lds, const Gemm g, const Sched& S, const Epi& E) {
;     ...
;             PG8_LDA(At, 1, 1); PG8_STAGE(PG8_SB(1, 0), b3, voffB); PG8_STAGE(PG8_SB(1, 1), b3 + hstep, voffB); PG8_STAGE(PG8_SA(1, 0), a3, voffA);
;             PG8_WAIT_V(8); PG8_WAIT_L(0); PG8_BAR; PG8_MMA(1, 0, At, B0); PG8_MMA(1, 1, At, B1); PG8_BAR; PG8_SCHED;
	s_add_i32 s56, s82, s34
	v_lshl_add_u64 v[200:201], v[200:201], 0, s[26:27]
	s_mov_b32 m0, s56
	ds_read_b128 v[188:191], v154 offset:49152
	ds_read_b128 v[192:195], v154 offset:50176
	ds_read_b128 v[196:199], v154 offset:51200
	ds_read_b128 v[206:209], v154 offset:52224
	ds_read_b128 v[210:213], v154 offset:53248
	ds_read_b128 v[214:217], v154 offset:54272
	ds_read_b128 v[218:221], v154 offset:55296
	ds_read_b128 v[222:225], v154 offset:56320
	global_load_lds_dwordx4 v[200:201], off
	s_add_i32 m0, s56, 0x2000
	s_add_u32 s54, s54, 0x40080
	v_lshl_add_u64 v[200:201], v[226:227], 0, s[26:27]
	s_addc_u32 s55, s55, 0
	s_add_i32 s56, s83, s34
	global_load_lds_dwordx4 v[200:201], off
	v_lshl_add_u64 v[200:201], s[54:55], 0, v[132:133]
	s_mov_b32 m0, s56
	s_nop 0
	global_load_lds_dwordx4 v[200:201], off
	v_lshl_add_u64 v[200:201], s[54:55], 0, v[128:129]
	s_add_i32 m0, s56, 0x2000
	s_nop 0
	global_load_lds_dwordx4 v[200:201], off
	s_waitcnt vmcnt(6)
	s_waitcnt lgkmcnt(0)
	s_barrier
	s_setprio 1
	s_waitcnt lgkmcnt(0)
	v_mfma_f32_16x16x32_bf16 v[60:63], v[146:149], v[188:191], v[60:63]
	v_mfma_f32_16x16x32_bf16 v[56:59], v[160:163], v[188:191], v[56:59]
	v_lshl_add_u64 v[200:201], v[228:229], 0, s[26:27]
	s_mov_b32 m0, s63
	s_nop 0
	global_load_lds_dwordx4 v[200:201], off
	v_mfma_f32_16x16x32_bf16 v[44:47], v[146:149], v[196:199], v[44:47]
	v_mfma_f32_16x16x32_bf16 v[40:43], v[160:163], v[196:199], v[40:43]
	v_mfma_f32_16x16x32_bf16 v[28:31], v[146:149], v[210:213], v[28:31]
	v_mfma_f32_16x16x32_bf16 v[24:27], v[160:163], v[210:213], v[24:27]
	v_lshl_add_u64 v[200:201], v[230:231], 0, s[26:27]
	s_mov_b32 m0, s64
	s_nop 0
	global_load_lds_dwordx4 v[200:201], off
	v_mfma_f32_16x16x32_bf16 v[12:15], v[146:149], v[218:221], v[12:15]
	v_mfma_f32_16x16x32_bf16 v[8:11], v[160:163], v[218:221], v[8:11]
	v_mfma_f32_16x16x32_bf16 v[60:63], v[156:159], v[192:195], v[60:63]
	v_mfma_f32_16x16x32_bf16 v[56:59], v[164:167], v[192:195], v[56:59]
	v_mfma_f32_16x16x32_bf16 v[44:47], v[156:159], v[206:209], v[44:47]
	v_mfma_f32_16x16x32_bf16 v[40:43], v[164:167], v[206:209], v[40:43]
	v_mfma_f32_16x16x32_bf16 v[28:31], v[156:159], v[214:217], v[28:31]
	v_mfma_f32_16x16x32_bf16 v[24:27], v[164:167], v[214:217], v[24:27]
	v_mfma_f32_16x16x32_bf16 v[12:15], v[156:159], v[222:225], v[12:15]
	v_mfma_f32_16x16x32_bf16 v[8:11], v[164:167], v[222:225], v[8:11]
	s_setprio 0
	s_setprio 1
	v_mfma_f32_16x16x32_bf16 v[52:55], v[168:171], v[188:191], v[52:55]
	v_mfma_f32_16x16x32_bf16 v[48:51], v[180:183], v[188:191], v[48:51]
	v_mfma_f32_16x16x32_bf16 v[36:39], v[168:171], v[196:199], v[36:39]
	v_mfma_f32_16x16x32_bf16 v[32:35], v[180:183], v[196:199], v[32:35]
	v_mfma_f32_16x16x32_bf16 v[20:23], v[168:171], v[210:213], v[20:23]
	v_mfma_f32_16x16x32_bf16 v[16:19], v[180:183], v[210:213], v[16:19]
	v_mfma_f32_16x16x32_bf16 v[4:7], v[168:171], v[218:221], v[4:7]
	v_mfma_f32_16x16x32_bf16 v[0:3], v[180:183], v[218:221], v[0:3]
	v_mfma_f32_16x16x32_bf16 v[52:55], v[172:175], v[192:195], v[52:55]
	v_mfma_f32_16x16x32_bf16 v[48:51], v[184:187], v[192:195], v[48:51]
	v_mfma_f32_16x16x32_bf16 v[36:39], v[172:175], v[206:209], v[36:39]
	v_mfma_f32_16x16x32_bf16 v[32:35], v[184:187], v[206:209], v[32:35]
	v_mfma_f32_16x16x32_bf16 v[20:23], v[172:175], v[214:217], v[20:23]
	v_mfma_f32_16x16x32_bf16 v[16:19], v[184:187], v[214:217], v[16:19]
	v_mfma_f32_16x16x32_bf16 v[4:7], v[172:175], v[222:225], v[4:7]
	v_mfma_f32_16x16x32_bf16 v[0:3], v[184:187], v[222:225], v[0:3]
	s_setprio 0
	s_barrier
	s_add_i32 s81, s81, 2
	s_add_u32 s52, s52, 0x100
	s_addc_u32 s53, s53, 0
	s_add_u32 s79, s79, 0x100
	s_addc_u32 s80, s80, 0
	s_cmp_gt_u32 s81, 13
	s_cbranch_scc0 .LBB0_1681
	s_and_b64 vcc, exec, s[28:29]
	s_cbranch_vccz .LBB0_1684
	s_barrier

; #define PG8_STAGE(bufoff, gbase, voff) do { _Pragma("unroll") for (int _i = 0; _i < 2; ++_i) \
;         __builtin_amdgcn_global_load_lds((const unsigned*)((const char*)(gbase) + (voff)[_i]), (PG8_LAS unsigned*)(lds + (bufoff) + ldsw + _i * 8192), 16, 0, 0); } while (0)
; #define PG8_LDA(dst, b, h) do { _Pragma("unroll") for (int m = 0; m < 4; ++m) _Pragma("unroll") for (int k = 0; k < 2; ++k) dst[m][k] = *(const PG8_LAS bf16x8*)(lds + PG8_SA(b, h) + aoff + m * 2048 + k * 1024); } while (0)
; #define PG8_LDB(dst, b, h) do { _Pragma("unroll") for (int n = 0; n < 2; ++n) _Pragma("unroll") for (int k = 0; k < 2; ++k) dst[n][k] = *(const PG8_LAS bf16x8*)(lds + PG8_SB(b, h) + boff + n * 2048 + k * 1024); } while (0)
; #define PG8_MMA(ai, bj, At, Bt) do { __builtin_amdgcn_s_setprio(1); _Pragma("unroll") for (int m = 0; m < 4; ++m) _Pragma("unroll") for (int n = 0; n < 2; ++n) _Pragma("unroll") for (int k = 0; k < 2; ++k) \
;         acc[ai][bj][m][n] = __builtin_amdgcn_mfma_f32_16x16x32_bf16(Bt[n][k], At[m][k], acc[ai][bj][m][n], 0, 0, 0); __builtin_amdgcn_s_setprio(0); } while (0)
; #define PG8_WAIT_V(n) asm volatile("s_waitcnt vmcnt(" #n ")" ::: "memory")
; #define PG8_WAIT_L(n) asm volatile("s_waitcnt lgkmcnt(" #n ")" ::: "memory")
; #define PG8_BAR __builtin_amdgcn_s_barrier()
; #define PG8_SCHED __builtin_amdgcn_sched_barrier(0)
; template <class Epi, class Sched, bool ALIGN_EPI = false, bool SP2 = false>
; __device__ __forceinline__ void gemm_phase(PG8_LAS unsigned char* lds, const Gemm g, const Sched& S, const Epi& E) {
;     ...
;         for (int t = 0; t < nt; t += 2) {
;             const bool last = (t == nt - 2);
;             const char* a1 = cA + (size_t)(t + 1) * kstep;
;             const char* a2 = last ? nA : cA + (size_t)(t + 2) * kstep; const char* b2 = last ? nB : cB + (size_t)(t + 2) * kstep;
;             const char* a3 = a2 + kstep; const char* b3 = b2 + kstep;
;             if (last && has_next) S.a_ready(nxt);
;             if constexpr (SP2) {
;             PG8_LDB(B0, 0, 0); PG8_LDB(B1, 0, 1); PG8_SCHED; PG8_LDA(At, 0, 0); PG8_STAGE(PG8_SA(1, 1), a1 + hstep, voffA);
;             PG8_WAIT_V(8); PG8_WAIT_L(0); PG8_BAR; PG8_MMA(0, 0, At, B0); PG8_MMA(0, 1, At, B1); PG8_BAR; PG8_SCHED;
;             PG8_LDA(At, 0, 1); PG8_STAGE(PG8_SB(0, 0), b2, voffB); PG8_STAGE(PG8_SB(0, 1), b2 + hstep, voffB); PG8_STAGE(PG8_SA(0, 0), a2, voffA);
.LBB0_1816:
	ds_read_b128 v[144:147], v151
	ds_read_b128 v[156:159], v151 offset:1024
	ds_read_b128 v[160:163], v151 offset:2048
	ds_read_b128 v[164:167], v151 offset:3072
	ds_read_b128 v[168:171], v152
	ds_read_b128 v[172:175], v152 offset:1024
	ds_read_b128 v[176:179], v152 offset:2048
	ds_read_b128 v[180:183], v152 offset:3072
	s_add_u32 s46, s44, 0xfffe0080
	s_addc_u32 s47, s45, -1
	s_cmp_eq_u32 s61, 4
	s_cselect_b32 s49, s29, s47
	s_cselect_b32 s48, s41, s46
	s_cselect_b32 s47, s27, s60
	s_cselect_b32 s46, s58, s59
	v_lshl_add_u64 v[218:219], s[44:45], 0, v[136:137]
	s_add_i32 m0, s33, 0xc000
	ds_read_b128 v[184:187], v153
	ds_read_b128 v[188:191], v153 offset:1024
	ds_read_b128 v[192:195], v153 offset:2048
	ds_read_b128 v[196:199], v153 offset:3072
	ds_read_b128 v[200:203], v153 offset:4096
	ds_read_b128 v[206:209], v153 offset:5120
	ds_read_b128 v[210:213], v153 offset:6144
	ds_read_b128 v[214:217], v153 offset:7168
	global_load_lds_dwordx4 v[218:219], off
	v_lshl_add_u64 v[218:219], s[44:45], 0, v[138:139]
	s_add_i32 m0, s33, 0xe000
	s_nop 0
	global_load_lds_dwordx4 v[218:219], off
	s_waitcnt vmcnt(8)
	s_waitcnt lgkmcnt(0)
	s_barrier
	s_setprio 1
	s_waitcnt lgkmcnt(0)
	v_mfma_f32_16x16x32_bf16 v[124:127], v[144:147], v[184:187], v[124:127]
	v_mfma_f32_16x16x32_bf16 v[120:123], v[160:163], v[184:187], v[120:123]
	v_mfma_f32_16x16x32_bf16 v[108:111], v[144:147], v[192:195], v[108:111]
	v_mfma_f32_16x16x32_bf16 v[104:107], v[160:163], v[192:195], v[104:107]
	v_mfma_f32_16x16x32_bf16 v[92:95], v[144:147], v[200:203], v[92:95]
	v_mfma_f32_16x16x32_bf16 v[88:91], v[160:163], v[200:203], v[88:91]
	v_mfma_f32_16x16x32_bf16 v[76:79], v[144:147], v[210:213], v[76:79]
	v_mfma_f32_16x16x32_bf16 v[72:75], v[160:163], v[210:213], v[72:75]
	v_mfma_f32_16x16x32_bf16 v[124:127], v[156:159], v[188:191], v[124:127]
	v_mfma_f32_16x16x32_bf16 v[120:123], v[164:167], v[188:191], v[120:123]
	v_mfma_f32_16x16x32_bf16 v[108:111], v[156:159], v[196:199], v[108:111]
	v_mfma_f32_16x16x32_bf16 v[104:107], v[164:167], v[196:199], v[104:107]
	v_mfma_f32_16x16x32_bf16 v[92:95], v[156:159], v[206:209], v[92:95]
	v_mfma_f32_16x16x32_bf16 v[88:91], v[164:167], v[206:209], v[88:91]
	v_mfma_f32_16x16x32_bf16 v[76:79], v[156:159], v[214:217], v[76:79]
	v_mfma_f32_16x16x32_bf16 v[72:75], v[164:167], v[214:217], v[72:75]
	s_setprio 0
	s_setprio 1
	v_mfma_f32_16x16x32_bf16 v[116:119], v[168:171], v[184:187], v[116:119]
	v_mfma_f32_16x16x32_bf16 v[112:115], v[176:179], v[184:187], v[112:115]
	v_mfma_f32_16x16x32_bf16 v[100:103], v[168:171], v[192:195], v[100:103]
	v_mfma_f32_16x16x32_bf16 v[96:99], v[176:179], v[192:195], v[96:99]
	v_mfma_f32_16x16x32_bf16 v[84:87], v[168:171], v[200:203], v[84:87]
	v_mfma_f32_16x16x32_bf16 v[80:83], v[176:179], v[200:203], v[80:83]
	v_mfma_f32_16x16x32_bf16 v[68:71], v[168:171], v[210:213], v[68:71]
	v_mfma_f32_16x16x32_bf16 v[64:67], v[176:179], v[210:213], v[64:67]
	v_mfma_f32_16x16x32_bf16 v[116:119], v[172:175], v[188:191], v[116:119]
	v_mfma_f32_16x16x32_bf16 v[112:115], v[180:183], v[188:191], v[112:115]
	v_mfma_f32_16x16x32_bf16 v[100:103], v[172:175], v[196:199], v[100:103]
	v_mfma_f32_16x16x32_bf16 v[96:99], v[180:183], v[196:199], v[96:99]
	v_mfma_f32_16x16x32_bf16 v[84:87], v[172:175], v[206:209], v[84:87]
	v_mfma_f32_16x16x32_bf16 v[80:83], v[180:183], v[206:209], v[80:83]
	v_mfma_f32_16x16x32_bf16 v[68:71], v[172:175], v[214:217], v[68:71]
	v_mfma_f32_16x16x32_bf16 v[64:67], v[180:183], v[214:217], v[64:67]
	s_setprio 0
	s_barrier
	s_add_i32 s62, s54, s15
	v_lshl_add_u64 v[218:219], s[46:47], 0, v[130:131]
	s_mov_b32 m0, s62
	ds_read_b128 v[184:187], v153 offset:16384
	ds_read_b128 v[188:191], v153 offset:17408
	ds_read_b128 v[192:195], v153 offset:18432
	ds_read_b128 v[196:199], v153 offset:19456
	ds_read_b128 v[200:203], v153 offset:20480
	ds_read_b128 v[206:209], v153 offset:21504
	ds_read_b128 v[210:213], v153 offset:22528
	ds_read_b128 v[214:217], v153 offset:23552
	global_load_lds_dwordx4 v[218:219], off
	s_add_i32 m0, s62, 0x2000
	s_add_u32 s62, s46, 0x20000
	v_lshl_add_u64 v[220:221], s[46:47], 0, v[134:135]
	s_addc_u32 s63, s47, 0
	s_add_i32 s64, s55, s15
	global_load_lds_dwordx4 v[220:221], off
	v_lshl_add_u64 v[222:223], s[62:63], 0, v[130:131]
	s_mov_b32 m0, s64
	global_load_lds_dwordx4 v[222:223], off
	v_lshl_add_u64 v[222:223], s[62:63], 0, v[134:135]
	s_add_i32 m0, s64, 0x2000
	s_nop 0
	global_load_lds_dwordx4 v[222:223], off
	s_waitcnt vmcnt(6)
	s_waitcnt lgkmcnt(0)
	s_barrier
; #define PG8_STAGE(bufoff, gbase, voff) do { _Pragma("unroll") for (int _i = 0; _i < 2; ++_i) \
;         __builtin_amdgcn_global_load_lds((const unsigned*)((const char*)(gbase) + (voff)[_i]), (PG8_LAS unsigned*)(lds + (bufoff) + ldsw + _i * 8192), 16, 0, 0); } while (0)
; #define PG8_LDA(dst, b, h) do { _Pragma("unroll") for (int m = 0; m < 4; ++m) _Pragma("unroll") for (int k = 0; k < 2; ++k) dst[m][k] = *(const PG8_LAS bf16x8*)(lds + PG8_SA(b, h) + aoff + m * 2048 + k * 1024); } while (0)
; #define PG8_LDB(dst, b, h) do { _Pragma("unroll") for (int n = 0; n < 2; ++n) _Pragma("unroll") for (int k = 0; k < 2; ++k) dst[n][k] = *(const PG8_LAS bf16x8*)(lds + PG8_SB(b, h) + boff + n * 2048 + k * 1024); } while (0)
; #define PG8_MMA(ai, bj, At, Bt) do { __builtin_amdgcn_s_setprio(1); _Pragma("unroll") for (int m = 0; m < 4; ++m) _Pragma("unroll") for (int n = 0; n < 2; ++n) _Pragma("unroll") for (int k = 0; k < 2; ++k) \
;         acc[ai][bj][m][n] = __builtin_amdgcn_mfma_f32_16x16x32_bf16(Bt[n][k], At[m][k], acc[ai][bj][m][n], 0, 0, 0); __builtin_amdgcn_s_setprio(0); } while (0)
; #define PG8_WAIT_V(n) asm volatile("s_waitcnt vmcnt(" #n ")" ::: "memory")
; #define PG8_WAIT_L(n) asm volatile("s_waitcnt lgkmcnt(" #n ")" ::: "memory")
; #define PG8_BAR __builtin_amdgcn_s_barrier()
; #define PG8_SCHED __builtin_amdgcn_sched_barrier(0)
; template <class Epi, class Sched, bool ALIGN_EPI = false, bool SP2 = false>
; __device__ __forceinline__ void gemm_phase(PG8_LAS unsigned char* lds, const Gemm g, const Sched& S, const Epi& E) {
;     ...
;             PG8_WAIT_V(8); PG8_WAIT_L(0); PG8_BAR; PG8_MMA(1, 0, At, B0); PG8_MMA(1, 1, At, B1); PG8_BAR; PG8_SCHED;
;             PG8_LDB(B0, 1, 0); PG8_LDB(B1, 1, 1); PG8_SCHED; PG8_LDA(At, 1, 0); PG8_STAGE(PG8_SA(0, 1), a2 + hstep, voffA);
;             PG8_WAIT_V(8); PG8_WAIT_L(0); PG8_BAR; PG8_MMA(0, 0, At, B0); PG8_MMA(0, 1, At, B1); PG8_BAR; PG8_SCHED;
	s_setprio 1
	s_waitcnt lgkmcnt(0)
	v_mfma_f32_16x16x32_bf16 v[60:63], v[144:147], v[184:187], v[60:63]
	v_mfma_f32_16x16x32_bf16 v[56:59], v[160:163], v[184:187], v[56:59]
	v_mfma_f32_16x16x32_bf16 v[44:47], v[144:147], v[192:195], v[44:47]
	v_mfma_f32_16x16x32_bf16 v[40:43], v[160:163], v[192:195], v[40:43]
	v_mfma_f32_16x16x32_bf16 v[28:31], v[144:147], v[200:203], v[28:31]
	v_mfma_f32_16x16x32_bf16 v[24:27], v[160:163], v[200:203], v[24:27]
	v_mfma_f32_16x16x32_bf16 v[12:15], v[144:147], v[210:213], v[12:15]
	v_mfma_f32_16x16x32_bf16 v[8:11], v[160:163], v[210:213], v[8:11]
	v_mfma_f32_16x16x32_bf16 v[60:63], v[156:159], v[188:191], v[60:63]
	v_mfma_f32_16x16x32_bf16 v[56:59], v[164:167], v[188:191], v[56:59]
	v_mfma_f32_16x16x32_bf16 v[44:47], v[156:159], v[196:199], v[44:47]
	v_mfma_f32_16x16x32_bf16 v[40:43], v[164:167], v[196:199], v[40:43]
	v_mfma_f32_16x16x32_bf16 v[28:31], v[156:159], v[206:209], v[28:31]
	v_mfma_f32_16x16x32_bf16 v[24:27], v[164:167], v[206:209], v[24:27]
	v_lshl_add_u64 v[222:223], s[48:49], 0, v[128:129]
	s_mov_b32 m0, s33
	s_nop 0
	global_load_lds_dwordx4 v[222:223], off
	v_mfma_f32_16x16x32_bf16 v[12:15], v[156:159], v[214:217], v[12:15]
	v_mfma_f32_16x16x32_bf16 v[8:11], v[164:167], v[214:217], v[8:11]
	s_setprio 0
	s_setprio 1
	v_mfma_f32_16x16x32_bf16 v[52:55], v[168:171], v[184:187], v[52:55]
	v_mfma_f32_16x16x32_bf16 v[48:51], v[176:179], v[184:187], v[48:51]
	v_mfma_f32_16x16x32_bf16 v[36:39], v[168:171], v[192:195], v[36:39]
	v_mfma_f32_16x16x32_bf16 v[32:35], v[176:179], v[192:195], v[32:35]
	v_mfma_f32_16x16x32_bf16 v[20:23], v[168:171], v[200:203], v[20:23]
	v_mfma_f32_16x16x32_bf16 v[16:19], v[176:179], v[200:203], v[16:19]
	v_mfma_f32_16x16x32_bf16 v[4:7], v[168:171], v[210:213], v[4:7]
	v_mfma_f32_16x16x32_bf16 v[0:3], v[176:179], v[210:213], v[0:3]
	v_mfma_f32_16x16x32_bf16 v[52:55], v[172:175], v[188:191], v[52:55]
	v_mfma_f32_16x16x32_bf16 v[48:51], v[180:183], v[188:191], v[48:51]
	v_mfma_f32_16x16x32_bf16 v[36:39], v[172:175], v[196:199], v[36:39]
	v_mfma_f32_16x16x32_bf16 v[32:35], v[180:183], v[196:199], v[32:35]
	v_mfma_f32_16x16x32_bf16 v[20:23], v[172:175], v[206:209], v[20:23]
	v_mfma_f32_16x16x32_bf16 v[16:19], v[180:183], v[206:209], v[16:19]
	v_lshl_add_u64 v[224:225], s[48:49], 0, v[132:133]
	s_mov_b32 m0, s34
	s_nop 0
	global_load_lds_dwordx4 v[224:225], off
	v_mfma_f32_16x16x32_bf16 v[4:7], v[172:175], v[214:217], v[4:7]
	v_mfma_f32_16x16x32_bf16 v[0:3], v[180:183], v[214:217], v[0:3]
	s_setprio 0
	s_barrier
	s_add_i32 s62, 0, 0x18000
	v_add_u32_e32 v155, s62, v149
	s_add_i32 s63, 0, 0x1c000
	ds_read_b128 v[144:147], v155
	ds_read_b128 v[156:159], v155 offset:1024
	ds_read_b128 v[160:163], v155 offset:2048
	ds_read_b128 v[164:167], v155 offset:3072
	v_add_u32_e32 v155, s63, v149
	ds_read_b128 v[168:171], v155
	ds_read_b128 v[172:175], v155 offset:1024
	ds_read_b128 v[176:179], v155 offset:2048
	ds_read_b128 v[180:183], v155 offset:3072
	s_add_u32 s48, s48, 0x20000
	s_addc_u32 s49, s49, 0
	s_mov_b32 m0, s43
	v_lshl_add_u64 v[226:227], s[48:49], 0, v[128:129]
	ds_read_b128 v[184:187], v153 offset:32768
	ds_read_b128 v[188:191], v153 offset:33792
	ds_read_b128 v[192:195], v153 offset:34816
	ds_read_b128 v[196:199], v153 offset:35840
	ds_read_b128 v[200:203], v153 offset:36864
	ds_read_b128 v[206:209], v153 offset:37888
	ds_read_b128 v[210:213], v153 offset:38912
	ds_read_b128 v[214:217], v153 offset:39936
	global_load_lds_dwordx4 v[226:227], off
	v_lshl_add_u64 v[226:227], s[48:49], 0, v[132:133]
	s_mov_b32 m0, s50
	s_nop 0
	global_load_lds_dwordx4 v[226:227], off
	s_waitcnt vmcnt(8)
	s_waitcnt lgkmcnt(0)
	s_barrier
	s_setprio 1
	s_waitcnt lgkmcnt(0)
	v_mfma_f32_16x16x32_bf16 v[124:127], v[144:147], v[184:187], v[124:127]
	v_mfma_f32_16x16x32_bf16 v[120:123], v[160:163], v[184:187], v[120:123]
	v_mfma_f32_16x16x32_bf16 v[108:111], v[144:147], v[192:195], v[108:111]
	v_mfma_f32_16x16x32_bf16 v[104:107], v[160:163], v[192:195], v[104:107]
	v_mfma_f32_16x16x32_bf16 v[92:95], v[144:147], v[200:203], v[92:95]
	v_mfma_f32_16x16x32_bf16 v[88:91], v[160:163], v[200:203], v[88:91]
	v_mfma_f32_16x16x32_bf16 v[76:79], v[144:147], v[210:213], v[76:79]
	v_mfma_f32_16x16x32_bf16 v[72:75], v[160:163], v[210:213], v[72:75]
	v_mfma_f32_16x16x32_bf16 v[124:127], v[156:159], v[188:191], v[124:127]
	v_mfma_f32_16x16x32_bf16 v[120:123], v[164:167], v[188:191], v[120:123]
	v_mfma_f32_16x16x32_bf16 v[108:111], v[156:159], v[196:199], v[108:111]
	v_mfma_f32_16x16x32_bf16 v[104:107], v[164:167], v[196:199], v[104:107]
	v_mfma_f32_16x16x32_bf16 v[92:95], v[156:159], v[206:209], v[92:95]
	v_mfma_f32_16x16x32_bf16 v[88:91], v[164:167], v[206:209], v[88:91]
	v_mfma_f32_16x16x32_bf16 v[76:79], v[156:159], v[214:217], v[76:79]
	v_mfma_f32_16x16x32_bf16 v[72:75], v[164:167], v[214:217], v[72:75]
	s_setprio 0
	s_setprio 1
	v_mfma_f32_16x16x32_bf16 v[116:119], v[168:171], v[184:187], v[116:119]
	v_mfma_f32_16x16x32_bf16 v[112:115], v[176:179], v[184:187], v[112:115]
	v_mfma_f32_16x16x32_bf16 v[100:103], v[168:171], v[192:195], v[100:103]
	v_mfma_f32_16x16x32_bf16 v[96:99], v[176:179], v[192:195], v[96:99]
	v_mfma_f32_16x16x32_bf16 v[84:87], v[168:171], v[200:203], v[84:87]
	v_mfma_f32_16x16x32_bf16 v[80:83], v[176:179], v[200:203], v[80:83]
	v_mfma_f32_16x16x32_bf16 v[68:71], v[168:171], v[210:213], v[68:71]
	v_mfma_f32_16x16x32_bf16 v[64:67], v[176:179], v[210:213], v[64:67]
	v_mfma_f32_16x16x32_bf16 v[116:119], v[172:175], v[188:191], v[116:119]
	v_mfma_f32_16x16x32_bf16 v[112:115], v[180:183], v[188:191], v[112:115]
	v_mfma_f32_16x16x32_bf16 v[100:103], v[172:175], v[196:199], v[100:103]
	v_mfma_f32_16x16x32_bf16 v[96:99], v[180:183], v[196:199], v[96:99]
	v_mfma_f32_16x16x32_bf16 v[84:87], v[172:175], v[206:209], v[84:87]
	v_mfma_f32_16x16x32_bf16 v[80:83], v[180:183], v[206:209], v[80:83]
	v_mfma_f32_16x16x32_bf16 v[68:71], v[172:175], v[214:217], v[68:71]
	v_mfma_f32_16x16x32_bf16 v[64:67], v[180:183], v[214:217], v[64:67]
	s_setprio 0
	s_barrier
; #define PG8_STAGE(bufoff, gbase, voff) do { _Pragma("unroll") for (int _i = 0; _i < 2; ++_i) \
;         __builtin_amdgcn_global_load_lds((const unsigned*)((const char*)(gbase) + (voff)[_i]), (PG8_LAS unsigned*)(lds + (bufoff) + ldsw + _i * 8192), 16, 0, 0); } while (0)
; #define PG8_LDA(dst, b, h) do { _Pragma("unroll") for (int m = 0; m < 4; ++m) _Pragma("unroll") for (int k = 0; k < 2; ++k) dst[m][k] = *(const PG8_LAS bf16x8*)(lds + PG8_SA(b, h) + aoff + m * 2048 + k * 1024); } while (0)
; #define PG8_MMA(ai, bj, At, Bt) do { __builtin_amdgcn_s_setprio(1); _Pragma("unroll") for (int m = 0; m < 4; ++m) _Pragma("unroll") for (int n = 0; n < 2; ++n) _Pragma("unroll") for (int k = 0; k < 2; ++k) \
;         acc[ai][bj][m][n] = __builtin_amdgcn_mfma_f32_16x16x32_bf16(Bt[n][k], At[m][k], acc[ai][bj][m][n], 0, 0, 0); __builtin_amdgcn_s_setprio(0); } while (0)
; #define PG8_WAIT_V(n) asm volatile("s_waitcnt vmcnt(" #n ")" ::: "memory")
; #define PG8_WAIT_L(n) asm volatile("s_waitcnt lgkmcnt(" #n ")" ::: "memory")
; #define PG8_BAR __builtin_amdgcn_s_barrier()
; #define PG8_SCHED __builtin_amdgcn_sched_barrier(0)
; template <class Epi, class Sched, bool ALIGN_EPI = false, bool SP2 = false>
; __device__ __forceinline__ void gemm_phase(PG8_LAS unsigned char* lds, const Gemm g, const Sched& S, const Epi& E) {
;     ...
;             PG8_LDA(At, 1, 1); PG8_STAGE(PG8_SB(1, 0), b3, voffB); PG8_STAGE(PG8_SB(1, 1), b3 + hstep, voffB); PG8_STAGE(PG8_SA(1, 0), a3, voffA);
;             PG8_WAIT_V(8); PG8_WAIT_L(0); PG8_BAR; PG8_MMA(1, 0, At, B0); PG8_MMA(1, 1, At, B1); PG8_BAR; PG8_SCHED;
	s_add_i32 s48, s62, s15
	v_lshl_add_u64 v[218:219], v[218:219], 0, s[12:13]
	s_mov_b32 m0, s48
	ds_read_b128 v[184:187], v153 offset:49152
	ds_read_b128 v[188:191], v153 offset:50176
	ds_read_b128 v[192:195], v153 offset:51200
	ds_read_b128 v[196:199], v153 offset:52224
	ds_read_b128 v[200:203], v153 offset:53248
	ds_read_b128 v[206:209], v153 offset:54272
	ds_read_b128 v[210:213], v153 offset:55296
	ds_read_b128 v[214:217], v153 offset:56320
	global_load_lds_dwordx4 v[218:219], off
	s_add_i32 m0, s48, 0x2000
	s_add_u32 s46, s46, 0x20080
	v_lshl_add_u64 v[218:219], v[220:221], 0, s[12:13]
	s_addc_u32 s47, s47, 0
	s_add_i32 s48, s63, s15
	global_load_lds_dwordx4 v[218:219], off
	v_lshl_add_u64 v[218:219], s[46:47], 0, v[130:131]
	s_mov_b32 m0, s48
	s_nop 0
	global_load_lds_dwordx4 v[218:219], off
	v_lshl_add_u64 v[218:219], s[46:47], 0, v[134:135]
	s_add_i32 m0, s48, 0x2000
	s_nop 0
	global_load_lds_dwordx4 v[218:219], off
	s_waitcnt vmcnt(6)
	s_waitcnt lgkmcnt(0)
	s_barrier
	s_setprio 1
	s_waitcnt lgkmcnt(0)
	v_mfma_f32_16x16x32_bf16 v[60:63], v[144:147], v[184:187], v[60:63]
	v_mfma_f32_16x16x32_bf16 v[56:59], v[160:163], v[184:187], v[56:59]
	v_lshl_add_u64 v[218:219], v[222:223], 0, s[12:13]
	s_mov_b32 m0, s52
	s_nop 0
	global_load_lds_dwordx4 v[218:219], off
	v_mfma_f32_16x16x32_bf16 v[44:47], v[144:147], v[192:195], v[44:47]
	v_mfma_f32_16x16x32_bf16 v[40:43], v[160:163], v[192:195], v[40:43]
	v_mfma_f32_16x16x32_bf16 v[28:31], v[144:147], v[200:203], v[28:31]
	v_mfma_f32_16x16x32_bf16 v[24:27], v[160:163], v[200:203], v[24:27]
	v_lshl_add_u64 v[218:219], v[224:225], 0, s[12:13]
	s_mov_b32 m0, s53
	s_nop 0
	global_load_lds_dwordx4 v[218:219], off
	v_mfma_f32_16x16x32_bf16 v[12:15], v[144:147], v[210:213], v[12:15]
	v_mfma_f32_16x16x32_bf16 v[8:11], v[160:163], v[210:213], v[8:11]
	v_mfma_f32_16x16x32_bf16 v[60:63], v[156:159], v[188:191], v[60:63]
	v_mfma_f32_16x16x32_bf16 v[56:59], v[164:167], v[188:191], v[56:59]
	v_mfma_f32_16x16x32_bf16 v[44:47], v[156:159], v[196:199], v[44:47]
	v_mfma_f32_16x16x32_bf16 v[40:43], v[164:167], v[196:199], v[40:43]
	v_mfma_f32_16x16x32_bf16 v[28:31], v[156:159], v[206:209], v[28:31]
	v_mfma_f32_16x16x32_bf16 v[24:27], v[164:167], v[206:209], v[24:27]
	v_mfma_f32_16x16x32_bf16 v[12:15], v[156:159], v[214:217], v[12:15]
	v_mfma_f32_16x16x32_bf16 v[8:11], v[164:167], v[214:217], v[8:11]
	s_setprio 0
	s_setprio 1
	v_mfma_f32_16x16x32_bf16 v[52:55], v[168:171], v[184:187], v[52:55]
	v_mfma_f32_16x16x32_bf16 v[48:51], v[176:179], v[184:187], v[48:51]
	v_mfma_f32_16x16x32_bf16 v[36:39], v[168:171], v[192:195], v[36:39]
	v_mfma_f32_16x16x32_bf16 v[32:35], v[176:179], v[192:195], v[32:35]
	v_mfma_f32_16x16x32_bf16 v[20:23], v[168:171], v[200:203], v[20:23]
	v_mfma_f32_16x16x32_bf16 v[16:19], v[176:179], v[200:203], v[16:19]
	v_mfma_f32_16x16x32_bf16 v[4:7], v[168:171], v[210:213], v[4:7]
	v_mfma_f32_16x16x32_bf16 v[0:3], v[176:179], v[210:213], v[0:3]
	v_mfma_f32_16x16x32_bf16 v[52:55], v[172:175], v[188:191], v[52:55]
	v_mfma_f32_16x16x32_bf16 v[48:51], v[180:183], v[188:191], v[48:51]
	v_mfma_f32_16x16x32_bf16 v[36:39], v[172:175], v[196:199], v[36:39]
	v_mfma_f32_16x16x32_bf16 v[32:35], v[180:183], v[196:199], v[32:35]
	v_mfma_f32_16x16x32_bf16 v[20:23], v[172:175], v[206:209], v[20:23]
	v_mfma_f32_16x16x32_bf16 v[16:19], v[180:183], v[206:209], v[16:19]
	v_mfma_f32_16x16x32_bf16 v[4:7], v[172:175], v[214:217], v[4:7]
	v_mfma_f32_16x16x32_bf16 v[0:3], v[180:183], v[214:217], v[0:3]
	s_setprio 0
	s_barrier
	s_add_i32 s61, s61, 2
	s_add_u32 s44, s44, 0x100
	s_addc_u32 s45, s45, 0
	s_add_u32 s59, s59, 0x100
	s_addc_u32 s60, s60, 0
	s_cmp_gt_u32 s61, 5
	s_cbranch_scc0 .LBB0_1816
	s_and_b64 vcc, exec, s[24:25]
	s_cbranch_vccz .LBB0_1819
	s_barrier

; #define PG8_STAGE(bufoff, gbase, voff) do { _Pragma("unroll") for (int _i = 0; _i < 2; ++_i) \
;         __builtin_amdgcn_global_load_lds((const unsigned*)((const char*)(gbase) + (voff)[_i]), (PG8_LAS unsigned*)(lds + (bufoff) + ldsw + _i * 8192), 16, 0, 0); } while (0)
; #define PG8_LDA(dst, b, h) do { _Pragma("unroll") for (int m = 0; m < 4; ++m) _Pragma("unroll") for (int k = 0; k < 2; ++k) dst[m][k] = *(const PG8_LAS bf16x8*)(lds + PG8_SA(b, h) + aoff + m * 2048 + k * 1024); } while (0)
; #define PG8_LDB(dst, b, h) do { _Pragma("unroll") for (int n = 0; n < 2; ++n) _Pragma("unroll") for (int k = 0; k < 2; ++k) dst[n][k] = *(const PG8_LAS bf16x8*)(lds + PG8_SB(b, h) + boff + n * 2048 + k * 1024); } while (0)
; #define PG8_MMA(ai, bj, At, Bt) do { __builtin_amdgcn_s_setprio(1); _Pragma("unroll") for (int m = 0; m < 4; ++m) _Pragma("unroll") for (int n = 0; n < 2; ++n) _Pragma("unroll") for (int k = 0; k < 2; ++k) \
;         acc[ai][bj][m][n] = __builtin_amdgcn_mfma_f32_16x16x32_bf16(Bt[n][k], At[m][k], acc[ai][bj][m][n], 0, 0, 0); __builtin_amdgcn_s_setprio(0); } while (0)
; #define PG8_WAIT_V(n) asm volatile("s_waitcnt vmcnt(" #n ")" ::: "memory")
; #define PG8_WAIT_L(n) asm volatile("s_waitcnt lgkmcnt(" #n ")" ::: "memory")
; #define PG8_BAR __builtin_amdgcn_s_barrier()
; #define PG8_SCHED __builtin_amdgcn_sched_barrier(0)
; template <class Epi, class Sched, bool ALIGN_EPI = false, bool SP2 = false>
; __device__ __forceinline__ void gemm_phase(PG8_LAS unsigned char* lds, const Gemm g, const Sched& S, const Epi& E) {
;     ...
;         for (int t = 0; t < nt; t += 2) {
;             const bool last = (t == nt - 2);
;             const char* a1 = cA + (size_t)(t + 1) * kstep;
;             const char* a2 = last ? nA : cA + (size_t)(t + 2) * kstep; const char* b2 = last ? nB : cB + (size_t)(t + 2) * kstep;
;             const char* a3 = a2 + kstep; const char* b3 = b2 + kstep;
;             if (last && has_next) S.a_ready(nxt);
;             if constexpr (SP2) {
;             PG8_LDB(B0, 0, 0); PG8_LDB(B1, 0, 1); PG8_SCHED; PG8_LDA(At, 0, 0); PG8_STAGE(PG8_SA(1, 1), a1 + hstep, voffA);
;             PG8_WAIT_V(8); PG8_WAIT_L(0); PG8_BAR; PG8_MMA(0, 0, At, B0); PG8_MMA(0, 1, At, B1); PG8_BAR; PG8_SCHED;
;             PG8_LDA(At, 0, 1); PG8_STAGE(PG8_SB(0, 0), b2, voffB); PG8_STAGE(PG8_SB(0, 1), b2 + hstep, voffB); PG8_STAGE(PG8_SA(0, 0), a2, voffA);
.LBB0_1900:
	ds_read_b128 v[144:147], v155
	ds_read_b128 v[148:151], v155 offset:1024
	ds_read_b128 v[160:163], v155 offset:2048
	ds_read_b128 v[164:167], v155 offset:3072
	ds_read_b128 v[168:171], v156
	ds_read_b128 v[172:175], v156 offset:1024
	ds_read_b128 v[176:179], v156 offset:2048
	ds_read_b128 v[180:183], v156 offset:3072
	s_add_u32 s40, s38, 0xfffc0080
	s_addc_u32 s41, s39, -1
	s_cmp_eq_u32 s57, 12
	s_cselect_b32 s43, s25, s41
	s_cselect_b32 s42, s53, s40
	s_cselect_b32 s41, s13, s56
	s_cselect_b32 s40, s54, s55
	v_lshl_add_u64 v[218:219], s[38:39], 0, v[136:137]
	s_add_i32 m0, s34, 0xc000
	ds_read_b128 v[184:187], v157
	ds_read_b128 v[188:191], v157 offset:1024
	ds_read_b128 v[192:195], v157 offset:2048
	ds_read_b128 v[196:199], v157 offset:3072
	ds_read_b128 v[200:203], v157 offset:4096
	ds_read_b128 v[206:209], v157 offset:5120
	ds_read_b128 v[210:213], v157 offset:6144
	ds_read_b128 v[214:217], v157 offset:7168
	global_load_lds_dwordx4 v[218:219], off
	v_lshl_add_u64 v[218:219], s[38:39], 0, v[138:139]
	s_add_i32 m0, s34, 0xe000
	s_nop 0
	global_load_lds_dwordx4 v[218:219], off
	s_waitcnt vmcnt(8)
	s_waitcnt lgkmcnt(0)
	s_barrier
	s_setprio 1
	s_waitcnt lgkmcnt(0)
	v_mfma_f32_16x16x32_bf16 v[124:127], v[144:147], v[184:187], v[124:127]
	v_mfma_f32_16x16x32_bf16 v[120:123], v[160:163], v[184:187], v[120:123]
	v_mfma_f32_16x16x32_bf16 v[108:111], v[144:147], v[192:195], v[108:111]
	v_mfma_f32_16x16x32_bf16 v[104:107], v[160:163], v[192:195], v[104:107]
	v_mfma_f32_16x16x32_bf16 v[92:95], v[144:147], v[200:203], v[92:95]
	v_mfma_f32_16x16x32_bf16 v[88:91], v[160:163], v[200:203], v[88:91]
	v_mfma_f32_16x16x32_bf16 v[76:79], v[144:147], v[210:213], v[76:79]
	v_mfma_f32_16x16x32_bf16 v[72:75], v[160:163], v[210:213], v[72:75]
	v_mfma_f32_16x16x32_bf16 v[124:127], v[148:151], v[188:191], v[124:127]
	v_mfma_f32_16x16x32_bf16 v[120:123], v[164:167], v[188:191], v[120:123]
	v_mfma_f32_16x16x32_bf16 v[108:111], v[148:151], v[196:199], v[108:111]
	v_mfma_f32_16x16x32_bf16 v[104:107], v[164:167], v[196:199], v[104:107]
	v_mfma_f32_16x16x32_bf16 v[92:95], v[148:151], v[206:209], v[92:95]
	v_mfma_f32_16x16x32_bf16 v[88:91], v[164:167], v[206:209], v[88:91]
	v_mfma_f32_16x16x32_bf16 v[76:79], v[148:151], v[214:217], v[76:79]
	v_mfma_f32_16x16x32_bf16 v[72:75], v[164:167], v[214:217], v[72:75]
	s_setprio 0
	s_setprio 1
	v_mfma_f32_16x16x32_bf16 v[116:119], v[168:171], v[184:187], v[116:119]
	v_mfma_f32_16x16x32_bf16 v[112:115], v[176:179], v[184:187], v[112:115]
	v_mfma_f32_16x16x32_bf16 v[100:103], v[168:171], v[192:195], v[100:103]
	v_mfma_f32_16x16x32_bf16 v[96:99], v[176:179], v[192:195], v[96:99]
	v_mfma_f32_16x16x32_bf16 v[84:87], v[168:171], v[200:203], v[84:87]
	v_mfma_f32_16x16x32_bf16 v[80:83], v[176:179], v[200:203], v[80:83]
	v_mfma_f32_16x16x32_bf16 v[68:71], v[168:171], v[210:213], v[68:71]
	v_mfma_f32_16x16x32_bf16 v[64:67], v[176:179], v[210:213], v[64:67]
	v_mfma_f32_16x16x32_bf16 v[116:119], v[172:175], v[188:191], v[116:119]
	v_mfma_f32_16x16x32_bf16 v[112:115], v[180:183], v[188:191], v[112:115]
	v_mfma_f32_16x16x32_bf16 v[100:103], v[172:175], v[196:199], v[100:103]
	v_mfma_f32_16x16x32_bf16 v[96:99], v[180:183], v[196:199], v[96:99]
	v_mfma_f32_16x16x32_bf16 v[84:87], v[172:175], v[206:209], v[84:87]
	v_mfma_f32_16x16x32_bf16 v[80:83], v[180:183], v[206:209], v[80:83]
	v_mfma_f32_16x16x32_bf16 v[68:71], v[172:175], v[214:217], v[68:71]
	v_mfma_f32_16x16x32_bf16 v[64:67], v[180:183], v[214:217], v[64:67]
	s_setprio 0
	s_barrier
	s_add_i32 s58, s49, s15
	v_lshl_add_u64 v[218:219], s[40:41], 0, v[132:133]
	s_mov_b32 m0, s58
	ds_read_b128 v[184:187], v157 offset:16384
	ds_read_b128 v[188:191], v157 offset:17408
	ds_read_b128 v[192:195], v157 offset:18432
	ds_read_b128 v[196:199], v157 offset:19456
	ds_read_b128 v[200:203], v157 offset:20480
	ds_read_b128 v[206:209], v157 offset:21504
	ds_read_b128 v[210:213], v157 offset:22528
	ds_read_b128 v[214:217], v157 offset:23552
	global_load_lds_dwordx4 v[218:219], off
	s_add_i32 m0, s58, 0x2000
	s_add_u32 s58, s40, 0x40000
	v_lshl_add_u64 v[220:221], s[40:41], 0, v[128:129]
	s_addc_u32 s59, s41, 0
	s_add_i32 s60, s50, s15
	global_load_lds_dwordx4 v[220:221], off
	v_lshl_add_u64 v[222:223], s[58:59], 0, v[132:133]
	s_mov_b32 m0, s60
	global_load_lds_dwordx4 v[222:223], off
	v_lshl_add_u64 v[222:223], s[58:59], 0, v[128:129]
	s_add_i32 m0, s60, 0x2000
	s_nop 0
	global_load_lds_dwordx4 v[222:223], off
	s_waitcnt vmcnt(6)
	s_waitcnt lgkmcnt(0)
	s_barrier
; #define PG8_STAGE(bufoff, gbase, voff) do { _Pragma("unroll") for (int _i = 0; _i < 2; ++_i) \
;         __builtin_amdgcn_global_load_lds((const unsigned*)((const char*)(gbase) + (voff)[_i]), (PG8_LAS unsigned*)(lds + (bufoff) + ldsw + _i * 8192), 16, 0, 0); } while (0)
; #define PG8_LDA(dst, b, h) do { _Pragma("unroll") for (int m = 0; m < 4; ++m) _Pragma("unroll") for (int k = 0; k < 2; ++k) dst[m][k] = *(const PG8_LAS bf16x8*)(lds + PG8_SA(b, h) + aoff + m * 2048 + k * 1024); } while (0)
; #define PG8_LDB(dst, b, h) do { _Pragma("unroll") for (int n = 0; n < 2; ++n) _Pragma("unroll") for (int k = 0; k < 2; ++k) dst[n][k] = *(const PG8_LAS bf16x8*)(lds + PG8_SB(b, h) + boff + n * 2048 + k * 1024); } while (0)
; #define PG8_MMA(ai, bj, At, Bt) do { __builtin_amdgcn_s_setprio(1); _Pragma("unroll") for (int m = 0; m < 4; ++m) _Pragma("unroll") for (int n = 0; n < 2; ++n) _Pragma("unroll") for (int k = 0; k < 2; ++k) \
;         acc[ai][bj][m][n] = __builtin_amdgcn_mfma_f32_16x16x32_bf16(Bt[n][k], At[m][k], acc[ai][bj][m][n], 0, 0, 0); __builtin_amdgcn_s_setprio(0); } while (0)
; #define PG8_WAIT_V(n) asm volatile("s_waitcnt vmcnt(" #n ")" ::: "memory")
; #define PG8_WAIT_L(n) asm volatile("s_waitcnt lgkmcnt(" #n ")" ::: "memory")
; #define PG8_BAR __builtin_amdgcn_s_barrier()
; #define PG8_SCHED __builtin_amdgcn_sched_barrier(0)
; template <class Epi, class Sched, bool ALIGN_EPI = false, bool SP2 = false>
; __device__ __forceinline__ void gemm_phase(PG8_LAS unsigned char* lds, const Gemm g, const Sched& S, const Epi& E) {
;     ...
;             PG8_WAIT_V(8); PG8_WAIT_L(0); PG8_BAR; PG8_MMA(1, 0, At, B0); PG8_MMA(1, 1, At, B1); PG8_BAR; PG8_SCHED;
;             PG8_LDB(B0, 1, 0); PG8_LDB(B1, 1, 1); PG8_SCHED; PG8_LDA(At, 1, 0); PG8_STAGE(PG8_SA(0, 1), a2 + hstep, voffA);
;             PG8_WAIT_V(8); PG8_WAIT_L(0); PG8_BAR; PG8_MMA(0, 0, At, B0); PG8_MMA(0, 1, At, B1); PG8_BAR; PG8_SCHED;
	s_setprio 1
	s_waitcnt lgkmcnt(0)
	v_mfma_f32_16x16x32_bf16 v[60:63], v[144:147], v[184:187], v[60:63]
	v_mfma_f32_16x16x32_bf16 v[56:59], v[160:163], v[184:187], v[56:59]
	v_mfma_f32_16x16x32_bf16 v[44:47], v[144:147], v[192:195], v[44:47]
	v_mfma_f32_16x16x32_bf16 v[40:43], v[160:163], v[192:195], v[40:43]
	v_mfma_f32_16x16x32_bf16 v[28:31], v[144:147], v[200:203], v[28:31]
	v_mfma_f32_16x16x32_bf16 v[24:27], v[160:163], v[200:203], v[24:27]
	v_mfma_f32_16x16x32_bf16 v[12:15], v[144:147], v[210:213], v[12:15]
	v_mfma_f32_16x16x32_bf16 v[8:11], v[160:163], v[210:213], v[8:11]
	v_mfma_f32_16x16x32_bf16 v[60:63], v[148:151], v[188:191], v[60:63]
	v_mfma_f32_16x16x32_bf16 v[56:59], v[164:167], v[188:191], v[56:59]
	v_mfma_f32_16x16x32_bf16 v[44:47], v[148:151], v[196:199], v[44:47]
	v_mfma_f32_16x16x32_bf16 v[40:43], v[164:167], v[196:199], v[40:43]
	v_mfma_f32_16x16x32_bf16 v[28:31], v[148:151], v[206:209], v[28:31]
	v_mfma_f32_16x16x32_bf16 v[24:27], v[164:167], v[206:209], v[24:27]
	v_lshl_add_u64 v[222:223], s[42:43], 0, v[134:135]
	s_mov_b32 m0, s34
	s_nop 0
	global_load_lds_dwordx4 v[222:223], off
	v_mfma_f32_16x16x32_bf16 v[12:15], v[148:151], v[214:217], v[12:15]
	v_mfma_f32_16x16x32_bf16 v[8:11], v[164:167], v[214:217], v[8:11]
	s_setprio 0
	s_setprio 1
	v_mfma_f32_16x16x32_bf16 v[52:55], v[168:171], v[184:187], v[52:55]
	v_mfma_f32_16x16x32_bf16 v[48:51], v[176:179], v[184:187], v[48:51]
	v_mfma_f32_16x16x32_bf16 v[36:39], v[168:171], v[192:195], v[36:39]
	v_mfma_f32_16x16x32_bf16 v[32:35], v[176:179], v[192:195], v[32:35]
	v_mfma_f32_16x16x32_bf16 v[20:23], v[168:171], v[200:203], v[20:23]
	v_mfma_f32_16x16x32_bf16 v[16:19], v[176:179], v[200:203], v[16:19]
	v_mfma_f32_16x16x32_bf16 v[4:7], v[168:171], v[210:213], v[4:7]
	v_mfma_f32_16x16x32_bf16 v[0:3], v[176:179], v[210:213], v[0:3]
	v_mfma_f32_16x16x32_bf16 v[52:55], v[172:175], v[188:191], v[52:55]
	v_mfma_f32_16x16x32_bf16 v[48:51], v[180:183], v[188:191], v[48:51]
	v_mfma_f32_16x16x32_bf16 v[36:39], v[172:175], v[196:199], v[36:39]
	v_mfma_f32_16x16x32_bf16 v[32:35], v[180:183], v[196:199], v[32:35]
	v_mfma_f32_16x16x32_bf16 v[20:23], v[172:175], v[206:209], v[20:23]
	v_mfma_f32_16x16x32_bf16 v[16:19], v[180:183], v[206:209], v[16:19]
	v_lshl_add_u64 v[224:225], s[42:43], 0, v[130:131]
	s_mov_b32 m0, s37
	s_nop 0
	global_load_lds_dwordx4 v[224:225], off
	v_mfma_f32_16x16x32_bf16 v[4:7], v[172:175], v[214:217], v[4:7]
	v_mfma_f32_16x16x32_bf16 v[0:3], v[180:183], v[214:217], v[0:3]
	s_setprio 0
	s_barrier
	s_add_i32 s58, 0, 0x18000
	v_add_u32_e32 v159, s58, v153
	s_add_i32 s59, 0, 0x1c000
	ds_read_b128 v[144:147], v159
	ds_read_b128 v[148:151], v159 offset:1024
	ds_read_b128 v[160:163], v159 offset:2048
	ds_read_b128 v[164:167], v159 offset:3072
	v_add_u32_e32 v159, s59, v153
	ds_read_b128 v[168:171], v159
	ds_read_b128 v[172:175], v159 offset:1024
	ds_read_b128 v[176:179], v159 offset:2048
	ds_read_b128 v[180:183], v159 offset:3072
	s_add_u32 s42, s42, 0x40000
	s_addc_u32 s43, s43, 0
	s_mov_b32 m0, s44
	v_lshl_add_u64 v[226:227], s[42:43], 0, v[134:135]
	ds_read_b128 v[184:187], v157 offset:32768
	ds_read_b128 v[188:191], v157 offset:33792
	ds_read_b128 v[192:195], v157 offset:34816
	ds_read_b128 v[196:199], v157 offset:35840
	ds_read_b128 v[200:203], v157 offset:36864
	ds_read_b128 v[206:209], v157 offset:37888
	ds_read_b128 v[210:213], v157 offset:38912
	ds_read_b128 v[214:217], v157 offset:39936
	global_load_lds_dwordx4 v[226:227], off
	v_lshl_add_u64 v[226:227], s[42:43], 0, v[130:131]
	s_mov_b32 m0, s45
	s_nop 0
	global_load_lds_dwordx4 v[226:227], off
	s_waitcnt vmcnt(8)
	s_waitcnt lgkmcnt(0)
	s_barrier
	s_setprio 1
	s_waitcnt lgkmcnt(0)
	v_mfma_f32_16x16x32_bf16 v[124:127], v[144:147], v[184:187], v[124:127]
	v_mfma_f32_16x16x32_bf16 v[120:123], v[160:163], v[184:187], v[120:123]
	v_mfma_f32_16x16x32_bf16 v[108:111], v[144:147], v[192:195], v[108:111]
	v_mfma_f32_16x16x32_bf16 v[104:107], v[160:163], v[192:195], v[104:107]
	v_mfma_f32_16x16x32_bf16 v[92:95], v[144:147], v[200:203], v[92:95]
	v_mfma_f32_16x16x32_bf16 v[88:91], v[160:163], v[200:203], v[88:91]
	v_mfma_f32_16x16x32_bf16 v[76:79], v[144:147], v[210:213], v[76:79]
	v_mfma_f32_16x16x32_bf16 v[72:75], v[160:163], v[210:213], v[72:75]
	v_mfma_f32_16x16x32_bf16 v[124:127], v[148:151], v[188:191], v[124:127]
	v_mfma_f32_16x16x32_bf16 v[120:123], v[164:167], v[188:191], v[120:123]
	v_mfma_f32_16x16x32_bf16 v[108:111], v[148:151], v[196:199], v[108:111]
	v_mfma_f32_16x16x32_bf16 v[104:107], v[164:167], v[196:199], v[104:107]
	v_mfma_f32_16x16x32_bf16 v[92:95], v[148:151], v[206:209], v[92:95]
	v_mfma_f32_16x16x32_bf16 v[88:91], v[164:167], v[206:209], v[88:91]
	v_mfma_f32_16x16x32_bf16 v[76:79], v[148:151], v[214:217], v[76:79]
	v_mfma_f32_16x16x32_bf16 v[72:75], v[164:167], v[214:217], v[72:75]
	s_setprio 0
	s_setprio 1
	v_mfma_f32_16x16x32_bf16 v[116:119], v[168:171], v[184:187], v[116:119]
	v_mfma_f32_16x16x32_bf16 v[112:115], v[176:179], v[184:187], v[112:115]
	v_mfma_f32_16x16x32_bf16 v[100:103], v[168:171], v[192:195], v[100:103]
	v_mfma_f32_16x16x32_bf16 v[96:99], v[176:179], v[192:195], v[96:99]
	v_mfma_f32_16x16x32_bf16 v[84:87], v[168:171], v[200:203], v[84:87]
	v_mfma_f32_16x16x32_bf16 v[80:83], v[176:179], v[200:203], v[80:83]
	v_mfma_f32_16x16x32_bf16 v[68:71], v[168:171], v[210:213], v[68:71]
	v_mfma_f32_16x16x32_bf16 v[64:67], v[176:179], v[210:213], v[64:67]
	v_mfma_f32_16x16x32_bf16 v[116:119], v[172:175], v[188:191], v[116:119]
	v_mfma_f32_16x16x32_bf16 v[112:115], v[180:183], v[188:191], v[112:115]
	v_mfma_f32_16x16x32_bf16 v[100:103], v[172:175], v[196:199], v[100:103]
	v_mfma_f32_16x16x32_bf16 v[96:99], v[180:183], v[196:199], v[96:99]
	v_mfma_f32_16x16x32_bf16 v[84:87], v[172:175], v[206:209], v[84:87]
	v_mfma_f32_16x16x32_bf16 v[80:83], v[180:183], v[206:209], v[80:83]
	v_mfma_f32_16x16x32_bf16 v[68:71], v[172:175], v[214:217], v[68:71]
	v_mfma_f32_16x16x32_bf16 v[64:67], v[180:183], v[214:217], v[64:67]
	s_setprio 0
	s_barrier
; #define PG8_STAGE(bufoff, gbase, voff) do { _Pragma("unroll") for (int _i = 0; _i < 2; ++_i) \
;         __builtin_amdgcn_global_load_lds((const unsigned*)((const char*)(gbase) + (voff)[_i]), (PG8_LAS unsigned*)(lds + (bufoff) + ldsw + _i * 8192), 16, 0, 0); } while (0)
; #define PG8_LDA(dst, b, h) do { _Pragma("unroll") for (int m = 0; m < 4; ++m) _Pragma("unroll") for (int k = 0; k < 2; ++k) dst[m][k] = *(const PG8_LAS bf16x8*)(lds + PG8_SA(b, h) + aoff + m * 2048 + k * 1024); } while (0)
; #define PG8_MMA(ai, bj, At, Bt) do { __builtin_amdgcn_s_setprio(1); _Pragma("unroll") for (int m = 0; m < 4; ++m) _Pragma("unroll") for (int n = 0; n < 2; ++n) _Pragma("unroll") for (int k = 0; k < 2; ++k) \
;         acc[ai][bj][m][n] = __builtin_amdgcn_mfma_f32_16x16x32_bf16(Bt[n][k], At[m][k], acc[ai][bj][m][n], 0, 0, 0); __builtin_amdgcn_s_setprio(0); } while (0)
; #define PG8_WAIT_V(n) asm volatile("s_waitcnt vmcnt(" #n ")" ::: "memory")
; #define PG8_WAIT_L(n) asm volatile("s_waitcnt lgkmcnt(" #n ")" ::: "memory")
; #define PG8_BAR __builtin_amdgcn_s_barrier()
; #define PG8_SCHED __builtin_amdgcn_sched_barrier(0)
; __device__ __forceinline__ float row_rs(const float* ssp, int row) { const unsigned long long v = ((const unsigned long long*)ssp)[row];
;     return __builtin_amdgcn_rsqf((float)v * (1.0f / 4294967296.0f) * (1.0f / 1024.0f) + RMS_EPS); }
; template <class Epi, class Sched, bool ALIGN_EPI = false, bool SP2 = false>
; __device__ __forceinline__ void gemm_phase(PG8_LAS unsigned char* lds, const Gemm g, const Sched& S, const Epi& E) {
;     ...
;             PG8_LDA(At, 1, 1); PG8_STAGE(PG8_SB(1, 0), b3, voffB); PG8_STAGE(PG8_SB(1, 1), b3 + hstep, voffB); PG8_STAGE(PG8_SA(1, 0), a3, voffA);
;             PG8_WAIT_V(8); PG8_WAIT_L(0); PG8_BAR; PG8_MMA(1, 0, At, B0); PG8_MMA(1, 1, At, B1); PG8_BAR; PG8_SCHED;
	s_add_i32 s42, s58, s15
	v_lshl_add_u64 v[218:219], v[218:219], 0, s[8:9]
	s_mov_b32 m0, s42
	ds_read_b128 v[184:187], v157 offset:49152
	ds_read_b128 v[188:191], v157 offset:50176
	ds_read_b128 v[192:195], v157 offset:51200
	ds_read_b128 v[196:199], v157 offset:52224
	ds_read_b128 v[200:203], v157 offset:53248
	ds_read_b128 v[206:209], v157 offset:54272
	ds_read_b128 v[210:213], v157 offset:55296
	ds_read_b128 v[214:217], v157 offset:56320
	global_load_lds_dwordx4 v[218:219], off
	s_add_i32 m0, s42, 0x2000
	s_add_u32 s40, s40, 0x40080
	v_lshl_add_u64 v[218:219], v[220:221], 0, s[8:9]
	s_addc_u32 s41, s41, 0
	s_add_i32 s42, s59, s15
	global_load_lds_dwordx4 v[218:219], off
	v_lshl_add_u64 v[218:219], s[40:41], 0, v[132:133]
	s_mov_b32 m0, s42
	s_nop 0
	global_load_lds_dwordx4 v[218:219], off
	v_lshl_add_u64 v[218:219], s[40:41], 0, v[128:129]
	s_add_i32 m0, s42, 0x2000
	s_nop 0
	global_load_lds_dwordx4 v[218:219], off
	s_waitcnt vmcnt(6)
	s_waitcnt lgkmcnt(0)
	s_barrier
	s_setprio 1
	s_waitcnt lgkmcnt(0)
	v_mfma_f32_16x16x32_bf16 v[60:63], v[144:147], v[184:187], v[60:63]
	v_mfma_f32_16x16x32_bf16 v[56:59], v[160:163], v[184:187], v[56:59]
	v_lshl_add_u64 v[218:219], v[222:223], 0, s[8:9]
	s_mov_b32 m0, s47
	s_nop 0
	global_load_lds_dwordx4 v[218:219], off
	v_mfma_f32_16x16x32_bf16 v[44:47], v[144:147], v[192:195], v[44:47]
	v_mfma_f32_16x16x32_bf16 v[40:43], v[160:163], v[192:195], v[40:43]
	v_mfma_f32_16x16x32_bf16 v[28:31], v[144:147], v[200:203], v[28:31]
	v_mfma_f32_16x16x32_bf16 v[24:27], v[160:163], v[200:203], v[24:27]
	v_lshl_add_u64 v[218:219], v[224:225], 0, s[8:9]
	s_mov_b32 m0, s48
	s_nop 0
	global_load_lds_dwordx4 v[218:219], off
	v_mfma_f32_16x16x32_bf16 v[12:15], v[144:147], v[210:213], v[12:15]
	v_mfma_f32_16x16x32_bf16 v[8:11], v[160:163], v[210:213], v[8:11]
	v_mfma_f32_16x16x32_bf16 v[60:63], v[148:151], v[188:191], v[60:63]
	v_mfma_f32_16x16x32_bf16 v[56:59], v[164:167], v[188:191], v[56:59]
	v_mfma_f32_16x16x32_bf16 v[44:47], v[148:151], v[196:199], v[44:47]
	v_mfma_f32_16x16x32_bf16 v[40:43], v[164:167], v[196:199], v[40:43]
	v_mfma_f32_16x16x32_bf16 v[28:31], v[148:151], v[206:209], v[28:31]
	v_mfma_f32_16x16x32_bf16 v[24:27], v[164:167], v[206:209], v[24:27]
	v_mfma_f32_16x16x32_bf16 v[12:15], v[148:151], v[214:217], v[12:15]
	v_mfma_f32_16x16x32_bf16 v[8:11], v[164:167], v[214:217], v[8:11]
	s_setprio 0
	s_setprio 1
	v_mfma_f32_16x16x32_bf16 v[52:55], v[168:171], v[184:187], v[52:55]
	v_mfma_f32_16x16x32_bf16 v[48:51], v[176:179], v[184:187], v[48:51]
	v_mfma_f32_16x16x32_bf16 v[36:39], v[168:171], v[192:195], v[36:39]
	v_mfma_f32_16x16x32_bf16 v[32:35], v[176:179], v[192:195], v[32:35]
	v_mfma_f32_16x16x32_bf16 v[20:23], v[168:171], v[200:203], v[20:23]
	v_mfma_f32_16x16x32_bf16 v[16:19], v[176:179], v[200:203], v[16:19]
	v_mfma_f32_16x16x32_bf16 v[4:7], v[168:171], v[210:213], v[4:7]
	v_mfma_f32_16x16x32_bf16 v[0:3], v[176:179], v[210:213], v[0:3]
	v_mfma_f32_16x16x32_bf16 v[52:55], v[172:175], v[188:191], v[52:55]
	v_mfma_f32_16x16x32_bf16 v[48:51], v[180:183], v[188:191], v[48:51]
	v_mfma_f32_16x16x32_bf16 v[36:39], v[172:175], v[196:199], v[36:39]
	v_mfma_f32_16x16x32_bf16 v[32:35], v[180:183], v[196:199], v[32:35]
	v_mfma_f32_16x16x32_bf16 v[20:23], v[172:175], v[206:209], v[20:23]
	v_mfma_f32_16x16x32_bf16 v[16:19], v[180:183], v[206:209], v[16:19]
	v_mfma_f32_16x16x32_bf16 v[4:7], v[172:175], v[214:217], v[4:7]
	v_mfma_f32_16x16x32_bf16 v[0:3], v[180:183], v[214:217], v[0:3]
	s_setprio 0
	s_barrier
	s_add_i32 s57, s57, 2
	s_add_u32 s38, s38, 0x100
	s_addc_u32 s39, s39, 0
	s_add_u32 s55, s55, 0x100
	s_addc_u32 s56, s56, 0
	s_cmp_gt_u32 s57, 13
	s_cbranch_scc0 .LBB0_1900
	v_lshl_add_u32 v144, s36, 8, v152
	v_ashrrev_i32_e32 v145, 31, v144
	v_lshl_add_u64 v[150:151], v[144:145], 3, s[0:1]
	global_load_dwordx2 v[182:183], v[150:151], off
	global_load_dwordx2 v[184:185], v[150:151], off offset:128
	global_load_dwordx2 v[186:187], v[150:151], off offset:256
	global_load_dwordx2 v[188:189], v[150:151], off offset:384
	global_load_dwordx2 v[190:191], v[150:151], off offset:1024
	global_load_dwordx2 v[192:193], v[150:151], off offset:1152
	global_load_dwordx2 v[194:195], v[150:151], off offset:1280
	global_load_dwordx2 v[196:197], v[150:151], off offset:1408
	s_and_b64 vcc, exec, s[10:11]
	s_cbranch_vccz .LBB0_1903
	s_barrier

; #define PG8_STAGE(bufoff, gbase, voff) do { _Pragma("unroll") for (int _i = 0; _i < 2; ++_i) \
;         __builtin_amdgcn_global_load_lds((const unsigned*)((const char*)(gbase) + (voff)[_i]), (PG8_LAS unsigned*)(lds + (bufoff) + ldsw + _i * 8192), 16, 0, 0); } while (0)
; #define PG8_LDA(dst, b, h) do { _Pragma("unroll") for (int m = 0; m < 4; ++m) _Pragma("unroll") for (int k = 0; k < 2; ++k) dst[m][k] = *(const PG8_LAS bf16x8*)(lds + PG8_SA(b, h) + aoff + m * 2048 + k * 1024); } while (0)
; #define PG8_LDB(dst, b, h) do { _Pragma("unroll") for (int n = 0; n < 2; ++n) _Pragma("unroll") for (int k = 0; k < 2; ++k) dst[n][k] = *(const PG8_LAS bf16x8*)(lds + PG8_SB(b, h) + boff + n * 2048 + k * 1024); } while (0)
; #define PG8_MMA(ai, bj, At, Bt) do { __builtin_amdgcn_s_setprio(1); _Pragma("unroll") for (int m = 0; m < 4; ++m) _Pragma("unroll") for (int n = 0; n < 2; ++n) _Pragma("unroll") for (int k = 0; k < 2; ++k) \
;         acc[ai][bj][m][n] = __builtin_amdgcn_mfma_f32_16x16x32_bf16(Bt[n][k], At[m][k], acc[ai][bj][m][n], 0, 0, 0); __builtin_amdgcn_s_setprio(0); } while (0)
; #define PG8_WAIT_V(n) asm volatile("s_waitcnt vmcnt(" #n ")" ::: "memory")
; #define PG8_WAIT_L(n) asm volatile("s_waitcnt lgkmcnt(" #n ")" ::: "memory")
; #define PG8_BAR __builtin_amdgcn_s_barrier()
; #define PG8_SCHED __builtin_amdgcn_sched_barrier(0)
; template <class Epi, class Sched, bool ALIGN_EPI = false, bool SP2 = false>
; __device__ __forceinline__ void gemm_phase(PG8_LAS unsigned char* lds, const Gemm g, const Sched& S, const Epi& E) {
;     ...
;         for (int t = 0; t < nt; t += 2) {
;             const bool last = (t == nt - 2);
;             const char* a1 = cA + (size_t)(t + 1) * kstep;
;             const char* a2 = last ? nA : cA + (size_t)(t + 2) * kstep; const char* b2 = last ? nB : cB + (size_t)(t + 2) * kstep;
;             const char* a3 = a2 + kstep; const char* b3 = b2 + kstep;
;             if (last && has_next) S.a_ready(nxt);
;             if constexpr (SP2) {
;             PG8_LDB(B0, 0, 0); PG8_LDB(B1, 0, 1); PG8_SCHED; PG8_LDA(At, 0, 0); PG8_STAGE(PG8_SA(1, 1), a1 + hstep, voffA);
;             PG8_WAIT_V(8); PG8_WAIT_L(0); PG8_BAR; PG8_MMA(0, 0, At, B0); PG8_MMA(0, 1, At, B1); PG8_BAR; PG8_SCHED;
;             PG8_LDA(At, 0, 1); PG8_STAGE(PG8_SB(0, 0), b2, voffB); PG8_STAGE(PG8_SB(0, 1), b2 + hstep, voffB); PG8_STAGE(PG8_SA(0, 0), a2, voffA);
.LBB0_1978:
	ds_read_b128 v[144:147], v151
	ds_read_b128 v[156:159], v151 offset:1024
	ds_read_b128 v[160:163], v151 offset:2048
	ds_read_b128 v[164:167], v151 offset:3072
	ds_read_b128 v[168:171], v152
	ds_read_b128 v[172:175], v152 offset:1024
	ds_read_b128 v[176:179], v152 offset:2048
	ds_read_b128 v[180:183], v152 offset:3072
	s_add_u32 s28, s26, 0x100
	s_addc_u32 s29, s27, 0
	s_cmp_eq_u32 s55, 40
	s_cselect_b32 s39, s1, s29
	s_cselect_b32 s38, s0, s28
	s_cselect_b32 s37, s25, s54
	s_cselect_b32 s36, s24, s53
	v_lshl_add_u64 v[218:219], s[26:27], 0, v[136:137]
	s_add_i32 m0, s33, 0xc000
	ds_read_b128 v[184:187], v153
	ds_read_b128 v[188:191], v153 offset:1024
	ds_read_b128 v[192:195], v153 offset:2048
	ds_read_b128 v[196:199], v153 offset:3072
	ds_read_b128 v[200:203], v153 offset:4096
	ds_read_b128 v[206:209], v153 offset:5120
	ds_read_b128 v[210:213], v153 offset:6144
	ds_read_b128 v[214:217], v153 offset:7168
	global_load_lds_dwordx4 v[218:219], off
	v_lshl_add_u64 v[218:219], s[26:27], 0, v[138:139]
	s_add_i32 m0, s33, 0xe000
	s_nop 0
	global_load_lds_dwordx4 v[218:219], off
	s_waitcnt vmcnt(8)
	s_waitcnt lgkmcnt(0)
	s_barrier
	s_setprio 1
	s_waitcnt lgkmcnt(0)
	v_mfma_f32_16x16x32_bf16 v[124:127], v[144:147], v[184:187], v[124:127]
	v_mfma_f32_16x16x32_bf16 v[120:123], v[160:163], v[184:187], v[120:123]
	v_mfma_f32_16x16x32_bf16 v[108:111], v[144:147], v[192:195], v[108:111]
	v_mfma_f32_16x16x32_bf16 v[104:107], v[160:163], v[192:195], v[104:107]
	v_mfma_f32_16x16x32_bf16 v[92:95], v[144:147], v[200:203], v[92:95]
	v_mfma_f32_16x16x32_bf16 v[88:91], v[160:163], v[200:203], v[88:91]
	v_mfma_f32_16x16x32_bf16 v[76:79], v[144:147], v[210:213], v[76:79]
	v_mfma_f32_16x16x32_bf16 v[72:75], v[160:163], v[210:213], v[72:75]
	v_mfma_f32_16x16x32_bf16 v[124:127], v[156:159], v[188:191], v[124:127]
	v_mfma_f32_16x16x32_bf16 v[120:123], v[164:167], v[188:191], v[120:123]
	v_mfma_f32_16x16x32_bf16 v[108:111], v[156:159], v[196:199], v[108:111]
	v_mfma_f32_16x16x32_bf16 v[104:107], v[164:167], v[196:199], v[104:107]
	v_mfma_f32_16x16x32_bf16 v[92:95], v[156:159], v[206:209], v[92:95]
	v_mfma_f32_16x16x32_bf16 v[88:91], v[164:167], v[206:209], v[88:91]
	v_mfma_f32_16x16x32_bf16 v[76:79], v[156:159], v[214:217], v[76:79]
	v_mfma_f32_16x16x32_bf16 v[72:75], v[164:167], v[214:217], v[72:75]
	s_setprio 0
	s_setprio 1
	v_mfma_f32_16x16x32_bf16 v[116:119], v[168:171], v[184:187], v[116:119]
	v_mfma_f32_16x16x32_bf16 v[112:115], v[176:179], v[184:187], v[112:115]
	v_mfma_f32_16x16x32_bf16 v[100:103], v[168:171], v[192:195], v[100:103]
	v_mfma_f32_16x16x32_bf16 v[96:99], v[176:179], v[192:195], v[96:99]
	v_mfma_f32_16x16x32_bf16 v[84:87], v[168:171], v[200:203], v[84:87]
	v_mfma_f32_16x16x32_bf16 v[80:83], v[176:179], v[200:203], v[80:83]
	v_mfma_f32_16x16x32_bf16 v[68:71], v[168:171], v[210:213], v[68:71]
	v_mfma_f32_16x16x32_bf16 v[64:67], v[176:179], v[210:213], v[64:67]
	v_mfma_f32_16x16x32_bf16 v[116:119], v[172:175], v[188:191], v[116:119]
	v_mfma_f32_16x16x32_bf16 v[112:115], v[180:183], v[188:191], v[112:115]
	v_mfma_f32_16x16x32_bf16 v[100:103], v[172:175], v[196:199], v[100:103]
	v_mfma_f32_16x16x32_bf16 v[96:99], v[180:183], v[196:199], v[96:99]
	v_mfma_f32_16x16x32_bf16 v[84:87], v[172:175], v[206:209], v[84:87]
	v_mfma_f32_16x16x32_bf16 v[80:83], v[180:183], v[206:209], v[80:83]
	v_mfma_f32_16x16x32_bf16 v[68:71], v[172:175], v[214:217], v[68:71]
	v_mfma_f32_16x16x32_bf16 v[64:67], v[180:183], v[214:217], v[64:67]
	s_setprio 0
	s_barrier
	s_add_i32 s26, s45, s15
	v_lshl_add_u64 v[218:219], s[36:37], 0, v[130:131]
	s_mov_b32 m0, s26
	ds_read_b128 v[184:187], v153 offset:16384
	ds_read_b128 v[188:191], v153 offset:17408
	ds_read_b128 v[192:195], v153 offset:18432
	ds_read_b128 v[196:199], v153 offset:19456
	ds_read_b128 v[200:203], v153 offset:20480
	ds_read_b128 v[206:209], v153 offset:21504
	ds_read_b128 v[210:213], v153 offset:22528
	ds_read_b128 v[214:217], v153 offset:23552
	global_load_lds_dwordx4 v[218:219], off
	s_add_i32 m0, s26, 0x2000
	s_add_u32 s26, s36, 0xb0000
	v_lshl_add_u64 v[220:221], s[36:37], 0, v[134:135]
	s_addc_u32 s27, s37, 0
	s_add_i32 s56, s46, s15
	global_load_lds_dwordx4 v[220:221], off
	v_lshl_add_u64 v[222:223], s[26:27], 0, v[130:131]
	s_mov_b32 m0, s56
	global_load_lds_dwordx4 v[222:223], off
	v_lshl_add_u64 v[222:223], s[26:27], 0, v[134:135]
	s_add_i32 m0, s56, 0x2000
	s_nop 0
	global_load_lds_dwordx4 v[222:223], off
	s_waitcnt vmcnt(6)
	s_waitcnt lgkmcnt(0)
	s_barrier
; #define PG8_STAGE(bufoff, gbase, voff) do { _Pragma("unroll") for (int _i = 0; _i < 2; ++_i) \
;         __builtin_amdgcn_global_load_lds((const unsigned*)((const char*)(gbase) + (voff)[_i]), (PG8_LAS unsigned*)(lds + (bufoff) + ldsw + _i * 8192), 16, 0, 0); } while (0)
; #define PG8_LDA(dst, b, h) do { _Pragma("unroll") for (int m = 0; m < 4; ++m) _Pragma("unroll") for (int k = 0; k < 2; ++k) dst[m][k] = *(const PG8_LAS bf16x8*)(lds + PG8_SA(b, h) + aoff + m * 2048 + k * 1024); } while (0)
; #define PG8_LDB(dst, b, h) do { _Pragma("unroll") for (int n = 0; n < 2; ++n) _Pragma("unroll") for (int k = 0; k < 2; ++k) dst[n][k] = *(const PG8_LAS bf16x8*)(lds + PG8_SB(b, h) + boff + n * 2048 + k * 1024); } while (0)
; #define PG8_MMA(ai, bj, At, Bt) do { __builtin_amdgcn_s_setprio(1); _Pragma("unroll") for (int m = 0; m < 4; ++m) _Pragma("unroll") for (int n = 0; n < 2; ++n) _Pragma("unroll") for (int k = 0; k < 2; ++k) \
;         acc[ai][bj][m][n] = __builtin_amdgcn_mfma_f32_16x16x32_bf16(Bt[n][k], At[m][k], acc[ai][bj][m][n], 0, 0, 0); __builtin_amdgcn_s_setprio(0); } while (0)
; #define PG8_WAIT_V(n) asm volatile("s_waitcnt vmcnt(" #n ")" ::: "memory")
; #define PG8_WAIT_L(n) asm volatile("s_waitcnt lgkmcnt(" #n ")" ::: "memory")
; #define PG8_BAR __builtin_amdgcn_s_barrier()
; #define PG8_SCHED __builtin_amdgcn_sched_barrier(0)
; template <class Epi, class Sched, bool ALIGN_EPI = false, bool SP2 = false>
; __device__ __forceinline__ void gemm_phase(PG8_LAS unsigned char* lds, const Gemm g, const Sched& S, const Epi& E) {
;     ...
;             PG8_WAIT_V(8); PG8_WAIT_L(0); PG8_BAR; PG8_MMA(1, 0, At, B0); PG8_MMA(1, 1, At, B1); PG8_BAR; PG8_SCHED;
;             PG8_LDB(B0, 1, 0); PG8_LDB(B1, 1, 1); PG8_SCHED; PG8_LDA(At, 1, 0); PG8_STAGE(PG8_SA(0, 1), a2 + hstep, voffA);
;             PG8_WAIT_V(8); PG8_WAIT_L(0); PG8_BAR; PG8_MMA(0, 0, At, B0); PG8_MMA(0, 1, At, B1); PG8_BAR; PG8_SCHED;
	s_setprio 1
	s_waitcnt lgkmcnt(0)
	v_mfma_f32_16x16x32_bf16 v[60:63], v[144:147], v[184:187], v[60:63]
	v_mfma_f32_16x16x32_bf16 v[56:59], v[160:163], v[184:187], v[56:59]
	v_mfma_f32_16x16x32_bf16 v[44:47], v[144:147], v[192:195], v[44:47]
	v_mfma_f32_16x16x32_bf16 v[40:43], v[160:163], v[192:195], v[40:43]
	v_mfma_f32_16x16x32_bf16 v[28:31], v[144:147], v[200:203], v[28:31]
	v_mfma_f32_16x16x32_bf16 v[24:27], v[160:163], v[200:203], v[24:27]
	v_mfma_f32_16x16x32_bf16 v[12:15], v[144:147], v[210:213], v[12:15]
	v_mfma_f32_16x16x32_bf16 v[8:11], v[160:163], v[210:213], v[8:11]
	v_mfma_f32_16x16x32_bf16 v[60:63], v[156:159], v[188:191], v[60:63]
	v_mfma_f32_16x16x32_bf16 v[56:59], v[164:167], v[188:191], v[56:59]
	v_mfma_f32_16x16x32_bf16 v[44:47], v[156:159], v[196:199], v[44:47]
	v_mfma_f32_16x16x32_bf16 v[40:43], v[164:167], v[196:199], v[40:43]
	v_mfma_f32_16x16x32_bf16 v[28:31], v[156:159], v[206:209], v[28:31]
	v_mfma_f32_16x16x32_bf16 v[24:27], v[164:167], v[206:209], v[24:27]
	v_lshl_add_u64 v[222:223], s[38:39], 0, v[128:129]
	s_mov_b32 m0, s33
	s_nop 0
	global_load_lds_dwordx4 v[222:223], off
	v_mfma_f32_16x16x32_bf16 v[12:15], v[156:159], v[214:217], v[12:15]
	v_mfma_f32_16x16x32_bf16 v[8:11], v[164:167], v[214:217], v[8:11]
	s_setprio 0
	s_setprio 1
	v_mfma_f32_16x16x32_bf16 v[52:55], v[168:171], v[184:187], v[52:55]
	v_mfma_f32_16x16x32_bf16 v[48:51], v[176:179], v[184:187], v[48:51]
	v_mfma_f32_16x16x32_bf16 v[36:39], v[168:171], v[192:195], v[36:39]
	v_mfma_f32_16x16x32_bf16 v[32:35], v[176:179], v[192:195], v[32:35]
	v_mfma_f32_16x16x32_bf16 v[20:23], v[168:171], v[200:203], v[20:23]
	v_mfma_f32_16x16x32_bf16 v[16:19], v[176:179], v[200:203], v[16:19]
	v_mfma_f32_16x16x32_bf16 v[4:7], v[168:171], v[210:213], v[4:7]
	v_mfma_f32_16x16x32_bf16 v[0:3], v[176:179], v[210:213], v[0:3]
	v_mfma_f32_16x16x32_bf16 v[52:55], v[172:175], v[188:191], v[52:55]
	v_mfma_f32_16x16x32_bf16 v[48:51], v[180:183], v[188:191], v[48:51]
	v_mfma_f32_16x16x32_bf16 v[36:39], v[172:175], v[196:199], v[36:39]
	v_mfma_f32_16x16x32_bf16 v[32:35], v[180:183], v[196:199], v[32:35]
	v_mfma_f32_16x16x32_bf16 v[20:23], v[172:175], v[206:209], v[20:23]
	v_mfma_f32_16x16x32_bf16 v[16:19], v[180:183], v[206:209], v[16:19]
	v_lshl_add_u64 v[224:225], s[38:39], 0, v[132:133]
	s_mov_b32 m0, s34
	s_nop 0
	global_load_lds_dwordx4 v[224:225], off
	v_mfma_f32_16x16x32_bf16 v[4:7], v[172:175], v[214:217], v[4:7]
	v_mfma_f32_16x16x32_bf16 v[0:3], v[180:183], v[214:217], v[0:3]
	s_setprio 0
	s_barrier
	s_add_i32 s56, 0, 0x18000
	v_add_u32_e32 v155, s56, v149
	s_add_i32 s57, 0, 0x1c000
	ds_read_b128 v[144:147], v155
	ds_read_b128 v[156:159], v155 offset:1024
	ds_read_b128 v[160:163], v155 offset:2048
	ds_read_b128 v[164:167], v155 offset:3072
	v_add_u32_e32 v155, s57, v149
	ds_read_b128 v[168:171], v155
	ds_read_b128 v[172:175], v155 offset:1024
	ds_read_b128 v[176:179], v155 offset:2048
	ds_read_b128 v[180:183], v155 offset:3072
	s_add_u32 s26, s38, 0xb0000
	s_addc_u32 s27, s39, 0
	s_mov_b32 m0, s40
	v_lshl_add_u64 v[226:227], s[26:27], 0, v[128:129]
	ds_read_b128 v[184:187], v153 offset:32768
	ds_read_b128 v[188:191], v153 offset:33792
	ds_read_b128 v[192:195], v153 offset:34816
	ds_read_b128 v[196:199], v153 offset:35840
	ds_read_b128 v[200:203], v153 offset:36864
	ds_read_b128 v[206:209], v153 offset:37888
	ds_read_b128 v[210:213], v153 offset:38912
	ds_read_b128 v[214:217], v153 offset:39936
	global_load_lds_dwordx4 v[226:227], off
	v_lshl_add_u64 v[226:227], s[26:27], 0, v[132:133]
	s_mov_b32 m0, s41
	s_nop 0
	global_load_lds_dwordx4 v[226:227], off
	s_waitcnt vmcnt(8)
	s_waitcnt lgkmcnt(0)
	s_barrier
	s_setprio 1
	s_waitcnt lgkmcnt(0)
	v_mfma_f32_16x16x32_bf16 v[124:127], v[144:147], v[184:187], v[124:127]
	v_mfma_f32_16x16x32_bf16 v[120:123], v[160:163], v[184:187], v[120:123]
	v_mfma_f32_16x16x32_bf16 v[108:111], v[144:147], v[192:195], v[108:111]
	v_mfma_f32_16x16x32_bf16 v[104:107], v[160:163], v[192:195], v[104:107]
	v_mfma_f32_16x16x32_bf16 v[92:95], v[144:147], v[200:203], v[92:95]
	v_mfma_f32_16x16x32_bf16 v[88:91], v[160:163], v[200:203], v[88:91]
	v_mfma_f32_16x16x32_bf16 v[76:79], v[144:147], v[210:213], v[76:79]
	v_mfma_f32_16x16x32_bf16 v[72:75], v[160:163], v[210:213], v[72:75]
	v_mfma_f32_16x16x32_bf16 v[124:127], v[156:159], v[188:191], v[124:127]
	v_mfma_f32_16x16x32_bf16 v[120:123], v[164:167], v[188:191], v[120:123]
	v_mfma_f32_16x16x32_bf16 v[108:111], v[156:159], v[196:199], v[108:111]
	v_mfma_f32_16x16x32_bf16 v[104:107], v[164:167], v[196:199], v[104:107]
	v_mfma_f32_16x16x32_bf16 v[92:95], v[156:159], v[206:209], v[92:95]
	v_mfma_f32_16x16x32_bf16 v[88:91], v[164:167], v[206:209], v[88:91]
	v_mfma_f32_16x16x32_bf16 v[76:79], v[156:159], v[214:217], v[76:79]
	v_mfma_f32_16x16x32_bf16 v[72:75], v[164:167], v[214:217], v[72:75]
	s_setprio 0
	s_setprio 1
	v_mfma_f32_16x16x32_bf16 v[116:119], v[168:171], v[184:187], v[116:119]
	v_mfma_f32_16x16x32_bf16 v[112:115], v[176:179], v[184:187], v[112:115]
	v_mfma_f32_16x16x32_bf16 v[100:103], v[168:171], v[192:195], v[100:103]
	v_mfma_f32_16x16x32_bf16 v[96:99], v[176:179], v[192:195], v[96:99]
	v_mfma_f32_16x16x32_bf16 v[84:87], v[168:171], v[200:203], v[84:87]
	v_mfma_f32_16x16x32_bf16 v[80:83], v[176:179], v[200:203], v[80:83]
	v_mfma_f32_16x16x32_bf16 v[68:71], v[168:171], v[210:213], v[68:71]
	v_mfma_f32_16x16x32_bf16 v[64:67], v[176:179], v[210:213], v[64:67]
	v_mfma_f32_16x16x32_bf16 v[116:119], v[172:175], v[188:191], v[116:119]
	v_mfma_f32_16x16x32_bf16 v[112:115], v[180:183], v[188:191], v[112:115]
	v_mfma_f32_16x16x32_bf16 v[100:103], v[172:175], v[196:199], v[100:103]
	v_mfma_f32_16x16x32_bf16 v[96:99], v[180:183], v[196:199], v[96:99]
	v_mfma_f32_16x16x32_bf16 v[84:87], v[172:175], v[206:209], v[84:87]
	v_mfma_f32_16x16x32_bf16 v[80:83], v[180:183], v[206:209], v[80:83]
	v_mfma_f32_16x16x32_bf16 v[68:71], v[172:175], v[214:217], v[68:71]
	v_mfma_f32_16x16x32_bf16 v[64:67], v[180:183], v[214:217], v[64:67]
	s_setprio 0
	s_barrier
; #define PG8_STAGE(bufoff, gbase, voff) do { _Pragma("unroll") for (int _i = 0; _i < 2; ++_i) \
;         __builtin_amdgcn_global_load_lds((const unsigned*)((const char*)(gbase) + (voff)[_i]), (PG8_LAS unsigned*)(lds + (bufoff) + ldsw + _i * 8192), 16, 0, 0); } while (0)
; #define PG8_LDA(dst, b, h) do { _Pragma("unroll") for (int m = 0; m < 4; ++m) _Pragma("unroll") for (int k = 0; k < 2; ++k) dst[m][k] = *(const PG8_LAS bf16x8*)(lds + PG8_SA(b, h) + aoff + m * 2048 + k * 1024); } while (0)
; #define PG8_MMA(ai, bj, At, Bt) do { __builtin_amdgcn_s_setprio(1); _Pragma("unroll") for (int m = 0; m < 4; ++m) _Pragma("unroll") for (int n = 0; n < 2; ++n) _Pragma("unroll") for (int k = 0; k < 2; ++k) \
;         acc[ai][bj][m][n] = __builtin_amdgcn_mfma_f32_16x16x32_bf16(Bt[n][k], At[m][k], acc[ai][bj][m][n], 0, 0, 0); __builtin_amdgcn_s_setprio(0); } while (0)
; #define PG8_WAIT_V(n) asm volatile("s_waitcnt vmcnt(" #n ")" ::: "memory")
; #define PG8_WAIT_L(n) asm volatile("s_waitcnt lgkmcnt(" #n ")" ::: "memory")
; #define PG8_BAR __builtin_amdgcn_s_barrier()
; #define PG8_SCHED __builtin_amdgcn_sched_barrier(0)
; template <class Epi, class Sched, bool ALIGN_EPI = false, bool SP2 = false>
; __device__ __forceinline__ void gemm_phase(PG8_LAS unsigned char* lds, const Gemm g, const Sched& S, const Epi& E) {
;     ...
;             PG8_LDA(At, 1, 1); PG8_STAGE(PG8_SB(1, 0), b3, voffB); PG8_STAGE(PG8_SB(1, 1), b3 + hstep, voffB); PG8_STAGE(PG8_SA(1, 0), a3, voffA);
;             PG8_WAIT_V(8); PG8_WAIT_L(0); PG8_BAR; PG8_MMA(1, 0, At, B0); PG8_MMA(1, 1, At, B1); PG8_BAR; PG8_SCHED;
	s_add_i32 s26, s56, s15
	v_lshl_add_u64 v[218:219], v[218:219], 0, s[12:13]
	s_mov_b32 m0, s26
	ds_read_b128 v[184:187], v153 offset:49152
	ds_read_b128 v[188:191], v153 offset:50176
	ds_read_b128 v[192:195], v153 offset:51200
	ds_read_b128 v[196:199], v153 offset:52224
	ds_read_b128 v[200:203], v153 offset:53248
	ds_read_b128 v[206:209], v153 offset:54272
	ds_read_b128 v[210:213], v153 offset:55296
	ds_read_b128 v[214:217], v153 offset:56320
	global_load_lds_dwordx4 v[218:219], off
	s_add_i32 m0, s26, 0x2000
	s_add_u32 s26, s36, 0xb0080
	v_lshl_add_u64 v[218:219], v[220:221], 0, s[12:13]
	s_addc_u32 s27, s37, 0
	s_add_i32 s36, s57, s15
	global_load_lds_dwordx4 v[218:219], off
	v_lshl_add_u64 v[218:219], s[26:27], 0, v[130:131]
	s_mov_b32 m0, s36
	s_nop 0
	global_load_lds_dwordx4 v[218:219], off
	v_lshl_add_u64 v[218:219], s[26:27], 0, v[134:135]
	s_add_i32 m0, s36, 0x2000
	s_nop 0
	global_load_lds_dwordx4 v[218:219], off
	s_waitcnt vmcnt(6)
	s_waitcnt lgkmcnt(0)
	s_barrier
	s_setprio 1
	s_waitcnt lgkmcnt(0)
	v_mfma_f32_16x16x32_bf16 v[60:63], v[144:147], v[184:187], v[60:63]
	v_mfma_f32_16x16x32_bf16 v[56:59], v[160:163], v[184:187], v[56:59]
	v_lshl_add_u64 v[218:219], v[222:223], 0, s[12:13]
	s_mov_b32 m0, s43
	s_nop 0
	global_load_lds_dwordx4 v[218:219], off
	v_mfma_f32_16x16x32_bf16 v[44:47], v[144:147], v[192:195], v[44:47]
	v_mfma_f32_16x16x32_bf16 v[40:43], v[160:163], v[192:195], v[40:43]
	v_mfma_f32_16x16x32_bf16 v[28:31], v[144:147], v[200:203], v[28:31]
	v_mfma_f32_16x16x32_bf16 v[24:27], v[160:163], v[200:203], v[24:27]
	v_lshl_add_u64 v[218:219], v[224:225], 0, s[12:13]
	s_mov_b32 m0, s44
	s_nop 0
	global_load_lds_dwordx4 v[218:219], off
	v_mfma_f32_16x16x32_bf16 v[12:15], v[144:147], v[210:213], v[12:15]
	v_mfma_f32_16x16x32_bf16 v[8:11], v[160:163], v[210:213], v[8:11]
	v_mfma_f32_16x16x32_bf16 v[60:63], v[156:159], v[188:191], v[60:63]
	v_mfma_f32_16x16x32_bf16 v[56:59], v[164:167], v[188:191], v[56:59]
	v_mfma_f32_16x16x32_bf16 v[44:47], v[156:159], v[196:199], v[44:47]
	v_mfma_f32_16x16x32_bf16 v[40:43], v[164:167], v[196:199], v[40:43]
	v_mfma_f32_16x16x32_bf16 v[28:31], v[156:159], v[206:209], v[28:31]
	v_mfma_f32_16x16x32_bf16 v[24:27], v[164:167], v[206:209], v[24:27]
	v_mfma_f32_16x16x32_bf16 v[12:15], v[156:159], v[214:217], v[12:15]
	v_mfma_f32_16x16x32_bf16 v[8:11], v[164:167], v[214:217], v[8:11]
	s_setprio 0
	s_setprio 1
	v_mfma_f32_16x16x32_bf16 v[52:55], v[168:171], v[184:187], v[52:55]
	v_mfma_f32_16x16x32_bf16 v[48:51], v[176:179], v[184:187], v[48:51]
	v_mfma_f32_16x16x32_bf16 v[36:39], v[168:171], v[192:195], v[36:39]
	v_mfma_f32_16x16x32_bf16 v[32:35], v[176:179], v[192:195], v[32:35]
	v_mfma_f32_16x16x32_bf16 v[20:23], v[168:171], v[200:203], v[20:23]
	v_mfma_f32_16x16x32_bf16 v[16:19], v[176:179], v[200:203], v[16:19]
	v_mfma_f32_16x16x32_bf16 v[4:7], v[168:171], v[210:213], v[4:7]
	v_mfma_f32_16x16x32_bf16 v[0:3], v[176:179], v[210:213], v[0:3]
	v_mfma_f32_16x16x32_bf16 v[52:55], v[172:175], v[188:191], v[52:55]
	v_mfma_f32_16x16x32_bf16 v[48:51], v[180:183], v[188:191], v[48:51]
	v_mfma_f32_16x16x32_bf16 v[36:39], v[172:175], v[196:199], v[36:39]
	v_mfma_f32_16x16x32_bf16 v[32:35], v[180:183], v[196:199], v[32:35]
	v_mfma_f32_16x16x32_bf16 v[20:23], v[172:175], v[206:209], v[20:23]
	v_mfma_f32_16x16x32_bf16 v[16:19], v[180:183], v[206:209], v[16:19]
	v_mfma_f32_16x16x32_bf16 v[4:7], v[172:175], v[214:217], v[4:7]
	v_mfma_f32_16x16x32_bf16 v[0:3], v[180:183], v[214:217], v[0:3]
	s_setprio 0
	s_barrier
	s_add_i32 s55, s55, 2
	s_add_u32 s53, s53, 0x100
	s_addc_u32 s54, s54, 0
	s_cmp_gt_u32 s55, 41
	s_mov_b64 s[26:27], s[28:29]
	s_cbranch_scc0 .LBB0_1978
	s_and_b64 vcc, exec, s[16:17]
	s_cbranch_vccz .LBB0_1981
	s_barrier
